# dynamic wave priority: s_setprio 3 at the start of each compute phase, 0 at its end (both wave groups)
# baseline (speedup 1.0000x reference)
.LBB0_103:
	s_ashr_i32 s23, s22, 31
	s_lshl_b64 s[2:3], s[22:23], 19
	s_add_u32 s58, s90, s2
	s_addc_u32 s59, s77, s3
	s_and_b64 s[2:3], s[46:47], exec
	s_cselect_b32 s1, s59, s49
	s_cselect_b32 s23, s58, s48
	s_add_u32 s34, s34, 0x3e080
	s_addc_u32 s35, s35, 0
	s_add_u32 s51, s48, 0x100
	v_mov_b32_e32 v2, 0
	s_addc_u32 s52, s49, 0
	s_mov_b32 s53, -2
	s_add_u32 s2, s34, 0xfffc2080
	s_addc_u32 s3, s35, -1
	s_add_i32 s12, 0, 0x10000
	v_add_u32_e32 v110, s12, v179
	ds_read_b128 v[98:101], v110
	ds_read_b128 v[102:105], v110 offset:1024
	ds_read_b128 v[106:109], v110 offset:2048
	ds_read_b128 v[110:113], v110 offset:3072
	s_cmp_eq_u32 s53, 12
	s_cselect_b32 s49, s97, s3
	s_cselect_b32 s48, s96, s2
	s_cselect_b32 s3, s1, s52
	s_cselect_b32 s2, s23, s51
	v_lshl_add_u64 v[174:175], s[34:35], 0, v[170:171]
	s_add_i32 m0, s85, 0xc000
	ds_read_b128 v[114:117], v184
	ds_read_b128 v[118:121], v184 offset:1024
	ds_read_b128 v[122:125], v184 offset:2048
	ds_read_b128 v[126:129], v184 offset:3072
	ds_read_b128 v[186:189], v184 offset:4096
	ds_read_b128 v[190:193], v184 offset:5120
	ds_read_b128 v[194:197], v184 offset:6144
	ds_read_b128 v[198:201], v184 offset:7168
	global_load_lds_dwordx4 v[174:175], off
	v_lshl_add_u64 v[174:175], s[34:35], 0, v[172:173]
	s_add_i32 m0, s85, 0xe000
	s_nop 0
	global_load_lds_dwordx4 v[174:175], off
	s_waitcnt lgkmcnt(8)
	s_add_i32 s54, 0, 0x14000
	v_add_u32_e32 v174, s54, v179
	s_add_i32 s12, s12, s78
	ds_read_b128 v[226:229], v174
	ds_read_b128 v[230:233], v174 offset:1024
	ds_read_b128 v[234:237], v174 offset:2048
	ds_read_b128 v[242:245], v174 offset:3072
	s_barrier
	s_waitcnt lgkmcnt(0)
	s_setprio 3
	s_nop 0
	v_mfma_f32_16x16x32_bf16 v[158:161], v[98:101], v[114:117], 0
	v_mfma_f32_16x16x32_bf16 v[154:157], v[106:109], v[114:117], 0
	v_mfma_f32_16x16x32_bf16 v[150:153], v[98:101], v[122:125], 0
	v_mfma_f32_16x16x32_bf16 v[146:149], v[106:109], v[122:125], 0
	v_mfma_f32_16x16x32_bf16 v[142:145], v[98:101], v[186:189], 0
	v_mfma_f32_16x16x32_bf16 v[138:141], v[106:109], v[186:189], 0
	v_mfma_f32_16x16x32_bf16 v[134:137], v[98:101], v[194:197], 0
	v_mfma_f32_16x16x32_bf16 v[130:133], v[106:109], v[194:197], 0
	v_mfma_f32_16x16x32_bf16 v[158:161], v[102:105], v[118:121], v[158:161]
	v_mfma_f32_16x16x32_bf16 v[154:157], v[110:113], v[118:121], v[154:157]
	v_mfma_f32_16x16x32_bf16 v[150:153], v[102:105], v[126:129], v[150:153]
	v_mfma_f32_16x16x32_bf16 v[146:149], v[110:113], v[126:129], v[146:149]
	v_mfma_f32_16x16x32_bf16 v[142:145], v[102:105], v[190:193], v[142:145]
	v_mfma_f32_16x16x32_bf16 v[138:141], v[110:113], v[190:193], v[138:141]
	v_mfma_f32_16x16x32_bf16 v[134:137], v[102:105], v[198:201], v[134:137]
	v_mfma_f32_16x16x32_bf16 v[130:133], v[110:113], v[198:201], v[130:133]
	v_mfma_f32_16x16x32_bf16 v[62:65], v[226:229], v[114:117], 0
	v_mfma_f32_16x16x32_bf16 v[58:61], v[234:237], v[114:117], 0
	v_mfma_f32_16x16x32_bf16 v[54:57], v[226:229], v[122:125], 0
	v_mfma_f32_16x16x32_bf16 v[50:53], v[234:237], v[122:125], 0
	v_mfma_f32_16x16x32_bf16 v[46:49], v[226:229], v[186:189], 0
	v_mfma_f32_16x16x32_bf16 v[42:45], v[234:237], v[186:189], 0
	v_mfma_f32_16x16x32_bf16 v[38:41], v[226:229], v[194:197], 0
	v_mfma_f32_16x16x32_bf16 v[34:37], v[234:237], v[194:197], 0
	v_mfma_f32_16x16x32_bf16 v[62:65], v[230:233], v[118:121], v[62:65]
	v_mfma_f32_16x16x32_bf16 v[58:61], v[242:245], v[118:121], v[58:61]
	v_mfma_f32_16x16x32_bf16 v[54:57], v[230:233], v[126:129], v[54:57]
	v_mfma_f32_16x16x32_bf16 v[50:53], v[242:245], v[126:129], v[50:53]
	s_mov_b32 m0, s85
	v_lshl_add_u64 v[248:249], s[48:49], 0, v[162:163]
	v_mfma_f32_16x16x32_bf16 v[46:49], v[230:233], v[190:193], v[46:49]
	v_mfma_f32_16x16x32_bf16 v[42:45], v[242:245], v[190:193], v[42:45]
	v_mfma_f32_16x16x32_bf16 v[38:41], v[230:233], v[198:201], v[38:41]
	v_mfma_f32_16x16x32_bf16 v[34:37], v[242:245], v[198:201], v[34:37]
	s_setprio 0
	s_barrier
	ds_read_b128 v[114:117], v184 offset:16384
	ds_read_b128 v[118:121], v184 offset:17408
	ds_read_b128 v[122:125], v184 offset:18432
	ds_read_b128 v[126:129], v184 offset:19456
	ds_read_b128 v[186:189], v184 offset:20480
	ds_read_b128 v[190:193], v184 offset:21504
	ds_read_b128 v[194:197], v184 offset:22528
	ds_read_b128 v[198:201], v184 offset:23552
	global_load_lds_dwordx4 v[248:249], off
	v_lshl_add_u64 v[250:251], s[48:49], 0, v[164:165]
	s_mov_b32 m0, s82
	s_nop 0
	global_load_lds_dwordx4 v[250:251], off
	v_lshl_add_u64 v[174:175], s[2:3], 0, v[0:1]
	s_mov_b32 m0, s12
	v_lshl_add_u64 v[246:247], s[2:3], 0, v[166:167]
	global_load_lds_dwordx4 v[174:175], off
	s_add_i32 m0, s12, 0x2000
	s_nop 0
	global_load_lds_dwordx4 v[246:247], off
	s_add_u32 s12, s2, 0x40000
	s_addc_u32 s13, s3, 0
	s_add_i32 s54, s54, s78
	v_lshl_add_u64 v[174:175], s[12:13], 0, v[0:1]
	s_mov_b32 m0, s54
	s_nop 0
	global_load_lds_dwordx4 v[174:175], off
	v_lshl_add_u64 v[174:175], s[12:13], 0, v[166:167]
	s_add_i32 m0, s54, 0x2000
	s_nop 0
	global_load_lds_dwordx4 v[174:175], off
	s_waitcnt vmcnt(6)
	s_barrier
	s_waitcnt lgkmcnt(0)
	s_setprio 3
	v_mfma_f32_16x16x32_bf16 v[94:97], v[98:101], v[114:117], 0
	v_mfma_f32_16x16x32_bf16 v[90:93], v[106:109], v[114:117], 0
	v_mfma_f32_16x16x32_bf16 v[86:89], v[98:101], v[122:125], 0
	v_mfma_f32_16x16x32_bf16 v[82:85], v[106:109], v[122:125], 0
	v_mfma_f32_16x16x32_bf16 v[78:81], v[98:101], v[186:189], 0
	v_mfma_f32_16x16x32_bf16 v[74:77], v[106:109], v[186:189], 0
	v_mfma_f32_16x16x32_bf16 v[70:73], v[98:101], v[194:197], 0
	v_mfma_f32_16x16x32_bf16 v[66:69], v[106:109], v[194:197], 0
	v_mfma_f32_16x16x32_bf16 v[94:97], v[102:105], v[118:121], v[94:97]
	v_mfma_f32_16x16x32_bf16 v[90:93], v[110:113], v[118:121], v[90:93]
	v_mfma_f32_16x16x32_bf16 v[86:89], v[102:105], v[126:129], v[86:89]
	v_mfma_f32_16x16x32_bf16 v[82:85], v[110:113], v[126:129], v[82:85]
	v_mfma_f32_16x16x32_bf16 v[78:81], v[102:105], v[190:193], v[78:81]
	v_mfma_f32_16x16x32_bf16 v[74:77], v[110:113], v[190:193], v[74:77]
	v_mfma_f32_16x16x32_bf16 v[70:73], v[102:105], v[198:201], v[70:73]
	v_mfma_f32_16x16x32_bf16 v[66:69], v[110:113], v[198:201], v[66:69]
	v_mfma_f32_16x16x32_bf16 v[30:33], v[226:229], v[114:117], 0
	v_mfma_f32_16x16x32_bf16 v[26:29], v[234:237], v[114:117], 0
	v_mfma_f32_16x16x32_bf16 v[22:25], v[226:229], v[122:125], 0
	v_mfma_f32_16x16x32_bf16 v[18:21], v[234:237], v[122:125], 0
	v_mfma_f32_16x16x32_bf16 v[14:17], v[226:229], v[186:189], 0
	v_mfma_f32_16x16x32_bf16 v[10:13], v[234:237], v[186:189], 0
	v_mfma_f32_16x16x32_bf16 v[6:9], v[226:229], v[194:197], 0
	v_mfma_f32_16x16x32_bf16 v[2:5], v[234:237], v[194:197], 0
	v_mfma_f32_16x16x32_bf16 v[30:33], v[230:233], v[118:121], v[30:33]
	v_mfma_f32_16x16x32_bf16 v[26:29], v[242:245], v[118:121], v[26:29]
	v_mfma_f32_16x16x32_bf16 v[22:25], v[230:233], v[126:129], v[22:25]
	v_mfma_f32_16x16x32_bf16 v[18:21], v[242:245], v[126:129], v[18:21]
	s_add_i32 s54, 0, 0x18000
	v_add_u32_e32 v110, s54, v179
	v_mfma_f32_16x16x32_bf16 v[14:17], v[230:233], v[190:193], v[14:17]
	v_mfma_f32_16x16x32_bf16 v[10:13], v[242:245], v[190:193], v[10:13]
	v_mfma_f32_16x16x32_bf16 v[6:9], v[230:233], v[198:201], v[6:9]
	v_mfma_f32_16x16x32_bf16 v[2:5], v[242:245], v[198:201], v[2:5]
	s_setprio 0
	s_barrier
	ds_read_b128 v[98:101], v110
	ds_read_b128 v[102:105], v110 offset:1024
	ds_read_b128 v[106:109], v110 offset:2048
	ds_read_b128 v[110:113], v110 offset:3072
	s_add_u32 s12, s48, 0x3e000
	s_addc_u32 s13, s49, 0
	s_mov_b32 m0, s89
	v_lshl_add_u64 v[226:227], s[12:13], 0, v[162:163]
	ds_read_b128 v[114:117], v184 offset:32768
	ds_read_b128 v[118:121], v184 offset:33792
	ds_read_b128 v[122:125], v184 offset:34816
	ds_read_b128 v[126:129], v184 offset:35840
	ds_read_b128 v[186:189], v184 offset:36864
	ds_read_b128 v[190:193], v184 offset:37888
	ds_read_b128 v[194:197], v184 offset:38912
	ds_read_b128 v[198:201], v184 offset:39936
	global_load_lds_dwordx4 v[226:227], off
	v_lshl_add_u64 v[226:227], s[12:13], 0, v[164:165]
	s_mov_b32 m0, s91
	s_nop 0
	global_load_lds_dwordx4 v[226:227], off
	s_waitcnt lgkmcnt(8)
	s_add_i32 s12, 0, 0x1c000
	s_add_i32 s13, s54, s78
	v_add_u32_e32 v242, s12, v179
	ds_read_b128 v[226:229], v242
	ds_read_b128 v[230:233], v242 offset:1024
	ds_read_b128 v[234:237], v242 offset:2048
	ds_read_b128 v[242:245], v242 offset:3072
	s_barrier
	s_waitcnt lgkmcnt(0)
	s_setprio 3
	s_nop 0
	v_mfma_f32_16x16x32_bf16 v[158:161], v[98:101], v[114:117], v[158:161]
	v_mfma_f32_16x16x32_bf16 v[154:157], v[106:109], v[114:117], v[154:157]
	v_mfma_f32_16x16x32_bf16 v[150:153], v[98:101], v[122:125], v[150:153]
	v_mfma_f32_16x16x32_bf16 v[146:149], v[106:109], v[122:125], v[146:149]
	v_mfma_f32_16x16x32_bf16 v[142:145], v[98:101], v[186:189], v[142:145]
	v_mfma_f32_16x16x32_bf16 v[138:141], v[106:109], v[186:189], v[138:141]
	v_mfma_f32_16x16x32_bf16 v[134:137], v[98:101], v[194:197], v[134:137]
	v_mfma_f32_16x16x32_bf16 v[130:133], v[106:109], v[194:197], v[130:133]
	v_mfma_f32_16x16x32_bf16 v[158:161], v[102:105], v[118:121], v[158:161]
	v_mfma_f32_16x16x32_bf16 v[154:157], v[110:113], v[118:121], v[154:157]
	v_mfma_f32_16x16x32_bf16 v[150:153], v[102:105], v[126:129], v[150:153]
	v_mfma_f32_16x16x32_bf16 v[146:149], v[110:113], v[126:129], v[146:149]
	v_mfma_f32_16x16x32_bf16 v[142:145], v[102:105], v[190:193], v[142:145]
	v_mfma_f32_16x16x32_bf16 v[138:141], v[110:113], v[190:193], v[138:141]
	v_mfma_f32_16x16x32_bf16 v[134:137], v[102:105], v[198:201], v[134:137]
	v_mfma_f32_16x16x32_bf16 v[130:133], v[110:113], v[198:201], v[130:133]
	v_mfma_f32_16x16x32_bf16 v[62:65], v[226:229], v[114:117], v[62:65]
	v_mfma_f32_16x16x32_bf16 v[58:61], v[234:237], v[114:117], v[58:61]
	v_mfma_f32_16x16x32_bf16 v[54:57], v[226:229], v[122:125], v[54:57]
	v_mfma_f32_16x16x32_bf16 v[50:53], v[234:237], v[122:125], v[50:53]
	v_mfma_f32_16x16x32_bf16 v[46:49], v[226:229], v[186:189], v[46:49]
	v_mfma_f32_16x16x32_bf16 v[42:45], v[234:237], v[186:189], v[42:45]
	v_mfma_f32_16x16x32_bf16 v[38:41], v[226:229], v[194:197], v[38:41]
	v_mfma_f32_16x16x32_bf16 v[34:37], v[234:237], v[194:197], v[34:37]
	v_mfma_f32_16x16x32_bf16 v[62:65], v[230:233], v[118:121], v[62:65]
	v_mfma_f32_16x16x32_bf16 v[58:61], v[242:245], v[118:121], v[58:61]
	v_mfma_f32_16x16x32_bf16 v[54:57], v[230:233], v[126:129], v[54:57]
	v_mfma_f32_16x16x32_bf16 v[50:53], v[242:245], v[126:129], v[50:53]
	s_mov_b32 m0, s79
	v_lshl_add_u64 v[174:175], v[248:249], 0, s[20:21]
	v_mfma_f32_16x16x32_bf16 v[46:49], v[230:233], v[190:193], v[46:49]
	v_mfma_f32_16x16x32_bf16 v[42:45], v[242:245], v[190:193], v[42:45]
	v_mfma_f32_16x16x32_bf16 v[38:41], v[230:233], v[198:201], v[38:41]
	v_mfma_f32_16x16x32_bf16 v[34:37], v[242:245], v[198:201], v[34:37]
	s_setprio 0
	s_barrier
	ds_read_b128 v[114:117], v184 offset:49152
	ds_read_b128 v[118:121], v184 offset:50176
	ds_read_b128 v[122:125], v184 offset:51200
	ds_read_b128 v[126:129], v184 offset:52224
	ds_read_b128 v[186:189], v184 offset:53248
	ds_read_b128 v[190:193], v184 offset:54272
	ds_read_b128 v[194:197], v184 offset:55296
	ds_read_b128 v[198:201], v184 offset:56320
	global_load_lds_dwordx4 v[174:175], off
	v_lshl_add_u64 v[174:175], v[250:251], 0, s[20:21]
	s_mov_b32 m0, s87
	s_nop 0
	global_load_lds_dwordx4 v[174:175], off
	v_lshl_add_u64 v[174:175], s[2:3], 0, v[0:1]
	v_lshl_add_u64 v[174:175], v[174:175], 0, s[20:21]
	s_mov_b32 m0, s13
	s_nop 0
	global_load_lds_dwordx4 v[174:175], off
	v_lshl_add_u64 v[174:175], v[246:247], 0, s[20:21]
	s_add_i32 m0, s13, 0x2000
	s_nop 0
	global_load_lds_dwordx4 v[174:175], off
	s_add_u32 s2, s2, 0x40080
	s_addc_u32 s3, s3, 0
	s_add_i32 s12, s12, s78
	v_lshl_add_u64 v[174:175], s[2:3], 0, v[0:1]
	s_mov_b32 m0, s12
	s_nop 0
	global_load_lds_dwordx4 v[174:175], off
	v_lshl_add_u64 v[174:175], s[2:3], 0, v[166:167]
	s_add_i32 m0, s12, 0x2000
	s_nop 0
	global_load_lds_dwordx4 v[174:175], off
	s_waitcnt vmcnt(6)
	s_barrier
	s_waitcnt lgkmcnt(0)
	s_setprio 3
	s_nop 0
	v_mfma_f32_16x16x32_bf16 v[94:97], v[98:101], v[114:117], v[94:97]
	v_mfma_f32_16x16x32_bf16 v[90:93], v[106:109], v[114:117], v[90:93]
	v_mfma_f32_16x16x32_bf16 v[86:89], v[98:101], v[122:125], v[86:89]
	v_mfma_f32_16x16x32_bf16 v[82:85], v[106:109], v[122:125], v[82:85]
	v_mfma_f32_16x16x32_bf16 v[78:81], v[98:101], v[186:189], v[78:81]
	v_mfma_f32_16x16x32_bf16 v[74:77], v[106:109], v[186:189], v[74:77]
	v_mfma_f32_16x16x32_bf16 v[70:73], v[98:101], v[194:197], v[70:73]
	v_mfma_f32_16x16x32_bf16 v[66:69], v[106:109], v[194:197], v[66:69]
	v_mfma_f32_16x16x32_bf16 v[94:97], v[102:105], v[118:121], v[94:97]
	v_mfma_f32_16x16x32_bf16 v[90:93], v[110:113], v[118:121], v[90:93]
	v_mfma_f32_16x16x32_bf16 v[86:89], v[102:105], v[126:129], v[86:89]
	v_mfma_f32_16x16x32_bf16 v[82:85], v[110:113], v[126:129], v[82:85]
	v_mfma_f32_16x16x32_bf16 v[78:81], v[102:105], v[190:193], v[78:81]
	v_mfma_f32_16x16x32_bf16 v[74:77], v[110:113], v[190:193], v[74:77]
	v_mfma_f32_16x16x32_bf16 v[70:73], v[102:105], v[198:201], v[70:73]
	v_mfma_f32_16x16x32_bf16 v[66:69], v[110:113], v[198:201], v[66:69]
	v_mfma_f32_16x16x32_bf16 v[30:33], v[226:229], v[114:117], v[30:33]
	v_mfma_f32_16x16x32_bf16 v[26:29], v[234:237], v[114:117], v[26:29]
	v_mfma_f32_16x16x32_bf16 v[22:25], v[226:229], v[122:125], v[22:25]
	v_mfma_f32_16x16x32_bf16 v[18:21], v[234:237], v[122:125], v[18:21]
	v_mfma_f32_16x16x32_bf16 v[14:17], v[226:229], v[186:189], v[14:17]
	v_mfma_f32_16x16x32_bf16 v[10:13], v[234:237], v[186:189], v[10:13]
	v_mfma_f32_16x16x32_bf16 v[6:9], v[226:229], v[194:197], v[6:9]
	v_mfma_f32_16x16x32_bf16 v[2:5], v[234:237], v[194:197], v[2:5]
	v_mfma_f32_16x16x32_bf16 v[30:33], v[230:233], v[118:121], v[30:33]
	v_mfma_f32_16x16x32_bf16 v[26:29], v[242:245], v[118:121], v[26:29]
	v_mfma_f32_16x16x32_bf16 v[22:25], v[230:233], v[126:129], v[22:25]
	v_mfma_f32_16x16x32_bf16 v[18:21], v[242:245], v[126:129], v[18:21]
	s_add_i32 s53, s53, 2
	s_add_u32 s34, s34, 0x100
	s_addc_u32 s35, s35, 0
	s_add_u32 s51, s51, 0x100
	s_addc_u32 s52, s52, 0
	s_cmp_gt_u32 s53, 13
	v_mfma_f32_16x16x32_bf16 v[14:17], v[230:233], v[190:193], v[14:17]
	v_mfma_f32_16x16x32_bf16 v[10:13], v[242:245], v[190:193], v[10:13]
	v_mfma_f32_16x16x32_bf16 v[6:9], v[230:233], v[198:201], v[6:9]
	v_mfma_f32_16x16x32_bf16 v[2:5], v[242:245], v[198:201], v[2:5]
	s_setprio 0
	s_barrier
	s_cbranch_scc1 .Lpeel_x_0
.LBB0_104:
	s_add_u32 s2, s34, 0xfffc2080
	s_addc_u32 s3, s35, -1
	s_add_i32 s12, 0, 0x10000
	v_add_u32_e32 v110, s12, v179
	ds_read_b128 v[98:101], v110
	ds_read_b128 v[102:105], v110 offset:1024
	ds_read_b128 v[106:109], v110 offset:2048
	ds_read_b128 v[110:113], v110 offset:3072
	s_cmp_eq_u32 s53, 12
	s_cselect_b32 s49, s97, s3
	s_cselect_b32 s48, s96, s2
	s_cselect_b32 s3, s1, s52
	s_cselect_b32 s2, s23, s51
	v_lshl_add_u64 v[174:175], s[34:35], 0, v[170:171]
	s_add_i32 m0, s85, 0xc000
	ds_read_b128 v[114:117], v184
	ds_read_b128 v[118:121], v184 offset:1024
	ds_read_b128 v[122:125], v184 offset:2048
	ds_read_b128 v[126:129], v184 offset:3072
	ds_read_b128 v[186:189], v184 offset:4096
	ds_read_b128 v[190:193], v184 offset:5120
	ds_read_b128 v[194:197], v184 offset:6144
	ds_read_b128 v[198:201], v184 offset:7168
	global_load_lds_dwordx4 v[174:175], off
	v_lshl_add_u64 v[174:175], s[34:35], 0, v[172:173]
	s_add_i32 m0, s85, 0xe000
	s_nop 0
	global_load_lds_dwordx4 v[174:175], off
	s_waitcnt lgkmcnt(8)
	s_add_i32 s54, 0, 0x14000
	v_add_u32_e32 v174, s54, v179
	s_add_i32 s12, s12, s78
	ds_read_b128 v[226:229], v174
	ds_read_b128 v[230:233], v174 offset:1024
	ds_read_b128 v[234:237], v174 offset:2048
	ds_read_b128 v[242:245], v174 offset:3072
	s_barrier
	s_waitcnt lgkmcnt(0)
	s_setprio 3
	s_nop 0
	v_mfma_f32_16x16x32_bf16 v[158:161], v[98:101], v[114:117], v[158:161]
	v_mfma_f32_16x16x32_bf16 v[154:157], v[106:109], v[114:117], v[154:157]
	v_mfma_f32_16x16x32_bf16 v[150:153], v[98:101], v[122:125], v[150:153]
	v_mfma_f32_16x16x32_bf16 v[146:149], v[106:109], v[122:125], v[146:149]
	v_mfma_f32_16x16x32_bf16 v[142:145], v[98:101], v[186:189], v[142:145]
	v_mfma_f32_16x16x32_bf16 v[138:141], v[106:109], v[186:189], v[138:141]
	v_mfma_f32_16x16x32_bf16 v[134:137], v[98:101], v[194:197], v[134:137]
	v_mfma_f32_16x16x32_bf16 v[130:133], v[106:109], v[194:197], v[130:133]
	v_mfma_f32_16x16x32_bf16 v[158:161], v[102:105], v[118:121], v[158:161]
	v_mfma_f32_16x16x32_bf16 v[154:157], v[110:113], v[118:121], v[154:157]
	v_mfma_f32_16x16x32_bf16 v[150:153], v[102:105], v[126:129], v[150:153]
	v_mfma_f32_16x16x32_bf16 v[146:149], v[110:113], v[126:129], v[146:149]
	v_mfma_f32_16x16x32_bf16 v[142:145], v[102:105], v[190:193], v[142:145]
	v_mfma_f32_16x16x32_bf16 v[138:141], v[110:113], v[190:193], v[138:141]
	v_mfma_f32_16x16x32_bf16 v[134:137], v[102:105], v[198:201], v[134:137]
	v_mfma_f32_16x16x32_bf16 v[130:133], v[110:113], v[198:201], v[130:133]
	v_mfma_f32_16x16x32_bf16 v[62:65], v[226:229], v[114:117], v[62:65]
	v_mfma_f32_16x16x32_bf16 v[58:61], v[234:237], v[114:117], v[58:61]
	v_mfma_f32_16x16x32_bf16 v[54:57], v[226:229], v[122:125], v[54:57]
	v_mfma_f32_16x16x32_bf16 v[50:53], v[234:237], v[122:125], v[50:53]
	v_mfma_f32_16x16x32_bf16 v[46:49], v[226:229], v[186:189], v[46:49]
	v_mfma_f32_16x16x32_bf16 v[42:45], v[234:237], v[186:189], v[42:45]
	v_mfma_f32_16x16x32_bf16 v[38:41], v[226:229], v[194:197], v[38:41]
	v_mfma_f32_16x16x32_bf16 v[34:37], v[234:237], v[194:197], v[34:37]
	v_mfma_f32_16x16x32_bf16 v[62:65], v[230:233], v[118:121], v[62:65]
	v_mfma_f32_16x16x32_bf16 v[58:61], v[242:245], v[118:121], v[58:61]
	v_mfma_f32_16x16x32_bf16 v[54:57], v[230:233], v[126:129], v[54:57]
	v_mfma_f32_16x16x32_bf16 v[50:53], v[242:245], v[126:129], v[50:53]
	s_mov_b32 m0, s85
	v_lshl_add_u64 v[248:249], s[48:49], 0, v[162:163]
	v_mfma_f32_16x16x32_bf16 v[46:49], v[230:233], v[190:193], v[46:49]
	v_mfma_f32_16x16x32_bf16 v[42:45], v[242:245], v[190:193], v[42:45]
	v_mfma_f32_16x16x32_bf16 v[38:41], v[230:233], v[198:201], v[38:41]
	v_mfma_f32_16x16x32_bf16 v[34:37], v[242:245], v[198:201], v[34:37]
	s_setprio 0
	s_barrier
	ds_read_b128 v[114:117], v184 offset:16384
	ds_read_b128 v[118:121], v184 offset:17408
	ds_read_b128 v[122:125], v184 offset:18432
	ds_read_b128 v[126:129], v184 offset:19456
	ds_read_b128 v[186:189], v184 offset:20480
	ds_read_b128 v[190:193], v184 offset:21504
	ds_read_b128 v[194:197], v184 offset:22528
	ds_read_b128 v[198:201], v184 offset:23552
	global_load_lds_dwordx4 v[248:249], off
	v_lshl_add_u64 v[250:251], s[48:49], 0, v[164:165]
	s_mov_b32 m0, s82
	s_nop 0
	global_load_lds_dwordx4 v[250:251], off
	v_lshl_add_u64 v[174:175], s[2:3], 0, v[0:1]
	s_mov_b32 m0, s12
	v_lshl_add_u64 v[246:247], s[2:3], 0, v[166:167]
	global_load_lds_dwordx4 v[174:175], off
	s_add_i32 m0, s12, 0x2000
	s_nop 0
	global_load_lds_dwordx4 v[246:247], off
	s_add_u32 s12, s2, 0x40000
	s_addc_u32 s13, s3, 0
	s_add_i32 s54, s54, s78
	v_lshl_add_u64 v[174:175], s[12:13], 0, v[0:1]
	s_mov_b32 m0, s54
	s_nop 0
	global_load_lds_dwordx4 v[174:175], off
	v_lshl_add_u64 v[174:175], s[12:13], 0, v[166:167]
	s_add_i32 m0, s54, 0x2000
	s_nop 0
	global_load_lds_dwordx4 v[174:175], off
	s_waitcnt vmcnt(6)
	s_barrier
	s_waitcnt lgkmcnt(0)
	s_setprio 3
	v_mfma_f32_16x16x32_bf16 v[94:97], v[98:101], v[114:117], v[94:97]
	v_mfma_f32_16x16x32_bf16 v[90:93], v[106:109], v[114:117], v[90:93]
	v_mfma_f32_16x16x32_bf16 v[86:89], v[98:101], v[122:125], v[86:89]
	v_mfma_f32_16x16x32_bf16 v[82:85], v[106:109], v[122:125], v[82:85]
	v_mfma_f32_16x16x32_bf16 v[78:81], v[98:101], v[186:189], v[78:81]
	v_mfma_f32_16x16x32_bf16 v[74:77], v[106:109], v[186:189], v[74:77]
	v_mfma_f32_16x16x32_bf16 v[70:73], v[98:101], v[194:197], v[70:73]
	v_mfma_f32_16x16x32_bf16 v[66:69], v[106:109], v[194:197], v[66:69]
	v_mfma_f32_16x16x32_bf16 v[94:97], v[102:105], v[118:121], v[94:97]
	v_mfma_f32_16x16x32_bf16 v[90:93], v[110:113], v[118:121], v[90:93]
	v_mfma_f32_16x16x32_bf16 v[86:89], v[102:105], v[126:129], v[86:89]
	v_mfma_f32_16x16x32_bf16 v[82:85], v[110:113], v[126:129], v[82:85]
	v_mfma_f32_16x16x32_bf16 v[78:81], v[102:105], v[190:193], v[78:81]
	v_mfma_f32_16x16x32_bf16 v[74:77], v[110:113], v[190:193], v[74:77]
	v_mfma_f32_16x16x32_bf16 v[70:73], v[102:105], v[198:201], v[70:73]
	v_mfma_f32_16x16x32_bf16 v[66:69], v[110:113], v[198:201], v[66:69]
	v_mfma_f32_16x16x32_bf16 v[30:33], v[226:229], v[114:117], v[30:33]
	v_mfma_f32_16x16x32_bf16 v[26:29], v[234:237], v[114:117], v[26:29]
	v_mfma_f32_16x16x32_bf16 v[22:25], v[226:229], v[122:125], v[22:25]
	v_mfma_f32_16x16x32_bf16 v[18:21], v[234:237], v[122:125], v[18:21]
	v_mfma_f32_16x16x32_bf16 v[14:17], v[226:229], v[186:189], v[14:17]
	v_mfma_f32_16x16x32_bf16 v[10:13], v[234:237], v[186:189], v[10:13]
	v_mfma_f32_16x16x32_bf16 v[6:9], v[226:229], v[194:197], v[6:9]
	v_mfma_f32_16x16x32_bf16 v[2:5], v[234:237], v[194:197], v[2:5]
	v_mfma_f32_16x16x32_bf16 v[30:33], v[230:233], v[118:121], v[30:33]
	v_mfma_f32_16x16x32_bf16 v[26:29], v[242:245], v[118:121], v[26:29]
	v_mfma_f32_16x16x32_bf16 v[22:25], v[230:233], v[126:129], v[22:25]
	v_mfma_f32_16x16x32_bf16 v[18:21], v[242:245], v[126:129], v[18:21]
	s_add_i32 s54, 0, 0x18000
	v_add_u32_e32 v110, s54, v179
	v_mfma_f32_16x16x32_bf16 v[14:17], v[230:233], v[190:193], v[14:17]
	v_mfma_f32_16x16x32_bf16 v[10:13], v[242:245], v[190:193], v[10:13]
	v_mfma_f32_16x16x32_bf16 v[6:9], v[230:233], v[198:201], v[6:9]
	v_mfma_f32_16x16x32_bf16 v[2:5], v[242:245], v[198:201], v[2:5]
	s_setprio 0
	s_barrier
	ds_read_b128 v[98:101], v110
	ds_read_b128 v[102:105], v110 offset:1024
	ds_read_b128 v[106:109], v110 offset:2048
	ds_read_b128 v[110:113], v110 offset:3072
	s_add_u32 s12, s48, 0x3e000
	s_addc_u32 s13, s49, 0
	s_mov_b32 m0, s89
	v_lshl_add_u64 v[226:227], s[12:13], 0, v[162:163]
	ds_read_b128 v[114:117], v184 offset:32768
	ds_read_b128 v[118:121], v184 offset:33792
	ds_read_b128 v[122:125], v184 offset:34816
	ds_read_b128 v[126:129], v184 offset:35840
	ds_read_b128 v[186:189], v184 offset:36864
	ds_read_b128 v[190:193], v184 offset:37888
	ds_read_b128 v[194:197], v184 offset:38912
	ds_read_b128 v[198:201], v184 offset:39936
	global_load_lds_dwordx4 v[226:227], off
	v_lshl_add_u64 v[226:227], s[12:13], 0, v[164:165]
	s_mov_b32 m0, s91
	s_nop 0
	global_load_lds_dwordx4 v[226:227], off
	s_waitcnt lgkmcnt(8)
	s_add_i32 s12, 0, 0x1c000
	s_add_i32 s13, s54, s78
	v_add_u32_e32 v242, s12, v179
	ds_read_b128 v[226:229], v242
	ds_read_b128 v[230:233], v242 offset:1024
	ds_read_b128 v[234:237], v242 offset:2048
	ds_read_b128 v[242:245], v242 offset:3072
	s_barrier
	s_waitcnt lgkmcnt(0)
	s_setprio 3
	s_nop 0
	v_mfma_f32_16x16x32_bf16 v[158:161], v[98:101], v[114:117], v[158:161]
	v_mfma_f32_16x16x32_bf16 v[154:157], v[106:109], v[114:117], v[154:157]
	v_mfma_f32_16x16x32_bf16 v[150:153], v[98:101], v[122:125], v[150:153]
	v_mfma_f32_16x16x32_bf16 v[146:149], v[106:109], v[122:125], v[146:149]
	v_mfma_f32_16x16x32_bf16 v[142:145], v[98:101], v[186:189], v[142:145]
	v_mfma_f32_16x16x32_bf16 v[138:141], v[106:109], v[186:189], v[138:141]
	v_mfma_f32_16x16x32_bf16 v[134:137], v[98:101], v[194:197], v[134:137]
	v_mfma_f32_16x16x32_bf16 v[130:133], v[106:109], v[194:197], v[130:133]
	v_mfma_f32_16x16x32_bf16 v[158:161], v[102:105], v[118:121], v[158:161]
	v_mfma_f32_16x16x32_bf16 v[154:157], v[110:113], v[118:121], v[154:157]
	v_mfma_f32_16x16x32_bf16 v[150:153], v[102:105], v[126:129], v[150:153]
	v_mfma_f32_16x16x32_bf16 v[146:149], v[110:113], v[126:129], v[146:149]
	v_mfma_f32_16x16x32_bf16 v[142:145], v[102:105], v[190:193], v[142:145]
	v_mfma_f32_16x16x32_bf16 v[138:141], v[110:113], v[190:193], v[138:141]
	v_mfma_f32_16x16x32_bf16 v[134:137], v[102:105], v[198:201], v[134:137]
	v_mfma_f32_16x16x32_bf16 v[130:133], v[110:113], v[198:201], v[130:133]
	v_mfma_f32_16x16x32_bf16 v[62:65], v[226:229], v[114:117], v[62:65]
	v_mfma_f32_16x16x32_bf16 v[58:61], v[234:237], v[114:117], v[58:61]
	v_mfma_f32_16x16x32_bf16 v[54:57], v[226:229], v[122:125], v[54:57]
	v_mfma_f32_16x16x32_bf16 v[50:53], v[234:237], v[122:125], v[50:53]
	v_mfma_f32_16x16x32_bf16 v[46:49], v[226:229], v[186:189], v[46:49]
	v_mfma_f32_16x16x32_bf16 v[42:45], v[234:237], v[186:189], v[42:45]
	v_mfma_f32_16x16x32_bf16 v[38:41], v[226:229], v[194:197], v[38:41]
	v_mfma_f32_16x16x32_bf16 v[34:37], v[234:237], v[194:197], v[34:37]
	v_mfma_f32_16x16x32_bf16 v[62:65], v[230:233], v[118:121], v[62:65]
	v_mfma_f32_16x16x32_bf16 v[58:61], v[242:245], v[118:121], v[58:61]
	v_mfma_f32_16x16x32_bf16 v[54:57], v[230:233], v[126:129], v[54:57]
	v_mfma_f32_16x16x32_bf16 v[50:53], v[242:245], v[126:129], v[50:53]
	s_mov_b32 m0, s79
	v_lshl_add_u64 v[174:175], v[248:249], 0, s[20:21]
	v_mfma_f32_16x16x32_bf16 v[46:49], v[230:233], v[190:193], v[46:49]
	v_mfma_f32_16x16x32_bf16 v[42:45], v[242:245], v[190:193], v[42:45]
	v_mfma_f32_16x16x32_bf16 v[38:41], v[230:233], v[198:201], v[38:41]
	v_mfma_f32_16x16x32_bf16 v[34:37], v[242:245], v[198:201], v[34:37]
	s_setprio 0
	s_barrier
	ds_read_b128 v[114:117], v184 offset:49152
	ds_read_b128 v[118:121], v184 offset:50176
	ds_read_b128 v[122:125], v184 offset:51200
	ds_read_b128 v[126:129], v184 offset:52224
	ds_read_b128 v[186:189], v184 offset:53248
	ds_read_b128 v[190:193], v184 offset:54272
	ds_read_b128 v[194:197], v184 offset:55296
	ds_read_b128 v[198:201], v184 offset:56320
	global_load_lds_dwordx4 v[174:175], off
	v_lshl_add_u64 v[174:175], v[250:251], 0, s[20:21]
	s_mov_b32 m0, s87
	s_nop 0
	global_load_lds_dwordx4 v[174:175], off
	v_lshl_add_u64 v[174:175], s[2:3], 0, v[0:1]
	v_lshl_add_u64 v[174:175], v[174:175], 0, s[20:21]
	s_mov_b32 m0, s13
	s_nop 0
	global_load_lds_dwordx4 v[174:175], off
	v_lshl_add_u64 v[174:175], v[246:247], 0, s[20:21]
	s_add_i32 m0, s13, 0x2000
	s_nop 0
	global_load_lds_dwordx4 v[174:175], off
	s_add_u32 s2, s2, 0x40080
	s_addc_u32 s3, s3, 0
	s_add_i32 s12, s12, s78
	v_lshl_add_u64 v[174:175], s[2:3], 0, v[0:1]
	s_mov_b32 m0, s12
	s_nop 0
	global_load_lds_dwordx4 v[174:175], off
	v_lshl_add_u64 v[174:175], s[2:3], 0, v[166:167]
	s_add_i32 m0, s12, 0x2000
	s_nop 0
	global_load_lds_dwordx4 v[174:175], off
	s_waitcnt vmcnt(6)
	s_barrier
	s_waitcnt lgkmcnt(0)
	s_setprio 3
	s_nop 0
	v_mfma_f32_16x16x32_bf16 v[94:97], v[98:101], v[114:117], v[94:97]
	v_mfma_f32_16x16x32_bf16 v[90:93], v[106:109], v[114:117], v[90:93]
	v_mfma_f32_16x16x32_bf16 v[86:89], v[98:101], v[122:125], v[86:89]
	v_mfma_f32_16x16x32_bf16 v[82:85], v[106:109], v[122:125], v[82:85]
	v_mfma_f32_16x16x32_bf16 v[78:81], v[98:101], v[186:189], v[78:81]
	v_mfma_f32_16x16x32_bf16 v[74:77], v[106:109], v[186:189], v[74:77]
	v_mfma_f32_16x16x32_bf16 v[70:73], v[98:101], v[194:197], v[70:73]
	v_mfma_f32_16x16x32_bf16 v[66:69], v[106:109], v[194:197], v[66:69]
	v_mfma_f32_16x16x32_bf16 v[94:97], v[102:105], v[118:121], v[94:97]
	v_mfma_f32_16x16x32_bf16 v[90:93], v[110:113], v[118:121], v[90:93]
	v_mfma_f32_16x16x32_bf16 v[86:89], v[102:105], v[126:129], v[86:89]
	v_mfma_f32_16x16x32_bf16 v[82:85], v[110:113], v[126:129], v[82:85]
	v_mfma_f32_16x16x32_bf16 v[78:81], v[102:105], v[190:193], v[78:81]
	v_mfma_f32_16x16x32_bf16 v[74:77], v[110:113], v[190:193], v[74:77]
	v_mfma_f32_16x16x32_bf16 v[70:73], v[102:105], v[198:201], v[70:73]
	v_mfma_f32_16x16x32_bf16 v[66:69], v[110:113], v[198:201], v[66:69]
	v_mfma_f32_16x16x32_bf16 v[30:33], v[226:229], v[114:117], v[30:33]
	v_mfma_f32_16x16x32_bf16 v[26:29], v[234:237], v[114:117], v[26:29]
	v_mfma_f32_16x16x32_bf16 v[22:25], v[226:229], v[122:125], v[22:25]
	v_mfma_f32_16x16x32_bf16 v[18:21], v[234:237], v[122:125], v[18:21]
	v_mfma_f32_16x16x32_bf16 v[14:17], v[226:229], v[186:189], v[14:17]
	v_mfma_f32_16x16x32_bf16 v[10:13], v[234:237], v[186:189], v[10:13]
	v_mfma_f32_16x16x32_bf16 v[6:9], v[226:229], v[194:197], v[6:9]
	v_mfma_f32_16x16x32_bf16 v[2:5], v[234:237], v[194:197], v[2:5]
	v_mfma_f32_16x16x32_bf16 v[30:33], v[230:233], v[118:121], v[30:33]
	v_mfma_f32_16x16x32_bf16 v[26:29], v[242:245], v[118:121], v[26:29]
	v_mfma_f32_16x16x32_bf16 v[22:25], v[230:233], v[126:129], v[22:25]
	v_mfma_f32_16x16x32_bf16 v[18:21], v[242:245], v[126:129], v[18:21]
	s_add_i32 s53, s53, 2
	s_add_u32 s34, s34, 0x100
	s_addc_u32 s35, s35, 0
	s_add_u32 s51, s51, 0x100
	s_addc_u32 s52, s52, 0
	s_cmp_gt_u32 s53, 13
	v_mfma_f32_16x16x32_bf16 v[14:17], v[230:233], v[190:193], v[14:17]
	v_mfma_f32_16x16x32_bf16 v[10:13], v[242:245], v[190:193], v[10:13]
	v_mfma_f32_16x16x32_bf16 v[6:9], v[230:233], v[198:201], v[6:9]
	v_mfma_f32_16x16x32_bf16 v[2:5], v[242:245], v[198:201], v[2:5]
	s_setprio 0
	s_barrier
	s_cbranch_scc0 .LBB0_104

.LBB0_149:
	v_ashrrev_i32_e32 v0, 2, v164
	v_mul_hi_i32 v2, v0, s22
	v_lshrrev_b32_e32 v4, 31, v2
	v_add_u32_e32 v159, v2, v4
	v_mul_lo_u32 v2, v159, 6
	s_waitcnt vmcnt(0)
	v_sub_u32_e32 v130, v0, v2
	s_mul_i32 s3, s62, 6
	v_add_u32_e32 v4, s3, v130
	v_ashrrev_i32_e32 v5, 31, v4
	v_lshlrev_b64 v[4:5], 2, v[4:5]
	v_mov_b32_e32 v3, v202
	v_lshl_add_u64 v[6:7], s[66:67], 0, v[4:5]
	global_load_dword v178, v[6:7], off
	v_and_b32_e32 v158, 15, v3
	v_bfe_u32 v8, v3, 4, 2
	v_lshlrev_b32_e32 v2, 7, v159
	v_lshl_add_u64 v[4:5], s[68:69], 0, v[4:5]
	v_lshlrev_b32_e32 v98, 6, v130
	global_load_dword v179, v[4:5], off
	v_ashrrev_i32_e32 v99, 31, v98
	v_mov_b64_e32 v[4:5], s[16:17]
	v_lshlrev_b64 v[134:135], 1, v[98:99]
	v_lshlrev_b32_e32 v102, 4, v8
	v_mov_b32_e32 v103, v1
	v_and_or_b32 v168, v165, s23, v158
	v_or_b32_e32 v167, v168, v2
	v_or_b32_e32 v166, 16, v167
	v_lshlrev_b32_e32 v0, 3, v8
	v_mad_i64_i32 v[6:7], s[14:15], v167, s57, v[4:5]
	v_mad_i64_i32 v[8:9], s[14:15], v166, s57, v[4:5]
	v_lshl_add_u64 v[100:101], v[6:7], 0, v[134:135]
	v_lshl_add_u64 v[104:105], v[8:9], 0, v[134:135]
	v_lshl_add_u64 v[6:7], v[100:101], 0, v[102:103]
	v_lshl_add_u64 v[8:9], v[104:105], 0, v[102:103]
	v_lshl_add_u64 v[100:101], v[100:101], 0, v[0:1]
	v_lshl_add_u64 v[106:107], v[100:101], 0, s[52:53]
	v_lshl_add_u64 v[132:133], s[24:25], 0, v[102:103]
	v_or_b32_e32 v171, 16, v168
	v_ashrrev_i32_e32 v131, 31, v130
	v_mov_b32_e32 v173, v1
	v_mov_b32_e32 v175, v1
	v_mov_b32_e32 v164, v180
	v_add_u32_e32 v180, v181, v180
	v_lshlrev_b32_e32 v165, 5, v164
	v_lshlrev_b32_e32 v10, 1, v3
	v_and_b32_e32 v10, 24, v10
	v_and_b32_e32 v3, 3, v3
	v_or3_b32 v3, v3, v10, v2
	v_or_b32_e32 v18, 64, v3
	v_mad_i64_i32 v[18:19], s[14:15], v18, s57, v[4:5]
	v_lshl_add_u64 v[18:19], v[18:19], 0, v[134:135]
	v_lshl_add_u64 v[34:35], v[18:19], 0, v[102:103]
	v_or_b32_e32 v18, 0x44, v3
	v_mad_i64_i32 v[18:19], s[14:15], v18, s57, v[4:5]
	v_lshl_add_u64 v[18:19], v[18:19], 0, v[134:135]
	v_lshl_add_u64 v[36:37], v[18:19], 0, v[102:103]
	v_or_b32_e32 v18, 0x60, v3
	v_mad_i64_i32 v[18:19], s[14:15], v18, s57, v[4:5]
	v_mad_i64_i32 v[10:11], s[14:15], v3, s57, v[4:5]
	v_or_b32_e32 v12, 4, v3
	v_or_b32_e32 v14, 32, v3
	v_or_b32_e32 v16, 36, v3
	v_lshl_add_u64 v[18:19], v[18:19], 0, v[134:135]
	v_or_b32_e32 v3, 0x64, v3
	v_mad_i64_i32 v[12:13], s[14:15], v12, s57, v[4:5]
	v_mad_i64_i32 v[14:15], s[14:15], v14, s57, v[4:5]
	v_mad_i64_i32 v[16:17], s[14:15], v16, s57, v[4:5]
	v_lshl_add_u64 v[94:95], v[18:19], 0, v[102:103]
	v_mad_i64_i32 v[4:5], s[14:15], v3, s57, v[4:5]
	v_or_b32_e32 v18, v98, v158
	v_ashrrev_i32_e32 v3, 31, v2
	v_lshl_add_u64 v[2:3], v[2:3], 1, s[18:19]
	v_mul_lo_u32 v18, v18, s35
	v_lshl_add_u64 v[2:3], v[2:3], 0, v[102:103]
	v_ashrrev_i32_e32 v19, 31, v18
	v_lshl_add_u64 v[110:111], v[18:19], 1, v[2:3]
	v_add_co_u32_e32 v112, vcc, s42, v110
	v_lshl_add_u64 v[12:13], v[12:13], 0, v[134:135]
	s_nop 0
	v_addc_co_u32_e32 v113, vcc, 0, v111, vcc
	v_add_co_u32_e32 v152, vcc, s43, v110
	v_lshl_add_u64 v[10:11], v[10:11], 0, v[134:135]
	v_lshl_add_u64 v[12:13], v[12:13], 0, v[102:103]
	v_lshl_add_u64 v[14:15], v[14:15], 0, v[134:135]
	v_lshl_add_u64 v[16:17], v[16:17], 0, v[134:135]
	v_addc_co_u32_e32 v153, vcc, 0, v111, vcc
	v_lshl_add_u64 v[10:11], v[10:11], 0, v[102:103]
	v_lshl_add_u64 v[14:15], v[14:15], 0, v[102:103]
	v_lshl_add_u64 v[16:17], v[16:17], 0, v[102:103]
	v_lshl_add_u64 v[4:5], v[4:5], 0, v[134:135]
	global_load_dwordx4 v[66:69], v[12:13], off offset:3648
	global_load_dwordx4 v[70:73], v[12:13], off offset:3584
	global_load_dwordx4 v[74:77], v[10:11], off offset:3648
	global_load_dwordx4 v[78:81], v[10:11], off offset:3584
	global_load_dwordx4 v[18:21], v[8:9], off offset:2880
	global_load_dwordx4 v[26:29], v[8:9], off offset:2816
	global_load_dwordx4 v[22:25], v[6:7], off offset:2880
	global_load_dwordx4 v[30:33], v[6:7], off offset:2816
	global_load_dwordx4 v[114:117], v[36:37], off offset:3648
	global_load_dwordx4 v[118:121], v[36:37], off offset:3584
	global_load_dwordx4 v[122:125], v[34:35], off offset:3648
	global_load_dwordx4 v[126:129], v[34:35], off offset:3584
	s_nop 0
	global_load_dwordx4 v[34:37], v[16:17], off offset:3648
	global_load_dwordx4 v[38:41], v[16:17], off offset:3584
	global_load_dwordx4 v[42:45], v[14:15], off offset:3648
	global_load_dwordx4 v[46:49], v[14:15], off offset:3584
	v_add_co_u32_e32 v154, vcc, s50, v110
	v_lshl_add_u64 v[4:5], v[4:5], 0, v[102:103]
	s_nop 0
	v_addc_co_u32_e32 v155, vcc, 0, v111, vcc
	global_load_dwordx4 v[50:53], v[112:113], off
	global_load_dwordx4 v[54:57], v[152:153], off
	global_load_dwordx4 v[58:61], v[154:155], off
	global_load_dwordx4 v[62:65], v[110:111], off
	global_load_dwordx4 v[82:85], v[4:5], off offset:3648
	global_load_dwordx4 v[86:89], v[4:5], off offset:3584
	global_load_dwordx4 v[90:93], v[94:95], off offset:3648
	s_nop 0
	global_load_dwordx4 v[94:97], v[94:95], off offset:3584
	s_nop 0
	global_load_dwordx4 v[2:5], v[112:113], off offset:64
	global_load_dwordx4 v[6:9], v[152:153], off offset:64
	global_load_dwordx4 v[10:13], v[154:155], off offset:64
	global_load_dwordx4 v[14:17], v[110:111], off offset:64
	v_add_co_u32_e32 v100, vcc, s51, v100
	v_lshl_add_u64 v[98:99], v[98:99], 2, s[38:39]
	s_nop 0
	v_addc_co_u32_e32 v101, vcc, 0, v101, vcc
	v_lshl_add_u64 v[156:157], v[98:99], 0, v[102:103]
	v_or_b32_e32 v108, 7, v0
	s_waitcnt vmcnt(0)
	v_mul_f32_e32 v169, 0x3fb8aa3b, v178
	v_mul_f32_e32 v170, 0x3fb8aa3b, v179
	global_load_dwordx2 v[150:151], v[100:101], off offset:1024
	global_load_dwordx2 v[148:149], v[106:107], off offset:32
	global_load_dwordx2 v[146:147], v[106:107], off offset:64
	global_load_dwordx2 v[144:145], v[106:107], off offset:96
	v_lshl_add_u64 v[100:101], v[104:105], 0, v[0:1]
	v_lshl_add_u64 v[104:105], v[100:101], 0, s[52:53]
	v_add_co_u32_e32 v100, vcc, s51, v100
	v_or_b32_e32 v106, 5, v0
	s_nop 0
	v_addc_co_u32_e32 v101, vcc, 0, v101, vcc
	global_load_dwordx2 v[142:143], v[100:101], off offset:1024
	global_load_dwordx2 v[140:141], v[104:105], off offset:32
	global_load_dwordx2 v[138:139], v[104:105], off offset:64
	global_load_dwordx2 v[136:137], v[104:105], off offset:96
	s_setprio 3
	v_mfma_f32_16x16x32_bf16 v[98:101], v[78:81], v[30:33], 0
	v_or_b32_e32 v107, 6, v0
	v_mfma_f32_16x16x32_bf16 v[78:81], v[78:81], v[26:29], 0
	v_mfma_f32_16x16x32_bf16 v[98:101], v[74:77], v[22:25], v[98:101]
	v_mfma_f32_16x16x32_bf16 v[74:77], v[74:77], v[18:21], v[78:81]
	v_mfma_f32_16x16x32_bf16 v[78:81], v[70:73], v[30:33], 0
	v_mfma_f32_16x16x32_bf16 v[70:73], v[70:73], v[26:29], 0
	v_mfma_f32_16x16x32_bf16 v[78:81], v[66:69], v[22:25], v[78:81]
	v_mfma_f32_16x16x32_bf16 v[66:69], v[66:69], v[18:21], v[70:73]
	s_nop 5
	v_sub_u32_e32 v71, v168, v0
	v_cvt_f32_u32_e32 v72, v71
	v_cmp_lt_i32_e32 vcc, -1, v71
	v_or_b32_e32 v70, 4, v0
	v_mul_f32_e32 v72, v169, v72
	v_exp_f32_e32 v72, v72
	s_nop 0
	v_cndmask_b32_e32 v72, 0, v72, vcc
	v_cmp_gt_i32_e32 vcc, 1, v71
	v_sub_u32_e32 v71, 0, v71
	v_cvt_f32_u32_e32 v71, v71
	v_mul_f32_e32 v71, v170, v71
	v_exp_f32_e32 v71, v71
	s_nop 0
	v_cndmask_b32_e32 v71, 0, v71, vcc
	v_add_f32_e32 v71, v72, v71
	v_or_b32_e32 v72, 1, v0
	v_sub_u32_e32 v73, v168, v72
	v_mul_f32_e32 v71, v71, v98
	v_cvt_f32_u32_e32 v98, v73
	v_cmp_lt_i32_e32 vcc, -1, v73
	v_sub_u32_e32 v72, v171, v72
	v_mul_f32_e32 v98, v169, v98
	v_exp_f32_e32 v98, v98
	s_nop 0
	v_cndmask_b32_e32 v98, 0, v98, vcc
	v_cmp_gt_i32_e32 vcc, 1, v73
	v_sub_u32_e32 v73, 0, v73
	v_cvt_f32_u32_e32 v73, v73
	v_mul_f32_e32 v73, v170, v73
	v_exp_f32_e32 v73, v73
	s_nop 0
	v_cndmask_b32_e32 v73, 0, v73, vcc
	v_add_f32_e32 v73, v98, v73
	v_or_b32_e32 v98, 2, v0
	v_mul_f32_e32 v73, v73, v99
	v_sub_u32_e32 v99, v168, v98
	v_cvt_f32_u32_e32 v102, v99
	v_cmp_lt_i32_e32 vcc, -1, v99
	v_mul_f32_e32 v102, v169, v102
	v_exp_f32_e32 v102, v102
	s_nop 0
	v_cndmask_b32_e32 v102, 0, v102, vcc
	v_cmp_gt_i32_e32 vcc, 1, v99
	v_sub_u32_e32 v99, 0, v99
	v_cvt_f32_u32_e32 v99, v99
	v_mul_f32_e32 v99, v170, v99
	v_exp_f32_e32 v99, v99
	s_nop 0
	v_cndmask_b32_e32 v99, 0, v99, vcc
	v_add_f32_e32 v99, v102, v99
	v_mul_f32_e32 v99, v99, v100
	v_or_b32_e32 v100, 3, v0
	v_sub_u32_e32 v102, v168, v100
	v_cvt_f32_u32_e32 v103, v102
	v_cmp_lt_i32_e32 vcc, -1, v102
	v_mul_f32_e32 v103, v169, v103
	v_exp_f32_e32 v103, v103
	s_nop 0
	v_cndmask_b32_e32 v103, 0, v103, vcc
	v_cmp_gt_i32_e32 vcc, 1, v102
	v_sub_u32_e32 v102, 0, v102
	v_cvt_f32_u32_e32 v102, v102
	v_mul_f32_e32 v102, v170, v102
	v_exp_f32_e32 v102, v102
	s_nop 0
	v_cndmask_b32_e32 v102, 0, v102, vcc
	v_add_f32_e32 v102, v103, v102
	v_mul_f32_e32 v101, v102, v101
	v_sub_u32_e32 v102, v168, v70
	v_cvt_f32_u32_e32 v103, v102
	v_cmp_lt_i32_e32 vcc, -1, v102
	v_sub_u32_e32 v70, v171, v70
	v_mul_f32_e32 v103, v169, v103
	v_exp_f32_e32 v103, v103
	s_nop 0
	v_cndmask_b32_e32 v103, 0, v103, vcc
	v_cmp_gt_i32_e32 vcc, 1, v102
	v_sub_u32_e32 v102, 0, v102
	v_cvt_f32_u32_e32 v102, v102
	v_mul_f32_e32 v102, v170, v102
	v_exp_f32_e32 v102, v102
	s_nop 0
	v_cndmask_b32_e32 v102, 0, v102, vcc
	v_add_f32_e32 v102, v103, v102
	v_mul_f32_e32 v78, v102, v78
	v_sub_u32_e32 v102, v168, v106
	v_cvt_f32_u32_e32 v103, v102
	v_cmp_lt_i32_e32 vcc, -1, v102
	v_mul_f32_e32 v103, v169, v103
	v_exp_f32_e32 v103, v103
	s_nop 0
	v_cndmask_b32_e32 v103, 0, v103, vcc
	v_cmp_gt_i32_e32 vcc, 1, v102
	v_sub_u32_e32 v102, 0, v102
	v_cvt_f32_u32_e32 v102, v102
	v_mul_f32_e32 v102, v170, v102
	v_exp_f32_e32 v102, v102
	s_nop 0
	v_cndmask_b32_e32 v102, 0, v102, vcc
	v_add_f32_e32 v102, v103, v102
	v_mul_f32_e32 v79, v102, v79
	v_sub_u32_e32 v102, v168, v107
	v_cvt_f32_u32_e32 v103, v102
	v_cmp_lt_i32_e32 vcc, -1, v102
	v_cvt_pk_bf16_f32 v104, v78, v79
	v_mul_f32_e32 v103, v169, v103
	v_exp_f32_e32 v103, v103
	s_nop 0
	v_cndmask_b32_e32 v103, 0, v103, vcc
	v_cmp_gt_i32_e32 vcc, 1, v102
	v_sub_u32_e32 v102, 0, v102
	v_cvt_f32_u32_e32 v102, v102
	v_mul_f32_e32 v102, v170, v102
	v_exp_f32_e32 v102, v102
	s_nop 0
	v_cndmask_b32_e32 v102, 0, v102, vcc
	v_add_f32_e32 v102, v103, v102
	v_mul_f32_e32 v80, v102, v80
	v_sub_u32_e32 v102, v168, v108
	v_cvt_f32_u32_e32 v103, v102
	v_cmp_lt_i32_e32 vcc, -1, v102
	v_mul_f32_e32 v103, v169, v103
	v_exp_f32_e32 v103, v103
	s_nop 0
	v_cndmask_b32_e32 v103, 0, v103, vcc
	v_cmp_gt_i32_e32 vcc, 1, v102
	v_sub_u32_e32 v102, 0, v102
	v_cvt_f32_u32_e32 v102, v102
	v_mul_f32_e32 v102, v170, v102
	v_exp_f32_e32 v102, v102
	s_nop 0
	v_cndmask_b32_e32 v102, 0, v102, vcc
	v_add_f32_e32 v102, v103, v102
	v_mul_f32_e32 v81, v102, v81
	v_cvt_pk_bf16_f32 v102, v71, v73
	v_sub_u32_e32 v71, v171, v0
	v_cvt_f32_u32_e32 v73, v71
	v_cmp_lt_i32_e32 vcc, -1, v71
	v_cvt_pk_bf16_f32 v103, v99, v101
	v_cvt_pk_bf16_f32 v105, v80, v81
	v_mul_f32_e32 v73, v169, v73
	v_exp_f32_e32 v73, v73
	v_mfma_f32_16x16x32_bf16 v[78:81], v[54:57], v[102:105], 0
	v_cndmask_b32_e32 v73, 0, v73, vcc
	v_cmp_gt_i32_e32 vcc, 1, v71
	v_sub_u32_e32 v71, 0, v71
	v_cvt_f32_u32_e32 v71, v71
	v_mul_f32_e32 v71, v170, v71
	v_exp_f32_e32 v71, v71
	s_nop 0
	v_cndmask_b32_e32 v71, 0, v71, vcc
	v_add_f32_e32 v71, v73, v71
	v_cvt_f32_u32_e32 v73, v72
	v_cmp_lt_i32_e32 vcc, -1, v72
	v_mul_f32_e32 v71, v71, v74
	v_mul_f32_e32 v73, v169, v73
	v_exp_f32_e32 v73, v73
	s_nop 0
	v_cndmask_b32_e32 v73, 0, v73, vcc
	v_cmp_gt_i32_e32 vcc, 1, v72
	v_sub_u32_e32 v72, 0, v72
	v_cvt_f32_u32_e32 v72, v72
	v_mul_f32_e32 v72, v170, v72
	v_exp_f32_e32 v72, v72
	s_nop 0
	v_cndmask_b32_e32 v72, 0, v72, vcc
	v_add_f32_e32 v72, v73, v72
	v_sub_u32_e32 v73, v171, v98
	v_cvt_f32_u32_e32 v74, v73
	v_cmp_lt_i32_e32 vcc, -1, v73
	v_mul_f32_e32 v72, v72, v75
	v_mul_f32_e32 v74, v169, v74
	v_exp_f32_e32 v74, v74
	s_nop 0
	v_cndmask_b32_e32 v74, 0, v74, vcc
	v_cmp_gt_i32_e32 vcc, 1, v73
	v_sub_u32_e32 v73, 0, v73
	v_cvt_f32_u32_e32 v73, v73
	v_mul_f32_e32 v73, v170, v73
	v_exp_f32_e32 v73, v73
	s_nop 0
	v_cndmask_b32_e32 v73, 0, v73, vcc
	v_add_f32_e32 v73, v74, v73
	v_sub_u32_e32 v74, v171, v100
	v_cvt_f32_u32_e32 v75, v74
	v_cmp_lt_i32_e32 vcc, -1, v74
	v_mul_f32_e32 v73, v73, v76
	v_mul_f32_e32 v75, v169, v75
	v_exp_f32_e32 v75, v75
	s_nop 0
	v_cndmask_b32_e32 v75, 0, v75, vcc
	v_cmp_gt_i32_e32 vcc, 1, v74
	v_sub_u32_e32 v74, 0, v74
	v_cvt_f32_u32_e32 v74, v74
	v_mul_f32_e32 v74, v170, v74
	v_exp_f32_e32 v74, v74
	s_nop 0
	v_cndmask_b32_e32 v74, 0, v74, vcc
	v_add_f32_e32 v74, v75, v74
	v_cvt_f32_u32_e32 v75, v70
	v_cmp_lt_i32_e32 vcc, -1, v70
	v_mul_f32_e32 v74, v74, v77
	v_mul_f32_e32 v75, v169, v75
	v_exp_f32_e32 v75, v75
	s_nop 0
	v_cndmask_b32_e32 v75, 0, v75, vcc
	v_cmp_gt_i32_e32 vcc, 1, v70
	v_sub_u32_e32 v70, 0, v70
	v_cvt_f32_u32_e32 v70, v70
	v_mul_f32_e32 v70, v170, v70
	v_exp_f32_e32 v70, v70
	s_nop 0
	v_cndmask_b32_e32 v70, 0, v70, vcc
	v_add_f32_e32 v70, v75, v70
	v_mul_f32_e32 v66, v70, v66
	v_sub_u32_e32 v70, v171, v106
	v_cvt_f32_u32_e32 v75, v70
	v_cmp_lt_i32_e32 vcc, -1, v70
	v_cvt_pk_bf16_f32 v106, v71, v72
	v_mul_f32_e32 v75, v169, v75
	v_exp_f32_e32 v75, v75
	s_nop 0
	v_cndmask_b32_e32 v75, 0, v75, vcc
	v_cmp_gt_i32_e32 vcc, 1, v70
	v_sub_u32_e32 v70, 0, v70
	v_cvt_f32_u32_e32 v70, v70
	v_mul_f32_e32 v70, v170, v70
	v_exp_f32_e32 v70, v70
	s_nop 0
	v_cndmask_b32_e32 v70, 0, v70, vcc
	v_add_f32_e32 v70, v75, v70
	v_mul_f32_e32 v67, v70, v67
	v_sub_u32_e32 v70, v171, v107
	v_cvt_f32_u32_e32 v75, v70
	v_cmp_lt_i32_e32 vcc, -1, v70
	v_cvt_pk_bf16_f32 v107, v73, v74
	v_mul_f32_e32 v75, v169, v75
	v_exp_f32_e32 v75, v75
	s_nop 0
	v_cndmask_b32_e32 v75, 0, v75, vcc
	v_cmp_gt_i32_e32 vcc, 1, v70
	v_sub_u32_e32 v70, 0, v70
	v_cvt_f32_u32_e32 v70, v70
	v_mul_f32_e32 v70, v170, v70
	v_exp_f32_e32 v70, v70
	s_nop 0
	v_cndmask_b32_e32 v70, 0, v70, vcc
	v_add_f32_e32 v70, v75, v70
	v_mul_f32_e32 v68, v70, v68
	v_sub_u32_e32 v70, v171, v108
	v_cvt_f32_u32_e32 v75, v70
	v_cmp_lt_i32_e32 vcc, -1, v70
	v_cvt_pk_bf16_f32 v108, v66, v67
	v_mul_f32_e32 v75, v169, v75
	v_exp_f32_e32 v75, v75
	s_nop 0
	v_cndmask_b32_e32 v75, 0, v75, vcc
	v_cmp_gt_i32_e32 vcc, 1, v70
	v_sub_u32_e32 v70, 0, v70
	v_cvt_f32_u32_e32 v70, v70
	v_mul_f32_e32 v70, v170, v70
	v_exp_f32_e32 v70, v70
	s_nop 0
	v_cndmask_b32_e32 v70, 0, v70, vcc
	v_add_f32_e32 v70, v75, v70
	v_mul_f32_e32 v69, v70, v69
	v_cvt_pk_bf16_f32 v109, v68, v69
	v_mfma_f32_16x16x32_bf16 v[66:69], v[62:65], v[102:105], 0
	v_mfma_f32_16x16x32_bf16 v[62:65], v[62:65], v[106:109], 0
	v_mfma_f32_16x16x32_bf16 v[70:73], v[58:61], v[102:105], 0
	v_mfma_f32_16x16x32_bf16 v[74:77], v[58:61], v[106:109], 0
	v_mfma_f32_16x16x32_bf16 v[98:101], v[54:57], v[106:109], 0
	v_or_b32_e32 v55, 32, v0
	v_or_b32_e32 v54, 36, v0
	v_mfma_f32_16x16x32_bf16 v[102:105], v[50:53], v[102:105], 0
	v_mfma_f32_16x16x32_bf16 v[106:109], v[50:53], v[106:109], 0
	v_mfma_f32_16x16x32_bf16 v[50:53], v[46:49], v[30:33], 0
	v_mfma_f32_16x16x32_bf16 v[46:49], v[46:49], v[26:29], 0
	v_mfma_f32_16x16x32_bf16 v[50:53], v[42:45], v[22:25], v[50:53]
	v_mfma_f32_16x16x32_bf16 v[42:45], v[42:45], v[18:21], v[46:49]
	v_mfma_f32_16x16x32_bf16 v[46:49], v[38:41], v[30:33], 0
	v_mfma_f32_16x16x32_bf16 v[38:41], v[38:41], v[26:29], 0
	v_mfma_f32_16x16x32_bf16 v[46:49], v[34:37], v[22:25], v[46:49]
	v_mfma_f32_16x16x32_bf16 v[34:37], v[34:37], v[18:21], v[38:41]
	s_nop 5
	v_sub_u32_e32 v38, v168, v55
	v_cvt_f32_u32_e32 v39, v38
	v_cmp_lt_i32_e32 vcc, -1, v38
	v_mul_f32_e32 v39, v169, v39
	v_exp_f32_e32 v39, v39
	s_nop 0
	v_cndmask_b32_e32 v39, 0, v39, vcc
	v_cmp_gt_i32_e32 vcc, 1, v38
	v_sub_u32_e32 v38, 0, v38
	v_cvt_f32_u32_e32 v38, v38
	v_mul_f32_e32 v38, v170, v38
	v_exp_f32_e32 v38, v38
	s_nop 0
	v_cndmask_b32_e32 v38, 0, v38, vcc
	v_add_f32_e32 v38, v39, v38
	v_mul_f32_e32 v38, v38, v50
	v_or_b32_e32 v50, 33, v0
	v_sub_u32_e32 v39, v168, v50
	v_cvt_f32_u32_e32 v40, v39
	v_cmp_lt_i32_e32 vcc, -1, v39
	v_mul_f32_e32 v40, v169, v40
	v_exp_f32_e32 v40, v40
	s_nop 0
	v_cndmask_b32_e32 v40, 0, v40, vcc
	v_cmp_gt_i32_e32 vcc, 1, v39
	v_sub_u32_e32 v39, 0, v39
	v_cvt_f32_u32_e32 v39, v39
	v_mul_f32_e32 v39, v170, v39
	v_exp_f32_e32 v39, v39
	s_nop 0
	v_cndmask_b32_e32 v39, 0, v39, vcc
	v_add_f32_e32 v39, v40, v39
	v_mul_f32_e32 v39, v39, v51
	v_or_b32_e32 v51, 34, v0
	v_sub_u32_e32 v40, v168, v51
	v_cvt_f32_u32_e32 v41, v40
	v_cmp_lt_i32_e32 vcc, -1, v40
	v_cvt_pk_bf16_f32 v38, v38, v39
	v_mul_f32_e32 v41, v169, v41
	v_exp_f32_e32 v41, v41
	s_nop 0
	v_cndmask_b32_e32 v41, 0, v41, vcc
	v_cmp_gt_i32_e32 vcc, 1, v40
	v_sub_u32_e32 v40, 0, v40
	v_cvt_f32_u32_e32 v40, v40
	v_mul_f32_e32 v40, v170, v40
	v_exp_f32_e32 v40, v40
	s_nop 0
	v_cndmask_b32_e32 v40, 0, v40, vcc
	v_add_f32_e32 v40, v41, v40
	v_mul_f32_e32 v40, v40, v52
	v_or_b32_e32 v52, 35, v0
	v_sub_u32_e32 v41, v168, v52
	v_cvt_f32_u32_e32 v56, v41
	v_cmp_lt_i32_e32 vcc, -1, v41
	v_mul_f32_e32 v56, v169, v56
	v_exp_f32_e32 v56, v56
	s_nop 0
	v_cndmask_b32_e32 v56, 0, v56, vcc
	v_cmp_gt_i32_e32 vcc, 1, v41
	v_sub_u32_e32 v41, 0, v41
	v_cvt_f32_u32_e32 v41, v41
	v_mul_f32_e32 v41, v170, v41
	v_exp_f32_e32 v41, v41
	s_nop 0
	v_cndmask_b32_e32 v41, 0, v41, vcc
	v_add_f32_e32 v41, v56, v41
	v_mul_f32_e32 v41, v41, v53
	v_sub_u32_e32 v53, v168, v54
	v_cvt_f32_u32_e32 v56, v53
	v_cmp_lt_i32_e32 vcc, -1, v53
	v_cvt_pk_bf16_f32 v39, v40, v41
	v_mul_f32_e32 v56, v169, v56
	v_exp_f32_e32 v56, v56
	s_nop 0
	v_cndmask_b32_e32 v56, 0, v56, vcc
	v_cmp_gt_i32_e32 vcc, 1, v53
	v_sub_u32_e32 v53, 0, v53
	v_cvt_f32_u32_e32 v53, v53
	v_mul_f32_e32 v53, v170, v53
	v_exp_f32_e32 v53, v53
	s_nop 0
	v_cndmask_b32_e32 v53, 0, v53, vcc
	v_add_f32_e32 v53, v56, v53
	v_mul_f32_e32 v46, v53, v46
	v_or_b32_e32 v53, 37, v0
	v_sub_u32_e32 v56, v168, v53
	v_cvt_f32_u32_e32 v57, v56
	v_cmp_lt_i32_e32 vcc, -1, v56
	v_mul_f32_e32 v57, v169, v57
	v_exp_f32_e32 v57, v57
	s_nop 0
	v_cndmask_b32_e32 v57, 0, v57, vcc
	v_cmp_gt_i32_e32 vcc, 1, v56
	v_sub_u32_e32 v56, 0, v56
	v_cvt_f32_u32_e32 v56, v56
	v_mul_f32_e32 v56, v170, v56
	v_exp_f32_e32 v56, v56
	s_nop 0
	v_cndmask_b32_e32 v56, 0, v56, vcc
	v_add_f32_e32 v56, v57, v56
	v_mul_f32_e32 v47, v56, v47
	v_or_b32_e32 v56, 38, v0
	v_sub_u32_e32 v57, v168, v56
	v_cvt_f32_u32_e32 v58, v57
	v_cmp_lt_i32_e32 vcc, -1, v57
	v_cvt_pk_bf16_f32 v40, v46, v47
	v_sub_u32_e32 v46, v171, v55
	v_mul_f32_e32 v58, v169, v58
	v_exp_f32_e32 v58, v58
	v_cvt_f32_u32_e32 v47, v46
	v_cndmask_b32_e32 v58, 0, v58, vcc
	v_cmp_gt_i32_e32 vcc, 1, v57
	v_sub_u32_e32 v57, 0, v57
	v_cvt_f32_u32_e32 v57, v57
	v_mul_f32_e32 v47, v169, v47
	v_exp_f32_e32 v47, v47
	v_mul_f32_e32 v57, v170, v57
	v_exp_f32_e32 v57, v57
	s_nop 0
	v_cndmask_b32_e32 v57, 0, v57, vcc
	v_add_f32_e32 v57, v58, v57
	v_mul_f32_e32 v48, v57, v48
	v_or_b32_e32 v57, 39, v0
	v_sub_u32_e32 v58, v168, v57
	v_cvt_f32_u32_e32 v59, v58
	v_cmp_lt_i32_e32 vcc, -1, v58
	v_mul_f32_e32 v59, v169, v59
	v_exp_f32_e32 v59, v59
	s_nop 0
	v_cndmask_b32_e32 v59, 0, v59, vcc
	v_cmp_gt_i32_e32 vcc, 1, v58
	v_sub_u32_e32 v58, 0, v58
	v_cvt_f32_u32_e32 v58, v58
	v_mul_f32_e32 v58, v170, v58
	v_exp_f32_e32 v58, v58
	s_nop 0
	v_cndmask_b32_e32 v58, 0, v58, vcc
	v_cmp_lt_i32_e32 vcc, -1, v46
	v_add_f32_e32 v58, v59, v58
	v_mul_f32_e32 v49, v58, v49
	v_cndmask_b32_e32 v47, 0, v47, vcc
	v_cmp_gt_i32_e32 vcc, 1, v46
	v_sub_u32_e32 v46, 0, v46
	v_cvt_f32_u32_e32 v46, v46
	v_cvt_pk_bf16_f32 v41, v48, v49
	v_mul_f32_e32 v46, v170, v46
	v_exp_f32_e32 v46, v46
	v_mfma_f32_16x16x32_bf16 v[58:61], v[10:13], v[38:41], v[70:73]
	v_cndmask_b32_e32 v46, 0, v46, vcc
	v_add_f32_e32 v46, v47, v46
	v_mul_f32_e32 v42, v46, v42
	v_sub_u32_e32 v46, v171, v50
	v_cvt_f32_u32_e32 v47, v46
	v_cmp_lt_i32_e32 vcc, -1, v46
	v_mul_f32_e32 v47, v169, v47
	v_exp_f32_e32 v47, v47
	s_nop 0
	v_cndmask_b32_e32 v47, 0, v47, vcc
	v_cmp_gt_i32_e32 vcc, 1, v46
	v_sub_u32_e32 v46, 0, v46
	v_cvt_f32_u32_e32 v46, v46
	v_mul_f32_e32 v46, v170, v46
	v_exp_f32_e32 v46, v46
	s_nop 0
	v_cndmask_b32_e32 v46, 0, v46, vcc
	v_add_f32_e32 v46, v47, v46
	v_mul_f32_e32 v43, v46, v43
	v_sub_u32_e32 v46, v171, v51
	v_cvt_f32_u32_e32 v47, v46
	v_cmp_lt_i32_e32 vcc, -1, v46
	v_mul_f32_e32 v47, v169, v47
	v_exp_f32_e32 v47, v47
	s_nop 0
	v_cndmask_b32_e32 v47, 0, v47, vcc
	v_cmp_gt_i32_e32 vcc, 1, v46
	v_sub_u32_e32 v46, 0, v46
	v_cvt_f32_u32_e32 v46, v46
	v_mul_f32_e32 v46, v170, v46
	v_exp_f32_e32 v46, v46
	s_nop 0
	v_cndmask_b32_e32 v46, 0, v46, vcc
	v_add_f32_e32 v46, v47, v46
	v_mul_f32_e32 v44, v46, v44
	v_sub_u32_e32 v46, v171, v52
	v_cvt_f32_u32_e32 v47, v46
	v_cmp_lt_i32_e32 vcc, -1, v46
	v_mul_f32_e32 v47, v169, v47
	v_exp_f32_e32 v47, v47
	s_nop 0
	v_cndmask_b32_e32 v47, 0, v47, vcc
	v_cmp_gt_i32_e32 vcc, 1, v46
	v_sub_u32_e32 v46, 0, v46
	v_cvt_f32_u32_e32 v46, v46
	v_mul_f32_e32 v46, v170, v46
	v_exp_f32_e32 v46, v46
	s_nop 0
	v_cndmask_b32_e32 v46, 0, v46, vcc
	v_add_f32_e32 v46, v47, v46
	v_mul_f32_e32 v45, v46, v45
	v_sub_u32_e32 v46, v171, v54
	v_cvt_f32_u32_e32 v47, v46
	v_cmp_lt_i32_e32 vcc, -1, v46
	v_mul_f32_e32 v47, v169, v47
	v_exp_f32_e32 v47, v47
	s_nop 0
	v_cndmask_b32_e32 v47, 0, v47, vcc
	v_cmp_gt_i32_e32 vcc, 1, v46
	v_sub_u32_e32 v46, 0, v46
	v_cvt_f32_u32_e32 v46, v46
	v_mul_f32_e32 v46, v170, v46
	v_exp_f32_e32 v46, v46
	s_nop 0
	v_cndmask_b32_e32 v46, 0, v46, vcc
	v_add_f32_e32 v46, v47, v46
	v_mul_f32_e32 v46, v46, v34
	v_sub_u32_e32 v34, v171, v53
	v_cvt_f32_u32_e32 v47, v34
	v_cmp_lt_i32_e32 vcc, -1, v34
	v_mfma_f32_16x16x32_bf16 v[50:53], v[14:17], v[38:41], v[66:69]
	v_mul_f32_e32 v47, v169, v47
	v_exp_f32_e32 v47, v47
	v_mfma_f32_16x16x32_bf16 v[66:69], v[6:9], v[38:41], v[78:81]
	v_cndmask_b32_e32 v47, 0, v47, vcc
	v_cmp_gt_i32_e32 vcc, 1, v34
	v_sub_u32_e32 v34, 0, v34
	v_cvt_f32_u32_e32 v34, v34
	v_mul_f32_e32 v34, v170, v34
	v_exp_f32_e32 v34, v34
	s_nop 0
	v_cndmask_b32_e32 v34, 0, v34, vcc
	v_add_f32_e32 v34, v47, v34
	v_mul_f32_e32 v47, v34, v35
	v_sub_u32_e32 v34, v171, v56
	v_cvt_f32_u32_e32 v35, v34
	v_cmp_lt_i32_e32 vcc, -1, v34
	v_mul_f32_e32 v35, v169, v35
	v_exp_f32_e32 v35, v35
	s_nop 0
	v_cndmask_b32_e32 v35, 0, v35, vcc
	v_cmp_gt_i32_e32 vcc, 1, v34
	v_sub_u32_e32 v34, 0, v34
	v_cvt_f32_u32_e32 v34, v34
	v_mul_f32_e32 v34, v170, v34
	v_exp_f32_e32 v34, v34
	s_nop 0
	v_cndmask_b32_e32 v34, 0, v34, vcc
	v_add_f32_e32 v34, v35, v34
	v_mul_f32_e32 v48, v34, v36
	v_sub_u32_e32 v34, v171, v57
	v_cvt_f32_u32_e32 v35, v34
	v_cmp_lt_i32_e32 vcc, -1, v34
	v_cvt_pk_bf16_f32 v36, v46, v47
	v_mul_f32_e32 v35, v169, v35
	v_exp_f32_e32 v35, v35
	s_nop 0
	v_cndmask_b32_e32 v35, 0, v35, vcc
	v_cmp_gt_i32_e32 vcc, 1, v34
	v_sub_u32_e32 v34, 0, v34
	v_cvt_f32_u32_e32 v34, v34
	v_mul_f32_e32 v34, v170, v34
	v_exp_f32_e32 v34, v34
	s_nop 0
	v_cndmask_b32_e32 v34, 0, v34, vcc
	v_add_f32_e32 v34, v35, v34
	v_mul_f32_e32 v37, v34, v37
	v_cvt_pk_bf16_f32 v34, v42, v43
	v_cvt_pk_bf16_f32 v35, v44, v45
	v_cvt_pk_bf16_f32 v37, v48, v37
	s_nop 1
	v_mfma_f32_16x16x32_bf16 v[54:57], v[14:17], v[34:37], v[62:65]
	v_mfma_f32_16x16x32_bf16 v[62:65], v[10:13], v[34:37], v[74:77]
	v_mfma_f32_16x16x32_bf16 v[70:73], v[6:9], v[34:37], v[98:101]
	v_mfma_f32_16x16x32_bf16 v[74:77], v[2:5], v[38:41], v[102:105]
	v_mfma_f32_16x16x32_bf16 v[78:81], v[2:5], v[34:37], v[106:109]
	global_load_dwordx4 v[34:37], v[112:113], off offset:192
	global_load_dwordx4 v[38:41], v[152:153], off offset:192
	global_load_dwordx4 v[42:45], v[154:155], off offset:192
	global_load_dwordx4 v[98:101], v[112:113], off offset:128
	global_load_dwordx4 v[102:105], v[152:153], off offset:128
	global_load_dwordx4 v[106:109], v[154:155], off offset:128
	global_load_dwordx4 v[46:49], v[110:111], off offset:192
	s_nop 0
	global_load_dwordx4 v[110:113], v[110:111], off offset:128
	s_nop 0
	global_load_dwordx4 v[2:5], v[156:157], off offset:192
	global_load_dwordx4 v[6:9], v[156:157], off offset:128
	global_load_dwordx4 v[10:13], v[156:157], off offset:64
	global_load_dwordx4 v[14:17], v[156:157], off
	v_mul_lo_u32 v154, v159, 12
	v_ashrrev_i32_e32 v155, 31, v154
	v_lshl_add_u64 v[152:153], v[154:155], 0, v[130:131]
	v_add_u32_e32 v154, 6, v154
	v_ashrrev_i32_e32 v155, 31, v154
	v_lshl_add_u64 v[130:131], v[154:155], 0, v[130:131]
	v_lshlrev_b64 v[152:153], 13, v[152:153]
	v_lshlrev_b32_e32 v156, 7, v158
	v_lshlrev_b64 v[130:131], 13, v[130:131]
	v_lshl_add_u64 v[160:161], v[132:133], 0, v[152:153]
	v_mov_b32_e32 v157, v1
	v_or_b32_e32 v172, 0x1000, v156
	v_or_b32_e32 v174, 0x1800, v156
	v_lshl_add_u64 v[130:131], v[132:133], 0, v[130:131]
	v_lshl_add_u64 v[152:153], v[160:161], 0, v[156:157]
	v_lshl_add_u64 v[158:159], v[160:161], 0, v[172:173]
	v_lshl_add_u64 v[162:163], v[160:161], 0, v[174:175]
	v_lshl_add_u64 v[154:155], v[130:131], 0, v[156:157]
	v_lshl_add_u64 v[156:157], v[130:131], 0, v[172:173]
	v_lshl_add_u64 v[160:161], v[130:131], 0, v[174:175]
	v_mfma_f32_16x16x32_bf16 v[130:133], v[126:129], v[30:33], 0
	v_or_b32_e32 v173, 64, v0
	v_or_b32_e32 v172, 0x44, v0
	s_waitcnt vmcnt(0)
	v_mfma_f32_16x16x32_bf16 v[126:129], v[126:129], v[26:29], 0
	v_mfma_f32_16x16x32_bf16 v[130:133], v[122:125], v[22:25], v[130:133]
	v_mfma_f32_16x16x32_bf16 v[122:125], v[122:125], v[18:21], v[126:129]
	v_mfma_f32_16x16x32_bf16 v[126:129], v[118:121], v[30:33], 0
	v_mfma_f32_16x16x32_bf16 v[118:121], v[118:121], v[26:29], 0
	v_mfma_f32_16x16x32_bf16 v[126:129], v[114:117], v[22:25], v[126:129]
	v_mfma_f32_16x16x32_bf16 v[114:117], v[114:117], v[18:21], v[118:121]
	s_nop 5
	v_sub_u32_e32 v118, v168, v173
	v_cvt_f32_u32_e32 v119, v118
	v_cmp_lt_i32_e32 vcc, -1, v118
	v_mul_f32_e32 v119, v169, v119
	v_exp_f32_e32 v119, v119
	s_nop 0
	v_cndmask_b32_e32 v119, 0, v119, vcc
	v_cmp_gt_i32_e32 vcc, 1, v118
	v_sub_u32_e32 v118, 0, v118
	v_cvt_f32_u32_e32 v118, v118
	v_mul_f32_e32 v118, v170, v118
	v_exp_f32_e32 v118, v118
	s_nop 0
	v_cndmask_b32_e32 v118, 0, v118, vcc
	v_add_f32_e32 v118, v119, v118
	v_mul_f32_e32 v118, v118, v130
	v_or_b32_e32 v130, 0x41, v0
	v_sub_u32_e32 v119, v168, v130
	v_cvt_f32_u32_e32 v120, v119
	v_cmp_lt_i32_e32 vcc, -1, v119
	v_mul_f32_e32 v120, v169, v120
	v_exp_f32_e32 v120, v120
	s_nop 0
	v_cndmask_b32_e32 v120, 0, v120, vcc
	v_cmp_gt_i32_e32 vcc, 1, v119
	v_sub_u32_e32 v119, 0, v119
	v_cvt_f32_u32_e32 v119, v119
	v_mul_f32_e32 v119, v170, v119
	v_exp_f32_e32 v119, v119
	s_nop 0
	v_cndmask_b32_e32 v119, 0, v119, vcc
	v_add_f32_e32 v119, v120, v119
	v_mul_f32_e32 v119, v119, v131
	v_or_b32_e32 v131, 0x42, v0
	v_sub_u32_e32 v120, v168, v131
	v_cvt_f32_u32_e32 v121, v120
	v_cmp_lt_i32_e32 vcc, -1, v120
	v_cvt_pk_bf16_f32 v118, v118, v119
	v_mul_f32_e32 v121, v169, v121
	v_exp_f32_e32 v121, v121
	s_nop 0
	v_cndmask_b32_e32 v121, 0, v121, vcc
	v_cmp_gt_i32_e32 vcc, 1, v120
	v_sub_u32_e32 v120, 0, v120
	v_cvt_f32_u32_e32 v120, v120
	v_mul_f32_e32 v120, v170, v120
	v_exp_f32_e32 v120, v120
	s_nop 0
	v_cndmask_b32_e32 v120, 0, v120, vcc
	v_add_f32_e32 v120, v121, v120
	v_mul_f32_e32 v120, v120, v132
	v_or_b32_e32 v132, 0x43, v0
	v_sub_u32_e32 v121, v168, v132
	v_cvt_f32_u32_e32 v174, v121
	v_cmp_lt_i32_e32 vcc, -1, v121
	v_mul_f32_e32 v174, v169, v174
	v_exp_f32_e32 v174, v174
	s_nop 0
	v_cndmask_b32_e32 v174, 0, v174, vcc
	v_cmp_gt_i32_e32 vcc, 1, v121
	v_sub_u32_e32 v121, 0, v121
	v_cvt_f32_u32_e32 v121, v121
	v_mul_f32_e32 v121, v170, v121
	v_exp_f32_e32 v121, v121
	s_nop 0
	v_cndmask_b32_e32 v121, 0, v121, vcc
	v_add_f32_e32 v121, v174, v121
	v_mul_f32_e32 v121, v121, v133
	v_sub_u32_e32 v133, v168, v172
	v_cvt_f32_u32_e32 v174, v133
	v_cmp_lt_i32_e32 vcc, -1, v133
	v_cvt_pk_bf16_f32 v119, v120, v121
	v_mul_f32_e32 v174, v169, v174
	v_exp_f32_e32 v174, v174
	s_nop 0
	v_cndmask_b32_e32 v174, 0, v174, vcc
	v_cmp_gt_i32_e32 vcc, 1, v133
	v_sub_u32_e32 v133, 0, v133
	v_cvt_f32_u32_e32 v133, v133
	v_mul_f32_e32 v133, v170, v133
	v_exp_f32_e32 v133, v133
	s_nop 0
	v_cndmask_b32_e32 v133, 0, v133, vcc
	v_add_f32_e32 v133, v174, v133
	v_mul_f32_e32 v133, v133, v126
	v_or_b32_e32 v126, 0x45, v0
	v_sub_u32_e32 v174, v168, v126
	v_cvt_f32_u32_e32 v175, v174
	v_cmp_lt_i32_e32 vcc, -1, v174
	v_mul_f32_e32 v175, v169, v175
	v_exp_f32_e32 v175, v175
	s_nop 0
	v_cndmask_b32_e32 v175, 0, v175, vcc
	v_cmp_gt_i32_e32 vcc, 1, v174
	v_sub_u32_e32 v174, 0, v174
	v_cvt_f32_u32_e32 v174, v174
	v_mul_f32_e32 v174, v170, v174
	v_exp_f32_e32 v174, v174
	s_nop 0
	v_cndmask_b32_e32 v174, 0, v174, vcc
	v_add_f32_e32 v174, v175, v174
	v_mul_f32_e32 v174, v174, v127
	v_or_b32_e32 v127, 0x46, v0
	v_sub_u32_e32 v175, v168, v127
	v_cvt_f32_u32_e32 v176, v175
	v_cmp_lt_i32_e32 vcc, -1, v175
	v_cvt_pk_bf16_f32 v120, v133, v174
	v_mul_f32_e32 v176, v169, v176
	v_exp_f32_e32 v176, v176
	s_nop 0
	v_cndmask_b32_e32 v176, 0, v176, vcc
	v_cmp_gt_i32_e32 vcc, 1, v175
	v_sub_u32_e32 v175, 0, v175
	v_cvt_f32_u32_e32 v175, v175
	v_mul_f32_e32 v175, v170, v175
	v_exp_f32_e32 v175, v175
	s_nop 0
	v_cndmask_b32_e32 v175, 0, v175, vcc
	v_add_f32_e32 v175, v176, v175
	v_mul_f32_e32 v175, v175, v128
	v_or_b32_e32 v128, 0x47, v0
	v_sub_u32_e32 v176, v168, v128
	v_cvt_f32_u32_e32 v177, v176
	v_cmp_lt_i32_e32 vcc, -1, v176
	v_mul_f32_e32 v177, v169, v177
	v_exp_f32_e32 v177, v177
	s_nop 0
	v_cndmask_b32_e32 v177, 0, v177, vcc
	v_cmp_gt_i32_e32 vcc, 1, v176
	v_sub_u32_e32 v176, 0, v176
	v_cvt_f32_u32_e32 v176, v176
	v_mul_f32_e32 v176, v170, v176
	v_exp_f32_e32 v176, v176
	s_nop 0
	v_cndmask_b32_e32 v176, 0, v176, vcc
	v_add_f32_e32 v176, v177, v176
	v_mul_f32_e32 v129, v176, v129
	v_cvt_pk_bf16_f32 v121, v175, v129
	v_sub_u32_e32 v129, v171, v173
	v_cvt_f32_u32_e32 v133, v129
	v_cmp_lt_i32_e32 vcc, -1, v129
	v_mfma_f32_16x16x32_bf16 v[74:77], v[98:101], v[118:121], v[74:77]
	v_mul_f32_e32 v133, v169, v133
	v_exp_f32_e32 v133, v133
	v_mfma_f32_16x16x32_bf16 v[66:69], v[102:105], v[118:121], v[66:69]
	v_cndmask_b32_e32 v133, 0, v133, vcc
	v_cmp_gt_i32_e32 vcc, 1, v129
	v_sub_u32_e32 v129, 0, v129
	v_cvt_f32_u32_e32 v129, v129
	v_mfma_f32_16x16x32_bf16 v[58:61], v[106:109], v[118:121], v[58:61]
	v_mul_f32_e32 v129, v170, v129
	v_exp_f32_e32 v129, v129
	v_mfma_f32_16x16x32_bf16 v[50:53], v[110:113], v[118:121], v[50:53]
	v_cndmask_b32_e32 v129, 0, v129, vcc
	v_add_f32_e32 v129, v133, v129
	v_mul_f32_e32 v122, v129, v122
	v_sub_u32_e32 v129, v171, v130
	v_cvt_f32_u32_e32 v130, v129
	v_cmp_lt_i32_e32 vcc, -1, v129
	v_mul_f32_e32 v130, v169, v130
	v_exp_f32_e32 v130, v130
	s_nop 0
	v_cndmask_b32_e32 v130, 0, v130, vcc
	v_cmp_gt_i32_e32 vcc, 1, v129
	v_sub_u32_e32 v129, 0, v129
	v_cvt_f32_u32_e32 v129, v129
	v_mul_f32_e32 v129, v170, v129
	v_exp_f32_e32 v129, v129
	s_nop 0
	v_cndmask_b32_e32 v129, 0, v129, vcc
	v_add_f32_e32 v129, v130, v129
	v_mul_f32_e32 v123, v129, v123
	v_sub_u32_e32 v129, v171, v131
	v_cvt_f32_u32_e32 v130, v129
	v_cmp_lt_i32_e32 vcc, -1, v129
	v_mul_f32_e32 v130, v169, v130
	v_exp_f32_e32 v130, v130
	s_nop 0
	v_cndmask_b32_e32 v130, 0, v130, vcc
	v_cmp_gt_i32_e32 vcc, 1, v129
	v_sub_u32_e32 v129, 0, v129
	v_cvt_f32_u32_e32 v129, v129
	v_mul_f32_e32 v129, v170, v129
	v_exp_f32_e32 v129, v129
	s_nop 0
	v_cndmask_b32_e32 v129, 0, v129, vcc
	v_add_f32_e32 v129, v130, v129
	v_mul_f32_e32 v124, v129, v124
	v_sub_u32_e32 v129, v171, v132
	v_cvt_f32_u32_e32 v130, v129
	v_cmp_lt_i32_e32 vcc, -1, v129
	v_mul_f32_e32 v130, v169, v130
	v_exp_f32_e32 v130, v130
	s_nop 0
	v_cndmask_b32_e32 v130, 0, v130, vcc
	v_cmp_gt_i32_e32 vcc, 1, v129
	v_sub_u32_e32 v129, 0, v129
	v_cvt_f32_u32_e32 v129, v129
	v_mul_f32_e32 v129, v170, v129
	v_exp_f32_e32 v129, v129
	s_nop 0
	v_cndmask_b32_e32 v129, 0, v129, vcc
	v_add_f32_e32 v129, v130, v129
	v_mul_f32_e32 v125, v129, v125
	v_sub_u32_e32 v129, v171, v172
	v_cvt_f32_u32_e32 v130, v129
	v_cmp_lt_i32_e32 vcc, -1, v129
	v_mul_f32_e32 v130, v169, v130
	v_exp_f32_e32 v130, v130
	s_nop 0
	v_cndmask_b32_e32 v130, 0, v130, vcc
	v_cmp_gt_i32_e32 vcc, 1, v129
	v_sub_u32_e32 v129, 0, v129
	v_cvt_f32_u32_e32 v129, v129
	v_mul_f32_e32 v129, v170, v129
	v_exp_f32_e32 v129, v129
	s_nop 0
	v_cndmask_b32_e32 v129, 0, v129, vcc
	v_add_f32_e32 v129, v130, v129
	v_mul_f32_e32 v129, v129, v114
	v_sub_u32_e32 v114, v171, v126
	v_cvt_f32_u32_e32 v126, v114
	v_cmp_lt_i32_e32 vcc, -1, v114
	v_mul_f32_e32 v126, v169, v126
	v_exp_f32_e32 v126, v126
	s_nop 0
	v_cndmask_b32_e32 v126, 0, v126, vcc
	v_cmp_gt_i32_e32 vcc, 1, v114
	v_sub_u32_e32 v114, 0, v114
	v_cvt_f32_u32_e32 v114, v114
	v_mul_f32_e32 v114, v170, v114
	v_exp_f32_e32 v114, v114
	s_nop 0
	v_cndmask_b32_e32 v114, 0, v114, vcc
	v_add_f32_e32 v114, v126, v114
	v_mul_f32_e32 v126, v114, v115
	v_sub_u32_e32 v114, v171, v127
	v_cvt_f32_u32_e32 v115, v114
	v_cmp_lt_i32_e32 vcc, -1, v114
	v_mul_f32_e32 v115, v169, v115
	v_exp_f32_e32 v115, v115
	s_nop 0
	v_cndmask_b32_e32 v115, 0, v115, vcc
	v_cmp_gt_i32_e32 vcc, 1, v114
	v_sub_u32_e32 v114, 0, v114
	v_cvt_f32_u32_e32 v114, v114
	v_mul_f32_e32 v114, v170, v114
	v_exp_f32_e32 v114, v114
	s_nop 0
	v_cndmask_b32_e32 v114, 0, v114, vcc
	v_add_f32_e32 v114, v115, v114
	v_mul_f32_e32 v127, v114, v116
	v_sub_u32_e32 v114, v171, v128
	v_cvt_f32_u32_e32 v115, v114
	v_cmp_lt_i32_e32 vcc, -1, v114
	v_cvt_pk_bf16_f32 v116, v129, v126
	v_mul_f32_e32 v115, v169, v115
	v_exp_f32_e32 v115, v115
	s_nop 0
	v_cndmask_b32_e32 v115, 0, v115, vcc
	v_cmp_gt_i32_e32 vcc, 1, v114
	v_sub_u32_e32 v114, 0, v114
	v_cvt_f32_u32_e32 v114, v114
	v_mul_f32_e32 v114, v170, v114
	v_exp_f32_e32 v114, v114
	s_nop 0
	v_cndmask_b32_e32 v114, 0, v114, vcc
	v_add_f32_e32 v114, v115, v114
	v_mul_f32_e32 v117, v114, v117
	v_cvt_pk_bf16_f32 v114, v122, v123
	v_cvt_pk_bf16_f32 v115, v124, v125
	v_cvt_pk_bf16_f32 v117, v127, v117
	s_nop 1
	s_nop 0
	v_mfma_f32_16x16x32_bf16 v[78:81], v[98:101], v[114:117], v[78:81]
	v_mfma_f32_16x16x32_bf16 v[98:101], v[94:97], v[30:33], 0
	v_mfma_f32_16x16x32_bf16 v[94:97], v[94:97], v[26:29], 0
	v_mfma_f32_16x16x32_bf16 v[98:101], v[90:93], v[22:25], v[98:101]
	v_mfma_f32_16x16x32_bf16 v[90:93], v[90:93], v[18:21], v[94:97]
	v_mfma_f32_16x16x32_bf16 v[94:97], v[86:89], v[30:33], 0
	v_mfma_f32_16x16x32_bf16 v[86:89], v[86:89], v[26:29], 0
	v_mfma_f32_16x16x32_bf16 v[70:73], v[102:105], v[114:117], v[70:73]
	v_or_b32_e32 v103, 0x60, v0
	v_or_b32_e32 v102, 0x64, v0
	v_mfma_f32_16x16x32_bf16 v[94:97], v[82:85], v[22:25], v[94:97]
	v_mfma_f32_16x16x32_bf16 v[82:85], v[82:85], v[18:21], v[86:89]
	s_nop 2
	v_sub_u32_e32 v86, v168, v103
	v_cvt_f32_u32_e32 v87, v86
	v_cmp_lt_i32_e32 vcc, -1, v86
	v_mfma_f32_16x16x32_bf16 v[62:65], v[106:109], v[114:117], v[62:65]
	v_mul_f32_e32 v87, v169, v87
	v_exp_f32_e32 v87, v87
	v_mfma_f32_16x16x32_bf16 v[54:57], v[110:113], v[114:117], v[54:57]
	v_cndmask_b32_e32 v87, 0, v87, vcc
	v_cmp_gt_i32_e32 vcc, 1, v86
	v_sub_u32_e32 v86, 0, v86
	v_cvt_f32_u32_e32 v86, v86
	v_mul_f32_e32 v86, v170, v86
	v_exp_f32_e32 v86, v86
	s_nop 0
	v_cndmask_b32_e32 v86, 0, v86, vcc
	v_add_f32_e32 v86, v87, v86
	v_mul_f32_e32 v86, v86, v98
	v_or_b32_e32 v98, 0x61, v0
	v_sub_u32_e32 v87, v168, v98
	v_cvt_f32_u32_e32 v88, v87
	v_cmp_lt_i32_e32 vcc, -1, v87
	v_mul_f32_e32 v88, v169, v88
	v_exp_f32_e32 v88, v88
	s_nop 0
	v_cndmask_b32_e32 v88, 0, v88, vcc
	v_cmp_gt_i32_e32 vcc, 1, v87
	v_sub_u32_e32 v87, 0, v87
	v_cvt_f32_u32_e32 v87, v87
	v_mul_f32_e32 v87, v170, v87
	v_exp_f32_e32 v87, v87
	s_nop 0
	v_cndmask_b32_e32 v87, 0, v87, vcc
	v_add_f32_e32 v87, v88, v87
	v_mul_f32_e32 v87, v87, v99
	v_or_b32_e32 v99, 0x62, v0
	v_sub_u32_e32 v88, v168, v99
	v_cvt_f32_u32_e32 v89, v88
	v_cmp_lt_i32_e32 vcc, -1, v88
	v_cvt_pk_bf16_f32 v86, v86, v87
	v_mul_f32_e32 v89, v169, v89
	v_exp_f32_e32 v89, v89
	s_nop 0
	v_cndmask_b32_e32 v89, 0, v89, vcc
	v_cmp_gt_i32_e32 vcc, 1, v88
	v_sub_u32_e32 v88, 0, v88
	v_cvt_f32_u32_e32 v88, v88
	v_mul_f32_e32 v88, v170, v88
	v_exp_f32_e32 v88, v88
	s_nop 0
	v_cndmask_b32_e32 v88, 0, v88, vcc
	v_add_f32_e32 v88, v89, v88
	v_mul_f32_e32 v88, v88, v100
	v_or_b32_e32 v100, 0x63, v0
	v_sub_u32_e32 v89, v168, v100
	v_cvt_f32_u32_e32 v104, v89
	v_cmp_lt_i32_e32 vcc, -1, v89
	v_mul_f32_e32 v104, v169, v104
	v_exp_f32_e32 v104, v104
	s_nop 0
	v_cndmask_b32_e32 v104, 0, v104, vcc
	v_cmp_gt_i32_e32 vcc, 1, v89
	v_sub_u32_e32 v89, 0, v89
	v_cvt_f32_u32_e32 v89, v89
	v_mul_f32_e32 v89, v170, v89
	v_exp_f32_e32 v89, v89
	s_nop 0
	v_cndmask_b32_e32 v89, 0, v89, vcc
	v_add_f32_e32 v89, v104, v89
	v_mul_f32_e32 v89, v89, v101
	v_sub_u32_e32 v101, v168, v102
	v_cvt_f32_u32_e32 v104, v101
	v_cmp_lt_i32_e32 vcc, -1, v101
	v_cvt_pk_bf16_f32 v87, v88, v89
	v_mul_f32_e32 v104, v169, v104
	v_exp_f32_e32 v104, v104
	s_nop 0
	v_cndmask_b32_e32 v104, 0, v104, vcc
	v_cmp_gt_i32_e32 vcc, 1, v101
	v_sub_u32_e32 v101, 0, v101
	v_cvt_f32_u32_e32 v101, v101
	v_mul_f32_e32 v101, v170, v101
	v_exp_f32_e32 v101, v101
	s_nop 0
	v_cndmask_b32_e32 v101, 0, v101, vcc
	v_add_f32_e32 v101, v104, v101
	v_mul_f32_e32 v101, v101, v94
	v_or_b32_e32 v94, 0x65, v0
	v_sub_u32_e32 v104, v168, v94
	v_cvt_f32_u32_e32 v105, v104
	v_cmp_lt_i32_e32 vcc, -1, v104
	v_sub_u32_e32 v94, v171, v94
	v_mul_f32_e32 v105, v169, v105
	v_exp_f32_e32 v105, v105
	s_nop 0
	v_cndmask_b32_e32 v105, 0, v105, vcc
	v_cmp_gt_i32_e32 vcc, 1, v104
	v_sub_u32_e32 v104, 0, v104
	v_cvt_f32_u32_e32 v104, v104
	v_mul_f32_e32 v104, v170, v104
	v_exp_f32_e32 v104, v104
	s_nop 0
	v_cndmask_b32_e32 v104, 0, v104, vcc
	v_add_f32_e32 v104, v105, v104
	v_mul_f32_e32 v104, v104, v95
	v_or_b32_e32 v95, 0x66, v0
	v_sub_u32_e32 v105, v168, v95
	v_cvt_f32_u32_e32 v106, v105
	v_cmp_lt_i32_e32 vcc, -1, v105
	v_cvt_pk_bf16_f32 v88, v101, v104
	v_mul_f32_e32 v106, v169, v106
	v_exp_f32_e32 v106, v106
	s_nop 0
	v_cndmask_b32_e32 v106, 0, v106, vcc
	v_cmp_gt_i32_e32 vcc, 1, v105
	v_sub_u32_e32 v105, 0, v105
	v_cvt_f32_u32_e32 v105, v105
	v_mul_f32_e32 v105, v170, v105
	v_exp_f32_e32 v105, v105
	s_nop 0
	v_cndmask_b32_e32 v105, 0, v105, vcc
	v_add_f32_e32 v105, v106, v105
	v_mul_f32_e32 v105, v105, v96
	v_or_b32_e32 v96, 0x67, v0
	v_sub_u32_e32 v106, v168, v96
	v_cvt_f32_u32_e32 v107, v106
	v_cmp_lt_i32_e32 vcc, -1, v106
	v_mul_f32_e32 v107, v169, v107
	v_exp_f32_e32 v107, v107
	s_nop 0
	v_cndmask_b32_e32 v107, 0, v107, vcc
	v_cmp_gt_i32_e32 vcc, 1, v106
	v_sub_u32_e32 v106, 0, v106
	v_cvt_f32_u32_e32 v106, v106
	v_mul_f32_e32 v106, v170, v106
	v_exp_f32_e32 v106, v106
	s_nop 0
	v_cndmask_b32_e32 v106, 0, v106, vcc
	v_add_f32_e32 v106, v107, v106
	v_mul_f32_e32 v97, v106, v97
	v_cvt_pk_bf16_f32 v89, v105, v97
	v_sub_u32_e32 v97, v171, v103
	v_cvt_f32_u32_e32 v101, v97
	v_cmp_lt_i32_e32 vcc, -1, v97
	v_mfma_f32_16x16x32_bf16 v[50:53], v[46:49], v[86:89], v[50:53]
	v_mul_f32_e32 v101, v169, v101
	v_exp_f32_e32 v101, v101
	v_mfma_f32_16x16x32_bf16 v[58:61], v[42:45], v[86:89], v[58:61]
	v_cndmask_b32_e32 v101, 0, v101, vcc
	v_cmp_gt_i32_e32 vcc, 1, v97
	v_sub_u32_e32 v97, 0, v97
	v_cvt_f32_u32_e32 v97, v97
	v_mul_f32_e32 v97, v170, v97
	v_exp_f32_e32 v97, v97
	s_nop 0
	v_cndmask_b32_e32 v97, 0, v97, vcc
	v_add_f32_e32 v97, v101, v97
	v_mul_f32_e32 v90, v97, v90
	v_sub_u32_e32 v97, v171, v98
	v_cvt_f32_u32_e32 v98, v97
	v_cmp_lt_i32_e32 vcc, -1, v97
	v_mul_f32_e32 v98, v169, v98
	v_exp_f32_e32 v98, v98
	s_nop 0
	v_cndmask_b32_e32 v98, 0, v98, vcc
	v_cmp_gt_i32_e32 vcc, 1, v97
	v_sub_u32_e32 v97, 0, v97
	v_cvt_f32_u32_e32 v97, v97
	v_mul_f32_e32 v97, v170, v97
	v_exp_f32_e32 v97, v97
	s_nop 0
	v_cndmask_b32_e32 v97, 0, v97, vcc
	v_add_f32_e32 v97, v98, v97
	v_mul_f32_e32 v91, v97, v91
	v_sub_u32_e32 v97, v171, v99
	v_cvt_f32_u32_e32 v98, v97
	v_cmp_lt_i32_e32 vcc, -1, v97
	v_cvt_pk_bf16_f32 v90, v90, v91
	v_mul_f32_e32 v98, v169, v98
	v_exp_f32_e32 v98, v98
	s_nop 0
	v_cndmask_b32_e32 v98, 0, v98, vcc
	v_cmp_gt_i32_e32 vcc, 1, v97
	v_sub_u32_e32 v97, 0, v97
	v_cvt_f32_u32_e32 v97, v97
	v_mul_f32_e32 v97, v170, v97
	v_exp_f32_e32 v97, v97
	s_nop 0
	v_cndmask_b32_e32 v97, 0, v97, vcc
	v_add_f32_e32 v97, v98, v97
	v_mul_f32_e32 v92, v97, v92
	v_sub_u32_e32 v97, v171, v100
	v_cvt_f32_u32_e32 v98, v97
	v_cmp_lt_i32_e32 vcc, -1, v97
	v_mul_f32_e32 v98, v169, v98
	v_exp_f32_e32 v98, v98
	s_nop 0
	v_cndmask_b32_e32 v98, 0, v98, vcc
	v_cmp_gt_i32_e32 vcc, 1, v97
	v_sub_u32_e32 v97, 0, v97
	v_cvt_f32_u32_e32 v97, v97
	v_mul_f32_e32 v97, v170, v97
	v_exp_f32_e32 v97, v97
	s_nop 0
	v_cndmask_b32_e32 v97, 0, v97, vcc
	v_add_f32_e32 v97, v98, v97
	v_mul_f32_e32 v93, v97, v93
	v_sub_u32_e32 v97, v171, v102
	v_cvt_f32_u32_e32 v98, v97
	v_cmp_lt_i32_e32 vcc, -1, v97
	v_cvt_pk_bf16_f32 v91, v92, v93
	v_mul_f32_e32 v98, v169, v98
	v_exp_f32_e32 v98, v98
	s_nop 0
	v_cndmask_b32_e32 v98, 0, v98, vcc
	v_cmp_gt_i32_e32 vcc, 1, v97
	v_sub_u32_e32 v97, 0, v97
	v_cvt_f32_u32_e32 v97, v97
	v_mul_f32_e32 v97, v170, v97
	v_exp_f32_e32 v97, v97
	s_nop 0
	v_cndmask_b32_e32 v97, 0, v97, vcc
	v_add_f32_e32 v97, v98, v97
	v_mul_f32_e32 v82, v97, v82
	v_cvt_f32_u32_e32 v97, v94
	v_cmp_lt_i32_e32 vcc, -1, v94
	v_mul_f32_e32 v97, v169, v97
	v_exp_f32_e32 v97, v97
	s_nop 0
	v_cndmask_b32_e32 v97, 0, v97, vcc
	v_cmp_gt_i32_e32 vcc, 1, v94
	v_sub_u32_e32 v94, 0, v94
	v_cvt_f32_u32_e32 v94, v94
	v_mul_f32_e32 v94, v170, v94
	v_exp_f32_e32 v94, v94
	s_nop 0
	v_cndmask_b32_e32 v94, 0, v94, vcc
	v_add_f32_e32 v94, v97, v94
	v_mul_f32_e32 v83, v94, v83
	v_sub_u32_e32 v94, v171, v95
	v_cvt_f32_u32_e32 v95, v94
	v_cmp_lt_i32_e32 vcc, -1, v94
	v_cvt_pk_bf16_f32 v92, v82, v83
	v_mul_f32_e32 v95, v169, v95
	v_exp_f32_e32 v95, v95
	s_nop 0
	v_cndmask_b32_e32 v95, 0, v95, vcc
	v_cmp_gt_i32_e32 vcc, 1, v94
	v_sub_u32_e32 v94, 0, v94
	v_cvt_f32_u32_e32 v94, v94
	v_mul_f32_e32 v94, v170, v94
	v_exp_f32_e32 v94, v94
	s_nop 0
	v_cndmask_b32_e32 v94, 0, v94, vcc
	v_add_f32_e32 v94, v95, v94
	v_mul_f32_e32 v84, v94, v84
	v_sub_u32_e32 v94, v171, v96
	v_cvt_f32_u32_e32 v95, v94
	v_cmp_lt_i32_e32 vcc, -1, v94
	v_mul_f32_e32 v95, v169, v95
	v_exp_f32_e32 v95, v95
	s_nop 0
	v_cndmask_b32_e32 v95, 0, v95, vcc
	v_cmp_gt_i32_e32 vcc, 1, v94
	v_sub_u32_e32 v94, 0, v94
	v_cvt_f32_u32_e32 v94, v94
	v_mul_f32_e32 v94, v170, v94
	v_exp_f32_e32 v94, v94
	s_nop 0
	v_cndmask_b32_e32 v94, 0, v94, vcc
	v_add_f32_e32 v94, v95, v94
	v_mul_f32_e32 v85, v94, v85
	v_cvt_pk_bf16_f32 v93, v84, v85
	v_cmp_lt_i32_e32 vcc, v210, v208
	v_mfma_f32_16x16x32_bf16 v[54:57], v[46:49], v[90:93], v[54:57]
	v_mfma_f32_16x16x32_bf16 v[62:65], v[42:45], v[90:93], v[62:65]
	v_mfma_f32_16x16x32_bf16 v[46:49], v[38:41], v[86:89], v[66:69]
	v_mfma_f32_16x16x32_bf16 v[66:69], v[38:41], v[90:93], v[70:73]
	v_mfma_f32_16x16x32_bf16 v[38:41], v[34:37], v[86:89], v[74:77]
	v_mfma_f32_16x16x32_bf16 v[70:73], v[34:37], v[90:93], v[78:81]
	global_load_dwordx4 v[34:37], v[162:163], off offset:64
	global_load_dwordx4 v[42:45], v[162:163], off
	global_load_dwordx4 v[74:77], v[158:159], off offset:64
	global_load_dwordx4 v[78:81], v[158:159], off
	global_load_dwordx4 v[82:85], v[152:153], off offset:2112
	global_load_dwordx4 v[86:89], v[152:153], off offset:2048
	global_load_dwordx4 v[90:93], v[152:153], off offset:64
	global_load_dwordx4 v[94:97], v[152:153], off
	global_load_dwordx4 v[98:101], v[160:161], off offset:64
	global_load_dwordx4 v[102:105], v[160:161], off
	global_load_dwordx4 v[106:109], v[156:157], off offset:64
	global_load_dwordx4 v[110:113], v[156:157], off
	global_load_dwordx4 v[114:117], v[154:155], off offset:2112
	global_load_dwordx4 v[118:121], v[154:155], off offset:2048
	global_load_dwordx4 v[122:125], v[154:155], off offset:64
	global_load_dwordx4 v[126:129], v[154:155], off
	s_waitcnt vmcnt(0)
	s_nop 0
	v_mfma_f32_16x16x32_bf16 v[130:133], v[94:97], v[30:33], 0
	v_mfma_f32_16x16x32_bf16 v[94:97], v[94:97], v[26:29], 0
	v_mfma_f32_16x16x32_bf16 v[130:133], v[90:93], v[22:25], v[130:133]
	v_mfma_f32_16x16x32_bf16 v[90:93], v[90:93], v[18:21], v[94:97]
	v_mfma_f32_16x16x32_bf16 v[94:97], v[86:89], v[30:33], 0
	v_mfma_f32_16x16x32_bf16 v[86:89], v[86:89], v[26:29], 0
	v_mfma_f32_16x16x32_bf16 v[94:97], v[82:85], v[22:25], v[94:97]
	v_mfma_f32_16x16x32_bf16 v[82:85], v[82:85], v[18:21], v[86:89]
	v_mfma_f32_16x16x32_bf16 v[86:89], v[78:81], v[30:33], 0
	v_mfma_f32_16x16x32_bf16 v[78:81], v[78:81], v[26:29], 0
	v_mfma_f32_16x16x32_bf16 v[86:89], v[74:77], v[22:25], v[86:89]
	v_mfma_f32_16x16x32_bf16 v[74:77], v[74:77], v[18:21], v[78:81]
	v_mfma_f32_16x16x32_bf16 v[78:81], v[42:45], v[30:33], 0
	v_mfma_f32_16x16x32_bf16 v[42:45], v[42:45], v[26:29], 0
	v_mfma_f32_16x16x32_bf16 v[78:81], v[34:37], v[22:25], v[78:81]
	v_mfma_f32_16x16x32_bf16 v[152:155], v[34:37], v[18:21], v[42:45]
	v_mfma_f32_16x16x32_bf16 v[34:37], v[126:129], v[30:33], 0
	v_mfma_f32_16x16x32_bf16 v[42:45], v[126:129], v[26:29], 0
	v_mfma_f32_16x16x32_bf16 v[126:129], v[122:125], v[22:25], v[34:37]
	v_mfma_f32_16x16x32_bf16 v[122:125], v[122:125], v[18:21], v[42:45]
	v_mfma_f32_16x16x32_bf16 v[34:37], v[118:121], v[30:33], 0
	v_mfma_f32_16x16x32_bf16 v[42:45], v[118:121], v[26:29], 0
	v_mfma_f32_16x16x32_bf16 v[118:121], v[114:117], v[22:25], v[34:37]
	v_mfma_f32_16x16x32_bf16 v[114:117], v[114:117], v[18:21], v[42:45]
	v_mfma_f32_16x16x32_bf16 v[34:37], v[110:113], v[30:33], 0
	v_mfma_f32_16x16x32_bf16 v[42:45], v[110:113], v[26:29], 0
	v_mfma_f32_16x16x32_bf16 v[30:33], v[102:105], v[30:33], 0
	v_mfma_f32_16x16x32_bf16 v[26:29], v[102:105], v[26:29], 0
	v_mfma_f32_16x16x32_bf16 v[34:37], v[106:109], v[22:25], v[34:37]
	v_mfma_f32_16x16x32_bf16 v[106:109], v[106:109], v[18:21], v[42:45]
	v_mfma_f32_16x16x32_bf16 v[22:25], v[98:101], v[22:25], v[30:33]
	v_mfma_f32_16x16x32_bf16 v[98:101], v[98:101], v[18:21], v[26:29]
	s_setprio 0
	v_sub_u32_e32 v18, 0x80, v171
	v_cvt_f32_ubyte0_e32 v18, v18
	v_mul_f32_e32 v18, v170, v18
	s_nop 0
	v_exp_f32_e32 v28, v18
	v_add_u32_e32 v18, 1, v168
	v_cvt_f32_ubyte0_e32 v18, v18
	v_mul_f32_e32 v18, v169, v18
	v_exp_f32_e32 v18, v18
	s_nop 0
	v_pk_fma_f32 v[20:21], v[18:19], v[80:81], v[40:41] op_sel_hi:[0,1,1]
	v_pk_fma_f32 v[26:27], v[18:19], v[78:79], v[38:39] op_sel_hi:[0,1,1]
	v_sub_u32_e32 v19, 0x80, v168
	v_cvt_f32_ubyte0_e32 v19, v19
	v_mul_f32_e32 v19, v170, v19
	v_exp_f32_e32 v30, v19
	s_nop 0
	v_pk_fma_f32 v[42:43], v[30:31], v[24:25], v[20:21] op_sel_hi:[0,1,1]
	v_pk_fma_f32 v[20:21], v[18:19], v[88:89], v[48:49] op_sel_hi:[0,1,1]
	v_pk_fma_f32 v[44:45], v[30:31], v[22:23], v[26:27] op_sel_hi:[0,1,1]
	v_pk_fma_f32 v[22:23], v[18:19], v[86:87], v[46:47] op_sel_hi:[0,1,1]
	v_pk_fma_f32 v[46:47], v[30:31], v[36:37], v[20:21] op_sel_hi:[0,1,1]
	v_pk_fma_f32 v[20:21], v[18:19], v[96:97], v[60:61] op_sel_hi:[0,1,1]
	v_pk_fma_f32 v[48:49], v[30:31], v[34:35], v[22:23] op_sel_hi:[0,1,1]
	v_pk_fma_f32 v[22:23], v[18:19], v[94:95], v[58:59] op_sel_hi:[0,1,1]
	v_pk_fma_f32 v[34:35], v[30:31], v[120:121], v[20:21] op_sel_hi:[0,1,1]
	v_pk_fma_f32 v[20:21], v[18:19], v[132:133], v[52:53] op_sel_hi:[0,1,1]
	v_pk_fma_f32 v[18:19], v[18:19], v[130:131], v[50:51] op_sel_hi:[0,1,1]
	v_pk_fma_f32 v[40:41], v[30:31], v[126:127], v[18:19] op_sel_hi:[0,1,1]
	v_add_u32_e32 v18, 17, v168
	v_cvt_f32_ubyte0_e32 v18, v18
	v_mul_f32_e32 v18, v169, v18
	v_exp_f32_e32 v18, v18
	v_pk_fma_f32 v[36:37], v[30:31], v[118:119], v[22:23] op_sel_hi:[0,1,1]
	v_pk_fma_f32 v[38:39], v[30:31], v[128:129], v[20:21] op_sel_hi:[0,1,1]
	v_and_b32_e32 v58, 0xffff0000, v151
	v_pk_fma_f32 v[26:27], v[18:19], v[154:155], v[72:73] op_sel_hi:[0,1,1]
	v_pk_fma_f32 v[50:51], v[18:19], v[152:153], v[70:71] op_sel_hi:[0,1,1]
	v_pk_fma_f32 v[30:31], v[18:19], v[76:77], v[68:69] op_sel_hi:[0,1,1]
	v_pk_fma_f32 v[32:33], v[18:19], v[74:75], v[66:67] op_sel_hi:[0,1,1]
	v_pk_fma_f32 v[20:21], v[18:19], v[84:85], v[64:65] op_sel_hi:[0,1,1]
	v_pk_fma_f32 v[52:53], v[18:19], v[82:83], v[62:63] op_sel_hi:[0,1,1]
	v_pk_fma_f32 v[22:23], v[18:19], v[92:93], v[56:57] op_sel_hi:[0,1,1]
	v_pk_fma_f32 v[18:19], v[18:19], v[90:91], v[54:55] op_sel_hi:[0,1,1]
	v_pk_fma_f32 v[22:23], v[28:29], v[124:125], v[22:23] op_sel_hi:[0,1,1]
	v_pk_fma_f32 v[24:25], v[28:29], v[122:123], v[18:19] op_sel_hi:[0,1,1]
	v_pk_fma_f32 v[18:19], v[28:29], v[116:117], v[20:21] op_sel_hi:[0,1,1]
	v_pk_fma_f32 v[20:21], v[28:29], v[114:115], v[52:53] op_sel_hi:[0,1,1]
	v_pk_fma_f32 v[30:31], v[28:29], v[108:109], v[30:31] op_sel_hi:[0,1,1]
	v_pk_fma_f32 v[32:33], v[28:29], v[106:107], v[32:33] op_sel_hi:[0,1,1]
	v_pk_fma_f32 v[26:27], v[28:29], v[100:101], v[26:27] op_sel_hi:[0,1,1]
	v_pk_fma_f32 v[28:29], v[28:29], v[98:99], v[50:51] op_sel_hi:[0,1,1]
	v_cndmask_b32_e32 v50, v207, v210, vcc
	v_cmp_lt_i32_e32 vcc, v209, v208
	v_lshlrev_b32_e32 v54, 2, v50
	v_mov_b32_e32 v51, v36
	v_cndmask_b32_e32 v50, v207, v209, vcc
	v_lshlrev_b32_e32 v55, 2, v50
	v_mov_b32_e32 v50, v40
	v_mov_b32_e32 v52, v41
	v_mov_b32_e32 v53, v37
	v_pk_add_f32 v[50:51], v[50:51], v[52:53]
	v_mov_b32_e32 v52, v38
	v_mov_b32_e32 v53, v34
	v_pk_add_f32 v[50:51], v[52:53], v[50:51]
	v_mov_b32_e32 v52, v39
	v_mov_b32_e32 v53, v35
	v_pk_add_f32 v[50:51], v[52:53], v[50:51]
	v_mov_b32_e32 v52, v49
	v_add_f32_e32 v50, 0, v50
	v_add_f32_e32 v56, v50, v51
	v_mov_b32_e32 v50, v48
	v_mov_b32_e32 v51, v44
	v_mov_b32_e32 v53, v45
	v_pk_add_f32 v[50:51], v[50:51], v[52:53]
	v_mov_b32_e32 v52, v46
	v_mov_b32_e32 v53, v42
	v_pk_add_f32 v[50:51], v[52:53], v[50:51]
	v_mov_b32_e32 v52, v47
	v_mov_b32_e32 v53, v43
	v_pk_add_f32 v[50:51], v[52:53], v[50:51]
	v_lshlrev_b32_e32 v57, 16, v151
	v_add_f32_e32 v50, v56, v50
	v_add_f32_e32 v50, v50, v51
	ds_bpermute_b32 v51, v54, v50
	s_waitcnt lgkmcnt(0)
	v_add_f32_e32 v50, v50, v51
	ds_bpermute_b32 v51, v55, v50
	s_waitcnt lgkmcnt(0)
	v_add_f32_e32 v51, v50, v51
	v_fmac_f32_e32 v41, 0xbc800000, v51
	v_fmamk_f32 v40, v51, 0xbc800000, v40
	v_mul_f32_e32 v56, v41, v41
	v_fmac_f32_e32 v56, v40, v40
	v_fmamk_f32 v38, v51, 0xbc800000, v38
	v_fmac_f32_e32 v56, v38, v38
	v_fmac_f32_e32 v39, 0xbc800000, v51
	v_fmac_f32_e32 v56, v39, v39
	v_fmamk_f32 v36, v51, 0xbc800000, v36
	v_fmac_f32_e32 v56, v36, v36
	v_fmac_f32_e32 v37, 0xbc800000, v51
	v_mul_f32_e32 v50, 0x3c800000, v51
	v_fmac_f32_e32 v56, v37, v37
	v_fmamk_f32 v34, v51, 0xbc800000, v34
	v_fmac_f32_e32 v56, v34, v34
	v_fmac_f32_e32 v35, 0xbc800000, v51
	v_pk_add_f32 v[48:49], v[48:49], v[50:51] op_sel_hi:[1,0] neg_lo:[0,1] neg_hi:[0,1]
	v_fmac_f32_e32 v56, v35, v35
	v_pk_mul_f32 v[52:53], v[48:49], v[48:49]
	s_nop 0
	v_add_f32_e32 v51, v52, v56
	v_add_f32_e32 v51, v53, v51
	v_pk_add_f32 v[46:47], v[46:47], v[50:51] op_sel_hi:[1,0] neg_lo:[0,1] neg_hi:[0,1]
	v_and_b32_e32 v56, 0xffff0000, v150
	v_pk_mul_f32 v[52:53], v[46:47], v[46:47]
	s_nop 0
	v_add_f32_e32 v51, v52, v51
	v_add_f32_e32 v51, v53, v51
	v_pk_add_f32 v[44:45], v[44:45], v[50:51] op_sel_hi:[1,0] neg_lo:[0,1] neg_hi:[0,1]
	s_nop 0
	v_pk_mul_f32 v[52:53], v[44:45], v[44:45]
	s_nop 0
	v_add_f32_e32 v51, v52, v51
	v_pk_add_f32 v[42:43], v[42:43], v[50:51] op_sel_hi:[1,0] neg_lo:[0,1] neg_hi:[0,1]
	v_add_f32_e32 v52, v53, v51
	v_pk_mul_f32 v[50:51], v[42:43], v[42:43]
	v_lshlrev_b32_e32 v53, 16, v150
	v_add_f32_e32 v50, v50, v52
	v_add_f32_e32 v50, v51, v50
	ds_bpermute_b32 v51, v54, v50
	s_waitcnt lgkmcnt(0)
	v_add_f32_e32 v50, v50, v51
	ds_bpermute_b32 v51, v55, v50
	s_waitcnt lgkmcnt(0)
	v_add_f32_e32 v50, v50, v51
	v_fmamk_f32 v50, v50, 0x3c800000, v203
	v_cmp_gt_f32_e32 vcc, s28, v50
	v_mul_f32_e32 v51, 0x4b800000, v50
	s_nop 0
	v_cndmask_b32_e32 v50, v50, v51, vcc
	v_rsq_f32_e32 v50, v50
	s_nop 0
	v_mul_f32_e32 v51, 0x45800000, v50
	v_cndmask_b32_e32 v52, v50, v51, vcc
	v_cmp_gt_i32_e32 vcc, s37, v167
	v_mul_f32_e32 v40, v40, v52
	v_mul_f32_e32 v38, v38, v52
	v_cndmask_b32_e64 v50, 3, 1, vcc
	v_add_u32_e32 v50, v50, v167
	v_ashrrev_i32_e32 v51, 31, v50
	v_lshlrev_b64 v[50:51], 11, v[50:51]
	v_mul_f32_e32 v40, v14, v40
	v_mul_f32_e32 v41, v41, v52
	v_mul_f32_e32 v38, v16, v38
	v_lshl_add_u64 v[50:51], s[8:9], 0, v[50:51]
	v_mul_f32_e32 v40, v40, v53
	v_mul_f32_e32 v41, v15, v41
	v_mul_f32_e32 v53, v38, v57
	v_mul_f32_e32 v38, v39, v52
	v_lshl_add_u64 v[50:51], v[50:51], 0, v[134:135]
	v_mul_f32_e32 v41, v41, v56
	v_mul_f32_e32 v38, v17, v38
	v_mul_f32_e32 v39, v38, v58
	v_cvt_pk_bf16_f32 v38, v40, v41
	v_lshl_add_u64 v[40:41], v[50:51], 0, v[0:1]
	v_lshl_add_u64 v[50:51], v[40:41], 0, s[54:55]
	v_add_co_u32_e32 v40, vcc, s34, v40
	v_mul_f32_e32 v36, v36, v52
	s_nop 0
	v_addc_co_u32_e32 v41, vcc, 0, v41, vcc
	v_mul_f32_e32 v34, v34, v52
	v_cvt_pk_bf16_f32 v39, v53, v39
	global_store_dwordx2 v[40:41], v[38:39], off offset:1280
	v_lshlrev_b32_e32 v38, 16, v148
	v_lshlrev_b32_e32 v40, 16, v149
	v_mul_f32_e32 v36, v10, v36
	v_mul_f32_e32 v34, v12, v34
	v_mul_f32_e32 v36, v36, v38
	v_mul_f32_e32 v38, v34, v40
	v_mul_f32_e32 v34, v35, v52
	v_and_b32_e32 v41, 0xffff0000, v149
	v_mul_f32_e32 v37, v37, v52
	v_mul_f32_e32 v34, v13, v34
	v_and_b32_e32 v39, 0xffff0000, v148
	v_mul_f32_e32 v37, v11, v37
	v_mul_f32_e32 v35, v34, v41
	v_mul_f32_e32 v37, v37, v39
	v_cvt_pk_bf16_f32 v34, v36, v37
	v_cvt_pk_bf16_f32 v35, v38, v35
	v_mul_f32_e32 v38, v48, v52
	global_store_dwordx2 v[50:51], v[34:35], off offset:32
	v_lshlrev_b32_e32 v34, 16, v146
	v_mul_f32_e32 v38, v6, v38
	v_mul_f32_e32 v34, v38, v34
	v_mul_f32_e32 v38, v49, v52
	v_and_b32_e32 v35, 0xffff0000, v146
	v_mul_f32_e32 v38, v7, v38
	v_mul_f32_e32 v35, v38, v35
	v_mul_f32_e32 v38, v46, v52
	v_lshlrev_b32_e32 v36, 16, v147
	v_mul_f32_e32 v38, v8, v38
	v_mul_f32_e32 v36, v38, v36
	v_mul_f32_e32 v38, v47, v52
	v_and_b32_e32 v37, 0xffff0000, v147
	v_mul_f32_e32 v38, v9, v38
	v_mul_f32_e32 v37, v38, v37
	v_cvt_pk_bf16_f32 v34, v34, v35
	v_mul_f32_e32 v38, v44, v52
	v_cvt_pk_bf16_f32 v35, v36, v37
	global_store_dwordx2 v[50:51], v[34:35], off offset:64
	v_lshlrev_b32_e32 v34, 16, v144
	v_mul_f32_e32 v38, v2, v38
	v_mul_f32_e32 v34, v38, v34
	v_mul_f32_e32 v38, v45, v52
	v_and_b32_e32 v35, 0xffff0000, v144
	v_mul_f32_e32 v38, v3, v38
	v_mul_f32_e32 v35, v38, v35
	v_mul_f32_e32 v38, v42, v52
	v_lshlrev_b32_e32 v36, 16, v145
	v_mul_f32_e32 v38, v4, v38
	v_mul_f32_e32 v36, v38, v36
	v_mul_f32_e32 v38, v43, v52
	v_and_b32_e32 v37, 0xffff0000, v145
	v_mul_f32_e32 v38, v5, v38
	v_mul_f32_e32 v37, v38, v37
	v_cvt_pk_bf16_f32 v34, v34, v35
	v_cvt_pk_bf16_f32 v35, v36, v37
	global_store_dwordx2 v[50:51], v[34:35], off offset:96
	v_mov_b32_e32 v34, v24
	v_mov_b32_e32 v35, v20
	v_mov_b32_e32 v36, v25
	v_mov_b32_e32 v37, v21
	v_pk_add_f32 v[34:35], v[34:35], v[36:37]
	v_mov_b32_e32 v36, v22
	v_mov_b32_e32 v37, v18
	v_pk_add_f32 v[34:35], v[36:37], v[34:35]
	v_mov_b32_e32 v36, v23
	v_mov_b32_e32 v37, v19
	v_pk_add_f32 v[34:35], v[36:37], v[34:35]
	v_mov_b32_e32 v36, v33
	v_add_f32_e32 v34, 0, v34
	v_add_f32_e32 v38, v34, v35
	v_mov_b32_e32 v34, v32
	v_mov_b32_e32 v35, v28
	v_mov_b32_e32 v37, v29
	v_pk_add_f32 v[34:35], v[34:35], v[36:37]
	v_mov_b32_e32 v36, v30
	v_mov_b32_e32 v37, v26
	v_pk_add_f32 v[34:35], v[36:37], v[34:35]
	v_mov_b32_e32 v36, v31
	v_mov_b32_e32 v37, v27
	v_pk_add_f32 v[34:35], v[36:37], v[34:35]
	v_lshlrev_b32_e32 v39, 16, v143
	v_add_f32_e32 v34, v38, v34
	v_add_f32_e32 v34, v34, v35
	ds_bpermute_b32 v35, v54, v34
	v_and_b32_e32 v40, 0xffff0000, v143
	s_waitcnt lgkmcnt(0)
	v_add_f32_e32 v34, v34, v35
	ds_bpermute_b32 v35, v55, v34
	s_waitcnt lgkmcnt(0)
	v_add_f32_e32 v35, v34, v35
	v_fmac_f32_e32 v25, 0xbc800000, v35
	v_fmamk_f32 v24, v35, 0xbc800000, v24
	v_mul_f32_e32 v38, v25, v25
	v_fmac_f32_e32 v38, v24, v24
	v_fmamk_f32 v22, v35, 0xbc800000, v22
	v_fmac_f32_e32 v38, v22, v22
	v_fmac_f32_e32 v23, 0xbc800000, v35
	v_fmac_f32_e32 v38, v23, v23
	v_fmamk_f32 v20, v35, 0xbc800000, v20
	v_fmac_f32_e32 v38, v20, v20
	v_fmac_f32_e32 v21, 0xbc800000, v35
	v_mul_f32_e32 v34, 0x3c800000, v35
	v_fmac_f32_e32 v38, v21, v21
	v_fmamk_f32 v18, v35, 0xbc800000, v18
	v_fmac_f32_e32 v38, v18, v18
	v_fmac_f32_e32 v19, 0xbc800000, v35
	v_pk_add_f32 v[32:33], v[32:33], v[34:35] op_sel_hi:[1,0] neg_lo:[0,1] neg_hi:[0,1]
	v_fmac_f32_e32 v38, v19, v19
	v_pk_mul_f32 v[36:37], v[32:33], v[32:33]
	s_nop 0
	v_add_f32_e32 v35, v36, v38
	v_add_f32_e32 v35, v37, v35
	v_pk_add_f32 v[30:31], v[30:31], v[34:35] op_sel_hi:[1,0] neg_lo:[0,1] neg_hi:[0,1]
	v_and_b32_e32 v38, 0xffff0000, v142
	v_pk_mul_f32 v[36:37], v[30:31], v[30:31]
	s_nop 0
	v_add_f32_e32 v35, v36, v35
	v_add_f32_e32 v35, v37, v35
	v_pk_add_f32 v[28:29], v[28:29], v[34:35] op_sel_hi:[1,0] neg_lo:[0,1] neg_hi:[0,1]
	s_nop 0
	v_pk_mul_f32 v[36:37], v[28:29], v[28:29]
	s_nop 0
	v_add_f32_e32 v35, v36, v35
	v_pk_add_f32 v[26:27], v[26:27], v[34:35] op_sel_hi:[1,0] neg_lo:[0,1] neg_hi:[0,1]
	v_add_f32_e32 v36, v37, v35
	v_pk_mul_f32 v[34:35], v[26:27], v[26:27]
	v_lshlrev_b32_e32 v37, 16, v142
	v_add_f32_e32 v34, v34, v36
	v_add_f32_e32 v34, v35, v34
	ds_bpermute_b32 v35, v54, v34
	s_waitcnt lgkmcnt(0)
	v_add_f32_e32 v34, v34, v35
	ds_bpermute_b32 v35, v55, v34
	s_waitcnt lgkmcnt(0)
	v_add_f32_e32 v34, v34, v35
	v_fmamk_f32 v34, v34, 0x3c800000, v203
	v_cmp_gt_f32_e32 vcc, s28, v34
	v_mul_f32_e32 v35, 0x4b800000, v34
	s_nop 0
	v_cndmask_b32_e32 v34, v34, v35, vcc
	v_rsq_f32_e32 v34, v34
	s_nop 0
	v_mul_f32_e32 v35, 0x45800000, v34
	v_cndmask_b32_e32 v36, v34, v35, vcc
	v_cmp_gt_i32_e32 vcc, s37, v166
	v_mul_f32_e32 v24, v24, v36
	v_mul_f32_e32 v22, v22, v36
	v_cndmask_b32_e64 v34, 3, 1, vcc
	v_add_u32_e32 v34, v34, v166
	v_ashrrev_i32_e32 v35, 31, v34
	v_lshlrev_b64 v[34:35], 11, v[34:35]
	v_mul_f32_e32 v14, v14, v24
	v_mul_f32_e32 v24, v25, v36
	v_mul_f32_e32 v16, v16, v22
	v_mul_f32_e32 v22, v23, v36
	v_lshl_add_u64 v[34:35], s[8:9], 0, v[34:35]
	v_mul_f32_e32 v15, v15, v24
	v_mul_f32_e32 v17, v17, v22
	v_lshl_add_u64 v[34:35], v[34:35], 0, v[134:135]
	v_mul_f32_e32 v14, v14, v37
	v_mul_f32_e32 v15, v15, v38
	v_mul_f32_e32 v16, v16, v39
	v_mul_f32_e32 v17, v17, v40
	v_cvt_pk_bf16_f32 v14, v14, v15
	v_cvt_pk_bf16_f32 v15, v16, v17
	v_lshl_add_u64 v[16:17], v[34:35], 0, v[0:1]
	v_lshl_add_u64 v[22:23], v[16:17], 0, s[54:55]
	v_add_co_u32_e32 v16, vcc, s34, v16
	v_lshlrev_b32_e32 v0, 16, v140
	s_nop 0
	v_addc_co_u32_e32 v17, vcc, 0, v17, vcc
	global_store_dwordx2 v[16:17], v[14:15], off offset:1280
	v_mul_f32_e32 v17, v20, v36
	v_mul_f32_e32 v10, v10, v17
	v_mul_f32_e32 v0, v10, v0
	v_mul_f32_e32 v10, v21, v36
	v_mul_f32_e32 v10, v11, v10
	v_mul_f32_e32 v11, v18, v36
	v_and_b32_e32 v14, 0xffff0000, v140
	v_mul_f32_e32 v11, v12, v11
	v_mul_f32_e32 v12, v19, v36
	v_mul_f32_e32 v10, v10, v14
	v_mul_f32_e32 v12, v13, v12
	v_mul_f32_e32 v13, v32, v36
	v_cvt_pk_bf16_f32 v10, v0, v10
	v_lshlrev_b32_e32 v0, 16, v138
	v_mul_f32_e32 v6, v6, v13
	v_lshlrev_b32_e32 v15, 16, v141
	v_mul_f32_e32 v0, v6, v0
	v_mul_f32_e32 v6, v33, v36
	v_and_b32_e32 v16, 0xffff0000, v141
	v_mul_f32_e32 v11, v11, v15
	v_mul_f32_e32 v6, v7, v6
	v_mul_f32_e32 v7, v30, v36
	v_mul_f32_e32 v12, v12, v16
	v_cvt_pk_bf16_f32 v11, v11, v12
	global_store_dwordx2 v[22:23], v[10:11], off offset:32
	v_and_b32_e32 v10, 0xffff0000, v138
	v_mul_f32_e32 v7, v8, v7
	v_mul_f32_e32 v8, v31, v36
	v_mul_f32_e32 v6, v6, v10
	v_mul_f32_e32 v8, v9, v8
	v_mul_f32_e32 v9, v28, v36
	v_lshlrev_b32_e32 v11, 16, v139
	v_cvt_pk_bf16_f32 v6, v0, v6
	v_lshlrev_b32_e32 v0, 16, v136
	v_mul_f32_e32 v2, v2, v9
	v_and_b32_e32 v12, 0xffff0000, v139
	v_mul_f32_e32 v7, v7, v11
	v_mul_f32_e32 v0, v2, v0
	v_mul_f32_e32 v2, v29, v36
	v_mul_f32_e32 v8, v8, v12
	v_cvt_pk_bf16_f32 v7, v7, v8
	v_mul_f32_e32 v2, v3, v2
	v_mul_f32_e32 v3, v26, v36
	global_store_dwordx2 v[22:23], v[6:7], off offset:64
	v_and_b32_e32 v6, 0xffff0000, v136
	v_lshlrev_b32_e32 v7, 16, v137
	v_mul_f32_e32 v3, v4, v3
	v_mul_f32_e32 v4, v27, v36
	v_cmp_le_i32_e32 vcc, s2, v164
	v_and_b32_e32 v8, 0xffff0000, v137
	v_mul_f32_e32 v2, v2, v6
	v_mul_f32_e32 v3, v3, v7
	v_mul_f32_e32 v4, v5, v4
	s_or_b64 s[40:41], vcc, s[40:41]
	v_mul_f32_e32 v4, v4, v8
	v_cvt_pk_bf16_f32 v2, v0, v2
	v_cvt_pk_bf16_f32 v3, v3, v4
	global_store_dwordx2 v[22:23], v[2:3], off offset:96
	s_andn2_b64 exec, exec, s[40:41]
	s_cbranch_execnz .LBB0_149

.LBB0_181:
	s_add_i32 s88, s44, -2
	s_add_u32 s34, s34, 0x80
	s_addc_u32 s35, s35, 0
	s_add_u32 s89, s42, 0x100
	v_mov_b32_e32 v2, 0
	s_addc_u32 s90, s43, 0
	s_mov_b32 s2, 0
	s_add_i32 s91, s2, 2
	s_add_u32 s12, s34, 0x80
	s_addc_u32 s3, s35, 0
	s_add_i32 s13, 0, 0x10000
	v_add_u32_e32 v142, s13, v183
	ds_read_b128 v[130:133], v142
	ds_read_b128 v[134:137], v142 offset:1024
	ds_read_b128 v[138:141], v142 offset:2048
	ds_read_b128 v[142:145], v142 offset:3072
	s_cmp_eq_u32 s88, s2
	s_cselect_b32 s2, s0, s12
	s_cselect_b32 s3, s1, s3
	s_cselect_b32 s43, s41, s90
	s_cselect_b32 s42, s40, s89
	v_lshl_add_u64 v[190:191], s[34:35], 0, v[174:175]
	s_add_i32 m0, s55, 0xc000
	ds_read_b128 v[146:149], v184
	ds_read_b128 v[150:153], v184 offset:1024
	ds_read_b128 v[154:157], v184 offset:2048
	ds_read_b128 v[158:161], v184 offset:3072
	ds_read_b128 v[162:165], v184 offset:4096
	ds_read_b128 v[166:169], v184 offset:5120
	ds_read_b128 v[178:181], v184 offset:6144
	ds_read_b128 v[186:189], v184 offset:7168
	global_load_lds_dwordx4 v[190:191], off
	v_lshl_add_u64 v[190:191], s[34:35], 0, v[176:177]
	s_add_i32 m0, s55, 0xe000
	s_nop 0
	global_load_lds_dwordx4 v[190:191], off
	s_waitcnt lgkmcnt(8)
	s_add_i32 s92, 0, 0x14000
	s_add_i32 s12, s13, s54
	v_add_u32_e32 v185, s92, v183
	ds_read_b128 v[190:193], v185
	ds_read_b128 v[194:197], v185 offset:1024
	ds_read_b128 v[198:201], v185 offset:2048
	ds_read_b128 v[226:229], v185 offset:3072
	s_barrier
	s_waitcnt lgkmcnt(0)
	s_setprio 3
	v_mfma_f32_16x16x32_bf16 v[126:129], v[130:133], v[146:149], 0
	v_mfma_f32_16x16x32_bf16 v[122:125], v[138:141], v[146:149], 0
	v_mfma_f32_16x16x32_bf16 v[118:121], v[130:133], v[154:157], 0
	v_mfma_f32_16x16x32_bf16 v[114:117], v[138:141], v[154:157], 0
	v_mfma_f32_16x16x32_bf16 v[110:113], v[130:133], v[162:165], 0
	v_mfma_f32_16x16x32_bf16 v[106:109], v[138:141], v[162:165], 0
	v_mfma_f32_16x16x32_bf16 v[102:105], v[130:133], v[178:181], 0
	v_mfma_f32_16x16x32_bf16 v[98:101], v[138:141], v[178:181], 0
	v_mfma_f32_16x16x32_bf16 v[126:129], v[134:137], v[150:153], v[126:129]
	v_mfma_f32_16x16x32_bf16 v[122:125], v[142:145], v[150:153], v[122:125]
	v_mfma_f32_16x16x32_bf16 v[118:121], v[134:137], v[158:161], v[118:121]
	v_mfma_f32_16x16x32_bf16 v[114:117], v[142:145], v[158:161], v[114:117]
	v_mfma_f32_16x16x32_bf16 v[110:113], v[134:137], v[166:169], v[110:113]
	v_mfma_f32_16x16x32_bf16 v[106:109], v[142:145], v[166:169], v[106:109]
	v_mfma_f32_16x16x32_bf16 v[102:105], v[134:137], v[186:189], v[102:105]
	v_mfma_f32_16x16x32_bf16 v[98:101], v[142:145], v[186:189], v[98:101]
	v_mfma_f32_16x16x32_bf16 v[62:65], v[190:193], v[146:149], 0
	v_mfma_f32_16x16x32_bf16 v[58:61], v[198:201], v[146:149], 0
	v_mfma_f32_16x16x32_bf16 v[54:57], v[190:193], v[154:157], 0
	v_mfma_f32_16x16x32_bf16 v[50:53], v[198:201], v[154:157], 0
	v_mfma_f32_16x16x32_bf16 v[46:49], v[190:193], v[162:165], 0
	v_mfma_f32_16x16x32_bf16 v[42:45], v[198:201], v[162:165], 0
	v_mfma_f32_16x16x32_bf16 v[38:41], v[190:193], v[178:181], 0
	v_mfma_f32_16x16x32_bf16 v[34:37], v[198:201], v[178:181], 0
	v_mfma_f32_16x16x32_bf16 v[62:65], v[194:197], v[150:153], v[62:65]
	v_mfma_f32_16x16x32_bf16 v[58:61], v[226:229], v[150:153], v[58:61]
	v_mfma_f32_16x16x32_bf16 v[54:57], v[194:197], v[158:161], v[54:57]
	v_mfma_f32_16x16x32_bf16 v[50:53], v[226:229], v[158:161], v[50:53]
	s_mov_b32 m0, s55
	v_lshl_add_u64 v[234:235], s[2:3], 0, v[170:171]
	v_mfma_f32_16x16x32_bf16 v[46:49], v[194:197], v[166:169], v[46:49]
	v_mfma_f32_16x16x32_bf16 v[42:45], v[226:229], v[166:169], v[42:45]
	v_mfma_f32_16x16x32_bf16 v[38:41], v[194:197], v[186:189], v[38:41]
	v_mfma_f32_16x16x32_bf16 v[34:37], v[226:229], v[186:189], v[34:37]
	s_setprio 0
	s_barrier
	ds_read_b128 v[146:149], v184 offset:16384
	ds_read_b128 v[150:153], v184 offset:17408
	ds_read_b128 v[154:157], v184 offset:18432
	ds_read_b128 v[158:161], v184 offset:19456
	ds_read_b128 v[162:165], v184 offset:20480
	ds_read_b128 v[166:169], v184 offset:21504
	ds_read_b128 v[178:181], v184 offset:22528
	ds_read_b128 v[186:189], v184 offset:23552
	global_load_lds_dwordx4 v[234:235], off
	v_lshl_add_u64 v[236:237], s[2:3], 0, v[172:173]
	s_mov_b32 m0, s58
	s_nop 0
	global_load_lds_dwordx4 v[236:237], off
	v_lshl_add_u64 v[230:231], s[42:43], 0, v[170:171]
	s_mov_b32 m0, s12
	s_nop 0
	global_load_lds_dwordx4 v[230:231], off
	v_lshl_add_u64 v[232:233], s[42:43], 0, v[172:173]
	s_add_i32 m0, s12, 0x2000
	s_nop 0
	global_load_lds_dwordx4 v[232:233], off
	s_add_u32 s12, s42, s18
	s_addc_u32 s13, s43, 0
	s_add_i32 s42, s92, s54
	v_lshl_add_u64 v[242:243], s[12:13], 0, v[170:171]
	s_mov_b32 m0, s42
	v_lshl_add_u64 v[244:245], s[12:13], 0, v[172:173]
	global_load_lds_dwordx4 v[242:243], off
	s_add_i32 m0, s42, 0x2000
	s_nop 0
	global_load_lds_dwordx4 v[244:245], off
	s_waitcnt vmcnt(6)
	s_barrier
	s_waitcnt lgkmcnt(0)
	s_setprio 3
	s_nop 0
	v_mfma_f32_16x16x32_bf16 v[94:97], v[130:133], v[146:149], 0
	v_mfma_f32_16x16x32_bf16 v[90:93], v[138:141], v[146:149], 0
	v_mfma_f32_16x16x32_bf16 v[86:89], v[130:133], v[154:157], 0
	v_mfma_f32_16x16x32_bf16 v[82:85], v[138:141], v[154:157], 0
	v_mfma_f32_16x16x32_bf16 v[78:81], v[130:133], v[162:165], 0
	v_mfma_f32_16x16x32_bf16 v[74:77], v[138:141], v[162:165], 0
	v_mfma_f32_16x16x32_bf16 v[70:73], v[130:133], v[178:181], 0
	v_mfma_f32_16x16x32_bf16 v[66:69], v[138:141], v[178:181], 0
	v_mfma_f32_16x16x32_bf16 v[94:97], v[134:137], v[150:153], v[94:97]
	v_mfma_f32_16x16x32_bf16 v[90:93], v[142:145], v[150:153], v[90:93]
	v_mfma_f32_16x16x32_bf16 v[86:89], v[134:137], v[158:161], v[86:89]
	v_mfma_f32_16x16x32_bf16 v[82:85], v[142:145], v[158:161], v[82:85]
	v_mfma_f32_16x16x32_bf16 v[78:81], v[134:137], v[166:169], v[78:81]
	v_mfma_f32_16x16x32_bf16 v[74:77], v[142:145], v[166:169], v[74:77]
	v_mfma_f32_16x16x32_bf16 v[70:73], v[134:137], v[186:189], v[70:73]
	v_mfma_f32_16x16x32_bf16 v[66:69], v[142:145], v[186:189], v[66:69]
	v_mfma_f32_16x16x32_bf16 v[30:33], v[190:193], v[146:149], 0
	v_mfma_f32_16x16x32_bf16 v[26:29], v[198:201], v[146:149], 0
	v_mfma_f32_16x16x32_bf16 v[22:25], v[190:193], v[154:157], 0
	v_mfma_f32_16x16x32_bf16 v[18:21], v[198:201], v[154:157], 0
	v_mfma_f32_16x16x32_bf16 v[14:17], v[190:193], v[162:165], 0
	v_mfma_f32_16x16x32_bf16 v[10:13], v[198:201], v[162:165], 0
	v_mfma_f32_16x16x32_bf16 v[6:9], v[190:193], v[178:181], 0
	v_mfma_f32_16x16x32_bf16 v[2:5], v[198:201], v[178:181], 0
	v_mfma_f32_16x16x32_bf16 v[30:33], v[194:197], v[150:153], v[30:33]
	v_mfma_f32_16x16x32_bf16 v[26:29], v[226:229], v[150:153], v[26:29]
	v_mfma_f32_16x16x32_bf16 v[22:25], v[194:197], v[158:161], v[22:25]
	v_mfma_f32_16x16x32_bf16 v[18:21], v[226:229], v[158:161], v[18:21]
	s_add_i32 s12, 0, 0x18000
	v_add_u32_e32 v142, s12, v183
	v_mfma_f32_16x16x32_bf16 v[14:17], v[194:197], v[166:169], v[14:17]
	v_mfma_f32_16x16x32_bf16 v[10:13], v[226:229], v[166:169], v[10:13]
	v_mfma_f32_16x16x32_bf16 v[6:9], v[194:197], v[186:189], v[6:9]
	v_mfma_f32_16x16x32_bf16 v[2:5], v[226:229], v[186:189], v[2:5]
	s_setprio 0
	s_barrier
	ds_read_b128 v[130:133], v142
	ds_read_b128 v[134:137], v142 offset:1024
	ds_read_b128 v[138:141], v142 offset:2048
	ds_read_b128 v[142:145], v142 offset:3072
	s_add_u32 s2, s2, s18
	s_addc_u32 s3, s3, 0
	s_mov_b32 m0, s59
	v_lshl_add_u64 v[190:191], s[2:3], 0, v[170:171]
	ds_read_b128 v[146:149], v184 offset:32768
	ds_read_b128 v[150:153], v184 offset:33792
	ds_read_b128 v[154:157], v184 offset:34816
	ds_read_b128 v[158:161], v184 offset:35840
	ds_read_b128 v[162:165], v184 offset:36864
	ds_read_b128 v[166:169], v184 offset:37888
	ds_read_b128 v[178:181], v184 offset:38912
	ds_read_b128 v[186:189], v184 offset:39936
	global_load_lds_dwordx4 v[190:191], off
	v_lshl_add_u64 v[190:191], s[2:3], 0, v[172:173]
	s_mov_b32 m0, s77
	s_nop 0
	global_load_lds_dwordx4 v[190:191], off
	s_waitcnt lgkmcnt(8)
	s_add_i32 s2, 0, 0x1c000
	s_add_i32 s3, s12, s54
	v_add_u32_e32 v185, s2, v183
	ds_read_b128 v[190:193], v185
	ds_read_b128 v[194:197], v185 offset:1024
	ds_read_b128 v[198:201], v185 offset:2048
	ds_read_b128 v[226:229], v185 offset:3072
	s_barrier
	s_waitcnt lgkmcnt(0)
	s_setprio 3
	v_mfma_f32_16x16x32_bf16 v[126:129], v[130:133], v[146:149], v[126:129]
	v_mfma_f32_16x16x32_bf16 v[122:125], v[138:141], v[146:149], v[122:125]
	v_mfma_f32_16x16x32_bf16 v[118:121], v[130:133], v[154:157], v[118:121]
	v_mfma_f32_16x16x32_bf16 v[114:117], v[138:141], v[154:157], v[114:117]
	v_mfma_f32_16x16x32_bf16 v[110:113], v[130:133], v[162:165], v[110:113]
	v_mfma_f32_16x16x32_bf16 v[106:109], v[138:141], v[162:165], v[106:109]
	v_mfma_f32_16x16x32_bf16 v[102:105], v[130:133], v[178:181], v[102:105]
	v_mfma_f32_16x16x32_bf16 v[98:101], v[138:141], v[178:181], v[98:101]
	v_mfma_f32_16x16x32_bf16 v[126:129], v[134:137], v[150:153], v[126:129]
	v_mfma_f32_16x16x32_bf16 v[122:125], v[142:145], v[150:153], v[122:125]
	v_mfma_f32_16x16x32_bf16 v[118:121], v[134:137], v[158:161], v[118:121]
	v_mfma_f32_16x16x32_bf16 v[114:117], v[142:145], v[158:161], v[114:117]
	v_mfma_f32_16x16x32_bf16 v[110:113], v[134:137], v[166:169], v[110:113]
	v_mfma_f32_16x16x32_bf16 v[106:109], v[142:145], v[166:169], v[106:109]
	v_mfma_f32_16x16x32_bf16 v[102:105], v[134:137], v[186:189], v[102:105]
	v_mfma_f32_16x16x32_bf16 v[98:101], v[142:145], v[186:189], v[98:101]
	v_mfma_f32_16x16x32_bf16 v[62:65], v[190:193], v[146:149], v[62:65]
	v_mfma_f32_16x16x32_bf16 v[58:61], v[198:201], v[146:149], v[58:61]
	v_mfma_f32_16x16x32_bf16 v[54:57], v[190:193], v[154:157], v[54:57]
	v_mfma_f32_16x16x32_bf16 v[50:53], v[198:201], v[154:157], v[50:53]
	v_mfma_f32_16x16x32_bf16 v[46:49], v[190:193], v[162:165], v[46:49]
	v_mfma_f32_16x16x32_bf16 v[42:45], v[198:201], v[162:165], v[42:45]
	v_mfma_f32_16x16x32_bf16 v[38:41], v[190:193], v[178:181], v[38:41]
	v_mfma_f32_16x16x32_bf16 v[34:37], v[198:201], v[178:181], v[34:37]
	v_mfma_f32_16x16x32_bf16 v[62:65], v[194:197], v[150:153], v[62:65]
	v_mfma_f32_16x16x32_bf16 v[58:61], v[226:229], v[150:153], v[58:61]
	v_mfma_f32_16x16x32_bf16 v[54:57], v[194:197], v[158:161], v[54:57]
	v_mfma_f32_16x16x32_bf16 v[50:53], v[226:229], v[158:161], v[50:53]
	s_mov_b32 m0, s80
	v_lshl_add_u64 v[234:235], v[234:235], 0, s[20:21]
	v_mfma_f32_16x16x32_bf16 v[46:49], v[194:197], v[166:169], v[46:49]
	v_mfma_f32_16x16x32_bf16 v[42:45], v[226:229], v[166:169], v[42:45]
	v_mfma_f32_16x16x32_bf16 v[38:41], v[194:197], v[186:189], v[38:41]
	v_mfma_f32_16x16x32_bf16 v[34:37], v[226:229], v[186:189], v[34:37]
	s_setprio 0
	s_barrier
	ds_read_b128 v[146:149], v184 offset:49152
	ds_read_b128 v[150:153], v184 offset:50176
	ds_read_b128 v[154:157], v184 offset:51200
	ds_read_b128 v[158:161], v184 offset:52224
	ds_read_b128 v[162:165], v184 offset:53248
	ds_read_b128 v[166:169], v184 offset:54272
	ds_read_b128 v[178:181], v184 offset:55296
	ds_read_b128 v[186:189], v184 offset:56320
	global_load_lds_dwordx4 v[234:235], off
	v_lshl_add_u64 v[236:237], v[236:237], 0, s[20:21]
	s_mov_b32 m0, s81
	s_nop 0
	global_load_lds_dwordx4 v[236:237], off
	v_lshl_add_u64 v[230:231], v[230:231], 0, s[20:21]
	s_mov_b32 m0, s3
	s_nop 0
	global_load_lds_dwordx4 v[230:231], off
	v_lshl_add_u64 v[230:231], v[232:233], 0, s[20:21]
	s_add_i32 m0, s3, 0x2000
	s_nop 0
	global_load_lds_dwordx4 v[230:231], off
	s_add_i32 s2, s2, s54
	v_lshl_add_u64 v[242:243], v[242:243], 0, s[20:21]
	s_mov_b32 m0, s2
	s_nop 0
	global_load_lds_dwordx4 v[242:243], off
	v_lshl_add_u64 v[244:245], v[244:245], 0, s[20:21]
	s_add_i32 m0, s2, 0x2000
	s_nop 0
	global_load_lds_dwordx4 v[244:245], off
	s_waitcnt vmcnt(6)
	s_barrier
	s_waitcnt lgkmcnt(0)
	s_setprio 3
	v_mfma_f32_16x16x32_bf16 v[94:97], v[130:133], v[146:149], v[94:97]
	v_mfma_f32_16x16x32_bf16 v[90:93], v[138:141], v[146:149], v[90:93]
	v_mfma_f32_16x16x32_bf16 v[86:89], v[130:133], v[154:157], v[86:89]
	v_mfma_f32_16x16x32_bf16 v[82:85], v[138:141], v[154:157], v[82:85]
	v_mfma_f32_16x16x32_bf16 v[78:81], v[130:133], v[162:165], v[78:81]
	v_mfma_f32_16x16x32_bf16 v[74:77], v[138:141], v[162:165], v[74:77]
	v_mfma_f32_16x16x32_bf16 v[70:73], v[130:133], v[178:181], v[70:73]
	v_mfma_f32_16x16x32_bf16 v[66:69], v[138:141], v[178:181], v[66:69]
	v_mfma_f32_16x16x32_bf16 v[94:97], v[134:137], v[150:153], v[94:97]
	v_mfma_f32_16x16x32_bf16 v[90:93], v[142:145], v[150:153], v[90:93]
	v_mfma_f32_16x16x32_bf16 v[86:89], v[134:137], v[158:161], v[86:89]
	v_mfma_f32_16x16x32_bf16 v[82:85], v[142:145], v[158:161], v[82:85]
	v_mfma_f32_16x16x32_bf16 v[78:81], v[134:137], v[166:169], v[78:81]
	v_mfma_f32_16x16x32_bf16 v[74:77], v[142:145], v[166:169], v[74:77]
	v_mfma_f32_16x16x32_bf16 v[70:73], v[134:137], v[186:189], v[70:73]
	v_mfma_f32_16x16x32_bf16 v[66:69], v[142:145], v[186:189], v[66:69]
	v_mfma_f32_16x16x32_bf16 v[30:33], v[190:193], v[146:149], v[30:33]
	v_mfma_f32_16x16x32_bf16 v[26:29], v[198:201], v[146:149], v[26:29]
	v_mfma_f32_16x16x32_bf16 v[22:25], v[190:193], v[154:157], v[22:25]
	v_mfma_f32_16x16x32_bf16 v[18:21], v[198:201], v[154:157], v[18:21]
	v_mfma_f32_16x16x32_bf16 v[14:17], v[190:193], v[162:165], v[14:17]
	v_mfma_f32_16x16x32_bf16 v[10:13], v[198:201], v[162:165], v[10:13]
	v_mfma_f32_16x16x32_bf16 v[6:9], v[190:193], v[178:181], v[6:9]
	v_mfma_f32_16x16x32_bf16 v[2:5], v[198:201], v[178:181], v[2:5]
	v_mfma_f32_16x16x32_bf16 v[30:33], v[194:197], v[150:153], v[30:33]
	v_mfma_f32_16x16x32_bf16 v[26:29], v[226:229], v[150:153], v[26:29]
	v_mfma_f32_16x16x32_bf16 v[22:25], v[194:197], v[158:161], v[22:25]
	v_mfma_f32_16x16x32_bf16 v[18:21], v[226:229], v[158:161], v[18:21]
	s_add_u32 s34, s34, 0x100
	s_addc_u32 s35, s35, 0
	s_add_u32 s89, s89, 0x100
	s_addc_u32 s90, s90, 0
	s_cmp_ge_i32 s91, s44
	s_mov_b32 s2, s91
	v_mfma_f32_16x16x32_bf16 v[14:17], v[194:197], v[166:169], v[14:17]
	v_mfma_f32_16x16x32_bf16 v[10:13], v[226:229], v[166:169], v[10:13]
	v_mfma_f32_16x16x32_bf16 v[6:9], v[194:197], v[186:189], v[6:9]
	v_mfma_f32_16x16x32_bf16 v[2:5], v[226:229], v[186:189], v[2:5]
	s_setprio 0
	s_barrier
	s_cbranch_scc1 .Lpeel_x_1
.LBB0_182:
	s_add_i32 s91, s2, 2
	s_add_u32 s12, s34, 0x80
	s_addc_u32 s3, s35, 0
	s_add_i32 s13, 0, 0x10000
	v_add_u32_e32 v142, s13, v183
	ds_read_b128 v[130:133], v142
	ds_read_b128 v[134:137], v142 offset:1024
	ds_read_b128 v[138:141], v142 offset:2048
	ds_read_b128 v[142:145], v142 offset:3072
	s_cmp_eq_u32 s88, s2
	s_cselect_b32 s2, s0, s12
	s_cselect_b32 s3, s1, s3
	s_cselect_b32 s43, s41, s90
	s_cselect_b32 s42, s40, s89
	v_lshl_add_u64 v[190:191], s[34:35], 0, v[174:175]
	s_add_i32 m0, s55, 0xc000
	ds_read_b128 v[146:149], v184
	ds_read_b128 v[150:153], v184 offset:1024
	ds_read_b128 v[154:157], v184 offset:2048
	ds_read_b128 v[158:161], v184 offset:3072
	ds_read_b128 v[162:165], v184 offset:4096
	ds_read_b128 v[166:169], v184 offset:5120
	ds_read_b128 v[178:181], v184 offset:6144
	ds_read_b128 v[186:189], v184 offset:7168
	global_load_lds_dwordx4 v[190:191], off
	v_lshl_add_u64 v[190:191], s[34:35], 0, v[176:177]
	s_add_i32 m0, s55, 0xe000
	s_nop 0
	global_load_lds_dwordx4 v[190:191], off
	s_waitcnt lgkmcnt(8)
	s_add_i32 s92, 0, 0x14000
	s_add_i32 s12, s13, s54
	v_add_u32_e32 v185, s92, v183
	ds_read_b128 v[190:193], v185
	ds_read_b128 v[194:197], v185 offset:1024
	ds_read_b128 v[198:201], v185 offset:2048
	ds_read_b128 v[226:229], v185 offset:3072
	s_barrier
	s_waitcnt lgkmcnt(0)
	s_setprio 3
	v_mfma_f32_16x16x32_bf16 v[126:129], v[130:133], v[146:149], v[126:129]
	v_mfma_f32_16x16x32_bf16 v[122:125], v[138:141], v[146:149], v[122:125]
	v_mfma_f32_16x16x32_bf16 v[118:121], v[130:133], v[154:157], v[118:121]
	v_mfma_f32_16x16x32_bf16 v[114:117], v[138:141], v[154:157], v[114:117]
	v_mfma_f32_16x16x32_bf16 v[110:113], v[130:133], v[162:165], v[110:113]
	v_mfma_f32_16x16x32_bf16 v[106:109], v[138:141], v[162:165], v[106:109]
	v_mfma_f32_16x16x32_bf16 v[102:105], v[130:133], v[178:181], v[102:105]
	v_mfma_f32_16x16x32_bf16 v[98:101], v[138:141], v[178:181], v[98:101]
	v_mfma_f32_16x16x32_bf16 v[126:129], v[134:137], v[150:153], v[126:129]
	v_mfma_f32_16x16x32_bf16 v[122:125], v[142:145], v[150:153], v[122:125]
	v_mfma_f32_16x16x32_bf16 v[118:121], v[134:137], v[158:161], v[118:121]
	v_mfma_f32_16x16x32_bf16 v[114:117], v[142:145], v[158:161], v[114:117]
	v_mfma_f32_16x16x32_bf16 v[110:113], v[134:137], v[166:169], v[110:113]
	v_mfma_f32_16x16x32_bf16 v[106:109], v[142:145], v[166:169], v[106:109]
	v_mfma_f32_16x16x32_bf16 v[102:105], v[134:137], v[186:189], v[102:105]
	v_mfma_f32_16x16x32_bf16 v[98:101], v[142:145], v[186:189], v[98:101]
	v_mfma_f32_16x16x32_bf16 v[62:65], v[190:193], v[146:149], v[62:65]
	v_mfma_f32_16x16x32_bf16 v[58:61], v[198:201], v[146:149], v[58:61]
	v_mfma_f32_16x16x32_bf16 v[54:57], v[190:193], v[154:157], v[54:57]
	v_mfma_f32_16x16x32_bf16 v[50:53], v[198:201], v[154:157], v[50:53]
	v_mfma_f32_16x16x32_bf16 v[46:49], v[190:193], v[162:165], v[46:49]
	v_mfma_f32_16x16x32_bf16 v[42:45], v[198:201], v[162:165], v[42:45]
	v_mfma_f32_16x16x32_bf16 v[38:41], v[190:193], v[178:181], v[38:41]
	v_mfma_f32_16x16x32_bf16 v[34:37], v[198:201], v[178:181], v[34:37]
	v_mfma_f32_16x16x32_bf16 v[62:65], v[194:197], v[150:153], v[62:65]
	v_mfma_f32_16x16x32_bf16 v[58:61], v[226:229], v[150:153], v[58:61]
	v_mfma_f32_16x16x32_bf16 v[54:57], v[194:197], v[158:161], v[54:57]
	v_mfma_f32_16x16x32_bf16 v[50:53], v[226:229], v[158:161], v[50:53]
	s_mov_b32 m0, s55
	v_lshl_add_u64 v[234:235], s[2:3], 0, v[170:171]
	v_mfma_f32_16x16x32_bf16 v[46:49], v[194:197], v[166:169], v[46:49]
	v_mfma_f32_16x16x32_bf16 v[42:45], v[226:229], v[166:169], v[42:45]
	v_mfma_f32_16x16x32_bf16 v[38:41], v[194:197], v[186:189], v[38:41]
	v_mfma_f32_16x16x32_bf16 v[34:37], v[226:229], v[186:189], v[34:37]
	s_setprio 0
	s_barrier
	ds_read_b128 v[146:149], v184 offset:16384
	ds_read_b128 v[150:153], v184 offset:17408
	ds_read_b128 v[154:157], v184 offset:18432
	ds_read_b128 v[158:161], v184 offset:19456
	ds_read_b128 v[162:165], v184 offset:20480
	ds_read_b128 v[166:169], v184 offset:21504
	ds_read_b128 v[178:181], v184 offset:22528
	ds_read_b128 v[186:189], v184 offset:23552
	global_load_lds_dwordx4 v[234:235], off
	v_lshl_add_u64 v[236:237], s[2:3], 0, v[172:173]
	s_mov_b32 m0, s58
	s_nop 0
	global_load_lds_dwordx4 v[236:237], off
	v_lshl_add_u64 v[230:231], s[42:43], 0, v[170:171]
	s_mov_b32 m0, s12
	s_nop 0
	global_load_lds_dwordx4 v[230:231], off
	v_lshl_add_u64 v[232:233], s[42:43], 0, v[172:173]
	s_add_i32 m0, s12, 0x2000
	s_nop 0
	global_load_lds_dwordx4 v[232:233], off
	s_add_u32 s12, s42, s18
	s_addc_u32 s13, s43, 0
	s_add_i32 s42, s92, s54
	v_lshl_add_u64 v[242:243], s[12:13], 0, v[170:171]
	s_mov_b32 m0, s42
	v_lshl_add_u64 v[244:245], s[12:13], 0, v[172:173]
	global_load_lds_dwordx4 v[242:243], off
	s_add_i32 m0, s42, 0x2000
	s_nop 0
	global_load_lds_dwordx4 v[244:245], off
	s_waitcnt vmcnt(6)
	s_barrier
	s_waitcnt lgkmcnt(0)
	s_setprio 3
	s_nop 0
	v_mfma_f32_16x16x32_bf16 v[94:97], v[130:133], v[146:149], v[94:97]
	v_mfma_f32_16x16x32_bf16 v[90:93], v[138:141], v[146:149], v[90:93]
	v_mfma_f32_16x16x32_bf16 v[86:89], v[130:133], v[154:157], v[86:89]
	v_mfma_f32_16x16x32_bf16 v[82:85], v[138:141], v[154:157], v[82:85]
	v_mfma_f32_16x16x32_bf16 v[78:81], v[130:133], v[162:165], v[78:81]
	v_mfma_f32_16x16x32_bf16 v[74:77], v[138:141], v[162:165], v[74:77]
	v_mfma_f32_16x16x32_bf16 v[70:73], v[130:133], v[178:181], v[70:73]
	v_mfma_f32_16x16x32_bf16 v[66:69], v[138:141], v[178:181], v[66:69]
	v_mfma_f32_16x16x32_bf16 v[94:97], v[134:137], v[150:153], v[94:97]
	v_mfma_f32_16x16x32_bf16 v[90:93], v[142:145], v[150:153], v[90:93]
	v_mfma_f32_16x16x32_bf16 v[86:89], v[134:137], v[158:161], v[86:89]
	v_mfma_f32_16x16x32_bf16 v[82:85], v[142:145], v[158:161], v[82:85]
	v_mfma_f32_16x16x32_bf16 v[78:81], v[134:137], v[166:169], v[78:81]
	v_mfma_f32_16x16x32_bf16 v[74:77], v[142:145], v[166:169], v[74:77]
	v_mfma_f32_16x16x32_bf16 v[70:73], v[134:137], v[186:189], v[70:73]
	v_mfma_f32_16x16x32_bf16 v[66:69], v[142:145], v[186:189], v[66:69]
	v_mfma_f32_16x16x32_bf16 v[30:33], v[190:193], v[146:149], v[30:33]
	v_mfma_f32_16x16x32_bf16 v[26:29], v[198:201], v[146:149], v[26:29]
	v_mfma_f32_16x16x32_bf16 v[22:25], v[190:193], v[154:157], v[22:25]
	v_mfma_f32_16x16x32_bf16 v[18:21], v[198:201], v[154:157], v[18:21]
	v_mfma_f32_16x16x32_bf16 v[14:17], v[190:193], v[162:165], v[14:17]
	v_mfma_f32_16x16x32_bf16 v[10:13], v[198:201], v[162:165], v[10:13]
	v_mfma_f32_16x16x32_bf16 v[6:9], v[190:193], v[178:181], v[6:9]
	v_mfma_f32_16x16x32_bf16 v[2:5], v[198:201], v[178:181], v[2:5]
	v_mfma_f32_16x16x32_bf16 v[30:33], v[194:197], v[150:153], v[30:33]
	v_mfma_f32_16x16x32_bf16 v[26:29], v[226:229], v[150:153], v[26:29]
	v_mfma_f32_16x16x32_bf16 v[22:25], v[194:197], v[158:161], v[22:25]
	v_mfma_f32_16x16x32_bf16 v[18:21], v[226:229], v[158:161], v[18:21]
	s_add_i32 s12, 0, 0x18000
	v_add_u32_e32 v142, s12, v183
	v_mfma_f32_16x16x32_bf16 v[14:17], v[194:197], v[166:169], v[14:17]
	v_mfma_f32_16x16x32_bf16 v[10:13], v[226:229], v[166:169], v[10:13]
	v_mfma_f32_16x16x32_bf16 v[6:9], v[194:197], v[186:189], v[6:9]
	v_mfma_f32_16x16x32_bf16 v[2:5], v[226:229], v[186:189], v[2:5]
	s_setprio 0
	s_barrier
	ds_read_b128 v[130:133], v142
	ds_read_b128 v[134:137], v142 offset:1024
	ds_read_b128 v[138:141], v142 offset:2048
	ds_read_b128 v[142:145], v142 offset:3072
	s_add_u32 s2, s2, s18
	s_addc_u32 s3, s3, 0
	s_mov_b32 m0, s59
	v_lshl_add_u64 v[190:191], s[2:3], 0, v[170:171]
	ds_read_b128 v[146:149], v184 offset:32768
	ds_read_b128 v[150:153], v184 offset:33792
	ds_read_b128 v[154:157], v184 offset:34816
	ds_read_b128 v[158:161], v184 offset:35840
	ds_read_b128 v[162:165], v184 offset:36864
	ds_read_b128 v[166:169], v184 offset:37888
	ds_read_b128 v[178:181], v184 offset:38912
	ds_read_b128 v[186:189], v184 offset:39936
	global_load_lds_dwordx4 v[190:191], off
	v_lshl_add_u64 v[190:191], s[2:3], 0, v[172:173]
	s_mov_b32 m0, s77
	s_nop 0
	global_load_lds_dwordx4 v[190:191], off
	s_waitcnt lgkmcnt(8)
	s_add_i32 s2, 0, 0x1c000
	s_add_i32 s3, s12, s54
	v_add_u32_e32 v185, s2, v183
	ds_read_b128 v[190:193], v185
	ds_read_b128 v[194:197], v185 offset:1024
	ds_read_b128 v[198:201], v185 offset:2048
	ds_read_b128 v[226:229], v185 offset:3072
	s_barrier
	s_waitcnt lgkmcnt(0)
	s_setprio 3
	v_mfma_f32_16x16x32_bf16 v[126:129], v[130:133], v[146:149], v[126:129]
	v_mfma_f32_16x16x32_bf16 v[122:125], v[138:141], v[146:149], v[122:125]
	v_mfma_f32_16x16x32_bf16 v[118:121], v[130:133], v[154:157], v[118:121]
	v_mfma_f32_16x16x32_bf16 v[114:117], v[138:141], v[154:157], v[114:117]
	v_mfma_f32_16x16x32_bf16 v[110:113], v[130:133], v[162:165], v[110:113]
	v_mfma_f32_16x16x32_bf16 v[106:109], v[138:141], v[162:165], v[106:109]
	v_mfma_f32_16x16x32_bf16 v[102:105], v[130:133], v[178:181], v[102:105]
	v_mfma_f32_16x16x32_bf16 v[98:101], v[138:141], v[178:181], v[98:101]
	v_mfma_f32_16x16x32_bf16 v[126:129], v[134:137], v[150:153], v[126:129]
	v_mfma_f32_16x16x32_bf16 v[122:125], v[142:145], v[150:153], v[122:125]
	v_mfma_f32_16x16x32_bf16 v[118:121], v[134:137], v[158:161], v[118:121]
	v_mfma_f32_16x16x32_bf16 v[114:117], v[142:145], v[158:161], v[114:117]
	v_mfma_f32_16x16x32_bf16 v[110:113], v[134:137], v[166:169], v[110:113]
	v_mfma_f32_16x16x32_bf16 v[106:109], v[142:145], v[166:169], v[106:109]
	v_mfma_f32_16x16x32_bf16 v[102:105], v[134:137], v[186:189], v[102:105]
	v_mfma_f32_16x16x32_bf16 v[98:101], v[142:145], v[186:189], v[98:101]
	v_mfma_f32_16x16x32_bf16 v[62:65], v[190:193], v[146:149], v[62:65]
	v_mfma_f32_16x16x32_bf16 v[58:61], v[198:201], v[146:149], v[58:61]
	v_mfma_f32_16x16x32_bf16 v[54:57], v[190:193], v[154:157], v[54:57]
	v_mfma_f32_16x16x32_bf16 v[50:53], v[198:201], v[154:157], v[50:53]
	v_mfma_f32_16x16x32_bf16 v[46:49], v[190:193], v[162:165], v[46:49]
	v_mfma_f32_16x16x32_bf16 v[42:45], v[198:201], v[162:165], v[42:45]
	v_mfma_f32_16x16x32_bf16 v[38:41], v[190:193], v[178:181], v[38:41]
	v_mfma_f32_16x16x32_bf16 v[34:37], v[198:201], v[178:181], v[34:37]
	v_mfma_f32_16x16x32_bf16 v[62:65], v[194:197], v[150:153], v[62:65]
	v_mfma_f32_16x16x32_bf16 v[58:61], v[226:229], v[150:153], v[58:61]
	v_mfma_f32_16x16x32_bf16 v[54:57], v[194:197], v[158:161], v[54:57]
	v_mfma_f32_16x16x32_bf16 v[50:53], v[226:229], v[158:161], v[50:53]
	s_mov_b32 m0, s80
	v_lshl_add_u64 v[234:235], v[234:235], 0, s[20:21]
	v_mfma_f32_16x16x32_bf16 v[46:49], v[194:197], v[166:169], v[46:49]
	v_mfma_f32_16x16x32_bf16 v[42:45], v[226:229], v[166:169], v[42:45]
	v_mfma_f32_16x16x32_bf16 v[38:41], v[194:197], v[186:189], v[38:41]
	v_mfma_f32_16x16x32_bf16 v[34:37], v[226:229], v[186:189], v[34:37]
	s_setprio 0
	s_barrier
	ds_read_b128 v[146:149], v184 offset:49152
	ds_read_b128 v[150:153], v184 offset:50176
	ds_read_b128 v[154:157], v184 offset:51200
	ds_read_b128 v[158:161], v184 offset:52224
	ds_read_b128 v[162:165], v184 offset:53248
	ds_read_b128 v[166:169], v184 offset:54272
	ds_read_b128 v[178:181], v184 offset:55296
	ds_read_b128 v[186:189], v184 offset:56320
	global_load_lds_dwordx4 v[234:235], off
	v_lshl_add_u64 v[236:237], v[236:237], 0, s[20:21]
	s_mov_b32 m0, s81
	s_nop 0
	global_load_lds_dwordx4 v[236:237], off
	v_lshl_add_u64 v[230:231], v[230:231], 0, s[20:21]
	s_mov_b32 m0, s3
	s_nop 0
	global_load_lds_dwordx4 v[230:231], off
	v_lshl_add_u64 v[230:231], v[232:233], 0, s[20:21]
	s_add_i32 m0, s3, 0x2000
	s_nop 0
	global_load_lds_dwordx4 v[230:231], off
	s_add_i32 s2, s2, s54
	v_lshl_add_u64 v[242:243], v[242:243], 0, s[20:21]
	s_mov_b32 m0, s2
	s_nop 0
	global_load_lds_dwordx4 v[242:243], off
	v_lshl_add_u64 v[244:245], v[244:245], 0, s[20:21]
	s_add_i32 m0, s2, 0x2000
	s_nop 0
	global_load_lds_dwordx4 v[244:245], off
	s_waitcnt vmcnt(6)
	s_barrier
	s_waitcnt lgkmcnt(0)
	s_setprio 3
	v_mfma_f32_16x16x32_bf16 v[94:97], v[130:133], v[146:149], v[94:97]
	v_mfma_f32_16x16x32_bf16 v[90:93], v[138:141], v[146:149], v[90:93]
	v_mfma_f32_16x16x32_bf16 v[86:89], v[130:133], v[154:157], v[86:89]
	v_mfma_f32_16x16x32_bf16 v[82:85], v[138:141], v[154:157], v[82:85]
	v_mfma_f32_16x16x32_bf16 v[78:81], v[130:133], v[162:165], v[78:81]
	v_mfma_f32_16x16x32_bf16 v[74:77], v[138:141], v[162:165], v[74:77]
	v_mfma_f32_16x16x32_bf16 v[70:73], v[130:133], v[178:181], v[70:73]
	v_mfma_f32_16x16x32_bf16 v[66:69], v[138:141], v[178:181], v[66:69]
	v_mfma_f32_16x16x32_bf16 v[94:97], v[134:137], v[150:153], v[94:97]
	v_mfma_f32_16x16x32_bf16 v[90:93], v[142:145], v[150:153], v[90:93]
	v_mfma_f32_16x16x32_bf16 v[86:89], v[134:137], v[158:161], v[86:89]
	v_mfma_f32_16x16x32_bf16 v[82:85], v[142:145], v[158:161], v[82:85]
	v_mfma_f32_16x16x32_bf16 v[78:81], v[134:137], v[166:169], v[78:81]
	v_mfma_f32_16x16x32_bf16 v[74:77], v[142:145], v[166:169], v[74:77]
	v_mfma_f32_16x16x32_bf16 v[70:73], v[134:137], v[186:189], v[70:73]
	v_mfma_f32_16x16x32_bf16 v[66:69], v[142:145], v[186:189], v[66:69]
	v_mfma_f32_16x16x32_bf16 v[30:33], v[190:193], v[146:149], v[30:33]
	v_mfma_f32_16x16x32_bf16 v[26:29], v[198:201], v[146:149], v[26:29]
	v_mfma_f32_16x16x32_bf16 v[22:25], v[190:193], v[154:157], v[22:25]
	v_mfma_f32_16x16x32_bf16 v[18:21], v[198:201], v[154:157], v[18:21]
	v_mfma_f32_16x16x32_bf16 v[14:17], v[190:193], v[162:165], v[14:17]
	v_mfma_f32_16x16x32_bf16 v[10:13], v[198:201], v[162:165], v[10:13]
	v_mfma_f32_16x16x32_bf16 v[6:9], v[190:193], v[178:181], v[6:9]
	v_mfma_f32_16x16x32_bf16 v[2:5], v[198:201], v[178:181], v[2:5]
	v_mfma_f32_16x16x32_bf16 v[30:33], v[194:197], v[150:153], v[30:33]
	v_mfma_f32_16x16x32_bf16 v[26:29], v[226:229], v[150:153], v[26:29]
	v_mfma_f32_16x16x32_bf16 v[22:25], v[194:197], v[158:161], v[22:25]
	v_mfma_f32_16x16x32_bf16 v[18:21], v[226:229], v[158:161], v[18:21]
	s_add_u32 s34, s34, 0x100
	s_addc_u32 s35, s35, 0
	s_add_u32 s89, s89, 0x100
	s_addc_u32 s90, s90, 0
	s_cmp_ge_i32 s91, s44
	s_mov_b32 s2, s91
	v_mfma_f32_16x16x32_bf16 v[14:17], v[194:197], v[166:169], v[14:17]
	v_mfma_f32_16x16x32_bf16 v[10:13], v[226:229], v[166:169], v[10:13]
	v_mfma_f32_16x16x32_bf16 v[6:9], v[194:197], v[186:189], v[6:9]
	v_mfma_f32_16x16x32_bf16 v[2:5], v[226:229], v[186:189], v[2:5]
	s_setprio 0
	s_barrier
	s_cbranch_scc0 .LBB0_182

.LBB0_322:
	s_or_b64 s[0:1], s[18:19], s[68:69]
	s_waitcnt vmcnt(0)
	s_or_b64 s[2:3], s[16:17], s[50:51]
	v_cndmask_b32_e64 v162, 0, 1, s[14:15]
	v_cndmask_b32_e64 v0, 0, 1, s[2:3]
	s_and_b64 s[14:15], s[2:3], s[0:1]
	s_mov_b32 s77, 0x5c000
	s_mov_b64 s[2:3], -1
	s_andn2_b64 vcc, exec, s[14:15]
	v_cmp_ne_u32_e64 s[38:39], 1, v0
	s_cbranch_vccz .LBB0_328
	v_mov_b64_e32 v[80:81], v[112:113]
	v_mov_b64_e32 v[76:77], v[108:109]
	v_mov_b64_e32 v[72:73], v[104:105]
	v_mov_b64_e32 v[68:69], v[100:101]
	s_and_b64 vcc, exec, s[38:39]
	v_mov_b32_e32 v3, v141
	v_mov_b64_e32 v[82:83], v[114:115]
	v_mov_b64_e32 v[78:79], v[110:111]
	v_mov_b64_e32 v[74:75], v[106:107]
	v_mov_b64_e32 v[70:71], v[102:103]
	s_cbranch_vccnz .LBB0_325
	v_cmp_lt_i32_e32 vcc, v210, v208
	v_bitop3_b32 v2, v164, v157, 4 bitop3:0x36
	v_lshl_add_u32 v134, v139, 9, 0
	v_cndmask_b32_e32 v0, v207, v210, vcc
	v_cmp_lt_i32_e32 vcc, v209, v208
	v_lshlrev_b32_e32 v142, 2, v0
	v_and_b32_e32 v135, 7, v138
	v_cndmask_b32_e32 v0, v207, v209, vcc
	v_lshlrev_b32_e32 v133, 2, v0
	v_and_or_b32 v0, v163, 24, v164
	v_lshl_add_u32 v0, v0, 7, 0
	v_lshl_add_u32 v146, v158, 4, v0
	ds_read_b128 v[68:71], v146
	v_lshl_add_u32 v145, v159, 4, v0
	ds_read_b128 v[72:75], v145
	s_waitcnt lgkmcnt(0)
	s_setprio 3
	v_mfma_f32_16x16x32_bf16 v[68:71], v[68:71], v[52:55], 0
	v_lshl_add_u32 v144, v2, 4, v0
	v_bitop3_b32 v2, v157, v164, 4 bitop3:0x14
	v_lshl_add_u32 v143, v2, 4, v0
	v_mfma_f32_16x16x32_bf16 v[68:71], v[72:75], v[56:59], v[68:71]
	ds_read_b128 v[72:75], v144 offset:512
	ds_read_b128 v[76:79], v143 offset:512
	s_waitcnt lgkmcnt(0)
	v_mfma_f32_16x16x32_bf16 v[72:75], v[72:75], v[52:55], 0
	s_nop 3
	v_max_f32_e32 v0, v69, v69
	v_max_f32_e32 v2, v68, v68
	v_max_f32_e32 v0, v2, v0
	v_mfma_f32_16x16x32_bf16 v[72:75], v[76:79], v[56:59], v[72:75]
	v_max_f32_e32 v2, v71, v71
	v_max_f32_e32 v3, v70, v70
	v_max_f32_e32 v2, v3, v2
	s_nop 4
	v_max_f32_e32 v3, v75, v75
	v_max_f32_e32 v76, v74, v74
	v_max_f32_e32 v3, v76, v3
	v_max3_f32 v3, v72, v73, v3
	v_max3_f32 v0, v0, v2, v3
	ds_bpermute_b32 v2, v142, v0
	s_waitcnt lgkmcnt(0)
	v_max_f32_e32 v2, v2, v2
	v_max_f32_e32 v0, v0, v2
	ds_bpermute_b32 v2, v133, v0
	s_waitcnt lgkmcnt(0)
	v_max3_f32 v3, v165, v0, v2
	v_sub_f32_e32 v0, v68, v3
	v_exp_f32_e32 v68, v0
	v_sub_f32_e32 v2, v69, v3
	v_exp_f32_e32 v69, v2
	v_sub_f32_e32 v2, v70, v3
	v_sub_f32_e32 v70, v71, v3
	v_exp_f32_e32 v120, v70
	v_sub_f32_e32 v70, v72, v3
	v_exp_f32_e32 v122, v70
	v_sub_f32_e32 v70, v73, v3
	v_add_f32_e32 v0, 0, v68
	v_exp_f32_e32 v124, v70
	v_sub_f32_e32 v70, v74, v3
	v_cvt_pk_bf16_f32 v72, v68, v69
	v_bitop3_b32 v68, v157, v138, 7 bitop3:0x78
	v_exp_f32_e32 v126, v70
	v_sub_f32_e32 v70, v75, v3
	v_lshl_add_u32 v121, v68, 4, v134
	v_add_f32_e32 v0, v69, v0
	v_exp_f32_e32 v128, v70
	ds_read_b128 v[68:71], v121 offset:32768
	v_sub_f32_e32 v76, v165, v3
	v_exp_f32_e32 v132, v76
	v_exp_f32_e32 v2, v2
	v_cvt_pk_bf16_f32 v73, v2, v120
	v_cvt_pk_bf16_f32 v74, v122, v124
	v_pk_mul_f32 v[78:79], v[102:103], v[132:133] op_sel_hi:[1,0]
	v_pk_mul_f32 v[76:77], v[100:101], v[132:133] op_sel_hi:[1,0]
	v_cvt_pk_bf16_f32 v75, v126, v128
	v_pk_mul_f32 v[118:119], v[110:111], v[132:133] op_sel_hi:[1,0]
	v_pk_mul_f32 v[116:117], v[108:109], v[132:133] op_sel_hi:[1,0]
	s_waitcnt lgkmcnt(0)
	v_mfma_f32_16x16x32_bf16 v[80:83], v[68:71], v[72:75], v[76:79]
	ds_read_b128 v[68:71], v121 offset:40960
	v_pk_mul_f32 v[150:151], v[114:115], v[132:133] op_sel_hi:[1,0]
	v_pk_mul_f32 v[148:149], v[112:113], v[132:133] op_sel_hi:[1,0]
	v_pk_mul_f32 v[78:79], v[106:107], v[132:133] op_sel_hi:[1,0]
	v_pk_mul_f32 v[76:77], v[104:105], v[132:133] op_sel_hi:[1,0]
	v_mul_f32_e32 v130, v141, v132
	s_waitcnt lgkmcnt(0)
	v_mfma_f32_16x16x32_bf16 v[76:79], v[68:71], v[72:75], v[76:79]
	ds_read_b128 v[68:71], v121 offset:49152
	s_waitcnt lgkmcnt(0)
	v_mfma_f32_16x16x32_bf16 v[68:71], v[68:71], v[72:75], v[116:119]
	s_nop 2
	ds_read_b128 v[116:119], v121 offset:57344
	s_waitcnt lgkmcnt(0)
	v_mfma_f32_16x16x32_bf16 v[72:75], v[116:119], v[72:75], v[148:151]
	ds_read_b128 v[116:119], v146 offset:4096
	s_nop 1
	ds_read_b128 v[148:151], v145 offset:4096
	s_waitcnt lgkmcnt(0)
	v_mfma_f32_16x16x32_bf16 v[116:119], v[116:119], v[52:55], 0
	v_mfma_f32_16x16x32_bf16 v[116:119], v[148:151], v[56:59], v[116:119]
	ds_read_b128 v[148:151], v144 offset:4608
	ds_read_b128 v[152:155], v143 offset:4608
	s_waitcnt lgkmcnt(0)
	v_mfma_f32_16x16x32_bf16 v[148:151], v[148:151], v[52:55], 0
	s_nop 3
	v_max_f32_e32 v121, v117, v117
	v_max_f32_e32 v123, v116, v116
	v_max_f32_e32 v121, v123, v121
	v_mfma_f32_16x16x32_bf16 v[148:151], v[152:155], v[56:59], v[148:151]
	v_max_f32_e32 v123, v119, v119
	v_max_f32_e32 v125, v118, v118
	v_max_f32_e32 v123, v125, v123
	s_nop 4
	v_max_f32_e32 v125, v151, v151
	v_max_f32_e32 v127, v150, v150
	v_max_f32_e32 v125, v127, v125
	v_max3_f32 v125, v148, v149, v125
	v_max3_f32 v121, v121, v123, v125
	ds_bpermute_b32 v123, v142, v121
	s_waitcnt lgkmcnt(0)
	v_max_f32_e32 v123, v123, v123
	v_max_f32_e32 v121, v121, v123
	ds_bpermute_b32 v123, v133, v121
	s_waitcnt lgkmcnt(0)
	v_max3_f32 v147, v3, v121, v123
	v_sub_f32_e32 v132, v3, v147
	v_sub_f32_e32 v3, v116, v147
	v_sub_f32_e32 v116, v117, v147
	v_exp_f32_e32 v121, v116
	v_sub_f32_e32 v116, v118, v147
	v_exp_f32_e32 v123, v116
	v_sub_f32_e32 v116, v119, v147
	v_exp_f32_e32 v3, v3
	v_exp_f32_e32 v125, v116
	v_sub_f32_e32 v116, v148, v147
	v_exp_f32_e32 v127, v116
	v_sub_f32_e32 v116, v149, v147
	v_exp_f32_e32 v129, v116
	v_sub_f32_e32 v116, v150, v147
	v_exp_f32_e32 v131, v116
	v_sub_f32_e32 v116, v151, v147
	v_exp_f32_e32 v119, v116
	v_pk_add_f32 v[116:117], v[2:3], v[0:1]
	v_exp_f32_e32 v132, v132
	v_pk_add_f32 v[116:117], v[120:121], v[116:117]
	v_bitop3_b32 v0, v157, v135, 4 bitop3:0x36
	v_pk_add_f32 v[116:117], v[122:123], v[116:117]
	v_lshl_add_u32 v0, v0, 4, v134
	v_pk_add_f32 v[116:117], v[124:125], v[116:117]
	v_pk_mul_f32 v[82:83], v[82:83], v[132:133] op_sel_hi:[1,0]
	v_pk_add_f32 v[116:117], v[126:127], v[116:117]
	v_pk_mul_f32 v[80:81], v[80:81], v[132:133] op_sel_hi:[1,0]
	v_pk_add_f32 v[116:117], v[128:129], v[116:117]
	v_cvt_pk_bf16_f32 v118, v127, v129
	v_pk_mul_f32 v[78:79], v[78:79], v[132:133] op_sel_hi:[1,0]
	v_pk_add_f32 v[116:117], v[130:131], v[116:117]
	v_pk_mul_f32 v[76:77], v[76:77], v[132:133] op_sel_hi:[1,0]
	v_add_f32_e32 v130, v117, v119
	v_fmac_f32_e32 v130, v116, v132
	v_cvt_pk_bf16_f32 v116, v3, v121
	v_cvt_pk_bf16_f32 v117, v123, v125
	ds_read_b128 v[120:123], v0 offset:32768
	v_cvt_pk_bf16_f32 v119, v131, v119
	v_pk_mul_f32 v[70:71], v[70:71], v[132:133] op_sel_hi:[1,0]
	s_waitcnt lgkmcnt(0)
	v_mfma_f32_16x16x32_bf16 v[80:83], v[120:123], v[116:119], v[80:83]
	ds_read_b128 v[120:123], v0 offset:40960
	v_pk_mul_f32 v[68:69], v[68:69], v[132:133] op_sel_hi:[1,0]
	v_pk_mul_f32 v[74:75], v[74:75], v[132:133] op_sel_hi:[1,0]
	s_waitcnt lgkmcnt(0)
	v_mfma_f32_16x16x32_bf16 v[76:79], v[120:123], v[116:119], v[76:79]
	ds_read_b128 v[120:123], v0 offset:49152
	v_pk_mul_f32 v[72:73], v[72:73], v[132:133] op_sel_hi:[1,0]
	s_waitcnt lgkmcnt(0)
	v_mfma_f32_16x16x32_bf16 v[148:151], v[120:123], v[116:119], v[68:71]
	s_nop 2
	ds_read_b128 v[68:71], v0 offset:57344
	s_waitcnt lgkmcnt(0)
	v_mfma_f32_16x16x32_bf16 v[116:119], v[68:71], v[116:119], v[72:75]
	ds_read_b128 v[68:71], v146 offset:8192
	s_nop 1
	ds_read_b128 v[72:75], v145 offset:8192
	s_waitcnt lgkmcnt(0)
	v_mfma_f32_16x16x32_bf16 v[68:71], v[68:71], v[52:55], 0
	v_mfma_f32_16x16x32_bf16 v[68:71], v[72:75], v[56:59], v[68:71]
	ds_read_b128 v[72:75], v144 offset:8704
	ds_read_b128 v[120:123], v143 offset:8704
	s_waitcnt lgkmcnt(0)
	v_mfma_f32_16x16x32_bf16 v[72:75], v[72:75], v[52:55], 0
	s_nop 3
	v_max_f32_e32 v0, v69, v69
	v_max_f32_e32 v2, v68, v68
	v_max_f32_e32 v0, v2, v0
	v_mfma_f32_16x16x32_bf16 v[72:75], v[120:123], v[56:59], v[72:75]
	v_max_f32_e32 v2, v71, v71
	v_max_f32_e32 v3, v70, v70
	v_max_f32_e32 v2, v3, v2
	s_nop 4
	v_max_f32_e32 v3, v75, v75
	v_max_f32_e32 v120, v74, v74
	v_max_f32_e32 v3, v120, v3
	v_max3_f32 v3, v72, v73, v3
	v_max3_f32 v0, v0, v2, v3
	ds_bpermute_b32 v2, v142, v0
	s_waitcnt lgkmcnt(0)
	v_max_f32_e32 v2, v2, v2
	v_max_f32_e32 v0, v0, v2
	ds_bpermute_b32 v2, v133, v0
	s_waitcnt lgkmcnt(0)
	v_max3_f32 v3, v147, v0, v2
	v_sub_f32_e32 v0, v68, v3
	v_exp_f32_e32 v68, v0
	v_sub_f32_e32 v2, v69, v3
	v_exp_f32_e32 v69, v2
	v_sub_f32_e32 v2, v70, v3
	v_sub_f32_e32 v70, v71, v3
	v_exp_f32_e32 v120, v70
	v_sub_f32_e32 v70, v72, v3
	v_exp_f32_e32 v122, v70
	v_sub_f32_e32 v70, v73, v3
	v_sub_f32_e32 v121, v147, v3
	v_add_f32_e32 v0, 0, v68
	v_exp_f32_e32 v124, v70
	v_sub_f32_e32 v70, v74, v3
	v_cvt_pk_bf16_f32 v152, v68, v69
	v_bitop3_b32 v68, v157, v135, 8 bitop3:0x36
	v_exp_f32_e32 v126, v70
	v_sub_f32_e32 v70, v75, v3
	v_exp_f32_e32 v132, v121
	v_lshl_add_u32 v121, v68, 4, v134
	v_add_f32_e32 v0, v69, v0
	v_exp_f32_e32 v128, v70
	ds_read_b128 v[68:71], v121 offset:32768
	v_pk_mul_f32 v[74:75], v[82:83], v[132:133] op_sel_hi:[1,0]
	v_pk_mul_f32 v[72:73], v[80:81], v[132:133] op_sel_hi:[1,0]
	v_exp_f32_e32 v2, v2
	v_cvt_pk_bf16_f32 v153, v2, v120
	v_cvt_pk_bf16_f32 v154, v122, v124
	v_cvt_pk_bf16_f32 v155, v126, v128
	v_pk_mul_f32 v[118:119], v[118:119], v[132:133] op_sel_hi:[1,0]
	s_waitcnt lgkmcnt(0)
	v_mfma_f32_16x16x32_bf16 v[80:83], v[68:71], v[152:155], v[72:75]
	ds_read_b128 v[68:71], v121 offset:40960
	v_pk_mul_f32 v[116:117], v[116:117], v[132:133] op_sel_hi:[1,0]
	s_nop 0
	v_pk_mul_f32 v[74:75], v[78:79], v[132:133] op_sel_hi:[1,0]
	v_pk_mul_f32 v[72:73], v[76:77], v[132:133] op_sel_hi:[1,0]
	v_pk_mul_f32 v[78:79], v[150:151], v[132:133] op_sel_hi:[1,0]
	v_pk_mul_f32 v[76:77], v[148:149], v[132:133] op_sel_hi:[1,0]
	s_waitcnt lgkmcnt(0)
	v_mfma_f32_16x16x32_bf16 v[68:71], v[68:71], v[152:155], v[72:75]
	s_nop 2
	ds_read_b128 v[72:75], v121 offset:49152
	v_mul_f32_e32 v130, v130, v132
	s_waitcnt lgkmcnt(0)
	v_mfma_f32_16x16x32_bf16 v[72:75], v[72:75], v[152:155], v[76:79]
	s_nop 2
	ds_read_b128 v[76:79], v121 offset:57344
	s_waitcnt lgkmcnt(0)
	v_mfma_f32_16x16x32_bf16 v[76:79], v[76:79], v[152:155], v[116:119]
	s_nop 2
	ds_read_b128 v[116:119], v146 offset:12288
	ds_read_b128 v[148:151], v145 offset:12288
	s_waitcnt lgkmcnt(0)
	v_mfma_f32_16x16x32_bf16 v[116:119], v[116:119], v[52:55], 0
	v_mfma_f32_16x16x32_bf16 v[116:119], v[148:151], v[56:59], v[116:119]
	ds_read_b128 v[148:151], v144 offset:12800
	ds_read_b128 v[152:155], v143 offset:12800
	s_waitcnt lgkmcnt(0)
	v_mfma_f32_16x16x32_bf16 v[148:151], v[148:151], v[52:55], 0
	s_nop 3
	v_max_f32_e32 v121, v117, v117
	v_max_f32_e32 v123, v116, v116
	v_max_f32_e32 v121, v123, v121
	v_mfma_f32_16x16x32_bf16 v[148:151], v[152:155], v[56:59], v[148:151]
	v_max_f32_e32 v123, v119, v119
	v_max_f32_e32 v125, v118, v118
	v_max_f32_e32 v123, v125, v123
	s_nop 4
	v_max_f32_e32 v125, v151, v151
	v_max_f32_e32 v127, v150, v150
	v_max_f32_e32 v125, v127, v125
	v_max3_f32 v125, v148, v149, v125
	v_max3_f32 v121, v121, v123, v125
	ds_bpermute_b32 v123, v142, v121
	s_waitcnt lgkmcnt(0)
	v_max_f32_e32 v123, v123, v123
	v_max_f32_e32 v121, v121, v123
	ds_bpermute_b32 v123, v133, v121
	s_waitcnt lgkmcnt(0)
	v_max3_f32 v147, v3, v121, v123
	v_sub_f32_e32 v132, v3, v147
	v_sub_f32_e32 v3, v116, v147
	v_sub_f32_e32 v116, v117, v147
	v_exp_f32_e32 v121, v116
	v_sub_f32_e32 v116, v118, v147
	v_exp_f32_e32 v123, v116
	v_sub_f32_e32 v116, v119, v147
	v_exp_f32_e32 v3, v3
	v_exp_f32_e32 v125, v116
	v_sub_f32_e32 v116, v148, v147
	v_exp_f32_e32 v127, v116
	v_sub_f32_e32 v116, v149, v147
	v_exp_f32_e32 v129, v116
	v_sub_f32_e32 v116, v150, v147
	v_exp_f32_e32 v131, v116
	v_sub_f32_e32 v116, v151, v147
	v_exp_f32_e32 v119, v116
	v_pk_add_f32 v[116:117], v[2:3], v[0:1]
	v_exp_f32_e32 v132, v132
	v_pk_add_f32 v[116:117], v[120:121], v[116:117]
	v_bitop3_b32 v0, v157, v135, 12 bitop3:0x36
	v_pk_add_f32 v[116:117], v[122:123], v[116:117]
	v_lshl_add_u32 v0, v0, 4, v134
	v_pk_add_f32 v[116:117], v[124:125], v[116:117]
	v_pk_mul_f32 v[82:83], v[82:83], v[132:133] op_sel_hi:[1,0]
	v_pk_add_f32 v[116:117], v[126:127], v[116:117]
	v_pk_mul_f32 v[80:81], v[80:81], v[132:133] op_sel_hi:[1,0]
	v_pk_add_f32 v[116:117], v[128:129], v[116:117]
	v_cvt_pk_bf16_f32 v118, v127, v129
	v_pk_mul_f32 v[70:71], v[70:71], v[132:133] op_sel_hi:[1,0]
	v_pk_add_f32 v[116:117], v[130:131], v[116:117]
	v_pk_mul_f32 v[68:69], v[68:69], v[132:133] op_sel_hi:[1,0]
	v_add_f32_e32 v130, v117, v119
	v_fmac_f32_e32 v130, v116, v132
	v_cvt_pk_bf16_f32 v116, v3, v121
	v_cvt_pk_bf16_f32 v117, v123, v125
	ds_read_b128 v[120:123], v0 offset:32768
	v_cvt_pk_bf16_f32 v119, v131, v119
	v_pk_mul_f32 v[74:75], v[74:75], v[132:133] op_sel_hi:[1,0]
	s_waitcnt lgkmcnt(0)
	v_mfma_f32_16x16x32_bf16 v[80:83], v[120:123], v[116:119], v[80:83]
	ds_read_b128 v[120:123], v0 offset:40960
	v_pk_mul_f32 v[72:73], v[72:73], v[132:133] op_sel_hi:[1,0]
	v_pk_mul_f32 v[78:79], v[78:79], v[132:133] op_sel_hi:[1,0]
	s_waitcnt lgkmcnt(0)
	v_mfma_f32_16x16x32_bf16 v[68:71], v[120:123], v[116:119], v[68:71]
	ds_read_b128 v[120:123], v0 offset:49152
	v_pk_mul_f32 v[76:77], v[76:77], v[132:133] op_sel_hi:[1,0]
	s_waitcnt lgkmcnt(0)
	v_mfma_f32_16x16x32_bf16 v[72:75], v[120:123], v[116:119], v[72:75]
	ds_read_b128 v[120:123], v0 offset:57344
	s_waitcnt lgkmcnt(0)
	v_mfma_f32_16x16x32_bf16 v[76:79], v[120:123], v[116:119], v[76:79]
	ds_read_b128 v[116:119], v146 offset:16384
	ds_read_b128 v[120:123], v145 offset:16384
	s_waitcnt lgkmcnt(0)
	v_mfma_f32_16x16x32_bf16 v[116:119], v[116:119], v[52:55], 0
	v_mfma_f32_16x16x32_bf16 v[116:119], v[120:123], v[56:59], v[116:119]
	ds_read_b128 v[120:123], v144 offset:16896
	ds_read_b128 v[124:127], v143 offset:16896
	s_waitcnt lgkmcnt(0)
	v_mfma_f32_16x16x32_bf16 v[120:123], v[120:123], v[52:55], 0
	s_nop 3
	v_max_f32_e32 v0, v117, v117
	v_max_f32_e32 v2, v116, v116
	v_max_f32_e32 v0, v2, v0
	v_mfma_f32_16x16x32_bf16 v[124:127], v[124:127], v[56:59], v[120:123]
	v_max_f32_e32 v2, v119, v119
	v_max_f32_e32 v3, v118, v118
	v_max_f32_e32 v2, v3, v2
	s_nop 4
	v_max_f32_e32 v3, v127, v127
	v_max_f32_e32 v120, v126, v126
	v_max_f32_e32 v3, v120, v3
	v_max3_f32 v3, v124, v125, v3
	v_max3_f32 v0, v0, v2, v3
	ds_bpermute_b32 v2, v142, v0
	s_waitcnt lgkmcnt(0)
	v_max_f32_e32 v2, v2, v2
	v_max_f32_e32 v0, v0, v2
	ds_bpermute_b32 v2, v133, v0
	s_waitcnt lgkmcnt(0)
	v_max3_f32 v3, v147, v0, v2
	v_sub_f32_e32 v121, v147, v3
	v_exp_f32_e32 v132, v121
	v_bitop3_b32 v121, v157, v135, 16 bitop3:0x36
	v_lshl_add_u32 v121, v121, 4, v134
	ds_read_b128 v[148:151], v121 offset:32768
	v_sub_f32_e32 v0, v116, v3
	v_sub_f32_e32 v2, v117, v3
	v_exp_f32_e32 v116, v0
	v_exp_f32_e32 v117, v2
	v_sub_f32_e32 v2, v118, v3
	v_sub_f32_e32 v118, v119, v3
	v_exp_f32_e32 v120, v118
	v_sub_f32_e32 v118, v124, v3
	v_exp_f32_e32 v122, v118
	v_sub_f32_e32 v118, v125, v3
	v_exp_f32_e32 v124, v118
	v_sub_f32_e32 v118, v126, v3
	v_add_f32_e32 v0, 0, v116
	v_exp_f32_e32 v126, v118
	v_sub_f32_e32 v118, v127, v3
	v_pk_mul_f32 v[82:83], v[82:83], v[132:133] op_sel_hi:[1,0]
	v_pk_mul_f32 v[80:81], v[80:81], v[132:133] op_sel_hi:[1,0]
	v_add_f32_e32 v0, v117, v0
	v_exp_f32_e32 v2, v2
	v_exp_f32_e32 v128, v118
	v_cvt_pk_bf16_f32 v116, v116, v117
	v_cvt_pk_bf16_f32 v117, v2, v120
	v_cvt_pk_bf16_f32 v118, v122, v124
	v_cvt_pk_bf16_f32 v119, v126, v128
	v_pk_mul_f32 v[70:71], v[70:71], v[132:133] op_sel_hi:[1,0]
	s_waitcnt lgkmcnt(0)
	v_mfma_f32_16x16x32_bf16 v[80:83], v[148:151], v[116:119], v[80:83]
	ds_read_b128 v[148:151], v121 offset:40960
	v_pk_mul_f32 v[68:69], v[68:69], v[132:133] op_sel_hi:[1,0]
	v_pk_mul_f32 v[74:75], v[74:75], v[132:133] op_sel_hi:[1,0]
	v_pk_mul_f32 v[72:73], v[72:73], v[132:133] op_sel_hi:[1,0]
	s_waitcnt lgkmcnt(0)
	v_mfma_f32_16x16x32_bf16 v[68:71], v[148:151], v[116:119], v[68:71]
	ds_read_b128 v[148:151], v121 offset:49152
	v_pk_mul_f32 v[78:79], v[78:79], v[132:133] op_sel_hi:[1,0]
	v_pk_mul_f32 v[76:77], v[76:77], v[132:133] op_sel_hi:[1,0]
	s_waitcnt lgkmcnt(0)
	v_mfma_f32_16x16x32_bf16 v[72:75], v[148:151], v[116:119], v[72:75]
	ds_read_b128 v[148:151], v121 offset:57344
	v_mul_f32_e32 v130, v130, v132
	s_waitcnt lgkmcnt(0)
	v_mfma_f32_16x16x32_bf16 v[76:79], v[148:151], v[116:119], v[76:79]
	ds_read_b128 v[116:119], v146 offset:20480
	ds_read_b128 v[148:151], v145 offset:20480
	s_waitcnt lgkmcnt(0)
	v_mfma_f32_16x16x32_bf16 v[116:119], v[116:119], v[52:55], 0
	v_mfma_f32_16x16x32_bf16 v[116:119], v[148:151], v[56:59], v[116:119]
	ds_read_b128 v[148:151], v144 offset:20992
	ds_read_b128 v[152:155], v143 offset:20992
	s_waitcnt lgkmcnt(0)
	v_mfma_f32_16x16x32_bf16 v[148:151], v[148:151], v[52:55], 0
	s_nop 3
	v_max_f32_e32 v121, v117, v117
	v_max_f32_e32 v123, v116, v116
	v_max_f32_e32 v121, v123, v121
	v_mfma_f32_16x16x32_bf16 v[148:151], v[152:155], v[56:59], v[148:151]
	v_max_f32_e32 v123, v119, v119
	v_max_f32_e32 v125, v118, v118
	v_max_f32_e32 v123, v125, v123
	s_nop 4
	v_max_f32_e32 v125, v151, v151
	v_max_f32_e32 v127, v150, v150
	v_max_f32_e32 v125, v127, v125
	v_max3_f32 v125, v148, v149, v125
	v_max3_f32 v121, v121, v123, v125
	ds_bpermute_b32 v123, v142, v121
	s_waitcnt lgkmcnt(0)
	v_max_f32_e32 v123, v123, v123
	v_max_f32_e32 v121, v121, v123
	ds_bpermute_b32 v123, v133, v121
	s_waitcnt lgkmcnt(0)
	v_max3_f32 v147, v3, v121, v123
	v_sub_f32_e32 v132, v3, v147
	v_sub_f32_e32 v3, v116, v147
	v_sub_f32_e32 v116, v117, v147
	v_exp_f32_e32 v121, v116
	v_sub_f32_e32 v116, v118, v147
	v_exp_f32_e32 v123, v116
	v_sub_f32_e32 v116, v119, v147
	v_exp_f32_e32 v3, v3
	v_exp_f32_e32 v125, v116
	v_sub_f32_e32 v116, v148, v147
	v_exp_f32_e32 v127, v116
	v_sub_f32_e32 v116, v149, v147
	v_exp_f32_e32 v129, v116
	v_sub_f32_e32 v116, v150, v147
	v_exp_f32_e32 v131, v116
	v_sub_f32_e32 v116, v151, v147
	v_exp_f32_e32 v119, v116
	v_pk_add_f32 v[116:117], v[2:3], v[0:1]
	v_exp_f32_e32 v132, v132
	v_pk_add_f32 v[116:117], v[120:121], v[116:117]
	v_bitop3_b32 v0, v157, v135, 20 bitop3:0x36
	v_pk_add_f32 v[116:117], v[122:123], v[116:117]
	v_lshl_add_u32 v0, v0, 4, v134
	v_pk_add_f32 v[116:117], v[124:125], v[116:117]
	v_pk_mul_f32 v[82:83], v[82:83], v[132:133] op_sel_hi:[1,0]
	v_pk_add_f32 v[116:117], v[126:127], v[116:117]
	v_pk_mul_f32 v[80:81], v[80:81], v[132:133] op_sel_hi:[1,0]
	v_pk_add_f32 v[116:117], v[128:129], v[116:117]
	v_cvt_pk_bf16_f32 v118, v127, v129
	v_pk_mul_f32 v[70:71], v[70:71], v[132:133] op_sel_hi:[1,0]
	v_pk_add_f32 v[116:117], v[130:131], v[116:117]
	v_pk_mul_f32 v[68:69], v[68:69], v[132:133] op_sel_hi:[1,0]
	v_add_f32_e32 v167, v117, v119
	v_fmac_f32_e32 v167, v116, v132
	v_cvt_pk_bf16_f32 v116, v3, v121
	v_cvt_pk_bf16_f32 v117, v123, v125
	ds_read_b128 v[120:123], v0 offset:32768
	v_cvt_pk_bf16_f32 v119, v131, v119
	v_pk_mul_f32 v[74:75], v[74:75], v[132:133] op_sel_hi:[1,0]
	s_waitcnt lgkmcnt(0)
	v_mfma_f32_16x16x32_bf16 v[80:83], v[120:123], v[116:119], v[80:83]
	ds_read_b128 v[120:123], v0 offset:40960
	v_pk_mul_f32 v[72:73], v[72:73], v[132:133] op_sel_hi:[1,0]
	s_waitcnt lgkmcnt(0)
	v_mfma_f32_16x16x32_bf16 v[148:151], v[120:123], v[116:119], v[68:71]
	s_nop 2
	ds_read_b128 v[68:71], v0 offset:49152
	s_waitcnt lgkmcnt(0)
	v_mfma_f32_16x16x32_bf16 v[152:155], v[68:71], v[116:119], v[72:75]
	ds_read_b128 v[68:71], v0 offset:57344
	s_nop 1
	v_pk_mul_f32 v[74:75], v[78:79], v[132:133] op_sel_hi:[1,0]
	v_pk_mul_f32 v[72:73], v[76:77], v[132:133] op_sel_hi:[1,0]
	s_waitcnt lgkmcnt(0)
	s_nop 0
	v_mfma_f32_16x16x32_bf16 v[116:119], v[68:71], v[116:119], v[72:75]
	ds_read_b128 v[68:71], v146 offset:24576
	s_nop 1
	ds_read_b128 v[72:75], v145 offset:24576
	s_waitcnt lgkmcnt(0)
	v_mfma_f32_16x16x32_bf16 v[68:71], v[68:71], v[52:55], 0
	v_mfma_f32_16x16x32_bf16 v[68:71], v[72:75], v[56:59], v[68:71]
	ds_read_b128 v[72:75], v144 offset:25088
	ds_read_b128 v[76:79], v143 offset:25088
	s_waitcnt lgkmcnt(0)
	v_mfma_f32_16x16x32_bf16 v[72:75], v[72:75], v[52:55], 0
	s_nop 3
	v_max_f32_e32 v0, v69, v69
	v_max_f32_e32 v2, v68, v68
	v_max_f32_e32 v0, v2, v0
	v_mfma_f32_16x16x32_bf16 v[72:75], v[76:79], v[56:59], v[72:75]
	v_max_f32_e32 v2, v71, v71
	v_max_f32_e32 v3, v70, v70
	v_max_f32_e32 v2, v3, v2
	s_nop 4
	v_max_f32_e32 v3, v75, v75
	v_max_f32_e32 v76, v74, v74
	v_max_f32_e32 v3, v76, v3
	v_max3_f32 v3, v72, v73, v3
	v_max3_f32 v0, v0, v2, v3
	ds_bpermute_b32 v2, v142, v0
	s_waitcnt lgkmcnt(0)
	v_max_f32_e32 v2, v2, v2
	v_max_f32_e32 v0, v0, v2
	ds_bpermute_b32 v2, v133, v0
	s_waitcnt lgkmcnt(0)
	v_max3_f32 v2, v147, v0, v2
	v_sub_f32_e32 v0, v68, v2
	v_sub_f32_e32 v70, v70, v2
	v_exp_f32_e32 v68, v0
	v_sub_f32_e32 v69, v69, v2
	v_exp_f32_e32 v120, v70
	v_sub_f32_e32 v70, v71, v2
	v_exp_f32_e32 v69, v69
	v_exp_f32_e32 v122, v70
	v_sub_f32_e32 v70, v72, v2
	v_sub_f32_e32 v3, v147, v2
	v_exp_f32_e32 v124, v70
	v_sub_f32_e32 v70, v73, v2
	v_exp_f32_e32 v126, v70
	v_sub_f32_e32 v70, v74, v2
	v_exp_f32_e32 v172, v3
	v_bitop3_b32 v3, v157, v135, 24 bitop3:0x36
	v_add_f32_e32 v0, 0, v68
	v_exp_f32_e32 v128, v70
	v_sub_f32_e32 v70, v75, v2
	v_lshl_add_u32 v3, v3, 4, v134
	v_add_f32_e32 v0, v69, v0
	v_exp_f32_e32 v130, v70
	v_cvt_pk_bf16_f32 v168, v68, v69
	ds_read_b128 v[68:71], v3 offset:32768
	v_pk_mul_f32 v[74:75], v[82:83], v[172:173] op_sel_hi:[1,0]
	v_pk_mul_f32 v[72:73], v[80:81], v[172:173] op_sel_hi:[1,0]
	v_cvt_pk_bf16_f32 v169, v120, v122
	v_cvt_pk_bf16_f32 v170, v124, v126
	v_cvt_pk_bf16_f32 v171, v128, v130
	v_pk_mul_f32 v[78:79], v[150:151], v[172:173] op_sel_hi:[1,0]
	v_pk_mul_f32 v[76:77], v[148:149], v[172:173] op_sel_hi:[1,0]
	s_waitcnt lgkmcnt(0)
	v_mfma_f32_16x16x32_bf16 v[68:71], v[68:71], v[168:171], v[72:75]
	v_mul_f32_e64 v82, v154, v172
	v_mul_f32_e64 v83, v155, v172
	v_pk_mul_f32 v[80:81], v[152:153], v[172:173] op_sel_hi:[1,0]
	ds_read_b128 v[72:75], v3 offset:40960
	s_waitcnt lgkmcnt(0)
	v_mfma_f32_16x16x32_bf16 v[72:75], v[72:75], v[168:171], v[76:79]
	s_nop 2
	ds_read_b128 v[76:79], v3 offset:49152
	v_pk_mul_f32 v[118:119], v[118:119], v[172:173] op_sel_hi:[1,0]
	v_pk_mul_f32 v[116:117], v[116:117], v[172:173] op_sel_hi:[1,0]
	s_waitcnt lgkmcnt(0)
	v_mfma_f32_16x16x32_bf16 v[76:79], v[76:79], v[168:171], v[80:83]
	s_nop 2
	ds_read_b128 v[80:83], v3 offset:57344
	v_mul_f32_e32 v132, v167, v172
	s_waitcnt lgkmcnt(0)
	v_mfma_f32_16x16x32_bf16 v[80:83], v[80:83], v[168:171], v[116:119]
	s_nop 2
	ds_read_b128 v[116:119], v146 offset:28672
	ds_read_b128 v[146:149], v145 offset:28672
	s_waitcnt lgkmcnt(0)
	v_mfma_f32_16x16x32_bf16 v[116:119], v[116:119], v[52:55], 0
	v_mfma_f32_16x16x32_bf16 v[116:119], v[146:149], v[56:59], v[116:119]
	ds_read_b128 v[144:147], v144 offset:29184
	ds_read_b128 v[148:151], v143 offset:29184
	s_waitcnt lgkmcnt(0)
	v_mfma_f32_16x16x32_bf16 v[144:147], v[144:147], v[52:55], 0
	s_nop 3
	v_max_f32_e32 v3, v117, v117
	v_max_f32_e32 v121, v116, v116
	v_max_f32_e32 v3, v121, v3
	v_mfma_f32_16x16x32_bf16 v[144:147], v[148:151], v[56:59], v[144:147]
	v_max_f32_e32 v121, v119, v119
	v_max_f32_e32 v123, v118, v118
	v_max_f32_e32 v121, v123, v121
	s_nop 4
	v_max_f32_e32 v123, v147, v147
	v_max_f32_e32 v125, v146, v146
	v_max_f32_e32 v123, v125, v123
	v_max3_f32 v123, v144, v145, v123
	v_max3_f32 v3, v3, v121, v123
	ds_bpermute_b32 v121, v142, v3
	s_waitcnt lgkmcnt(0)
	v_max_f32_e32 v121, v121, v121
	v_max_f32_e32 v3, v3, v121
	ds_bpermute_b32 v121, v133, v3
	s_waitcnt lgkmcnt(0)
	v_max3_f32 v3, v2, v3, v121
	v_sub_f32_e32 v116, v116, v3
	v_exp_f32_e32 v121, v116
	v_sub_f32_e32 v116, v117, v3
	v_exp_f32_e32 v123, v116
	v_sub_f32_e32 v116, v118, v3
	v_exp_f32_e32 v125, v116
	v_sub_f32_e32 v116, v119, v3
	v_exp_f32_e32 v127, v116
	v_sub_f32_e32 v116, v144, v3
	v_exp_f32_e32 v129, v116
	v_sub_f32_e32 v116, v145, v3
	v_exp_f32_e32 v131, v116
	v_sub_f32_e32 v116, v146, v3
	v_exp_f32_e32 v133, v116
	v_pk_add_f32 v[116:117], v[120:121], v[0:1]
	v_sub_f32_e32 v2, v2, v3
	v_pk_add_f32 v[116:117], v[122:123], v[116:117]
	v_sub_f32_e32 v3, v147, v3
	v_pk_add_f32 v[116:117], v[124:125], v[116:117]
	v_exp_f32_e32 v119, v3
	v_pk_add_f32 v[116:117], v[126:127], v[116:117]
	v_exp_f32_e32 v2, v2
	v_pk_add_f32 v[116:117], v[128:129], v[116:117]
	v_bitop3_b32 v0, v157, v135, 28 bitop3:0x36
	v_pk_add_f32 v[116:117], v[130:131], v[116:117]
	v_lshl_add_u32 v0, v0, 4, v134
	v_pk_add_f32 v[116:117], v[132:133], v[116:117]
	v_cvt_pk_bf16_f32 v118, v129, v131
	s_nop 0
	v_add_f32_e32 v3, v117, v119
	v_fmac_f32_e32 v3, v116, v2
	v_cvt_pk_bf16_f32 v116, v121, v123
	ds_read_b128 v[120:123], v0 offset:32768
	v_pk_mul_f32 v[70:71], v[70:71], v[2:3] op_sel_hi:[1,0]
	v_pk_mul_f32 v[68:69], v[68:69], v[2:3] op_sel_hi:[1,0]
	v_cvt_pk_bf16_f32 v117, v125, v127
	v_cvt_pk_bf16_f32 v119, v133, v119
	v_pk_mul_f32 v[74:75], v[74:75], v[2:3] op_sel_hi:[1,0]
	v_pk_mul_f32 v[72:73], v[72:73], v[2:3] op_sel_hi:[1,0]
	s_waitcnt lgkmcnt(0)
	v_mfma_f32_16x16x32_bf16 v[68:71], v[120:123], v[116:119], v[68:71]
	ds_read_b128 v[120:123], v0 offset:40960
	v_pk_mul_f32 v[78:79], v[78:79], v[2:3] op_sel_hi:[1,0]
	v_pk_mul_f32 v[76:77], v[76:77], v[2:3] op_sel_hi:[1,0]
	s_waitcnt lgkmcnt(0)
	v_mfma_f32_16x16x32_bf16 v[72:75], v[120:123], v[116:119], v[72:75]
	ds_read_b128 v[120:123], v0 offset:49152
	v_pk_mul_f32 v[82:83], v[82:83], v[2:3] op_sel_hi:[1,0]
	v_pk_mul_f32 v[80:81], v[80:81], v[2:3] op_sel_hi:[1,0]
	s_waitcnt lgkmcnt(0)
	v_mfma_f32_16x16x32_bf16 v[76:79], v[120:123], v[116:119], v[76:79]
	ds_read_b128 v[120:123], v0 offset:57344
	s_waitcnt lgkmcnt(0)
	v_mfma_f32_16x16x32_bf16 v[80:83], v[120:123], v[116:119], v[80:83]
	s_setprio 0
.LBB0_325:
	s_andn2_b64 vcc, exec, s[0:1]
	s_cbranch_vccnz .LBB0_327
	v_cmp_lt_i32_e32 vcc, v210, v208
	v_bitop3_b32 v124, v157, v164, 4 bitop3:0x14
	v_lshl_add_u32 v2, v139, 9, 0
	v_cndmask_b32_e32 v0, v207, v210, vcc
	v_cmp_lt_i32_e32 vcc, v209, v208
	v_lshlrev_b32_e32 v169, 2, v0
	v_and_b32_e32 v167, 7, v138
	v_cndmask_b32_e32 v0, v207, v209, vcc
	v_lshlrev_b32_e32 v168, 2, v0
	v_and_or_b32 v0, v163, 24, v164
	v_lshl_add_u32 v0, v0, 7, 0
	v_lshl_add_u32 v173, v158, 4, v0
	ds_read_b128 v[116:119], v173
	v_lshl_add_u32 v172, v159, 4, v0
	ds_read_b128 v[120:123], v172
	s_waitcnt lgkmcnt(0)
	s_setprio 3
	v_mfma_f32_16x16x32_bf16 v[116:119], v[116:119], v[60:63], 0
	v_lshl_add_u32 v170, v124, 4, v0
	ds_read_b128 v[124:127], v170 offset:512
	s_mov_b64 s[2:3], 0
	v_mfma_f32_16x16x32_bf16 v[116:119], v[120:123], v[64:67], v[116:119]
	v_bitop3_b32 v120, v164, v157, 4 bitop3:0x36
	v_lshl_add_u32 v171, v120, 4, v0
	ds_read_b128 v[120:123], v171 offset:512
	s_waitcnt lgkmcnt(0)
	v_mfma_f32_16x16x32_bf16 v[120:123], v[120:123], v[60:63], 0
	s_nop 2
	v_max_f32_e32 v0, v117, v117
	v_mfma_f32_16x16x32_bf16 v[120:123], v[124:127], v[64:67], v[120:123]
	v_max_f32_e32 v124, v116, v116
	v_max_f32_e32 v0, v124, v0
	v_max_f32_e32 v124, v119, v119
	v_max_f32_e32 v125, v118, v118
	v_max_f32_e32 v124, v125, v124
	s_nop 2
	v_max_f32_e32 v125, v123, v123
	v_max_f32_e32 v126, v122, v122
	v_max_f32_e32 v125, v126, v125
	v_max3_f32 v125, v120, v121, v125
	v_max3_f32 v0, v0, v124, v125
	ds_bpermute_b32 v124, v169, v0
	s_waitcnt lgkmcnt(0)
	v_max_f32_e32 v124, v124, v124
	v_max_f32_e32 v0, v0, v124
	ds_bpermute_b32 v124, v168, v0
	s_waitcnt lgkmcnt(0)
	v_max3_f32 v143, v166, v0, v124
	v_sub_f32_e32 v0, v116, v143
	v_exp_f32_e32 v116, v0
	v_sub_f32_e32 v118, v118, v143
	v_sub_f32_e32 v117, v117, v143
	v_exp_f32_e32 v142, v118
	v_sub_f32_e32 v118, v119, v143
	v_exp_f32_e32 v117, v117
	v_exp_f32_e32 v144, v118
	v_sub_f32_e32 v118, v120, v143
	v_exp_f32_e32 v146, v118
	v_sub_f32_e32 v118, v121, v143
	v_add_f32_e32 v0, 0, v116
	v_exp_f32_e32 v148, v118
	v_sub_f32_e32 v118, v122, v143
	v_cvt_pk_bf16_f32 v120, v116, v117
	v_bitop3_b32 v116, v157, v138, 7 bitop3:0x78
	v_exp_f32_e32 v150, v118
	v_sub_f32_e32 v118, v123, v143
	v_lshl_add_u32 v145, v116, 4, v2
	v_add_f32_e32 v0, v117, v0
	v_exp_f32_e32 v152, v118
	ds_read_b128 v[116:119], v145 offset:32768
	v_sub_f32_e32 v124, v166, v143
	v_exp_f32_e32 v174, v124
	v_cvt_pk_bf16_f32 v121, v142, v144
	v_cvt_pk_bf16_f32 v122, v146, v148
	v_cvt_pk_bf16_f32 v123, v150, v152
	s_nop 0
	v_pk_mul_f32 v[126:127], v[94:95], v[174:175] op_sel_hi:[1,0]
	v_pk_mul_f32 v[124:125], v[92:93], v[174:175] op_sel_hi:[1,0]
	v_pk_mul_f32 v[134:135], v[86:87], v[174:175] op_sel_hi:[1,0]
	v_pk_mul_f32 v[132:133], v[84:85], v[174:175] op_sel_hi:[1,0]
	s_waitcnt lgkmcnt(0)
	v_mfma_f32_16x16x32_bf16 v[128:131], v[116:119], v[120:123], v[124:127]
	ds_read_b128 v[116:119], v145 offset:40960
	v_mul_f32_e32 v154, v140, v174
	v_pk_mul_f32 v[176:177], v[98:99], v[174:175] op_sel_hi:[1,0]
	v_pk_mul_f32 v[126:127], v[90:91], v[174:175] op_sel_hi:[1,0]
	v_pk_mul_f32 v[124:125], v[88:89], v[174:175] op_sel_hi:[1,0]
	v_pk_mul_f32 v[174:175], v[96:97], v[174:175] op_sel_hi:[1,0]
	s_waitcnt lgkmcnt(0)
	v_mfma_f32_16x16x32_bf16 v[124:127], v[116:119], v[120:123], v[124:127]
	ds_read_b128 v[116:119], v145 offset:49152
	s_waitcnt lgkmcnt(0)
	v_mfma_f32_16x16x32_bf16 v[116:119], v[116:119], v[120:123], v[132:135]
	s_nop 2
	ds_read_b128 v[132:135], v145 offset:57344
	s_waitcnt lgkmcnt(0)
	v_mfma_f32_16x16x32_bf16 v[120:123], v[132:135], v[120:123], v[174:177]
	ds_read_b128 v[132:135], v173 offset:4096
	s_nop 1
	ds_read_b128 v[174:177], v172 offset:4096
	s_waitcnt lgkmcnt(0)
	v_mfma_f32_16x16x32_bf16 v[132:135], v[132:135], v[60:63], 0
	v_mfma_f32_16x16x32_bf16 v[132:135], v[174:177], v[64:67], v[132:135]
	ds_read_b128 v[174:177], v171 offset:4608
	ds_read_b128 v[178:181], v170 offset:4608
	s_waitcnt lgkmcnt(0)
	v_mfma_f32_16x16x32_bf16 v[174:177], v[174:177], v[60:63], 0
	s_nop 3
	v_max_f32_e32 v145, v133, v133
	v_max_f32_e32 v147, v132, v132
	v_max_f32_e32 v145, v147, v145
	v_mfma_f32_16x16x32_bf16 v[174:177], v[178:181], v[64:67], v[174:177]
	v_max_f32_e32 v147, v135, v135
	v_max_f32_e32 v149, v134, v134
	v_max_f32_e32 v147, v149, v147
	s_nop 4
	v_max_f32_e32 v149, v177, v177
	v_max_f32_e32 v151, v176, v176
	v_max_f32_e32 v149, v151, v149
	v_max3_f32 v149, v174, v175, v149
	v_max3_f32 v145, v145, v147, v149
	ds_bpermute_b32 v147, v169, v145
	s_waitcnt lgkmcnt(0)
	v_max_f32_e32 v147, v147, v147
	v_max_f32_e32 v145, v145, v147
	ds_bpermute_b32 v147, v168, v145
	s_waitcnt lgkmcnt(0)
	v_max3_f32 v179, v143, v145, v147
	v_sub_f32_e32 v132, v132, v179
	v_sub_f32_e32 v178, v143, v179
	v_exp_f32_e32 v143, v132
	v_sub_f32_e32 v132, v133, v179
	v_exp_f32_e32 v145, v132
	v_sub_f32_e32 v132, v134, v179
	v_exp_f32_e32 v147, v132
	v_sub_f32_e32 v132, v135, v179
	v_exp_f32_e32 v149, v132
	v_sub_f32_e32 v132, v174, v179
	v_exp_f32_e32 v151, v132
	v_sub_f32_e32 v132, v175, v179
	v_exp_f32_e32 v153, v132
	v_sub_f32_e32 v132, v176, v179
	v_exp_f32_e32 v155, v132
	v_sub_f32_e32 v132, v177, v179
	v_exp_f32_e32 v135, v132
	v_pk_add_f32 v[132:133], v[142:143], v[0:1]
	v_exp_f32_e32 v178, v178
	v_pk_add_f32 v[132:133], v[144:145], v[132:133]
	v_bitop3_b32 v0, v157, v167, 4 bitop3:0x36
	v_pk_add_f32 v[132:133], v[146:147], v[132:133]
	v_lshl_add_u32 v0, v0, 4, v2
	v_pk_add_f32 v[132:133], v[148:149], v[132:133]
	v_pk_mul_f32 v[130:131], v[130:131], v[178:179] op_sel_hi:[1,0]
	v_pk_add_f32 v[132:133], v[150:151], v[132:133]
	v_pk_mul_f32 v[128:129], v[128:129], v[178:179] op_sel_hi:[1,0]
	v_pk_add_f32 v[132:133], v[152:153], v[132:133]
	v_cvt_pk_bf16_f32 v134, v151, v153
	v_pk_mul_f32 v[126:127], v[126:127], v[178:179] op_sel_hi:[1,0]
	v_pk_add_f32 v[132:133], v[154:155], v[132:133]
	v_pk_mul_f32 v[124:125], v[124:125], v[178:179] op_sel_hi:[1,0]
	v_add_f32_e32 v154, v133, v135
	v_fmac_f32_e32 v154, v132, v178
	v_cvt_pk_bf16_f32 v132, v143, v145
	ds_read_b128 v[142:145], v0 offset:32768
	v_cvt_pk_bf16_f32 v133, v147, v149
	v_cvt_pk_bf16_f32 v135, v155, v135
	v_pk_mul_f32 v[118:119], v[118:119], v[178:179] op_sel_hi:[1,0]
	s_waitcnt lgkmcnt(0)
	v_mfma_f32_16x16x32_bf16 v[128:131], v[142:145], v[132:135], v[128:131]
	ds_read_b128 v[142:145], v0 offset:40960
	v_pk_mul_f32 v[116:117], v[116:117], v[178:179] op_sel_hi:[1,0]
	v_pk_mul_f32 v[122:123], v[122:123], v[178:179] op_sel_hi:[1,0]
	s_waitcnt lgkmcnt(0)
	v_mfma_f32_16x16x32_bf16 v[124:127], v[142:145], v[132:135], v[124:127]
	ds_read_b128 v[142:145], v0 offset:49152
	v_pk_mul_f32 v[120:121], v[120:121], v[178:179] op_sel_hi:[1,0]
	s_waitcnt lgkmcnt(0)
	v_mfma_f32_16x16x32_bf16 v[174:177], v[142:145], v[132:135], v[116:119]
	s_nop 2
	ds_read_b128 v[116:119], v0 offset:57344
	s_waitcnt lgkmcnt(0)
	v_mfma_f32_16x16x32_bf16 v[132:135], v[116:119], v[132:135], v[120:123]
	ds_read_b128 v[116:119], v173 offset:8192
	s_nop 1
	ds_read_b128 v[120:123], v172 offset:8192
	s_waitcnt lgkmcnt(0)
	v_mfma_f32_16x16x32_bf16 v[116:119], v[116:119], v[60:63], 0
	v_mfma_f32_16x16x32_bf16 v[116:119], v[120:123], v[64:67], v[116:119]
	ds_read_b128 v[120:123], v171 offset:8704
	ds_read_b128 v[142:145], v170 offset:8704
	s_waitcnt lgkmcnt(0)
	v_mfma_f32_16x16x32_bf16 v[120:123], v[120:123], v[60:63], 0
	s_nop 3
	v_max_f32_e32 v0, v117, v117
	v_mfma_f32_16x16x32_bf16 v[120:123], v[142:145], v[64:67], v[120:123]
	v_max_f32_e32 v142, v116, v116
	v_max_f32_e32 v0, v142, v0
	v_max_f32_e32 v142, v119, v119
	v_max_f32_e32 v143, v118, v118
	v_max_f32_e32 v142, v143, v142
	s_nop 2
	v_max_f32_e32 v143, v123, v123
	v_max_f32_e32 v144, v122, v122
	v_max_f32_e32 v143, v144, v143
	v_max3_f32 v143, v120, v121, v143
	v_max3_f32 v0, v0, v142, v143
	ds_bpermute_b32 v142, v169, v0
	s_waitcnt lgkmcnt(0)
	v_max_f32_e32 v142, v142, v142
	v_max_f32_e32 v0, v0, v142
	ds_bpermute_b32 v142, v168, v0
	s_waitcnt lgkmcnt(0)
	v_max3_f32 v143, v179, v0, v142
	v_sub_f32_e32 v0, v116, v143
	v_exp_f32_e32 v116, v0
	v_sub_f32_e32 v118, v118, v143
	v_sub_f32_e32 v117, v117, v143
	v_exp_f32_e32 v142, v118
	v_sub_f32_e32 v118, v119, v143
	v_exp_f32_e32 v117, v117
	v_exp_f32_e32 v144, v118
	v_sub_f32_e32 v118, v120, v143
	v_exp_f32_e32 v146, v118
	v_sub_f32_e32 v118, v121, v143
	v_sub_f32_e32 v145, v179, v143
	v_add_f32_e32 v0, 0, v116
	v_exp_f32_e32 v148, v118
	v_sub_f32_e32 v118, v122, v143
	v_cvt_pk_bf16_f32 v178, v116, v117
	v_bitop3_b32 v116, v157, v167, 8 bitop3:0x36
	v_exp_f32_e32 v150, v118
	v_sub_f32_e32 v118, v123, v143
	v_exp_f32_e32 v182, v145
	v_lshl_add_u32 v145, v116, 4, v2
	v_add_f32_e32 v0, v117, v0
	v_exp_f32_e32 v152, v118
	ds_read_b128 v[116:119], v145 offset:32768
	v_pk_mul_f32 v[122:123], v[130:131], v[182:183] op_sel_hi:[1,0]
	v_pk_mul_f32 v[120:121], v[128:129], v[182:183] op_sel_hi:[1,0]
	v_cvt_pk_bf16_f32 v179, v142, v144
	v_cvt_pk_bf16_f32 v180, v146, v148
	v_cvt_pk_bf16_f32 v181, v150, v152
	v_pk_mul_f32 v[134:135], v[134:135], v[182:183] op_sel_hi:[1,0]
	v_pk_mul_f32 v[132:133], v[132:133], v[182:183] op_sel_hi:[1,0]
	s_waitcnt lgkmcnt(0)
	v_mfma_f32_16x16x32_bf16 v[128:131], v[116:119], v[178:181], v[120:123]
	ds_read_b128 v[116:119], v145 offset:40960
	v_mul_f32_e32 v154, v154, v182
	s_nop 0
	v_pk_mul_f32 v[122:123], v[126:127], v[182:183] op_sel_hi:[1,0]
	v_pk_mul_f32 v[120:121], v[124:125], v[182:183] op_sel_hi:[1,0]
	v_pk_mul_f32 v[126:127], v[176:177], v[182:183] op_sel_hi:[1,0]
	v_pk_mul_f32 v[124:125], v[174:175], v[182:183] op_sel_hi:[1,0]
	s_waitcnt lgkmcnt(0)
	v_mfma_f32_16x16x32_bf16 v[116:119], v[116:119], v[178:181], v[120:123]
	s_nop 2
	ds_read_b128 v[120:123], v145 offset:49152
	s_waitcnt lgkmcnt(0)
	v_mfma_f32_16x16x32_bf16 v[120:123], v[120:123], v[178:181], v[124:127]
	s_nop 2
	ds_read_b128 v[124:127], v145 offset:57344
	s_waitcnt lgkmcnt(0)
	v_mfma_f32_16x16x32_bf16 v[124:127], v[124:127], v[178:181], v[132:135]
	s_nop 2
	ds_read_b128 v[132:135], v173 offset:12288
	ds_read_b128 v[174:177], v172 offset:12288
	s_waitcnt lgkmcnt(0)
	v_mfma_f32_16x16x32_bf16 v[132:135], v[132:135], v[60:63], 0
	v_mfma_f32_16x16x32_bf16 v[132:135], v[174:177], v[64:67], v[132:135]
	ds_read_b128 v[174:177], v171 offset:12800
	ds_read_b128 v[178:181], v170 offset:12800
	s_waitcnt lgkmcnt(0)
	v_mfma_f32_16x16x32_bf16 v[174:177], v[174:177], v[60:63], 0
	s_nop 3
	v_max_f32_e32 v145, v133, v133
	v_max_f32_e32 v147, v132, v132
	v_max_f32_e32 v145, v147, v145
	v_mfma_f32_16x16x32_bf16 v[174:177], v[178:181], v[64:67], v[174:177]
	v_max_f32_e32 v147, v135, v135
	v_max_f32_e32 v149, v134, v134
	v_max_f32_e32 v147, v149, v147
	s_nop 4
	v_max_f32_e32 v149, v177, v177
	v_max_f32_e32 v151, v176, v176
	v_max_f32_e32 v149, v151, v149
	v_max3_f32 v149, v174, v175, v149
	v_max3_f32 v145, v145, v147, v149
	ds_bpermute_b32 v147, v169, v145
	s_waitcnt lgkmcnt(0)
	v_max_f32_e32 v147, v147, v147
	v_max_f32_e32 v145, v145, v147
	ds_bpermute_b32 v147, v168, v145
	s_waitcnt lgkmcnt(0)
	v_max3_f32 v178, v143, v145, v147
	v_sub_f32_e32 v132, v132, v178
	v_sub_f32_e32 v179, v143, v178
	v_exp_f32_e32 v143, v132
	v_sub_f32_e32 v132, v133, v178
	v_exp_f32_e32 v145, v132
	v_sub_f32_e32 v132, v134, v178
	v_exp_f32_e32 v147, v132
	v_sub_f32_e32 v132, v135, v178
	v_exp_f32_e32 v149, v132
	v_sub_f32_e32 v132, v174, v178
	v_exp_f32_e32 v151, v132
	v_sub_f32_e32 v132, v175, v178
	v_exp_f32_e32 v153, v132
	v_sub_f32_e32 v132, v176, v178
	v_exp_f32_e32 v155, v132
	v_sub_f32_e32 v132, v177, v178
	v_exp_f32_e32 v135, v132
	v_pk_add_f32 v[132:133], v[142:143], v[0:1]
	v_exp_f32_e32 v174, v179
	v_pk_add_f32 v[132:133], v[144:145], v[132:133]
	v_bitop3_b32 v0, v157, v167, 12 bitop3:0x36
	v_pk_add_f32 v[132:133], v[146:147], v[132:133]
	v_lshl_add_u32 v0, v0, 4, v2
	v_pk_add_f32 v[132:133], v[148:149], v[132:133]
	v_pk_mul_f32 v[130:131], v[130:131], v[174:175] op_sel_hi:[1,0]
	v_pk_add_f32 v[132:133], v[150:151], v[132:133]
	v_pk_mul_f32 v[128:129], v[128:129], v[174:175] op_sel_hi:[1,0]
	v_pk_add_f32 v[132:133], v[152:153], v[132:133]
	v_cvt_pk_bf16_f32 v134, v151, v153
	v_pk_mul_f32 v[118:119], v[118:119], v[174:175] op_sel_hi:[1,0]
	v_pk_add_f32 v[132:133], v[154:155], v[132:133]
	v_pk_mul_f32 v[116:117], v[116:117], v[174:175] op_sel_hi:[1,0]
	v_add_f32_e32 v154, v133, v135
	v_fmac_f32_e32 v154, v132, v174
	v_cvt_pk_bf16_f32 v132, v143, v145
	ds_read_b128 v[142:145], v0 offset:32768
	v_cvt_pk_bf16_f32 v133, v147, v149
	v_cvt_pk_bf16_f32 v135, v155, v135
	v_pk_mul_f32 v[122:123], v[122:123], v[174:175] op_sel_hi:[1,0]
	s_waitcnt lgkmcnt(0)
	v_mfma_f32_16x16x32_bf16 v[128:131], v[142:145], v[132:135], v[128:131]
	ds_read_b128 v[142:145], v0 offset:40960
	v_pk_mul_f32 v[120:121], v[120:121], v[174:175] op_sel_hi:[1,0]
	v_pk_mul_f32 v[126:127], v[126:127], v[174:175] op_sel_hi:[1,0]
	s_waitcnt lgkmcnt(0)
	v_mfma_f32_16x16x32_bf16 v[116:119], v[142:145], v[132:135], v[116:119]
	ds_read_b128 v[142:145], v0 offset:49152
	v_pk_mul_f32 v[124:125], v[124:125], v[174:175] op_sel_hi:[1,0]
	s_waitcnt lgkmcnt(0)
	v_mfma_f32_16x16x32_bf16 v[120:123], v[142:145], v[132:135], v[120:123]
	ds_read_b128 v[142:145], v0 offset:57344
	s_waitcnt lgkmcnt(0)
	v_mfma_f32_16x16x32_bf16 v[124:127], v[142:145], v[132:135], v[124:127]
	ds_read_b128 v[132:135], v173 offset:16384
	ds_read_b128 v[142:145], v172 offset:16384
	s_waitcnt lgkmcnt(0)
	v_mfma_f32_16x16x32_bf16 v[132:135], v[132:135], v[60:63], 0
	v_mfma_f32_16x16x32_bf16 v[132:135], v[142:145], v[64:67], v[132:135]
	ds_read_b128 v[142:145], v171 offset:16896
	ds_read_b128 v[146:149], v170 offset:16896
	s_waitcnt lgkmcnt(0)
	v_mfma_f32_16x16x32_bf16 v[142:145], v[142:145], v[60:63], 0
	s_nop 3
	v_max_f32_e32 v0, v133, v133
	v_mfma_f32_16x16x32_bf16 v[148:151], v[146:149], v[64:67], v[142:145]
	s_nop 2
	v_max_f32_e32 v142, v132, v132
	v_max_f32_e32 v0, v142, v0
	v_max_f32_e32 v142, v135, v135
	v_max_f32_e32 v143, v134, v134
	v_max_f32_e32 v142, v143, v142
	v_max_f32_e32 v143, v151, v151
	v_max_f32_e32 v144, v150, v150
	v_max_f32_e32 v143, v144, v143
	v_max3_f32 v143, v148, v149, v143
	v_max3_f32 v0, v0, v142, v143
	ds_bpermute_b32 v142, v169, v0
	s_waitcnt lgkmcnt(0)
	v_max_f32_e32 v142, v142, v142
	v_max_f32_e32 v0, v0, v142
	ds_bpermute_b32 v142, v168, v0
	s_waitcnt lgkmcnt(0)
	v_max3_f32 v143, v178, v0, v142
	v_sub_f32_e32 v145, v178, v143
	v_exp_f32_e32 v178, v145
	v_bitop3_b32 v145, v157, v167, 16 bitop3:0x36
	v_lshl_add_u32 v145, v145, 4, v2
	ds_read_b128 v[174:177], v145 offset:32768
	v_sub_f32_e32 v0, v132, v143
	v_sub_f32_e32 v134, v134, v143
	v_exp_f32_e32 v132, v0
	v_sub_f32_e32 v133, v133, v143
	v_exp_f32_e32 v142, v134
	v_sub_f32_e32 v134, v135, v143
	v_exp_f32_e32 v133, v133
	v_exp_f32_e32 v144, v134
	v_sub_f32_e32 v134, v148, v143
	v_exp_f32_e32 v146, v134
	v_sub_f32_e32 v134, v149, v143
	v_exp_f32_e32 v148, v134
	v_sub_f32_e32 v134, v150, v143
	v_add_f32_e32 v0, 0, v132
	v_exp_f32_e32 v150, v134
	v_sub_f32_e32 v134, v151, v143
	v_pk_mul_f32 v[130:131], v[130:131], v[178:179] op_sel_hi:[1,0]
	v_pk_mul_f32 v[128:129], v[128:129], v[178:179] op_sel_hi:[1,0]
	v_add_f32_e32 v0, v133, v0
	v_exp_f32_e32 v152, v134
	v_cvt_pk_bf16_f32 v132, v132, v133
	v_cvt_pk_bf16_f32 v133, v142, v144
	v_cvt_pk_bf16_f32 v134, v146, v148
	v_cvt_pk_bf16_f32 v135, v150, v152
	v_pk_mul_f32 v[118:119], v[118:119], v[178:179] op_sel_hi:[1,0]
	s_waitcnt lgkmcnt(0)
	v_mfma_f32_16x16x32_bf16 v[128:131], v[174:177], v[132:135], v[128:131]
	ds_read_b128 v[174:177], v145 offset:40960
	v_pk_mul_f32 v[116:117], v[116:117], v[178:179] op_sel_hi:[1,0]
	v_pk_mul_f32 v[122:123], v[122:123], v[178:179] op_sel_hi:[1,0]
	v_pk_mul_f32 v[120:121], v[120:121], v[178:179] op_sel_hi:[1,0]
	s_waitcnt lgkmcnt(0)
	v_mfma_f32_16x16x32_bf16 v[116:119], v[174:177], v[132:135], v[116:119]
	ds_read_b128 v[174:177], v145 offset:49152
	v_pk_mul_f32 v[126:127], v[126:127], v[178:179] op_sel_hi:[1,0]
	v_pk_mul_f32 v[124:125], v[124:125], v[178:179] op_sel_hi:[1,0]
	s_waitcnt lgkmcnt(0)
	v_mfma_f32_16x16x32_bf16 v[120:123], v[174:177], v[132:135], v[120:123]
	ds_read_b128 v[174:177], v145 offset:57344
	v_mul_f32_e32 v154, v154, v178
	s_waitcnt lgkmcnt(0)
	v_mfma_f32_16x16x32_bf16 v[124:127], v[174:177], v[132:135], v[124:127]
	ds_read_b128 v[132:135], v173 offset:20480
	ds_read_b128 v[174:177], v172 offset:20480
	s_waitcnt lgkmcnt(0)
	v_mfma_f32_16x16x32_bf16 v[132:135], v[132:135], v[60:63], 0
	v_mfma_f32_16x16x32_bf16 v[132:135], v[174:177], v[64:67], v[132:135]
	ds_read_b128 v[174:177], v171 offset:20992
	ds_read_b128 v[178:181], v170 offset:20992
	s_waitcnt lgkmcnt(0)
	v_mfma_f32_16x16x32_bf16 v[174:177], v[174:177], v[60:63], 0
	s_nop 3
	v_max_f32_e32 v145, v133, v133
	v_max_f32_e32 v147, v132, v132
	v_max_f32_e32 v145, v147, v145
	v_mfma_f32_16x16x32_bf16 v[174:177], v[178:181], v[64:67], v[174:177]
	v_max_f32_e32 v147, v135, v135
	v_max_f32_e32 v149, v134, v134
	v_max_f32_e32 v147, v149, v147
	s_nop 4
	v_max_f32_e32 v149, v177, v177
	v_max_f32_e32 v151, v176, v176
	v_max_f32_e32 v149, v151, v149
	v_max3_f32 v149, v174, v175, v149
	v_max3_f32 v145, v145, v147, v149
	ds_bpermute_b32 v147, v169, v145
	s_waitcnt lgkmcnt(0)
	v_max_f32_e32 v147, v147, v147
	v_max_f32_e32 v145, v145, v147
	ds_bpermute_b32 v147, v168, v145
	s_waitcnt lgkmcnt(0)
	v_max3_f32 v183, v143, v145, v147
	v_sub_f32_e32 v132, v132, v183
	v_sub_f32_e32 v178, v143, v183
	v_exp_f32_e32 v143, v132
	v_sub_f32_e32 v132, v133, v183
	v_exp_f32_e32 v145, v132
	v_sub_f32_e32 v132, v134, v183
	v_exp_f32_e32 v147, v132
	v_sub_f32_e32 v132, v135, v183
	v_exp_f32_e32 v149, v132
	v_sub_f32_e32 v132, v174, v183
	v_exp_f32_e32 v151, v132
	v_sub_f32_e32 v132, v175, v183
	v_exp_f32_e32 v153, v132
	v_sub_f32_e32 v132, v176, v183
	v_exp_f32_e32 v155, v132
	v_sub_f32_e32 v132, v177, v183
	v_exp_f32_e32 v135, v132
	v_pk_add_f32 v[132:133], v[142:143], v[0:1]
	v_exp_f32_e32 v182, v178
	v_pk_add_f32 v[132:133], v[144:145], v[132:133]
	v_bitop3_b32 v0, v157, v167, 20 bitop3:0x36
	v_pk_add_f32 v[132:133], v[146:147], v[132:133]
	v_lshl_add_u32 v0, v0, 4, v2
	v_pk_add_f32 v[132:133], v[148:149], v[132:133]
	v_pk_mul_f32 v[130:131], v[130:131], v[182:183] op_sel_hi:[1,0]
	v_pk_add_f32 v[132:133], v[150:151], v[132:133]
	v_pk_mul_f32 v[128:129], v[128:129], v[182:183] op_sel_hi:[1,0]
	v_pk_add_f32 v[132:133], v[152:153], v[132:133]
	v_cvt_pk_bf16_f32 v134, v151, v153
	v_pk_mul_f32 v[118:119], v[118:119], v[182:183] op_sel_hi:[1,0]
	v_pk_add_f32 v[132:133], v[154:155], v[132:133]
	v_pk_mul_f32 v[116:117], v[116:117], v[182:183] op_sel_hi:[1,0]
	v_add_f32_e32 v154, v133, v135
	v_fmac_f32_e32 v154, v132, v182
	v_cvt_pk_bf16_f32 v132, v143, v145
	ds_read_b128 v[142:145], v0 offset:32768
	v_cvt_pk_bf16_f32 v133, v147, v149
	v_cvt_pk_bf16_f32 v135, v155, v135
	v_pk_mul_f32 v[122:123], v[122:123], v[182:183] op_sel_hi:[1,0]
	s_waitcnt lgkmcnt(0)
	v_mfma_f32_16x16x32_bf16 v[128:131], v[142:145], v[132:135], v[128:131]
	ds_read_b128 v[142:145], v0 offset:40960
	v_pk_mul_f32 v[120:121], v[120:121], v[182:183] op_sel_hi:[1,0]
	s_waitcnt lgkmcnt(0)
	v_mfma_f32_16x16x32_bf16 v[174:177], v[142:145], v[132:135], v[116:119]
	s_nop 2
	ds_read_b128 v[116:119], v0 offset:49152
	s_waitcnt lgkmcnt(0)
	v_mfma_f32_16x16x32_bf16 v[178:181], v[116:119], v[132:135], v[120:123]
	ds_read_b128 v[116:119], v0 offset:57344
	s_nop 1
	v_pk_mul_f32 v[122:123], v[126:127], v[182:183] op_sel_hi:[1,0]
	v_pk_mul_f32 v[120:121], v[124:125], v[182:183] op_sel_hi:[1,0]
	s_waitcnt lgkmcnt(0)
	s_nop 0
	v_mfma_f32_16x16x32_bf16 v[132:135], v[116:119], v[132:135], v[120:123]
	ds_read_b128 v[116:119], v173 offset:24576
	s_nop 1
	ds_read_b128 v[120:123], v172 offset:24576
	s_waitcnt lgkmcnt(0)
	v_mfma_f32_16x16x32_bf16 v[116:119], v[116:119], v[60:63], 0
	v_mfma_f32_16x16x32_bf16 v[116:119], v[120:123], v[64:67], v[116:119]
	ds_read_b128 v[120:123], v171 offset:25088
	ds_read_b128 v[124:127], v170 offset:25088
	s_waitcnt lgkmcnt(0)
	v_mfma_f32_16x16x32_bf16 v[120:123], v[120:123], v[60:63], 0
	s_nop 3
	v_max_f32_e32 v0, v117, v117
	v_mfma_f32_16x16x32_bf16 v[120:123], v[124:127], v[64:67], v[120:123]
	v_max_f32_e32 v124, v116, v116
	v_max_f32_e32 v0, v124, v0
	v_max_f32_e32 v124, v119, v119
	v_max_f32_e32 v125, v118, v118
	v_max_f32_e32 v124, v125, v124
	s_nop 2
	v_max_f32_e32 v125, v123, v123
	v_max_f32_e32 v126, v122, v122
	v_max_f32_e32 v125, v126, v125
	v_max3_f32 v125, v120, v121, v125
	v_max3_f32 v0, v0, v124, v125
	ds_bpermute_b32 v124, v169, v0
	s_waitcnt lgkmcnt(0)
	v_max_f32_e32 v124, v124, v124
	v_max_f32_e32 v0, v0, v124
	ds_bpermute_b32 v124, v168, v0
	s_waitcnt lgkmcnt(0)
	v_max3_f32 v143, v183, v0, v124
	v_sub_f32_e32 v0, v116, v143
	v_exp_f32_e32 v116, v0
	v_sub_f32_e32 v118, v118, v143
	v_sub_f32_e32 v117, v117, v143
	v_exp_f32_e32 v142, v118
	v_sub_f32_e32 v118, v119, v143
	v_exp_f32_e32 v117, v117
	v_exp_f32_e32 v144, v118
	v_sub_f32_e32 v118, v120, v143
	v_exp_f32_e32 v146, v118
	v_sub_f32_e32 v118, v121, v143
	v_add_f32_e32 v0, 0, v116
	v_exp_f32_e32 v148, v118
	v_sub_f32_e32 v118, v122, v143
	v_cvt_pk_bf16_f32 v182, v116, v117
	v_bitop3_b32 v116, v157, v167, 24 bitop3:0x36
	v_exp_f32_e32 v150, v118
	v_sub_f32_e32 v118, v123, v143
	v_lshl_add_u32 v145, v116, 4, v2
	v_add_f32_e32 v0, v117, v0
	v_exp_f32_e32 v152, v118
	ds_read_b128 v[116:119], v145 offset:32768
	v_sub_f32_e32 v124, v183, v143
	v_exp_f32_e32 v186, v124
	v_cvt_pk_bf16_f32 v183, v142, v144
	v_cvt_pk_bf16_f32 v184, v146, v148
	v_cvt_pk_bf16_f32 v185, v150, v152
	s_nop 0
	v_pk_mul_f32 v[122:123], v[130:131], v[186:187] op_sel_hi:[1,0]
	v_pk_mul_f32 v[120:121], v[128:129], v[186:187] op_sel_hi:[1,0]
	v_pk_mul_f32 v[126:127], v[176:177], v[186:187] op_sel_hi:[1,0]
	v_pk_mul_f32 v[124:125], v[174:175], v[186:187] op_sel_hi:[1,0]
	s_waitcnt lgkmcnt(0)
	v_mfma_f32_16x16x32_bf16 v[116:119], v[116:119], v[182:185], v[120:123]
	v_mul_f32_e64 v130, v180, v186
	v_mul_f32_e64 v131, v181, v186
	v_pk_mul_f32 v[128:129], v[178:179], v[186:187] op_sel_hi:[1,0]
	v_pk_mul_f32 v[134:135], v[134:135], v[186:187] op_sel_hi:[1,0]
	ds_read_b128 v[120:123], v145 offset:40960
	s_waitcnt lgkmcnt(0)
	v_mfma_f32_16x16x32_bf16 v[120:123], v[120:123], v[182:185], v[124:127]
	s_nop 2
	ds_read_b128 v[124:127], v145 offset:49152
	v_pk_mul_f32 v[132:133], v[132:133], v[186:187] op_sel_hi:[1,0]
	v_mul_f32_e32 v154, v154, v186
	s_waitcnt lgkmcnt(0)
	v_mfma_f32_16x16x32_bf16 v[124:127], v[124:127], v[182:185], v[128:131]
	s_nop 2
	ds_read_b128 v[128:131], v145 offset:57344
	s_waitcnt lgkmcnt(0)
	v_mfma_f32_16x16x32_bf16 v[128:131], v[128:131], v[182:185], v[132:135]
	s_nop 2
	ds_read_b128 v[132:135], v173 offset:28672
	ds_read_b128 v[172:175], v172 offset:28672
	s_waitcnt lgkmcnt(0)
	v_mfma_f32_16x16x32_bf16 v[132:135], v[132:135], v[60:63], 0
	v_mfma_f32_16x16x32_bf16 v[132:135], v[172:175], v[64:67], v[132:135]
	ds_read_b128 v[172:175], v171 offset:29184
	ds_read_b128 v[176:179], v170 offset:29184
	s_waitcnt lgkmcnt(0)
	v_mfma_f32_16x16x32_bf16 v[170:173], v[172:175], v[60:63], 0
	s_nop 3
	v_max_f32_e32 v145, v133, v133
	v_max_f32_e32 v147, v132, v132
	v_max_f32_e32 v145, v147, v145
	v_mfma_f32_16x16x32_bf16 v[170:173], v[176:179], v[64:67], v[170:173]
	v_max_f32_e32 v147, v135, v135
	v_max_f32_e32 v149, v134, v134
	v_max_f32_e32 v147, v149, v147
	s_nop 4
	v_max_f32_e32 v149, v173, v173
	v_max_f32_e32 v151, v172, v172
	v_max_f32_e32 v149, v151, v149
	v_max3_f32 v149, v170, v171, v149
	v_max3_f32 v145, v145, v147, v149
	ds_bpermute_b32 v147, v169, v145
	s_waitcnt lgkmcnt(0)
	v_max_f32_e32 v147, v147, v147
	v_max_f32_e32 v145, v145, v147
	ds_bpermute_b32 v147, v168, v145
	s_waitcnt lgkmcnt(0)
	v_max3_f32 v168, v143, v145, v147
	v_sub_f32_e32 v132, v132, v168
	v_sub_f32_e32 v174, v143, v168
	v_exp_f32_e32 v143, v132
	v_sub_f32_e32 v132, v133, v168
	v_exp_f32_e32 v145, v132
	v_sub_f32_e32 v132, v134, v168
	v_exp_f32_e32 v147, v132
	v_sub_f32_e32 v132, v135, v168
	v_exp_f32_e32 v149, v132
	v_sub_f32_e32 v132, v170, v168
	v_exp_f32_e32 v151, v132
	v_sub_f32_e32 v132, v171, v168
	v_exp_f32_e32 v153, v132
	v_sub_f32_e32 v132, v172, v168
	v_exp_f32_e32 v155, v132
	v_sub_f32_e32 v132, v173, v168
	v_exp_f32_e32 v169, v132
	v_pk_add_f32 v[132:133], v[142:143], v[0:1]
	v_exp_f32_e32 v168, v174
	v_pk_add_f32 v[132:133], v[144:145], v[132:133]
	v_cvt_pk_bf16_f32 v134, v151, v153
	v_cvt_pk_bf16_f32 v135, v155, v169
	v_pk_mul_f32 v[118:119], v[118:119], v[168:169] op_sel_hi:[1,0]
	v_pk_add_f32 v[132:133], v[146:147], v[132:133]
	v_pk_mul_f32 v[116:117], v[116:117], v[168:169] op_sel_hi:[1,0]
	v_pk_add_f32 v[132:133], v[148:149], v[132:133]
	v_pk_mul_f32 v[122:123], v[122:123], v[168:169] op_sel_hi:[1,0]
	v_pk_add_f32 v[132:133], v[150:151], v[132:133]
	v_pk_mul_f32 v[120:121], v[120:121], v[168:169] op_sel_hi:[1,0]
	v_pk_add_f32 v[132:133], v[152:153], v[132:133]
	v_pk_mul_f32 v[126:127], v[126:127], v[168:169] op_sel_hi:[1,0]
	v_pk_add_f32 v[132:133], v[154:155], v[132:133]
	v_pk_mul_f32 v[124:125], v[124:125], v[168:169] op_sel_hi:[1,0]
	v_add_f32_e32 v0, v133, v169
	v_pk_fma_f32 v[170:171], v[132:133], v[168:169], v[0:1] op_sel_hi:[1,1,0]
	v_bitop3_b32 v0, v157, v167, 28 bitop3:0x36
	v_lshl_add_u32 v0, v0, 4, v2
	v_cvt_pk_bf16_f32 v132, v143, v145
	ds_read_b128 v[142:145], v0 offset:32768
	v_cvt_pk_bf16_f32 v133, v147, v149
	v_pk_mul_f32 v[130:131], v[130:131], v[168:169] op_sel_hi:[1,0]
	s_waitcnt lgkmcnt(0)
	v_mfma_f32_16x16x32_bf16 v[116:119], v[142:145], v[132:135], v[116:119]
	ds_read_b128 v[142:145], v0 offset:40960
	v_pk_mul_f32 v[128:129], v[128:129], v[168:169] op_sel_hi:[1,0]
	v_mov_b32_e32 v171, v3
	s_waitcnt lgkmcnt(0)
	v_mfma_f32_16x16x32_bf16 v[120:123], v[142:145], v[132:135], v[120:123]
	ds_read_b128 v[142:145], v0 offset:49152
	v_mov_b64_e32 v[2:3], v[170:171]
	s_waitcnt lgkmcnt(0)
	v_mfma_f32_16x16x32_bf16 v[124:127], v[142:145], v[132:135], v[124:127]
	ds_read_b128 v[142:145], v0 offset:57344
	s_waitcnt lgkmcnt(0)
	v_mfma_f32_16x16x32_bf16 v[128:131], v[142:145], v[132:135], v[128:131]
	s_setprio 0
	s_branch .LBB0_328

.LBB0_330:
	v_add_u32_e32 v72, s2, v70
	v_add_u32_e32 v76, s2, v69
	v_add_u32_e32 v116, s2, v68
	v_add_u32_e32 v120, s2, v3
	ds_read_b128 v[72:75], v72
	ds_read_b128 v[76:79], v76
	ds_read_b128 v[116:119], v116
	ds_read_b128 v[120:123], v120
	s_waitcnt lgkmcnt(0)
	s_setprio 3
	v_mfma_f32_16x16x32_bf16 v[80:83], v[72:75], v[52:55], 0
	v_xor_b32_e32 v128, v71, v142
	v_lshl_add_u32 v148, v128, 4, v143
	ds_read_b128 v[128:131], v148 offset:32768
	v_mfma_f32_16x16x32_bf16 v[124:127], v[116:119], v[52:55], 0
	s_addk_i32 s2, 0x1000
	v_add_u32_e32 v71, 4, v71
	s_cmpk_eq_u32 s2, 0x8000
	v_mfma_f32_16x16x32_bf16 v[116:119], v[116:119], v[60:63], 0
	v_mfma_f32_16x16x32_bf16 v[72:75], v[72:75], v[60:63], 0
	v_mfma_f32_16x16x32_bf16 v[80:83], v[76:79], v[56:59], v[80:83]
	v_mfma_f32_16x16x32_bf16 v[124:127], v[120:123], v[56:59], v[124:127]
	v_mfma_f32_16x16x32_bf16 v[116:119], v[120:123], v[64:67], v[116:119]
	s_nop 5
	v_max_f32_e32 v120, v81, v81
	v_max_f32_e32 v121, v80, v80
	v_max_f32_e32 v122, v83, v83
	v_mfma_f32_16x16x32_bf16 v[72:75], v[76:79], v[64:67], v[72:75]
	v_max_f32_e32 v123, v82, v82
	v_max_f32_e32 v152, v127, v127
	v_max_f32_e32 v153, v126, v126
	v_max_f32_e32 v120, v121, v120
	v_max_f32_e32 v121, v123, v122
	v_max_f32_e32 v122, v153, v152
	v_max_f32_e32 v169, v119, v119
	v_max_f32_e32 v170, v118, v118
	v_max3_f32 v122, v124, v125, v122
	v_max_f32_e32 v154, v73, v73
	v_max_f32_e32 v155, v72, v72
	v_max_f32_e32 v167, v75, v75
	v_max_f32_e32 v168, v74, v74
	v_max_f32_e32 v153, v170, v169
	v_max3_f32 v120, v120, v121, v122
	v_max_f32_e32 v123, v155, v154
	v_max_f32_e32 v152, v168, v167
	v_max3_f32 v153, v116, v117, v153
	ds_bpermute_b32 v122, v0, v120
	v_max3_f32 v121, v123, v152, v153
	ds_bpermute_b32 v123, v0, v121
	ds_read_b128 v[76:79], v148 offset:40960
	ds_read_b128 v[132:135], v148 offset:49152
	ds_read_b128 v[148:151], v148 offset:57344
	s_waitcnt lgkmcnt(0)
	v_max_f32_e32 v122, v122, v122
	v_max_f32_e32 v120, v120, v122
	v_max_f32_e32 v123, v123, v123
	ds_bpermute_b32 v122, v2, v120
	v_max_f32_e32 v121, v121, v123
	ds_bpermute_b32 v123, v2, v121
	s_waitcnt lgkmcnt(0)
	v_max3_f32 v120, v165, v120, v122
	v_sub_f32_e32 v122, v165, v120
	v_max3_f32 v121, v166, v121, v123
	v_exp_f32_e32 v168, v122
	v_sub_f32_e32 v126, v126, v120
	v_sub_f32_e32 v167, v166, v121
	v_sub_f32_e32 v170, v117, v121
	v_sub_f32_e32 v80, v80, v120
	v_sub_f32_e32 v72, v72, v121
	v_exp_f32_e32 v153, v126
	v_exp_f32_e32 v126, v170
	v_exp_f32_e32 v170, v167
	v_sub_f32_e32 v81, v81, v120
	v_sub_f32_e32 v82, v82, v120
	v_sub_f32_e32 v83, v83, v120
	v_sub_f32_e32 v73, v73, v121
	v_sub_f32_e32 v169, v116, v121
	v_exp_f32_e32 v117, v80
	v_exp_f32_e32 v116, v72
	v_sub_f32_e32 v124, v124, v120
	v_sub_f32_e32 v152, v125, v120
	v_sub_f32_e32 v154, v127, v120
	v_sub_f32_e32 v74, v74, v121
	v_sub_f32_e32 v75, v75, v121
	v_sub_f32_e32 v171, v118, v121
	v_sub_f32_e32 v172, v119, v121
	v_mov_b32_e32 v166, v121
	v_exp_f32_e32 v119, v81
	v_exp_f32_e32 v121, v82
	v_exp_f32_e32 v123, v83
	v_exp_f32_e32 v118, v73
	v_pk_mul_f32 v[82:83], v[102:103], v[168:169] op_sel_hi:[1,0]
	v_pk_mul_f32 v[80:81], v[100:101], v[168:169] op_sel_hi:[1,0]
	v_mov_b32_e32 v165, v120
	v_exp_f32_e32 v125, v124
	v_exp_f32_e32 v127, v152
	v_exp_f32_e32 v155, v154
	v_exp_f32_e32 v120, v74
	v_exp_f32_e32 v122, v75
	v_exp_f32_e32 v152, v171
	v_cvt_pk_bf16_f32 v72, v117, v119
	v_cvt_pk_bf16_f32 v73, v121, v123
	v_cvt_pk_bf16_f32 v74, v125, v127
	v_cvt_pk_bf16_f32 v75, v153, v155
	v_pk_mul_f32 v[106:107], v[106:107], v[168:169] op_sel_hi:[1,0]
	v_mfma_f32_16x16x32_bf16 v[100:103], v[128:131], v[72:75], v[80:83]
	v_mul_f32_e64 v104, v104, v168
	v_mul_f32_e64 v105, v105, v168
	v_pk_mul_f32 v[114:115], v[114:115], v[168:169] op_sel_hi:[1,0]
	v_pk_mul_f32 v[112:113], v[112:113], v[168:169] op_sel_hi:[1,0]
	v_pk_mul_f32 v[82:83], v[110:111], v[168:169] op_sel_hi:[1,0]
	v_pk_mul_f32 v[80:81], v[108:109], v[168:169] op_sel_hi:[1,0]
	v_mov_b32_e32 v171, v168
	v_mfma_f32_16x16x32_bf16 v[104:107], v[76:79], v[72:75], v[104:107]
	v_exp_f32_e32 v124, v169
	v_exp_f32_e32 v154, v172
	v_mfma_f32_16x16x32_bf16 v[108:111], v[132:135], v[72:75], v[80:83]
	v_cvt_pk_bf16_f32 v80, v116, v118
	v_cvt_pk_bf16_f32 v81, v120, v122
	v_cvt_pk_bf16_f32 v82, v124, v126
	v_mfma_f32_16x16x32_bf16 v[112:115], v[148:151], v[72:75], v[112:115]
	v_mul_f32_e64 v74, v94, v170
	v_mul_f32_e64 v75, v95, v170
	v_pk_mul_f32 v[72:73], v[92:93], v[170:171] op_sel_hi:[1,0]
	v_cvt_pk_bf16_f32 v83, v152, v154
	v_pk_add_f32 v[116:117], v[116:117], 0 op_sel_hi:[1,0]
	s_nop 0
	v_mfma_f32_16x16x32_bf16 v[92:95], v[128:131], v[80:83], v[72:75]
	s_nop 2
	v_mul_f32_e64 v74, v90, v170
	v_mul_f32_e64 v75, v91, v170
	v_pk_mul_f32 v[72:73], v[88:89], v[170:171] op_sel_hi:[1,0]
	s_nop 1
	v_mfma_f32_16x16x32_bf16 v[88:91], v[76:79], v[80:83], v[72:75]
	v_add_f32_e64 v76, v118, v116
	v_add_f32_e64 v77, v119, v117
	v_pk_add_f32 v[76:77], v[120:121], v[76:77]
	v_pk_mul_f32 v[74:75], v[86:87], v[170:171] op_sel_hi:[1,0]
	v_pk_mul_f32 v[72:73], v[84:85], v[170:171] op_sel_hi:[1,0]
	s_nop 1
	v_mfma_f32_16x16x32_bf16 v[84:87], v[132:135], v[80:83], v[72:75]
	s_nop 2
	v_mul_f32_e64 v74, v98, v170
	v_mul_f32_e64 v75, v99, v170
	v_pk_mul_f32 v[72:73], v[96:97], v[170:171] op_sel_hi:[1,0]
	s_nop 1
	v_mfma_f32_16x16x32_bf16 v[96:99], v[148:151], v[80:83], v[72:75]
	s_setprio 0
	s_nop 2
	v_add_f32_e64 v72, v122, v76
	v_add_f32_e64 v73, v123, v77
	v_pk_add_f32 v[72:73], v[124:125], v[72:73]
	s_nop 0
	v_pk_add_f32 v[72:73], v[126:127], v[72:73]
	s_nop 0
	v_pk_add_f32 v[72:73], v[152:153], v[72:73]
	s_nop 0
	v_pk_add_f32 v[72:73], v[154:155], v[72:73]
	s_nop 0
	v_pk_fma_f32 v[140:141], v[140:141], v[170:171], v[72:73]
	s_cbranch_scc0 .LBB0_330
	v_mov_b64_e32 v[68:69], v[100:101]
	v_mov_b64_e32 v[72:73], v[104:105]
	v_mov_b64_e32 v[76:77], v[108:109]
	v_mov_b64_e32 v[80:81], v[112:113]
	v_mov_b64_e32 v[130:131], v[98:99]
	v_mov_b64_e32 v[118:119], v[94:95]
	v_mov_b64_e32 v[122:123], v[90:91]
	v_mov_b64_e32 v[126:127], v[86:87]
	v_mov_b64_e32 v[2:3], v[140:141]
	v_mov_b64_e32 v[70:71], v[102:103]
	v_mov_b64_e32 v[74:75], v[106:107]
	v_mov_b64_e32 v[78:79], v[110:111]
	v_mov_b64_e32 v[82:83], v[114:115]
	v_mov_b64_e32 v[128:129], v[96:97]
	v_mov_b64_e32 v[116:117], v[92:93]
	v_mov_b64_e32 v[120:121], v[88:89]
	v_mov_b64_e32 v[124:125], v[84:85]
.LBB0_332:
	s_or_b64 s[48:49], s[52:53], s[64:65]
	s_or_b64 s[2:3], s[40:41], s[66:67]
	v_cndmask_b32_e64 v0, 0, 1, s[2:3]
	s_and_b64 s[14:15], s[2:3], s[48:49]
	s_mov_b64 s[2:3], -1
	s_andn2_b64 vcc, exec, s[14:15]
	v_cmp_ne_u32_e64 s[40:41], 1, v0
	s_cbranch_vccz .LBB0_337
	v_mov_b64_e32 v[54:55], v[22:23]
	v_mov_b64_e32 v[58:59], v[26:27]
	v_mov_b64_e32 v[62:63], v[34:35]
	v_mov_b64_e32 v[66:67], v[46:47]
	s_and_b64 vcc, exec, s[40:41]
	v_bitop3_b32 v102, v157, v138, 7 bitop3:0x78
	v_and_or_b32 v103, v163, 24, v164
	v_bitop3_b32 v148, v157, v142, 4 bitop3:0x36
	v_bitop3_b32 v141, v157, v142, 8 bitop3:0x36
	v_bitop3_b32 v140, v157, v142, 12 bitop3:0x36
	v_bitop3_b32 v138, v157, v142, 16 bitop3:0x36
	v_bitop3_b32 v104, v157, v142, 20 bitop3:0x36
	v_mov_b64_e32 v[52:53], v[20:21]
	v_mov_b64_e32 v[56:57], v[24:25]
	v_mov_b64_e32 v[60:61], v[32:33]
	v_mov_b64_e32 v[64:65], v[44:45]
	v_mov_b32_e32 v105, v137
	s_cbranch_vccnz .LBB0_335
	v_cmp_lt_i32_e32 vcc, v210, v208
	v_lshl_add_u32 v91, v102, 4, v143
	s_nop 0
	v_cndmask_b32_e32 v0, v207, v210, vcc
	v_cmp_lt_i32_e32 vcc, v209, v208
	v_lshlrev_b32_e32 v106, 2, v0
	s_nop 0
	v_cndmask_b32_e32 v0, v207, v209, vcc
	v_lshlrev_b32_e32 v105, 2, v0
	v_lshl_add_u32 v0, v103, 7, 0
	v_lshl_add_u32 v110, v158, 4, v0
	ds_read_b128 v[52:55], v110
	v_lshl_add_u32 v109, v159, 4, v0
	ds_read_b128 v[56:59], v109
	s_waitcnt lgkmcnt(0)
	s_setprio 3
	v_mfma_f32_16x16x32_bf16 v[52:55], v[52:55], v[4:7], 0
	v_lshl_add_u32 v108, v144, 4, v0
	v_lshl_add_u32 v107, v146, 4, v0
	ds_read_b128 v[60:63], v107 offset:512
	v_mfma_f32_16x16x32_bf16 v[52:55], v[56:59], v[8:11], v[52:55]
	ds_read_b128 v[56:59], v108 offset:512
	s_waitcnt lgkmcnt(0)
	v_mfma_f32_16x16x32_bf16 v[56:59], v[56:59], v[4:7], 0
	s_nop 4
	v_max_f32_e32 v0, v53, v53
	v_mfma_f32_16x16x32_bf16 v[56:59], v[60:63], v[8:11], v[56:59]
	v_max_f32_e32 v60, v52, v52
	v_max_f32_e32 v0, v60, v0
	v_max_f32_e32 v60, v55, v55
	v_max_f32_e32 v61, v54, v54
	v_max_f32_e32 v60, v61, v60
	s_nop 2
	v_max_f32_e32 v61, v59, v59
	v_max_f32_e32 v62, v58, v58
	v_max_f32_e32 v61, v62, v61
	v_max3_f32 v61, v56, v57, v61
	v_max3_f32 v0, v0, v60, v61
	ds_bpermute_b32 v60, v106, v0
	s_waitcnt lgkmcnt(0)
	v_max_f32_e32 v60, v60, v60
	v_max_f32_e32 v0, v0, v60
	ds_bpermute_b32 v60, v105, v0
	s_waitcnt lgkmcnt(0)
	v_max3_f32 v89, v161, v0, v60
	v_sub_f32_e32 v0, v52, v89
	v_sub_f32_e32 v54, v54, v89
	v_exp_f32_e32 v52, v0
	v_sub_f32_e32 v53, v53, v89
	v_exp_f32_e32 v88, v54
	v_sub_f32_e32 v54, v55, v89
	v_exp_f32_e32 v53, v53
	v_exp_f32_e32 v90, v54
	v_sub_f32_e32 v54, v56, v89
	v_exp_f32_e32 v92, v54
	v_sub_f32_e32 v54, v57, v89
	v_exp_f32_e32 v94, v54
	v_sub_f32_e32 v54, v58, v89
	v_add_f32_e32 v0, 0, v52
	v_exp_f32_e32 v96, v54
	v_sub_f32_e32 v54, v59, v89
	v_add_f32_e32 v0, v53, v0
	v_exp_f32_e32 v98, v54
	v_cvt_pk_bf16_f32 v56, v52, v53
	ds_read_b128 v[52:55], v91 offset:32768
	v_sub_f32_e32 v60, v161, v89
	v_exp_f32_e32 v112, v60
	v_cvt_pk_bf16_f32 v57, v88, v90
	v_cvt_pk_bf16_f32 v58, v92, v94
	v_cvt_pk_bf16_f32 v59, v96, v98
	s_nop 0
	v_pk_mul_f32 v[62:63], v[22:23], v[112:113] op_sel_hi:[1,0]
	v_pk_mul_f32 v[60:61], v[20:21], v[112:113] op_sel_hi:[1,0]
	v_pk_mul_f32 v[86:87], v[34:35], v[112:113] op_sel_hi:[1,0]
	v_pk_mul_f32 v[84:85], v[32:33], v[112:113] op_sel_hi:[1,0]
	s_waitcnt lgkmcnt(0)
	v_mfma_f32_16x16x32_bf16 v[64:67], v[52:55], v[56:59], v[60:63]
	ds_read_b128 v[52:55], v91 offset:40960
	v_mul_f32_e32 v100, v137, v112
	v_pk_mul_f32 v[114:115], v[46:47], v[112:113] op_sel_hi:[1,0]
	v_pk_mul_f32 v[62:63], v[26:27], v[112:113] op_sel_hi:[1,0]
	v_pk_mul_f32 v[60:61], v[24:25], v[112:113] op_sel_hi:[1,0]
	v_pk_mul_f32 v[112:113], v[44:45], v[112:113] op_sel_hi:[1,0]
	s_waitcnt lgkmcnt(0)
	v_mfma_f32_16x16x32_bf16 v[60:63], v[52:55], v[56:59], v[60:63]
	ds_read_b128 v[52:55], v91 offset:49152
	s_waitcnt lgkmcnt(0)
	v_mfma_f32_16x16x32_bf16 v[52:55], v[52:55], v[56:59], v[84:87]
	s_nop 2
	ds_read_b128 v[84:87], v91 offset:57344
	s_waitcnt lgkmcnt(0)
	v_mfma_f32_16x16x32_bf16 v[56:59], v[84:87], v[56:59], v[112:115]
	ds_read_b128 v[84:87], v110 offset:4096
	s_nop 1
	ds_read_b128 v[112:115], v109 offset:4096
	s_waitcnt lgkmcnt(0)
	v_mfma_f32_16x16x32_bf16 v[84:87], v[84:87], v[4:7], 0
	v_mfma_f32_16x16x32_bf16 v[84:87], v[112:115], v[8:11], v[84:87]
	ds_read_b128 v[112:115], v108 offset:4608
	ds_read_b128 v[132:135], v107 offset:4608
	s_waitcnt lgkmcnt(0)
	v_mfma_f32_16x16x32_bf16 v[112:115], v[112:115], v[4:7], 0
	s_nop 3
	v_max_f32_e32 v91, v85, v85
	v_max_f32_e32 v93, v84, v84
	v_max_f32_e32 v91, v93, v91
	v_mfma_f32_16x16x32_bf16 v[112:115], v[132:135], v[8:11], v[112:115]
	v_max_f32_e32 v93, v87, v87
	v_max_f32_e32 v95, v86, v86
	v_max_f32_e32 v93, v95, v93
	s_nop 4
	v_max_f32_e32 v95, v115, v115
	v_max_f32_e32 v97, v114, v114
	v_max_f32_e32 v95, v97, v95
	v_max3_f32 v95, v112, v113, v95
	v_max3_f32 v91, v91, v93, v95
	ds_bpermute_b32 v93, v106, v91
	s_waitcnt lgkmcnt(0)
	v_max_f32_e32 v93, v93, v93
	v_max_f32_e32 v91, v91, v93
	ds_bpermute_b32 v93, v105, v91
	s_waitcnt lgkmcnt(0)
	v_max3_f32 v111, v89, v91, v93
	v_sub_f32_e32 v84, v84, v111
	v_sub_f32_e32 v132, v89, v111
	v_exp_f32_e32 v89, v84
	v_sub_f32_e32 v84, v85, v111
	v_exp_f32_e32 v91, v84
	v_sub_f32_e32 v84, v86, v111
	v_exp_f32_e32 v93, v84
	v_sub_f32_e32 v84, v87, v111
	v_exp_f32_e32 v95, v84
	v_sub_f32_e32 v84, v112, v111
	v_exp_f32_e32 v97, v84
	v_sub_f32_e32 v84, v113, v111
	v_exp_f32_e32 v99, v84
	v_sub_f32_e32 v84, v114, v111
	v_exp_f32_e32 v101, v84
	v_sub_f32_e32 v84, v115, v111
	v_exp_f32_e32 v87, v84
	v_pk_add_f32 v[84:85], v[88:89], v[0:1]
	v_exp_f32_e32 v132, v132
	v_pk_add_f32 v[84:85], v[90:91], v[84:85]
	v_lshl_add_u32 v0, v148, 4, v143
	v_pk_add_f32 v[84:85], v[92:93], v[84:85]
	v_pk_mul_f32 v[66:67], v[66:67], v[132:133] op_sel_hi:[1,0]
	v_pk_add_f32 v[84:85], v[94:95], v[84:85]
	v_pk_mul_f32 v[64:65], v[64:65], v[132:133] op_sel_hi:[1,0]
	v_pk_add_f32 v[84:85], v[96:97], v[84:85]
	v_cvt_pk_bf16_f32 v86, v97, v99
	v_pk_mul_f32 v[62:63], v[62:63], v[132:133] op_sel_hi:[1,0]
	v_pk_add_f32 v[84:85], v[98:99], v[84:85]
	v_pk_mul_f32 v[60:61], v[60:61], v[132:133] op_sel_hi:[1,0]
	v_pk_add_f32 v[84:85], v[100:101], v[84:85]
	v_pk_mul_f32 v[54:55], v[54:55], v[132:133] op_sel_hi:[1,0]
	v_add_f32_e32 v100, v85, v87
	v_fmac_f32_e32 v100, v84, v132
	v_cvt_pk_bf16_f32 v84, v89, v91
	ds_read_b128 v[88:91], v0 offset:32768
	v_cvt_pk_bf16_f32 v85, v93, v95
	v_cvt_pk_bf16_f32 v87, v101, v87
	v_pk_mul_f32 v[52:53], v[52:53], v[132:133] op_sel_hi:[1,0]
	s_waitcnt lgkmcnt(0)
	v_mfma_f32_16x16x32_bf16 v[64:67], v[88:91], v[84:87], v[64:67]
	ds_read_b128 v[88:91], v0 offset:40960
	v_pk_mul_f32 v[58:59], v[58:59], v[132:133] op_sel_hi:[1,0]
	v_pk_mul_f32 v[56:57], v[56:57], v[132:133] op_sel_hi:[1,0]
	s_waitcnt lgkmcnt(0)
	v_mfma_f32_16x16x32_bf16 v[60:63], v[88:91], v[84:87], v[60:63]
	ds_read_b128 v[88:91], v0 offset:49152
	s_waitcnt lgkmcnt(0)
	v_mfma_f32_16x16x32_bf16 v[112:115], v[88:91], v[84:87], v[52:55]
	s_nop 2
	ds_read_b128 v[52:55], v0 offset:57344
	s_waitcnt lgkmcnt(0)
	v_mfma_f32_16x16x32_bf16 v[84:87], v[52:55], v[84:87], v[56:59]
	ds_read_b128 v[52:55], v110 offset:8192
	s_nop 1
	ds_read_b128 v[56:59], v109 offset:8192
	s_waitcnt lgkmcnt(0)
	v_mfma_f32_16x16x32_bf16 v[52:55], v[52:55], v[4:7], 0
	v_mfma_f32_16x16x32_bf16 v[52:55], v[56:59], v[8:11], v[52:55]
	ds_read_b128 v[56:59], v108 offset:8704
	ds_read_b128 v[88:91], v107 offset:8704
	s_waitcnt lgkmcnt(0)
	v_mfma_f32_16x16x32_bf16 v[56:59], v[56:59], v[4:7], 0
	s_nop 3
	v_max_f32_e32 v0, v53, v53
	v_mfma_f32_16x16x32_bf16 v[56:59], v[88:91], v[8:11], v[56:59]
	v_max_f32_e32 v88, v52, v52
	v_max_f32_e32 v0, v88, v0
	v_max_f32_e32 v88, v55, v55
	v_max_f32_e32 v89, v54, v54
	v_max_f32_e32 v88, v89, v88
	s_nop 2
	v_max_f32_e32 v89, v59, v59
	v_max_f32_e32 v90, v58, v58
	v_max_f32_e32 v89, v90, v89
	v_max3_f32 v89, v56, v57, v89
	v_max3_f32 v0, v0, v88, v89
	ds_bpermute_b32 v88, v106, v0
	s_waitcnt lgkmcnt(0)
	v_max_f32_e32 v88, v88, v88
	v_max_f32_e32 v0, v0, v88
	ds_bpermute_b32 v88, v105, v0
	s_waitcnt lgkmcnt(0)
	v_max3_f32 v89, v111, v0, v88
	v_sub_f32_e32 v0, v52, v89
	v_sub_f32_e32 v54, v54, v89
	v_exp_f32_e32 v52, v0
	v_sub_f32_e32 v53, v53, v89
	v_exp_f32_e32 v88, v54
	v_sub_f32_e32 v54, v55, v89
	v_exp_f32_e32 v53, v53
	v_exp_f32_e32 v90, v54
	v_sub_f32_e32 v54, v56, v89
	v_exp_f32_e32 v92, v54
	v_sub_f32_e32 v54, v57, v89
	v_sub_f32_e32 v91, v111, v89
	v_exp_f32_e32 v94, v54
	v_sub_f32_e32 v54, v58, v89
	v_add_f32_e32 v0, 0, v52
	v_exp_f32_e32 v96, v54
	v_sub_f32_e32 v54, v59, v89
	v_exp_f32_e32 v150, v91
	v_lshl_add_u32 v91, v141, 4, v143
	v_add_f32_e32 v0, v53, v0
	v_exp_f32_e32 v98, v54
	v_cvt_pk_bf16_f32 v132, v52, v53
	ds_read_b128 v[52:55], v91 offset:32768
	v_pk_mul_f32 v[58:59], v[66:67], v[150:151] op_sel_hi:[1,0]
	v_pk_mul_f32 v[56:57], v[64:65], v[150:151] op_sel_hi:[1,0]
	v_cvt_pk_bf16_f32 v133, v88, v90
	v_cvt_pk_bf16_f32 v134, v92, v94
	v_cvt_pk_bf16_f32 v135, v96, v98
	v_pk_mul_f32 v[86:87], v[86:87], v[150:151] op_sel_hi:[1,0]
	v_pk_mul_f32 v[84:85], v[84:85], v[150:151] op_sel_hi:[1,0]
	s_waitcnt lgkmcnt(0)
	v_mfma_f32_16x16x32_bf16 v[64:67], v[52:55], v[132:135], v[56:59]
	ds_read_b128 v[52:55], v91 offset:40960
	v_mul_f32_e32 v100, v100, v150
	s_nop 0
	v_pk_mul_f32 v[58:59], v[62:63], v[150:151] op_sel_hi:[1,0]
	v_pk_mul_f32 v[56:57], v[60:61], v[150:151] op_sel_hi:[1,0]
	v_pk_mul_f32 v[62:63], v[114:115], v[150:151] op_sel_hi:[1,0]
	v_pk_mul_f32 v[60:61], v[112:113], v[150:151] op_sel_hi:[1,0]
	s_waitcnt lgkmcnt(0)
	v_mfma_f32_16x16x32_bf16 v[52:55], v[52:55], v[132:135], v[56:59]
	s_nop 2
	ds_read_b128 v[56:59], v91 offset:49152
	s_waitcnt lgkmcnt(0)
	v_mfma_f32_16x16x32_bf16 v[56:59], v[56:59], v[132:135], v[60:63]
	s_nop 2
	ds_read_b128 v[60:63], v91 offset:57344
	s_waitcnt lgkmcnt(0)
	v_mfma_f32_16x16x32_bf16 v[60:63], v[60:63], v[132:135], v[84:87]
	s_nop 2
	ds_read_b128 v[84:87], v110 offset:12288
	ds_read_b128 v[112:115], v109 offset:12288
	s_waitcnt lgkmcnt(0)
	v_mfma_f32_16x16x32_bf16 v[84:87], v[84:87], v[4:7], 0
	v_mfma_f32_16x16x32_bf16 v[84:87], v[112:115], v[8:11], v[84:87]
	ds_read_b128 v[112:115], v108 offset:12800
	ds_read_b128 v[132:135], v107 offset:12800
	s_waitcnt lgkmcnt(0)
	v_mfma_f32_16x16x32_bf16 v[112:115], v[112:115], v[4:7], 0
	s_nop 3
	v_max_f32_e32 v91, v85, v85
	v_max_f32_e32 v93, v84, v84
	v_max_f32_e32 v91, v93, v91
	v_mfma_f32_16x16x32_bf16 v[112:115], v[132:135], v[8:11], v[112:115]
	v_max_f32_e32 v93, v87, v87
	v_max_f32_e32 v95, v86, v86
	v_max_f32_e32 v93, v95, v93
	s_nop 4
	v_max_f32_e32 v95, v115, v115
	v_max_f32_e32 v97, v114, v114
	v_max_f32_e32 v95, v97, v95
	v_max3_f32 v95, v112, v113, v95
	v_max3_f32 v91, v91, v93, v95
	ds_bpermute_b32 v93, v106, v91
	s_waitcnt lgkmcnt(0)
	v_max_f32_e32 v93, v93, v93
	v_max_f32_e32 v91, v91, v93
	ds_bpermute_b32 v93, v105, v91
	s_waitcnt lgkmcnt(0)
	v_max3_f32 v111, v89, v91, v93
	v_sub_f32_e32 v84, v84, v111
	v_sub_f32_e32 v132, v89, v111
	v_exp_f32_e32 v89, v84
	v_sub_f32_e32 v84, v85, v111
	v_exp_f32_e32 v91, v84
	v_sub_f32_e32 v84, v86, v111
	v_exp_f32_e32 v93, v84
	v_sub_f32_e32 v84, v87, v111
	v_exp_f32_e32 v95, v84
	v_sub_f32_e32 v84, v112, v111
	v_exp_f32_e32 v97, v84
	v_sub_f32_e32 v84, v113, v111
	v_exp_f32_e32 v99, v84
	v_sub_f32_e32 v84, v114, v111
	v_exp_f32_e32 v101, v84
	v_sub_f32_e32 v84, v115, v111
	v_exp_f32_e32 v87, v84
	v_pk_add_f32 v[84:85], v[88:89], v[0:1]
	v_exp_f32_e32 v112, v132
	v_pk_add_f32 v[84:85], v[90:91], v[84:85]
	v_lshl_add_u32 v0, v140, 4, v143
	v_pk_add_f32 v[84:85], v[92:93], v[84:85]
	v_pk_mul_f32 v[66:67], v[66:67], v[112:113] op_sel_hi:[1,0]
	v_pk_add_f32 v[84:85], v[94:95], v[84:85]
	v_pk_mul_f32 v[64:65], v[64:65], v[112:113] op_sel_hi:[1,0]
	v_pk_add_f32 v[84:85], v[96:97], v[84:85]
	v_cvt_pk_bf16_f32 v86, v97, v99
	v_pk_mul_f32 v[54:55], v[54:55], v[112:113] op_sel_hi:[1,0]
	v_pk_add_f32 v[84:85], v[98:99], v[84:85]
	v_pk_mul_f32 v[52:53], v[52:53], v[112:113] op_sel_hi:[1,0]
	v_pk_add_f32 v[84:85], v[100:101], v[84:85]
	v_pk_mul_f32 v[58:59], v[58:59], v[112:113] op_sel_hi:[1,0]
	v_add_f32_e32 v100, v85, v87
	v_fmac_f32_e32 v100, v84, v112
	v_cvt_pk_bf16_f32 v84, v89, v91
	ds_read_b128 v[88:91], v0 offset:32768
	v_cvt_pk_bf16_f32 v85, v93, v95
	v_cvt_pk_bf16_f32 v87, v101, v87
	v_pk_mul_f32 v[56:57], v[56:57], v[112:113] op_sel_hi:[1,0]
	s_waitcnt lgkmcnt(0)
	v_mfma_f32_16x16x32_bf16 v[64:67], v[88:91], v[84:87], v[64:67]
	ds_read_b128 v[88:91], v0 offset:40960
	v_pk_mul_f32 v[62:63], v[62:63], v[112:113] op_sel_hi:[1,0]
	v_pk_mul_f32 v[60:61], v[60:61], v[112:113] op_sel_hi:[1,0]
	s_waitcnt lgkmcnt(0)
	v_mfma_f32_16x16x32_bf16 v[52:55], v[88:91], v[84:87], v[52:55]
	ds_read_b128 v[88:91], v0 offset:49152
	s_waitcnt lgkmcnt(0)
	v_mfma_f32_16x16x32_bf16 v[56:59], v[88:91], v[84:87], v[56:59]
	ds_read_b128 v[88:91], v0 offset:57344
	s_waitcnt lgkmcnt(0)
	v_mfma_f32_16x16x32_bf16 v[60:63], v[88:91], v[84:87], v[60:63]
	ds_read_b128 v[84:87], v110 offset:16384
	ds_read_b128 v[88:91], v109 offset:16384
	s_waitcnt lgkmcnt(0)
	v_mfma_f32_16x16x32_bf16 v[84:87], v[84:87], v[4:7], 0
	v_mfma_f32_16x16x32_bf16 v[84:87], v[88:91], v[8:11], v[84:87]
	ds_read_b128 v[88:91], v108 offset:16896
	ds_read_b128 v[92:95], v107 offset:16896
	s_waitcnt lgkmcnt(0)
	v_mfma_f32_16x16x32_bf16 v[88:91], v[88:91], v[4:7], 0
	s_nop 3
	v_max_f32_e32 v0, v85, v85
	v_mfma_f32_16x16x32_bf16 v[94:97], v[92:95], v[8:11], v[88:91]
	s_nop 2
	v_max_f32_e32 v88, v84, v84
	v_max_f32_e32 v0, v88, v0
	v_max_f32_e32 v88, v87, v87
	v_max_f32_e32 v89, v86, v86
	v_max_f32_e32 v88, v89, v88
	v_max_f32_e32 v89, v97, v97
	v_max_f32_e32 v90, v96, v96
	v_max_f32_e32 v89, v90, v89
	v_max3_f32 v89, v94, v95, v89
	v_max3_f32 v0, v0, v88, v89
	ds_bpermute_b32 v88, v106, v0
	s_waitcnt lgkmcnt(0)
	v_max_f32_e32 v88, v88, v88
	v_max_f32_e32 v0, v0, v88
	ds_bpermute_b32 v88, v105, v0
	s_waitcnt lgkmcnt(0)
	v_max3_f32 v89, v111, v0, v88
	v_sub_f32_e32 v91, v111, v89
	v_exp_f32_e32 v132, v91
	v_lshl_add_u32 v91, v138, 4, v143
	ds_read_b128 v[112:115], v91 offset:32768
	v_sub_f32_e32 v0, v84, v89
	v_sub_f32_e32 v86, v86, v89
	v_exp_f32_e32 v84, v0
	v_sub_f32_e32 v85, v85, v89
	v_exp_f32_e32 v88, v86
	v_sub_f32_e32 v86, v87, v89
	v_exp_f32_e32 v85, v85
	v_exp_f32_e32 v90, v86
	v_sub_f32_e32 v86, v94, v89
	v_exp_f32_e32 v92, v86
	v_sub_f32_e32 v86, v95, v89
	v_exp_f32_e32 v94, v86
	v_sub_f32_e32 v86, v96, v89
	v_add_f32_e32 v0, 0, v84
	v_exp_f32_e32 v96, v86
	v_sub_f32_e32 v86, v97, v89
	v_pk_mul_f32 v[66:67], v[66:67], v[132:133] op_sel_hi:[1,0]
	v_pk_mul_f32 v[64:65], v[64:65], v[132:133] op_sel_hi:[1,0]
	v_add_f32_e32 v0, v85, v0
	v_exp_f32_e32 v98, v86
	v_cvt_pk_bf16_f32 v84, v84, v85
	v_cvt_pk_bf16_f32 v85, v88, v90
	v_cvt_pk_bf16_f32 v86, v92, v94
	v_cvt_pk_bf16_f32 v87, v96, v98
	v_pk_mul_f32 v[54:55], v[54:55], v[132:133] op_sel_hi:[1,0]
	s_waitcnt lgkmcnt(0)
	v_mfma_f32_16x16x32_bf16 v[64:67], v[112:115], v[84:87], v[64:67]
	ds_read_b128 v[112:115], v91 offset:40960
	v_pk_mul_f32 v[52:53], v[52:53], v[132:133] op_sel_hi:[1,0]
	v_pk_mul_f32 v[58:59], v[58:59], v[132:133] op_sel_hi:[1,0]
	v_pk_mul_f32 v[56:57], v[56:57], v[132:133] op_sel_hi:[1,0]
	s_waitcnt lgkmcnt(0)
	v_mfma_f32_16x16x32_bf16 v[52:55], v[112:115], v[84:87], v[52:55]
	ds_read_b128 v[112:115], v91 offset:49152
	v_pk_mul_f32 v[62:63], v[62:63], v[132:133] op_sel_hi:[1,0]
	v_pk_mul_f32 v[60:61], v[60:61], v[132:133] op_sel_hi:[1,0]
	s_waitcnt lgkmcnt(0)
	v_mfma_f32_16x16x32_bf16 v[56:59], v[112:115], v[84:87], v[56:59]
	ds_read_b128 v[112:115], v91 offset:57344
	v_mul_f32_e32 v100, v100, v132
	s_waitcnt lgkmcnt(0)
	v_mfma_f32_16x16x32_bf16 v[60:63], v[112:115], v[84:87], v[60:63]
	ds_read_b128 v[84:87], v110 offset:20480
	ds_read_b128 v[112:115], v109 offset:20480
	s_waitcnt lgkmcnt(0)
	v_mfma_f32_16x16x32_bf16 v[84:87], v[84:87], v[4:7], 0
	v_mfma_f32_16x16x32_bf16 v[84:87], v[112:115], v[8:11], v[84:87]
	ds_read_b128 v[112:115], v108 offset:20992
	ds_read_b128 v[132:135], v107 offset:20992
	s_waitcnt lgkmcnt(0)
	v_mfma_f32_16x16x32_bf16 v[112:115], v[112:115], v[4:7], 0
	s_nop 3
	v_max_f32_e32 v91, v85, v85
	v_max_f32_e32 v93, v84, v84
	v_max_f32_e32 v91, v93, v91
	v_mfma_f32_16x16x32_bf16 v[112:115], v[132:135], v[8:11], v[112:115]
	v_max_f32_e32 v93, v87, v87
	v_max_f32_e32 v95, v86, v86
	v_max_f32_e32 v93, v95, v93
	s_nop 4
	v_max_f32_e32 v95, v115, v115
	v_max_f32_e32 v97, v114, v114
	v_max_f32_e32 v95, v97, v95
	v_max3_f32 v95, v112, v113, v95
	v_max3_f32 v91, v91, v93, v95
	ds_bpermute_b32 v93, v106, v91
	s_waitcnt lgkmcnt(0)
	v_max_f32_e32 v93, v93, v93
	v_max_f32_e32 v91, v91, v93
	ds_bpermute_b32 v93, v105, v91
	s_waitcnt lgkmcnt(0)
	v_max3_f32 v111, v89, v91, v93
	v_sub_f32_e32 v84, v84, v111
	v_sub_f32_e32 v132, v89, v111
	v_exp_f32_e32 v89, v84
	v_sub_f32_e32 v84, v85, v111
	v_exp_f32_e32 v91, v84
	v_sub_f32_e32 v84, v86, v111
	v_exp_f32_e32 v93, v84
	v_sub_f32_e32 v84, v87, v111
	v_exp_f32_e32 v95, v84
	v_sub_f32_e32 v84, v112, v111
	v_exp_f32_e32 v97, v84
	v_sub_f32_e32 v84, v113, v111
	v_exp_f32_e32 v99, v84
	v_sub_f32_e32 v84, v114, v111
	v_exp_f32_e32 v101, v84
	v_sub_f32_e32 v84, v115, v111
	v_exp_f32_e32 v87, v84
	v_pk_add_f32 v[84:85], v[88:89], v[0:1]
	v_exp_f32_e32 v150, v132
	v_pk_add_f32 v[84:85], v[90:91], v[84:85]
	v_lshl_add_u32 v0, v104, 4, v143
	v_pk_add_f32 v[84:85], v[92:93], v[84:85]
	v_pk_mul_f32 v[66:67], v[66:67], v[150:151] op_sel_hi:[1,0]
	v_pk_add_f32 v[84:85], v[94:95], v[84:85]
	v_pk_mul_f32 v[64:65], v[64:65], v[150:151] op_sel_hi:[1,0]
	v_pk_add_f32 v[84:85], v[96:97], v[84:85]
	v_cvt_pk_bf16_f32 v86, v97, v99
	v_pk_mul_f32 v[54:55], v[54:55], v[150:151] op_sel_hi:[1,0]
	v_pk_add_f32 v[84:85], v[98:99], v[84:85]
	v_pk_mul_f32 v[52:53], v[52:53], v[150:151] op_sel_hi:[1,0]
	v_pk_add_f32 v[84:85], v[100:101], v[84:85]
	v_pk_mul_f32 v[58:59], v[58:59], v[150:151] op_sel_hi:[1,0]
	v_add_f32_e32 v100, v85, v87
	v_fmac_f32_e32 v100, v84, v150
	v_cvt_pk_bf16_f32 v84, v89, v91
	ds_read_b128 v[88:91], v0 offset:32768
	v_cvt_pk_bf16_f32 v85, v93, v95
	v_cvt_pk_bf16_f32 v87, v101, v87
	v_pk_mul_f32 v[56:57], v[56:57], v[150:151] op_sel_hi:[1,0]
	s_waitcnt lgkmcnt(0)
	v_mfma_f32_16x16x32_bf16 v[64:67], v[88:91], v[84:87], v[64:67]
	ds_read_b128 v[88:91], v0 offset:40960
	s_waitcnt lgkmcnt(0)
	v_mfma_f32_16x16x32_bf16 v[112:115], v[88:91], v[84:87], v[52:55]
	s_nop 2
	ds_read_b128 v[52:55], v0 offset:49152
	s_waitcnt lgkmcnt(0)
	v_mfma_f32_16x16x32_bf16 v[132:135], v[52:55], v[84:87], v[56:59]
	ds_read_b128 v[52:55], v0 offset:57344
	s_nop 1
	v_pk_mul_f32 v[58:59], v[62:63], v[150:151] op_sel_hi:[1,0]
	v_pk_mul_f32 v[56:57], v[60:61], v[150:151] op_sel_hi:[1,0]
	s_waitcnt lgkmcnt(0)
	s_nop 0
	v_mfma_f32_16x16x32_bf16 v[84:87], v[52:55], v[84:87], v[56:59]
	ds_read_b128 v[52:55], v110 offset:24576
	s_nop 1
	ds_read_b128 v[56:59], v109 offset:24576
	s_waitcnt lgkmcnt(0)
	v_mfma_f32_16x16x32_bf16 v[52:55], v[52:55], v[4:7], 0
	v_mfma_f32_16x16x32_bf16 v[52:55], v[56:59], v[8:11], v[52:55]
	ds_read_b128 v[56:59], v108 offset:25088
	ds_read_b128 v[60:63], v107 offset:25088
	s_waitcnt lgkmcnt(0)
	v_mfma_f32_16x16x32_bf16 v[56:59], v[56:59], v[4:7], 0
	s_nop 3
	v_max_f32_e32 v0, v53, v53
	v_mfma_f32_16x16x32_bf16 v[56:59], v[60:63], v[8:11], v[56:59]
	v_max_f32_e32 v60, v52, v52
	v_max_f32_e32 v0, v60, v0
	v_max_f32_e32 v60, v55, v55
	v_max_f32_e32 v61, v54, v54
	v_max_f32_e32 v60, v61, v60
	s_nop 2
	v_max_f32_e32 v61, v59, v59
	v_max_f32_e32 v62, v58, v58
	v_max_f32_e32 v61, v62, v61
	v_max3_f32 v61, v56, v57, v61
	v_max3_f32 v0, v0, v60, v61
	ds_bpermute_b32 v60, v106, v0
	s_waitcnt lgkmcnt(0)
	v_max_f32_e32 v60, v60, v60
	v_max_f32_e32 v0, v0, v60
	ds_bpermute_b32 v60, v105, v0
	s_waitcnt lgkmcnt(0)
	v_max3_f32 v89, v111, v0, v60
	v_sub_f32_e32 v0, v52, v89
	v_exp_f32_e32 v52, v0
	v_sub_f32_e32 v54, v54, v89
	v_sub_f32_e32 v53, v53, v89
	v_exp_f32_e32 v88, v54
	v_sub_f32_e32 v54, v55, v89
	v_exp_f32_e32 v53, v53
	v_exp_f32_e32 v90, v54
	v_sub_f32_e32 v54, v56, v89
	v_exp_f32_e32 v92, v54
	v_sub_f32_e32 v54, v57, v89
	v_add_f32_e32 v0, 0, v52
	v_exp_f32_e32 v94, v54
	v_sub_f32_e32 v54, v58, v89
	v_cvt_pk_bf16_f32 v150, v52, v53
	v_bitop3_b32 v52, v157, v142, 24 bitop3:0x36
	v_exp_f32_e32 v96, v54
	v_sub_f32_e32 v54, v59, v89
	v_lshl_add_u32 v91, v52, 4, v143
	v_add_f32_e32 v0, v53, v0
	v_exp_f32_e32 v98, v54
	ds_read_b128 v[52:55], v91 offset:32768
	v_sub_f32_e32 v60, v111, v89
	v_exp_f32_e32 v154, v60
	v_cvt_pk_bf16_f32 v151, v88, v90
	v_cvt_pk_bf16_f32 v152, v92, v94
	v_cvt_pk_bf16_f32 v153, v96, v98
	s_nop 0
	v_pk_mul_f32 v[58:59], v[66:67], v[154:155] op_sel_hi:[1,0]
	v_pk_mul_f32 v[56:57], v[64:65], v[154:155] op_sel_hi:[1,0]
	v_pk_mul_f32 v[62:63], v[114:115], v[154:155] op_sel_hi:[1,0]
	v_pk_mul_f32 v[60:61], v[112:113], v[154:155] op_sel_hi:[1,0]
	s_waitcnt lgkmcnt(0)
	v_mfma_f32_16x16x32_bf16 v[52:55], v[52:55], v[150:153], v[56:59]
	v_mul_f32_e64 v66, v134, v154
	v_mul_f32_e64 v67, v135, v154
	v_pk_mul_f32 v[64:65], v[132:133], v[154:155] op_sel_hi:[1,0]
	v_pk_mul_f32 v[86:87], v[86:87], v[154:155] op_sel_hi:[1,0]
	ds_read_b128 v[56:59], v91 offset:40960
	s_waitcnt lgkmcnt(0)
	v_mfma_f32_16x16x32_bf16 v[56:59], v[56:59], v[150:153], v[60:63]
	s_nop 2
	ds_read_b128 v[60:63], v91 offset:49152
	v_pk_mul_f32 v[84:85], v[84:85], v[154:155] op_sel_hi:[1,0]
	v_mul_f32_e32 v100, v100, v154
	s_waitcnt lgkmcnt(0)
	v_mfma_f32_16x16x32_bf16 v[60:63], v[60:63], v[150:153], v[64:67]
	s_nop 2
	ds_read_b128 v[64:67], v91 offset:57344
	s_waitcnt lgkmcnt(0)
	v_mfma_f32_16x16x32_bf16 v[64:67], v[64:67], v[150:153], v[84:87]
	s_nop 2
	ds_read_b128 v[84:87], v110 offset:28672
	ds_read_b128 v[110:113], v109 offset:28672
	s_waitcnt lgkmcnt(0)
	v_mfma_f32_16x16x32_bf16 v[84:87], v[84:87], v[4:7], 0
	v_mfma_f32_16x16x32_bf16 v[84:87], v[110:113], v[8:11], v[84:87]
	ds_read_b128 v[108:111], v108 offset:29184
	ds_read_b128 v[112:115], v107 offset:29184
	s_waitcnt lgkmcnt(0)
	v_mfma_f32_16x16x32_bf16 v[108:111], v[108:111], v[4:7], 0
	s_nop 3
	v_max_f32_e32 v91, v85, v85
	v_max_f32_e32 v93, v84, v84
	v_max_f32_e32 v91, v93, v91
	v_mfma_f32_16x16x32_bf16 v[108:111], v[112:115], v[8:11], v[108:111]
	v_max_f32_e32 v93, v87, v87
	v_max_f32_e32 v95, v86, v86
	v_max_f32_e32 v93, v95, v93
	s_nop 4
	v_max_f32_e32 v95, v111, v111
	v_max_f32_e32 v97, v110, v110
	v_max_f32_e32 v95, v97, v95
	v_max3_f32 v95, v108, v109, v95
	v_max3_f32 v91, v91, v93, v95
	ds_bpermute_b32 v93, v106, v91
	s_waitcnt lgkmcnt(0)
	v_max_f32_e32 v93, v93, v93
	v_max_f32_e32 v91, v91, v93
	ds_bpermute_b32 v93, v105, v91
	s_waitcnt lgkmcnt(0)
	v_max3_f32 v105, v89, v91, v93
	v_sub_f32_e32 v84, v84, v105
	v_sub_f32_e32 v106, v89, v105
	v_exp_f32_e32 v89, v84
	v_sub_f32_e32 v84, v85, v105
	v_exp_f32_e32 v91, v84
	v_sub_f32_e32 v84, v86, v105
	v_exp_f32_e32 v93, v84
	v_sub_f32_e32 v84, v87, v105
	v_exp_f32_e32 v95, v84
	v_sub_f32_e32 v84, v108, v105
	v_exp_f32_e32 v97, v84
	v_sub_f32_e32 v84, v109, v105
	v_exp_f32_e32 v99, v84
	v_sub_f32_e32 v84, v110, v105
	v_exp_f32_e32 v101, v84
	v_sub_f32_e32 v84, v111, v105
	v_exp_f32_e32 v87, v84
	v_pk_add_f32 v[84:85], v[88:89], v[0:1]
	v_exp_f32_e32 v106, v106
	v_pk_add_f32 v[84:85], v[90:91], v[84:85]
	v_bitop3_b32 v0, v157, v142, 28 bitop3:0x36
	v_pk_add_f32 v[84:85], v[92:93], v[84:85]
	v_lshl_add_u32 v0, v0, 4, v143
	v_pk_add_f32 v[84:85], v[94:95], v[84:85]
	v_pk_mul_f32 v[54:55], v[54:55], v[106:107] op_sel_hi:[1,0]
	v_pk_add_f32 v[84:85], v[96:97], v[84:85]
	v_pk_mul_f32 v[52:53], v[52:53], v[106:107] op_sel_hi:[1,0]
	v_pk_add_f32 v[84:85], v[98:99], v[84:85]
	v_cvt_pk_bf16_f32 v86, v97, v99
	v_pk_mul_f32 v[58:59], v[58:59], v[106:107] op_sel_hi:[1,0]
	v_pk_add_f32 v[84:85], v[100:101], v[84:85]
	v_pk_mul_f32 v[56:57], v[56:57], v[106:107] op_sel_hi:[1,0]
	v_add_f32_e32 v105, v85, v87
	v_fmac_f32_e32 v105, v84, v106
	v_cvt_pk_bf16_f32 v84, v89, v91
	ds_read_b128 v[88:91], v0 offset:32768
	v_cvt_pk_bf16_f32 v85, v93, v95
	v_cvt_pk_bf16_f32 v87, v101, v87
	v_pk_mul_f32 v[62:63], v[62:63], v[106:107] op_sel_hi:[1,0]
	s_waitcnt lgkmcnt(0)
	v_mfma_f32_16x16x32_bf16 v[52:55], v[88:91], v[84:87], v[52:55]
	ds_read_b128 v[88:91], v0 offset:40960
	v_pk_mul_f32 v[60:61], v[60:61], v[106:107] op_sel_hi:[1,0]
	v_pk_mul_f32 v[66:67], v[66:67], v[106:107] op_sel_hi:[1,0]
	s_waitcnt lgkmcnt(0)
	v_mfma_f32_16x16x32_bf16 v[56:59], v[88:91], v[84:87], v[56:59]
	ds_read_b128 v[88:91], v0 offset:49152
	v_pk_mul_f32 v[64:65], v[64:65], v[106:107] op_sel_hi:[1,0]
	s_waitcnt lgkmcnt(0)
	v_mfma_f32_16x16x32_bf16 v[60:63], v[88:91], v[84:87], v[60:63]
	ds_read_b128 v[88:91], v0 offset:57344
	s_waitcnt lgkmcnt(0)
	v_mfma_f32_16x16x32_bf16 v[64:67], v[88:91], v[84:87], v[64:67]
	s_setprio 0
.LBB0_335:
	s_andn2_b64 vcc, exec, s[48:49]
	s_cbranch_vccnz .LBB0_516
	v_cmp_lt_i32_e32 vcc, v210, v208
	v_lshl_add_u32 v109, v102, 4, v143
	s_nop 0
	v_cndmask_b32_e32 v0, v207, v210, vcc
	v_cmp_lt_i32_e32 vcc, v209, v208
	v_lshlrev_b32_e32 v150, 2, v0
	s_nop 0
	v_cndmask_b32_e32 v0, v207, v209, vcc
	v_lshlrev_b32_e32 v149, 2, v0
	v_lshl_add_u32 v0, v103, 7, 0
	v_lshl_add_u32 v154, v158, 4, v0
	ds_read_b128 v[84:87], v154
	v_lshl_add_u32 v153, v159, 4, v0
	ds_read_b128 v[88:91], v153
	s_waitcnt lgkmcnt(0)
	s_setprio 3
	v_mfma_f32_16x16x32_bf16 v[84:87], v[84:87], v[12:15], 0
	v_lshl_add_u32 v152, v144, 4, v0
	v_lshl_add_u32 v151, v146, 4, v0
	ds_read_b128 v[92:95], v151 offset:512
	v_mfma_f32_16x16x32_bf16 v[84:87], v[88:91], v[16:19], v[84:87]
	ds_read_b128 v[88:91], v152 offset:512
	s_waitcnt lgkmcnt(0)
	v_mfma_f32_16x16x32_bf16 v[88:91], v[88:91], v[12:15], 0
	s_nop 4
	v_max_f32_e32 v0, v85, v85
	v_mfma_f32_16x16x32_bf16 v[88:91], v[92:95], v[16:19], v[88:91]
	v_max_f32_e32 v92, v84, v84
	v_max_f32_e32 v0, v92, v0
	v_max_f32_e32 v92, v87, v87
	v_max_f32_e32 v93, v86, v86
	v_max_f32_e32 v92, v93, v92
	s_nop 2
	v_max_f32_e32 v93, v91, v91
	v_max_f32_e32 v94, v90, v90
	v_max_f32_e32 v93, v94, v93
	v_max3_f32 v93, v88, v89, v93
	v_max3_f32 v0, v0, v92, v93
	ds_bpermute_b32 v92, v150, v0
	s_waitcnt lgkmcnt(0)
	v_max_f32_e32 v92, v92, v92
	v_max_f32_e32 v0, v0, v92
	ds_bpermute_b32 v92, v149, v0
	s_waitcnt lgkmcnt(0)
	v_max3_f32 v107, v160, v0, v92
	v_sub_f32_e32 v0, v84, v107
	v_sub_f32_e32 v86, v86, v107
	v_exp_f32_e32 v84, v0
	v_sub_f32_e32 v85, v85, v107
	v_exp_f32_e32 v106, v86
	v_sub_f32_e32 v86, v87, v107
	v_exp_f32_e32 v85, v85
	v_exp_f32_e32 v108, v86
	v_sub_f32_e32 v86, v88, v107
	v_exp_f32_e32 v110, v86
	v_sub_f32_e32 v86, v89, v107
	v_exp_f32_e32 v112, v86
	v_sub_f32_e32 v86, v90, v107
	v_add_f32_e32 v0, 0, v84
	v_exp_f32_e32 v114, v86
	v_sub_f32_e32 v86, v91, v107
	v_add_f32_e32 v0, v85, v0
	v_exp_f32_e32 v132, v86
	v_cvt_pk_bf16_f32 v88, v84, v85
	ds_read_b128 v[84:87], v109 offset:32768
	v_sub_f32_e32 v92, v160, v107
	v_exp_f32_e32 v164, v92
	v_cvt_pk_bf16_f32 v89, v106, v108
	v_cvt_pk_bf16_f32 v90, v110, v112
	v_cvt_pk_bf16_f32 v91, v114, v132
	s_nop 0
	v_pk_mul_f32 v[94:95], v[30:31], v[164:165] op_sel_hi:[1,0]
	v_pk_mul_f32 v[92:93], v[28:29], v[164:165] op_sel_hi:[1,0]
	v_pk_mul_f32 v[102:103], v[42:43], v[164:165] op_sel_hi:[1,0]
	v_pk_mul_f32 v[100:101], v[40:41], v[164:165] op_sel_hi:[1,0]
	s_waitcnt lgkmcnt(0)
	v_mfma_f32_16x16x32_bf16 v[96:99], v[84:87], v[88:91], v[92:95]
	ds_read_b128 v[84:87], v109 offset:40960
	v_mul_f32_e32 v134, v136, v164
	v_pk_mul_f32 v[166:167], v[50:51], v[164:165] op_sel_hi:[1,0]
	v_pk_mul_f32 v[94:95], v[38:39], v[164:165] op_sel_hi:[1,0]
	v_pk_mul_f32 v[92:93], v[36:37], v[164:165] op_sel_hi:[1,0]
	v_pk_mul_f32 v[164:165], v[48:49], v[164:165] op_sel_hi:[1,0]
	s_waitcnt lgkmcnt(0)
	v_mfma_f32_16x16x32_bf16 v[92:95], v[84:87], v[88:91], v[92:95]
	ds_read_b128 v[84:87], v109 offset:49152
	s_waitcnt lgkmcnt(0)
	v_mfma_f32_16x16x32_bf16 v[84:87], v[84:87], v[88:91], v[100:103]
	s_nop 2
	ds_read_b128 v[100:103], v109 offset:57344
	s_waitcnt lgkmcnt(0)
	v_mfma_f32_16x16x32_bf16 v[88:91], v[100:103], v[88:91], v[164:167]
	ds_read_b128 v[100:103], v154 offset:4096
	s_nop 1
	ds_read_b128 v[164:167], v153 offset:4096
	s_waitcnt lgkmcnt(0)
	v_mfma_f32_16x16x32_bf16 v[100:103], v[100:103], v[12:15], 0
	v_mfma_f32_16x16x32_bf16 v[100:103], v[164:167], v[16:19], v[100:103]
	ds_read_b128 v[164:167], v152 offset:4608
	ds_read_b128 v[168:171], v151 offset:4608
	s_waitcnt lgkmcnt(0)
	v_mfma_f32_16x16x32_bf16 v[164:167], v[164:167], v[12:15], 0
	s_nop 3
	v_max_f32_e32 v109, v101, v101
	v_max_f32_e32 v111, v100, v100
	v_max_f32_e32 v109, v111, v109
	v_mfma_f32_16x16x32_bf16 v[164:167], v[168:171], v[16:19], v[164:167]
	v_max_f32_e32 v111, v103, v103
	v_max_f32_e32 v113, v102, v102
	v_max_f32_e32 v111, v113, v111
	s_nop 4
	v_max_f32_e32 v113, v167, v167
	v_max_f32_e32 v115, v166, v166
	v_max_f32_e32 v113, v115, v113
	v_max3_f32 v113, v164, v165, v113
	v_max3_f32 v109, v109, v111, v113
	ds_bpermute_b32 v111, v150, v109
	s_waitcnt lgkmcnt(0)
	v_max_f32_e32 v111, v111, v111
	v_max_f32_e32 v109, v109, v111
	ds_bpermute_b32 v111, v149, v109
	s_waitcnt lgkmcnt(0)
	v_max3_f32 v155, v107, v109, v111
	v_sub_f32_e32 v100, v100, v155
	v_sub_f32_e32 v163, v107, v155
	v_exp_f32_e32 v107, v100
	v_sub_f32_e32 v100, v101, v155
	v_exp_f32_e32 v109, v100
	v_sub_f32_e32 v100, v102, v155
	v_exp_f32_e32 v111, v100
	v_sub_f32_e32 v100, v103, v155
	v_exp_f32_e32 v113, v100
	v_sub_f32_e32 v100, v164, v155
	v_exp_f32_e32 v115, v100
	v_sub_f32_e32 v100, v165, v155
	v_exp_f32_e32 v133, v100
	v_sub_f32_e32 v100, v166, v155
	v_exp_f32_e32 v135, v100
	v_sub_f32_e32 v100, v167, v155
	v_exp_f32_e32 v103, v100
	v_pk_add_f32 v[100:101], v[106:107], v[0:1]
	v_exp_f32_e32 v168, v163
	v_pk_add_f32 v[100:101], v[108:109], v[100:101]
	v_lshl_add_u32 v0, v148, 4, v143
	v_pk_add_f32 v[100:101], v[110:111], v[100:101]
	v_pk_mul_f32 v[98:99], v[98:99], v[168:169] op_sel_hi:[1,0]
	v_pk_add_f32 v[100:101], v[112:113], v[100:101]
	v_pk_mul_f32 v[96:97], v[96:97], v[168:169] op_sel_hi:[1,0]
	v_pk_add_f32 v[100:101], v[114:115], v[100:101]
	v_cvt_pk_bf16_f32 v102, v115, v133
	v_pk_mul_f32 v[94:95], v[94:95], v[168:169] op_sel_hi:[1,0]
	v_pk_add_f32 v[100:101], v[132:133], v[100:101]
	v_pk_mul_f32 v[92:93], v[92:93], v[168:169] op_sel_hi:[1,0]
	v_pk_add_f32 v[100:101], v[134:135], v[100:101]
	v_pk_mul_f32 v[86:87], v[86:87], v[168:169] op_sel_hi:[1,0]
	v_add_f32_e32 v134, v101, v103
	v_fmac_f32_e32 v134, v100, v168
	v_cvt_pk_bf16_f32 v100, v107, v109
	ds_read_b128 v[106:109], v0 offset:32768
	v_cvt_pk_bf16_f32 v101, v111, v113
	v_cvt_pk_bf16_f32 v103, v135, v103
	v_pk_mul_f32 v[84:85], v[84:85], v[168:169] op_sel_hi:[1,0]
	s_waitcnt lgkmcnt(0)
	v_mfma_f32_16x16x32_bf16 v[96:99], v[106:109], v[100:103], v[96:99]
	ds_read_b128 v[106:109], v0 offset:40960
	v_pk_mul_f32 v[90:91], v[90:91], v[168:169] op_sel_hi:[1,0]
	v_pk_mul_f32 v[88:89], v[88:89], v[168:169] op_sel_hi:[1,0]
	s_waitcnt lgkmcnt(0)
	v_mfma_f32_16x16x32_bf16 v[92:95], v[106:109], v[100:103], v[92:95]
	ds_read_b128 v[106:109], v0 offset:49152
	s_waitcnt lgkmcnt(0)
	v_mfma_f32_16x16x32_bf16 v[164:167], v[106:109], v[100:103], v[84:87]
	s_nop 2
	ds_read_b128 v[84:87], v0 offset:57344
	s_waitcnt lgkmcnt(0)
	v_mfma_f32_16x16x32_bf16 v[100:103], v[84:87], v[100:103], v[88:91]
	ds_read_b128 v[84:87], v154 offset:8192
	s_nop 1
	ds_read_b128 v[88:91], v153 offset:8192
	s_waitcnt lgkmcnt(0)
	v_mfma_f32_16x16x32_bf16 v[84:87], v[84:87], v[12:15], 0
	v_mfma_f32_16x16x32_bf16 v[84:87], v[88:91], v[16:19], v[84:87]
	ds_read_b128 v[88:91], v152 offset:8704
	ds_read_b128 v[106:109], v151 offset:8704
	s_waitcnt lgkmcnt(0)
	v_mfma_f32_16x16x32_bf16 v[88:91], v[88:91], v[12:15], 0
	s_nop 3
	v_max_f32_e32 v0, v85, v85
	v_mfma_f32_16x16x32_bf16 v[88:91], v[106:109], v[16:19], v[88:91]
	v_max_f32_e32 v106, v84, v84
	v_max_f32_e32 v0, v106, v0
	v_max_f32_e32 v106, v87, v87
	v_max_f32_e32 v107, v86, v86
	v_max_f32_e32 v106, v107, v106
	s_nop 2
	v_max_f32_e32 v107, v91, v91
	v_max_f32_e32 v108, v90, v90
	v_max_f32_e32 v107, v108, v107
	v_max3_f32 v107, v88, v89, v107
	v_max3_f32 v0, v0, v106, v107
	ds_bpermute_b32 v106, v150, v0
	s_waitcnt lgkmcnt(0)
	v_max_f32_e32 v106, v106, v106
	v_max_f32_e32 v0, v0, v106
	ds_bpermute_b32 v106, v149, v0
	s_waitcnt lgkmcnt(0)
	v_max3_f32 v107, v155, v0, v106
	v_sub_f32_e32 v0, v84, v107
	v_sub_f32_e32 v86, v86, v107
	v_exp_f32_e32 v84, v0
	v_sub_f32_e32 v85, v85, v107
	v_exp_f32_e32 v106, v86
	v_sub_f32_e32 v86, v87, v107
	v_exp_f32_e32 v85, v85
	v_exp_f32_e32 v108, v86
	v_sub_f32_e32 v86, v88, v107
	v_exp_f32_e32 v110, v86
	v_sub_f32_e32 v86, v89, v107
	v_sub_f32_e32 v109, v155, v107
	v_exp_f32_e32 v112, v86
	v_sub_f32_e32 v86, v90, v107
	v_add_f32_e32 v0, 0, v84
	v_exp_f32_e32 v114, v86
	v_sub_f32_e32 v86, v91, v107
	v_exp_f32_e32 v148, v109
	v_lshl_add_u32 v109, v141, 4, v143
	v_add_f32_e32 v0, v85, v0
	v_exp_f32_e32 v132, v86
	v_cvt_pk_bf16_f32 v168, v84, v85
	ds_read_b128 v[84:87], v109 offset:32768
	v_pk_mul_f32 v[90:91], v[98:99], v[148:149] op_sel_hi:[1,0]
	v_pk_mul_f32 v[88:89], v[96:97], v[148:149] op_sel_hi:[1,0]
	v_cvt_pk_bf16_f32 v169, v106, v108
	v_cvt_pk_bf16_f32 v170, v110, v112
	v_cvt_pk_bf16_f32 v171, v114, v132
	v_pk_mul_f32 v[102:103], v[102:103], v[148:149] op_sel_hi:[1,0]
	v_pk_mul_f32 v[100:101], v[100:101], v[148:149] op_sel_hi:[1,0]
	s_waitcnt lgkmcnt(0)
	v_mfma_f32_16x16x32_bf16 v[96:99], v[84:87], v[168:171], v[88:91]
	ds_read_b128 v[84:87], v109 offset:40960
	v_mul_f32_e32 v134, v134, v148
	s_nop 0
	v_pk_mul_f32 v[90:91], v[94:95], v[148:149] op_sel_hi:[1,0]
	v_pk_mul_f32 v[88:89], v[92:93], v[148:149] op_sel_hi:[1,0]
	v_pk_mul_f32 v[94:95], v[166:167], v[148:149] op_sel_hi:[1,0]
	v_pk_mul_f32 v[92:93], v[164:165], v[148:149] op_sel_hi:[1,0]
	s_waitcnt lgkmcnt(0)
	v_mfma_f32_16x16x32_bf16 v[84:87], v[84:87], v[168:171], v[88:91]
	s_nop 2
	ds_read_b128 v[88:91], v109 offset:49152
	s_waitcnt lgkmcnt(0)
	v_mfma_f32_16x16x32_bf16 v[88:91], v[88:91], v[168:171], v[92:95]
	s_nop 2
	ds_read_b128 v[92:95], v109 offset:57344
	s_waitcnt lgkmcnt(0)
	v_mfma_f32_16x16x32_bf16 v[92:95], v[92:95], v[168:171], v[100:103]
	s_nop 2
	ds_read_b128 v[100:103], v154 offset:12288
	ds_read_b128 v[164:167], v153 offset:12288
	s_waitcnt lgkmcnt(0)
	v_mfma_f32_16x16x32_bf16 v[100:103], v[100:103], v[12:15], 0
	v_mfma_f32_16x16x32_bf16 v[100:103], v[164:167], v[16:19], v[100:103]
	ds_read_b128 v[164:167], v152 offset:12800
	ds_read_b128 v[168:171], v151 offset:12800
	s_waitcnt lgkmcnt(0)
	v_mfma_f32_16x16x32_bf16 v[164:167], v[164:167], v[12:15], 0
	s_nop 3
	v_max_f32_e32 v109, v101, v101
	v_max_f32_e32 v111, v100, v100
	v_max_f32_e32 v109, v111, v109
	v_mfma_f32_16x16x32_bf16 v[164:167], v[168:171], v[16:19], v[164:167]
	v_max_f32_e32 v111, v103, v103
	v_max_f32_e32 v113, v102, v102
	v_max_f32_e32 v111, v113, v111
	s_nop 4
	v_max_f32_e32 v113, v167, v167
	v_max_f32_e32 v115, v166, v166
	v_max_f32_e32 v113, v115, v113
	v_max3_f32 v113, v164, v165, v113
	v_max3_f32 v109, v109, v111, v113
	ds_bpermute_b32 v111, v150, v109
	s_waitcnt lgkmcnt(0)
	v_max_f32_e32 v111, v111, v111
	v_max_f32_e32 v109, v109, v111
	ds_bpermute_b32 v111, v149, v109
	s_waitcnt lgkmcnt(0)
	v_max3_f32 v141, v107, v109, v111
	v_sub_f32_e32 v100, v100, v141
	v_sub_f32_e32 v148, v107, v141
	v_exp_f32_e32 v107, v100
	v_sub_f32_e32 v100, v101, v141
	v_exp_f32_e32 v109, v100
	v_sub_f32_e32 v100, v102, v141
	v_exp_f32_e32 v111, v100
	v_sub_f32_e32 v100, v103, v141
	v_exp_f32_e32 v113, v100
	v_sub_f32_e32 v100, v164, v141
	v_exp_f32_e32 v115, v100
	v_sub_f32_e32 v100, v165, v141
	v_exp_f32_e32 v133, v100
	v_sub_f32_e32 v100, v166, v141
	v_exp_f32_e32 v135, v100
	v_sub_f32_e32 v100, v167, v141
	v_exp_f32_e32 v103, v100
	v_pk_add_f32 v[100:101], v[106:107], v[0:1]
	v_exp_f32_e32 v148, v148
	v_pk_add_f32 v[100:101], v[108:109], v[100:101]
	v_lshl_add_u32 v0, v140, 4, v143
	v_pk_add_f32 v[100:101], v[110:111], v[100:101]
	v_pk_mul_f32 v[98:99], v[98:99], v[148:149] op_sel_hi:[1,0]
	v_pk_add_f32 v[100:101], v[112:113], v[100:101]
	v_pk_mul_f32 v[96:97], v[96:97], v[148:149] op_sel_hi:[1,0]
	v_pk_add_f32 v[100:101], v[114:115], v[100:101]
	v_cvt_pk_bf16_f32 v102, v115, v133
	v_pk_mul_f32 v[86:87], v[86:87], v[148:149] op_sel_hi:[1,0]
	v_pk_add_f32 v[100:101], v[132:133], v[100:101]
	v_pk_mul_f32 v[84:85], v[84:85], v[148:149] op_sel_hi:[1,0]
	v_pk_add_f32 v[100:101], v[134:135], v[100:101]
	v_pk_mul_f32 v[90:91], v[90:91], v[148:149] op_sel_hi:[1,0]
	v_add_f32_e32 v134, v101, v103
	v_fmac_f32_e32 v134, v100, v148
	v_cvt_pk_bf16_f32 v100, v107, v109
	ds_read_b128 v[106:109], v0 offset:32768
	v_cvt_pk_bf16_f32 v101, v111, v113
	v_cvt_pk_bf16_f32 v103, v135, v103
	v_pk_mul_f32 v[88:89], v[88:89], v[148:149] op_sel_hi:[1,0]
	s_waitcnt lgkmcnt(0)
	v_mfma_f32_16x16x32_bf16 v[96:99], v[106:109], v[100:103], v[96:99]
	ds_read_b128 v[106:109], v0 offset:40960
	v_pk_mul_f32 v[94:95], v[94:95], v[148:149] op_sel_hi:[1,0]
	v_pk_mul_f32 v[92:93], v[92:93], v[148:149] op_sel_hi:[1,0]
	s_waitcnt lgkmcnt(0)
	v_mfma_f32_16x16x32_bf16 v[84:87], v[106:109], v[100:103], v[84:87]
	ds_read_b128 v[106:109], v0 offset:49152
	s_waitcnt lgkmcnt(0)
	v_mfma_f32_16x16x32_bf16 v[88:91], v[106:109], v[100:103], v[88:91]
	ds_read_b128 v[106:109], v0 offset:57344
	s_waitcnt lgkmcnt(0)
	v_mfma_f32_16x16x32_bf16 v[92:95], v[106:109], v[100:103], v[92:95]
	ds_read_b128 v[100:103], v154 offset:16384
	ds_read_b128 v[106:109], v153 offset:16384
	s_waitcnt lgkmcnt(0)
	v_mfma_f32_16x16x32_bf16 v[100:103], v[100:103], v[12:15], 0
	v_mfma_f32_16x16x32_bf16 v[100:103], v[106:109], v[16:19], v[100:103]
	ds_read_b128 v[106:109], v152 offset:16896
	ds_read_b128 v[110:113], v151 offset:16896
	s_waitcnt lgkmcnt(0)
	v_mfma_f32_16x16x32_bf16 v[106:109], v[106:109], v[12:15], 0
	s_nop 3
	v_max_f32_e32 v0, v101, v101
	v_mfma_f32_16x16x32_bf16 v[112:115], v[110:113], v[16:19], v[106:109]
	s_nop 2
	v_max_f32_e32 v106, v100, v100
	v_max_f32_e32 v0, v106, v0
	v_max_f32_e32 v106, v103, v103
	v_max_f32_e32 v107, v102, v102
	v_max_f32_e32 v106, v107, v106
	v_max_f32_e32 v107, v115, v115
	v_max_f32_e32 v108, v114, v114
	v_max_f32_e32 v107, v108, v107
	v_max3_f32 v107, v112, v113, v107
	v_max3_f32 v0, v0, v106, v107
	ds_bpermute_b32 v106, v150, v0
	s_waitcnt lgkmcnt(0)
	v_max_f32_e32 v106, v106, v106
	v_max_f32_e32 v0, v0, v106
	ds_bpermute_b32 v106, v149, v0
	s_waitcnt lgkmcnt(0)
	v_max3_f32 v107, v141, v0, v106
	v_sub_f32_e32 v109, v141, v107
	v_exp_f32_e32 v140, v109
	v_lshl_add_u32 v109, v138, 4, v143
	ds_read_b128 v[164:167], v109 offset:32768
	v_sub_f32_e32 v0, v100, v107
	v_sub_f32_e32 v102, v102, v107
	v_exp_f32_e32 v100, v0
	v_sub_f32_e32 v101, v101, v107
	v_exp_f32_e32 v106, v102
	v_sub_f32_e32 v102, v103, v107
	v_exp_f32_e32 v101, v101
	v_exp_f32_e32 v108, v102
	v_sub_f32_e32 v102, v112, v107
	v_exp_f32_e32 v110, v102
	v_sub_f32_e32 v102, v113, v107
	v_exp_f32_e32 v112, v102
	v_sub_f32_e32 v102, v114, v107
	v_add_f32_e32 v0, 0, v100
	v_exp_f32_e32 v114, v102
	v_sub_f32_e32 v102, v115, v107
	v_pk_mul_f32 v[98:99], v[98:99], v[140:141] op_sel_hi:[1,0]
	v_pk_mul_f32 v[96:97], v[96:97], v[140:141] op_sel_hi:[1,0]
	v_add_f32_e32 v0, v101, v0
	v_exp_f32_e32 v132, v102
	v_cvt_pk_bf16_f32 v100, v100, v101
	v_cvt_pk_bf16_f32 v101, v106, v108
	v_cvt_pk_bf16_f32 v102, v110, v112
	v_cvt_pk_bf16_f32 v103, v114, v132
	v_pk_mul_f32 v[86:87], v[86:87], v[140:141] op_sel_hi:[1,0]
	s_waitcnt lgkmcnt(0)
	v_mfma_f32_16x16x32_bf16 v[96:99], v[164:167], v[100:103], v[96:99]
	ds_read_b128 v[164:167], v109 offset:40960
	v_pk_mul_f32 v[84:85], v[84:85], v[140:141] op_sel_hi:[1,0]
	v_pk_mul_f32 v[90:91], v[90:91], v[140:141] op_sel_hi:[1,0]
	v_pk_mul_f32 v[88:89], v[88:89], v[140:141] op_sel_hi:[1,0]
	s_waitcnt lgkmcnt(0)
	v_mfma_f32_16x16x32_bf16 v[84:87], v[164:167], v[100:103], v[84:87]
	ds_read_b128 v[164:167], v109 offset:49152
	v_pk_mul_f32 v[94:95], v[94:95], v[140:141] op_sel_hi:[1,0]
	v_pk_mul_f32 v[92:93], v[92:93], v[140:141] op_sel_hi:[1,0]
	s_waitcnt lgkmcnt(0)
	v_mfma_f32_16x16x32_bf16 v[88:91], v[164:167], v[100:103], v[88:91]
	ds_read_b128 v[164:167], v109 offset:57344
	v_mul_f32_e32 v134, v134, v140
	s_waitcnt lgkmcnt(0)
	v_mfma_f32_16x16x32_bf16 v[92:95], v[164:167], v[100:103], v[92:95]
	ds_read_b128 v[100:103], v154 offset:20480
	ds_read_b128 v[164:167], v153 offset:20480
	s_waitcnt lgkmcnt(0)
	v_mfma_f32_16x16x32_bf16 v[100:103], v[100:103], v[12:15], 0
	v_mfma_f32_16x16x32_bf16 v[100:103], v[164:167], v[16:19], v[100:103]
	ds_read_b128 v[164:167], v152 offset:20992
	ds_read_b128 v[168:171], v151 offset:20992
	s_waitcnt lgkmcnt(0)
	v_mfma_f32_16x16x32_bf16 v[164:167], v[164:167], v[12:15], 0
	s_nop 3
	v_max_f32_e32 v109, v101, v101
	v_max_f32_e32 v111, v100, v100
	v_max_f32_e32 v109, v111, v109
	v_mfma_f32_16x16x32_bf16 v[164:167], v[168:171], v[16:19], v[164:167]
	v_max_f32_e32 v111, v103, v103
	v_max_f32_e32 v113, v102, v102
	v_max_f32_e32 v111, v113, v111
	s_nop 4
	v_max_f32_e32 v113, v167, v167
	v_max_f32_e32 v115, v166, v166
	v_max_f32_e32 v113, v115, v113
	v_max3_f32 v113, v164, v165, v113
	v_max3_f32 v109, v109, v111, v113
	ds_bpermute_b32 v111, v150, v109
	s_waitcnt lgkmcnt(0)
	v_max_f32_e32 v111, v111, v111
	v_max_f32_e32 v109, v109, v111
	ds_bpermute_b32 v111, v149, v109
	s_waitcnt lgkmcnt(0)
	v_max3_f32 v140, v107, v109, v111
	v_sub_f32_e32 v100, v100, v140
	v_sub_f32_e32 v138, v107, v140
	v_exp_f32_e32 v107, v100
	v_sub_f32_e32 v100, v101, v140
	v_exp_f32_e32 v109, v100
	v_sub_f32_e32 v100, v102, v140
	v_exp_f32_e32 v111, v100
	v_sub_f32_e32 v100, v103, v140
	v_exp_f32_e32 v113, v100
	v_sub_f32_e32 v100, v164, v140
	v_exp_f32_e32 v115, v100
	v_sub_f32_e32 v100, v165, v140
	v_exp_f32_e32 v133, v100
	v_sub_f32_e32 v100, v166, v140
	v_exp_f32_e32 v135, v100
	v_sub_f32_e32 v100, v167, v140
	v_exp_f32_e32 v103, v100
	v_pk_add_f32 v[100:101], v[106:107], v[0:1]
	v_exp_f32_e32 v138, v138
	v_pk_add_f32 v[100:101], v[108:109], v[100:101]
	v_lshl_add_u32 v0, v104, 4, v143
	v_pk_add_f32 v[100:101], v[110:111], v[100:101]
	v_pk_mul_f32 v[98:99], v[98:99], v[138:139] op_sel_hi:[1,0]
	v_pk_add_f32 v[100:101], v[112:113], v[100:101]
	v_pk_mul_f32 v[96:97], v[96:97], v[138:139] op_sel_hi:[1,0]
	v_pk_add_f32 v[100:101], v[114:115], v[100:101]
	v_cvt_pk_bf16_f32 v102, v115, v133
	v_pk_mul_f32 v[86:87], v[86:87], v[138:139] op_sel_hi:[1,0]
	v_pk_add_f32 v[100:101], v[132:133], v[100:101]
	v_pk_mul_f32 v[84:85], v[84:85], v[138:139] op_sel_hi:[1,0]
	v_pk_add_f32 v[100:101], v[134:135], v[100:101]
	v_pk_mul_f32 v[90:91], v[90:91], v[138:139] op_sel_hi:[1,0]
	v_add_f32_e32 v134, v101, v103
	v_fmac_f32_e32 v134, v100, v138
	v_cvt_pk_bf16_f32 v100, v107, v109
	ds_read_b128 v[106:109], v0 offset:32768
	v_cvt_pk_bf16_f32 v101, v111, v113
	v_cvt_pk_bf16_f32 v103, v135, v103
	v_pk_mul_f32 v[88:89], v[88:89], v[138:139] op_sel_hi:[1,0]
	s_waitcnt lgkmcnt(0)
	v_mfma_f32_16x16x32_bf16 v[96:99], v[106:109], v[100:103], v[96:99]
	ds_read_b128 v[106:109], v0 offset:40960
	v_pk_mul_f32 v[94:95], v[94:95], v[138:139] op_sel_hi:[1,0]
	v_pk_mul_f32 v[92:93], v[92:93], v[138:139] op_sel_hi:[1,0]
	s_waitcnt lgkmcnt(0)
	v_mfma_f32_16x16x32_bf16 v[84:87], v[106:109], v[100:103], v[84:87]
	ds_read_b128 v[106:109], v0 offset:49152
	s_waitcnt lgkmcnt(0)
	v_mfma_f32_16x16x32_bf16 v[88:91], v[106:109], v[100:103], v[88:91]
	ds_read_b128 v[106:109], v0 offset:57344
	s_waitcnt lgkmcnt(0)
	v_mfma_f32_16x16x32_bf16 v[100:103], v[106:109], v[100:103], v[92:95]
	s_nop 2
	ds_read_b128 v[92:95], v154 offset:24576
	ds_read_b128 v[106:109], v153 offset:24576
	s_waitcnt lgkmcnt(0)
	v_mfma_f32_16x16x32_bf16 v[92:95], v[92:95], v[12:15], 0
	v_mfma_f32_16x16x32_bf16 v[92:95], v[106:109], v[16:19], v[92:95]
	ds_read_b128 v[106:109], v152 offset:25088
	ds_read_b128 v[110:113], v151 offset:25088
	s_waitcnt lgkmcnt(0)
	v_mfma_f32_16x16x32_bf16 v[106:109], v[106:109], v[12:15], 0
	s_nop 3
	v_max_f32_e32 v0, v93, v93
	v_max_f32_e32 v104, v92, v92
	v_max_f32_e32 v0, v104, v0
	v_mfma_f32_16x16x32_bf16 v[112:115], v[110:113], v[16:19], v[106:109]
	v_max_f32_e32 v104, v95, v95
	s_nop 1
	v_max_f32_e32 v106, v94, v94
	v_max_f32_e32 v104, v106, v104
	s_nop 2
	v_max_f32_e32 v106, v115, v115
	v_max_f32_e32 v107, v114, v114
	v_max_f32_e32 v106, v107, v106
	v_max3_f32 v106, v112, v113, v106
	v_max3_f32 v0, v0, v104, v106
	ds_bpermute_b32 v104, v150, v0
	s_waitcnt lgkmcnt(0)
	v_max_f32_e32 v104, v104, v104
	v_max_f32_e32 v0, v0, v104
	ds_bpermute_b32 v104, v149, v0
	s_waitcnt lgkmcnt(0)
	v_max3_f32 v104, v140, v0, v104
	v_sub_f32_e32 v0, v92, v104
	v_exp_f32_e32 v92, v0
	v_sub_f32_e32 v94, v94, v104
	v_sub_f32_e32 v93, v93, v104
	v_exp_f32_e32 v106, v94
	v_sub_f32_e32 v94, v95, v104
	v_exp_f32_e32 v93, v93
	v_exp_f32_e32 v108, v94
	v_sub_f32_e32 v94, v112, v104
	v_exp_f32_e32 v110, v94
	v_sub_f32_e32 v94, v113, v104
	v_sub_f32_e32 v107, v140, v104
	v_add_f32_e32 v0, 0, v92
	v_exp_f32_e32 v112, v94
	v_sub_f32_e32 v94, v114, v104
	v_cvt_pk_bf16_f32 v164, v92, v93
	v_bitop3_b32 v92, v157, v142, 24 bitop3:0x36
	v_exp_f32_e32 v114, v94
	v_sub_f32_e32 v94, v115, v104
	v_exp_f32_e32 v138, v107
	v_lshl_add_u32 v107, v92, 4, v143
	v_add_f32_e32 v0, v93, v0
	v_exp_f32_e32 v132, v94
	ds_read_b128 v[92:95], v107 offset:32768
	v_pk_mul_f32 v[98:99], v[98:99], v[138:139] op_sel_hi:[1,0]
	v_pk_mul_f32 v[96:97], v[96:97], v[138:139] op_sel_hi:[1,0]
	v_cvt_pk_bf16_f32 v165, v106, v108
	v_cvt_pk_bf16_f32 v166, v110, v112
	v_cvt_pk_bf16_f32 v167, v114, v132
	v_pk_mul_f32 v[86:87], v[86:87], v[138:139] op_sel_hi:[1,0]
	v_pk_mul_f32 v[84:85], v[84:85], v[138:139] op_sel_hi:[1,0]
	s_waitcnt lgkmcnt(0)
	v_mfma_f32_16x16x32_bf16 v[96:99], v[92:95], v[164:167], v[96:99]
	ds_read_b128 v[92:95], v107 offset:40960
	v_pk_mul_f32 v[90:91], v[90:91], v[138:139] op_sel_hi:[1,0]
	v_pk_mul_f32 v[88:89], v[88:89], v[138:139] op_sel_hi:[1,0]
	s_waitcnt lgkmcnt(0)
	v_mfma_f32_16x16x32_bf16 v[92:95], v[92:95], v[164:167], v[84:87]
	s_nop 2
	ds_read_b128 v[84:87], v107 offset:49152
	v_pk_mul_f32 v[102:103], v[102:103], v[138:139] op_sel_hi:[1,0]
	v_pk_mul_f32 v[100:101], v[100:101], v[138:139] op_sel_hi:[1,0]
	s_waitcnt lgkmcnt(0)
	v_mfma_f32_16x16x32_bf16 v[88:91], v[84:87], v[164:167], v[88:91]
	ds_read_b128 v[84:87], v107 offset:57344
	v_mul_f32_e32 v134, v134, v138
	s_waitcnt lgkmcnt(0)
	v_mfma_f32_16x16x32_bf16 v[84:87], v[84:87], v[164:167], v[100:103]
	s_nop 2
	ds_read_b128 v[100:103], v154 offset:28672
	ds_read_b128 v[164:167], v153 offset:28672
	s_waitcnt lgkmcnt(0)
	v_mfma_f32_16x16x32_bf16 v[100:103], v[100:103], v[12:15], 0
	v_mfma_f32_16x16x32_bf16 v[100:103], v[164:167], v[16:19], v[100:103]
	ds_read_b128 v[152:155], v152 offset:29184
	ds_read_b128 v[164:167], v151 offset:29184
	s_waitcnt lgkmcnt(0)
	v_mfma_f32_16x16x32_bf16 v[152:155], v[152:155], v[12:15], 0
	s_nop 3
	v_max_f32_e32 v107, v101, v101
	v_max_f32_e32 v109, v100, v100
	v_max_f32_e32 v107, v109, v107
	v_mfma_f32_16x16x32_bf16 v[152:155], v[164:167], v[16:19], v[152:155]
	v_max_f32_e32 v109, v103, v103
	v_max_f32_e32 v111, v102, v102
	v_max_f32_e32 v109, v111, v109
	s_nop 4
	v_max_f32_e32 v111, v155, v155
	v_max_f32_e32 v113, v154, v154
	v_max_f32_e32 v111, v113, v111
	v_max3_f32 v111, v152, v153, v111
	v_max3_f32 v107, v107, v109, v111
	ds_bpermute_b32 v109, v150, v107
	s_waitcnt lgkmcnt(0)
	v_max_f32_e32 v109, v109, v109
	v_max_f32_e32 v107, v107, v109
	ds_bpermute_b32 v109, v149, v107
	s_waitcnt lgkmcnt(0)
	v_max3_f32 v138, v104, v107, v109
	v_sub_f32_e32 v100, v100, v138
	v_exp_f32_e32 v107, v100
	v_sub_f32_e32 v100, v101, v138
	v_exp_f32_e32 v109, v100
	v_sub_f32_e32 v100, v102, v138
	v_exp_f32_e32 v111, v100
	v_sub_f32_e32 v100, v103, v138
	v_exp_f32_e32 v113, v100
	v_sub_f32_e32 v100, v152, v138
	v_exp_f32_e32 v115, v100
	v_sub_f32_e32 v100, v153, v138
	v_exp_f32_e32 v133, v100
	v_sub_f32_e32 v100, v154, v138
	v_exp_f32_e32 v135, v100
	v_sub_f32_e32 v100, v155, v138
	v_exp_f32_e32 v141, v100
	v_pk_add_f32 v[100:101], v[106:107], v[0:1]
	v_sub_f32_e32 v104, v104, v138
	v_pk_add_f32 v[100:101], v[108:109], v[100:101]
	v_exp_f32_e32 v140, v104
	v_pk_add_f32 v[100:101], v[110:111], v[100:101]
	v_cvt_pk_bf16_f32 v102, v115, v133
	v_cvt_pk_bf16_f32 v103, v135, v141
	v_pk_mul_f32 v[98:99], v[98:99], v[140:141] op_sel_hi:[1,0]
	v_pk_add_f32 v[100:101], v[112:113], v[100:101]
	v_pk_mul_f32 v[96:97], v[96:97], v[140:141] op_sel_hi:[1,0]
	v_pk_add_f32 v[100:101], v[114:115], v[100:101]
	v_pk_mul_f32 v[94:95], v[94:95], v[140:141] op_sel_hi:[1,0]
	v_pk_add_f32 v[100:101], v[132:133], v[100:101]
	v_pk_mul_f32 v[92:93], v[92:93], v[140:141] op_sel_hi:[1,0]
	v_pk_add_f32 v[100:101], v[134:135], v[100:101]
	v_pk_mul_f32 v[90:91], v[90:91], v[140:141] op_sel_hi:[1,0]
	v_add_f32_e32 v0, v101, v141
	v_pk_fma_f32 v[148:149], v[100:101], v[140:141], v[0:1] op_sel_hi:[1,1,0]
	v_bitop3_b32 v0, v157, v142, 28 bitop3:0x36
	v_lshl_add_u32 v0, v0, 4, v143
	v_cvt_pk_bf16_f32 v100, v107, v109
	ds_read_b128 v[106:109], v0 offset:32768
	v_cvt_pk_bf16_f32 v101, v111, v113
	v_pk_mul_f32 v[88:89], v[88:89], v[140:141] op_sel_hi:[1,0]
	s_waitcnt lgkmcnt(0)
	v_mfma_f32_16x16x32_bf16 v[96:99], v[106:109], v[100:103], v[96:99]
	ds_read_b128 v[106:109], v0 offset:40960
	v_pk_mul_f32 v[86:87], v[86:87], v[140:141] op_sel_hi:[1,0]
	v_pk_mul_f32 v[84:85], v[84:85], v[140:141] op_sel_hi:[1,0]
	s_waitcnt lgkmcnt(0)
	v_mfma_f32_16x16x32_bf16 v[92:95], v[106:109], v[100:103], v[92:95]
	ds_read_b128 v[106:109], v0 offset:49152
	v_mov_b32_e32 v149, v105
	v_mov_b64_e32 v[104:105], v[148:149]
	s_waitcnt lgkmcnt(0)
	v_mfma_f32_16x16x32_bf16 v[88:91], v[106:109], v[100:103], v[88:91]
	ds_read_b128 v[106:109], v0 offset:57344
	s_waitcnt lgkmcnt(0)
	v_mfma_f32_16x16x32_bf16 v[84:87], v[106:109], v[100:103], v[84:87]
	s_setprio 0
	s_branch .LBB0_517

.LBB0_339:
	v_add_u32_e32 v58, s2, v56
	v_add_u32_e32 v62, s2, v55
	v_add_u32_e32 v66, s2, v54
	v_add_u32_e32 v67, s2, v53
	ds_read_b128 v[58:61], v58
	ds_read_b128 v[62:65], v62
	ds_read_b128 v[88:91], v66
	ds_read_b128 v[92:95], v67
	s_waitcnt lgkmcnt(0)
	s_setprio 3
	v_mfma_f32_16x16x32_bf16 v[84:87], v[58:61], v[4:7], 0
	v_xor_b32_e32 v66, v57, v142
	v_lshl_add_u32 v66, v66, 4, v143
	ds_read_b128 v[100:103], v66 offset:32768
	v_mfma_f32_16x16x32_bf16 v[96:99], v[88:91], v[4:7], 0
	s_addk_i32 s2, 0x1000
	v_add_u32_e32 v57, 4, v57
	s_cmpk_eq_u32 s2, 0x8000
	v_mfma_f32_16x16x32_bf16 v[88:91], v[88:91], v[12:15], 0
	v_mfma_f32_16x16x32_bf16 v[58:61], v[58:61], v[12:15], 0
	v_mfma_f32_16x16x32_bf16 v[84:87], v[62:65], v[8:11], v[84:87]
	v_mfma_f32_16x16x32_bf16 v[96:99], v[92:95], v[8:11], v[96:99]
	v_mfma_f32_16x16x32_bf16 v[88:91], v[92:95], v[16:19], v[88:91]
	s_nop 5
	v_max_f32_e32 v67, v84, v84
	v_max_f32_e32 v92, v87, v87
	v_max_f32_e32 v93, v86, v86
	v_mfma_f32_16x16x32_bf16 v[58:61], v[62:65], v[16:19], v[58:61]
	ds_read_b128 v[62:65], v66 offset:40960
	ds_read_b128 v[104:107], v66 offset:49152
	ds_read_b128 v[108:111], v66 offset:57344
	v_max_f32_e32 v66, v85, v85
	v_max_f32_e32 v94, v99, v99
	v_max_f32_e32 v95, v98, v98
	v_max_f32_e32 v132, v91, v91
	v_max_f32_e32 v133, v90, v90
	v_max_f32_e32 v66, v67, v66
	v_max_f32_e32 v67, v93, v92
	v_max_f32_e32 v92, v95, v94
	v_max_f32_e32 v112, v59, v59
	v_max_f32_e32 v113, v58, v58
	v_max_f32_e32 v114, v61, v61
	v_max_f32_e32 v115, v60, v60
	v_max_f32_e32 v95, v133, v132
	v_max3_f32 v92, v96, v97, v92
	v_max_f32_e32 v93, v113, v112
	v_max_f32_e32 v94, v115, v114
	v_max3_f32 v95, v88, v89, v95
	v_max3_f32 v66, v66, v67, v92
	v_max3_f32 v67, v93, v94, v95
	ds_bpermute_b32 v92, v0, v66
	ds_bpermute_b32 v93, v0, v67
	s_waitcnt lgkmcnt(0)
	v_max_f32_e32 v92, v92, v92
	v_max_f32_e32 v93, v93, v93
	v_max_f32_e32 v66, v66, v92
	v_max_f32_e32 v67, v67, v93
	ds_bpermute_b32 v92, v52, v66
	ds_bpermute_b32 v93, v52, v67
	s_waitcnt lgkmcnt(0)
	v_max3_f32 v66, v161, v66, v92
	v_max3_f32 v67, v160, v67, v93
	v_sub_f32_e32 v92, v161, v66
	v_sub_f32_e32 v84, v84, v66
	v_sub_f32_e32 v114, v160, v67
	v_sub_f32_e32 v58, v58, v67
	v_sub_f32_e32 v59, v59, v67
	v_sub_f32_e32 v60, v60, v67
	v_sub_f32_e32 v61, v61, v67
	v_sub_f32_e32 v115, v88, v67
	v_sub_f32_e32 v132, v89, v67
	v_sub_f32_e32 v133, v90, v67
	v_sub_f32_e32 v134, v91, v67
	v_mov_b32_e32 v160, v67
	v_exp_f32_e32 v67, v84
	v_exp_f32_e32 v84, v92
	v_sub_f32_e32 v85, v85, v66
	v_sub_f32_e32 v86, v86, v66
	v_sub_f32_e32 v87, v87, v66
	v_sub_f32_e32 v94, v96, v66
	v_sub_f32_e32 v96, v97, v66
	v_sub_f32_e32 v98, v98, v66
	v_sub_f32_e32 v112, v99, v66
	v_mov_b32_e32 v161, v66
	v_exp_f32_e32 v66, v58
	v_exp_f32_e32 v89, v85
	v_exp_f32_e32 v88, v59
	v_exp_f32_e32 v91, v86
	v_exp_f32_e32 v90, v60
	v_exp_f32_e32 v93, v87
	v_exp_f32_e32 v92, v61
	v_cvt_pk_bf16_f32 v58, v67, v89
	v_cvt_pk_bf16_f32 v59, v91, v93
	v_pk_mul_f32 v[22:23], v[22:23], v[84:85] op_sel_hi:[1,0]
	v_pk_mul_f32 v[20:21], v[20:21], v[84:85] op_sel_hi:[1,0]
	v_pk_mul_f32 v[26:27], v[26:27], v[84:85] op_sel_hi:[1,0]
	v_pk_mul_f32 v[24:25], v[24:25], v[84:85] op_sel_hi:[1,0]
	v_pk_mul_f32 v[34:35], v[34:35], v[84:85] op_sel_hi:[1,0]
	v_pk_mul_f32 v[32:33], v[32:33], v[84:85] op_sel_hi:[1,0]
	v_pk_mul_f32 v[46:47], v[46:47], v[84:85] op_sel_hi:[1,0]
	v_pk_mul_f32 v[44:45], v[44:45], v[84:85] op_sel_hi:[1,0]
	v_exp_f32_e32 v95, v94
	v_exp_f32_e32 v97, v96
	v_exp_f32_e32 v99, v98
	v_exp_f32_e32 v113, v112
	v_exp_f32_e32 v94, v115
	v_exp_f32_e32 v114, v114
	v_cvt_pk_bf16_f32 v60, v95, v97
	v_cvt_pk_bf16_f32 v61, v99, v113
	v_exp_f32_e32 v96, v132
	v_mfma_f32_16x16x32_bf16 v[20:23], v[100:103], v[58:61], v[20:23]
	v_exp_f32_e32 v98, v133
	v_exp_f32_e32 v112, v134
	v_mov_b32_e32 v115, v84
	v_mfma_f32_16x16x32_bf16 v[24:27], v[62:65], v[58:61], v[24:27]
	v_mul_f32_e64 v30, v30, v114
	v_mul_f32_e64 v31, v31, v114
	v_pk_mul_f32 v[28:29], v[28:29], v[114:115] op_sel_hi:[1,0]
	v_pk_mul_f32 v[38:39], v[38:39], v[114:115] op_sel_hi:[1,0]
	v_mfma_f32_16x16x32_bf16 v[32:35], v[104:107], v[58:61], v[32:35]
	v_mul_f32_e64 v36, v36, v114
	v_mul_f32_e64 v37, v37, v114
	v_pk_mul_f32 v[42:43], v[42:43], v[114:115] op_sel_hi:[1,0]
	v_pk_mul_f32 v[40:41], v[40:41], v[114:115] op_sel_hi:[1,0]
	v_mfma_f32_16x16x32_bf16 v[44:47], v[108:111], v[58:61], v[44:47]
	v_add_f32_e64 v58, v66, 0
	v_add_f32_e64 v59, v67, 0
	v_pk_mul_f32 v[50:51], v[50:51], v[114:115] op_sel_hi:[1,0]
	v_pk_add_f32 v[58:59], v[88:89], v[58:59]
	v_pk_mul_f32 v[48:49], v[48:49], v[114:115] op_sel_hi:[1,0]
	v_pk_add_f32 v[58:59], v[90:91], v[58:59]
	v_cvt_pk_bf16_f32 v84, v66, v88
	v_cvt_pk_bf16_f32 v85, v90, v92
	v_cvt_pk_bf16_f32 v86, v94, v96
	v_cvt_pk_bf16_f32 v87, v98, v112
	s_nop 0
	v_pk_add_f32 v[58:59], v[92:93], v[58:59]
	v_mfma_f32_16x16x32_bf16 v[28:31], v[100:103], v[84:87], v[28:31]
	v_add_f32_e64 v58, v94, v58
	v_add_f32_e64 v59, v95, v59
	v_pk_add_f32 v[58:59], v[96:97], v[58:59]
	v_mfma_f32_16x16x32_bf16 v[36:39], v[62:65], v[84:87], v[36:39]
	v_add_f32_e64 v58, v98, v58
	v_add_f32_e64 v59, v99, v59
	v_pk_add_f32 v[58:59], v[112:113], v[58:59]
	v_mfma_f32_16x16x32_bf16 v[40:43], v[104:107], v[84:87], v[40:43]
	v_fma_f32 v136, v136, v114, v58
	v_fma_f32 v137, v137, v115, v59
	v_mfma_f32_16x16x32_bf16 v[48:51], v[108:111], v[84:87], v[48:51]
	s_setprio 0
	s_cbranch_scc0 .LBB0_339
	s_nop 6
	v_mov_b64_e32 v[86:87], v[50:51]
	v_mov_b64_e32 v[90:91], v[42:43]
	v_mov_b64_e32 v[94:95], v[38:39]
	v_mov_b64_e32 v[98:99], v[30:31]
	v_mov_b64_e32 v[66:67], v[46:47]
	v_mov_b64_e32 v[62:63], v[34:35]
	v_mov_b64_e32 v[58:59], v[26:27]
	v_mov_b64_e32 v[54:55], v[22:23]
	v_mov_b64_e32 v[104:105], v[136:137]
	v_mov_b64_e32 v[84:85], v[48:49]
	v_mov_b64_e32 v[88:89], v[40:41]
	v_mov_b64_e32 v[92:93], v[36:37]
	v_mov_b64_e32 v[96:97], v[28:29]
	v_mov_b64_e32 v[64:65], v[44:45]
	v_mov_b64_e32 v[60:61], v[32:33]
	v_mov_b64_e32 v[56:57], v[24:25]
	v_mov_b64_e32 v[52:53], v[20:21]
	v_lshlrev_b32_e32 v0, 2, v157
	s_and_b64 vcc, exec, s[38:39]
	v_lshlrev_b32_e32 v0, 1, v0
	s_cbranch_vccz .LBB0_518

.LBB0_347:
	v_ashrrev_i32_e32 v7, 1, v4
	v_mul_hi_i32 v8, v7, s16
	v_lshrrev_b32_e32 v9, 31, v8
	v_add_u32_e32 v9, v8, v9
	v_mul_lo_u32 v8, v9, 6
	v_sub_u32_e32 v8, v7, v8
	v_mul_lo_u32 v10, v8, s18
	v_ashrrev_i32_e32 v11, 31, v10
	v_lshlrev_b32_e32 v12, 7, v9
	v_lshl_or_b32 v7, v9, 1, v6
	v_ashrrev_i32_e32 v9, 31, v8
	v_mov_b32_e32 v0, v202
	v_ashrrev_i32_e32 v13, 31, v12
	v_lshlrev_b64 v[10:11], 1, v[10:11]
	v_mad_i64_i32 v[8:9], s[2:3], v7, 6, v[8:9]
	v_lshl_add_u64 v[14:15], v[2:3], 0, v[10:11]
	v_lshlrev_b64 v[12:13], 1, v[12:13]
	v_lshlrev_b64 v[172:173], 14, v[8:9]
	v_bfe_u32 v174, v0, 4, 2
	v_lshl_add_u64 v[8:9], s[12:13], 0, v[10:11]
	v_lshl_add_u64 v[14:15], v[14:15], 0, v[12:13]
	v_and_b32_e32 v7, 15, v0
	v_lshl_add_u64 v[8:9], v[8:9], 0, v[12:13]
	v_lshlrev_b32_e32 v0, 4, v174
	v_lshl_add_u64 v[8:9], v[8:9], 0, v[0:1]
	v_lshl_add_u64 v[10:11], v[14:15], 0, v[0:1]
	v_mul_u32_u24_e32 v0, 0x4100, v7
	v_lshlrev_b32_e32 v0, 1, v0
	v_lshl_add_u64 v[104:105], v[10:11], 0, v[0:1]
	v_lshl_add_u64 v[108:109], v[8:9], 0, v[0:1]
	v_add_co_u32_e32 v8, vcc, s17, v104
	v_lshl_add_u64 v[132:133], v[108:109], 0, s[22:23]
	s_nop 0
	v_addc_co_u32_e32 v9, vcc, 0, v105, vcc
	v_add_co_u32_e32 v12, vcc, s17, v108
	v_lshl_add_u64 v[128:129], v[104:105], 0, s[22:23]
	s_nop 0
	v_addc_co_u32_e32 v13, vcc, 0, v109, vcc
	v_add_co_u32_e32 v16, vcc, s18, v104
	v_lshl_add_u64 v[124:125], v[108:109], 0, s[34:35]
	s_nop 0
	v_addc_co_u32_e32 v17, vcc, 0, v105, vcc
	v_add_co_u32_e32 v20, vcc, s18, v108
	v_lshl_add_u64 v[120:121], v[104:105], 0, s[34:35]
	s_nop 0
	v_addc_co_u32_e32 v21, vcc, 0, v109, vcc
	v_add_co_u32_e32 v24, vcc, s19, v104
	v_lshl_add_u64 v[116:117], v[108:109], 0, s[38:39]
	s_nop 0
	v_addc_co_u32_e32 v25, vcc, 0, v105, vcc
	v_add_co_u32_e32 v28, vcc, s19, v108
	v_lshl_add_u64 v[112:113], v[104:105], 0, s[38:39]
	s_nop 0
	v_addc_co_u32_e32 v29, vcc, 0, v109, vcc
	global_load_dwordx4 v[8:11], v[8:9], off
	v_or_b32_e32 v175, 16, v7
	global_load_dwordx4 v[12:15], v[12:13], off
	v_or_b32_e32 v176, 32, v7
	global_load_dwordx4 v[16:19], v[16:17], off
	v_or_b32_e32 v177, 48, v7
	global_load_dwordx4 v[20:23], v[20:21], off
	v_add_u32_e32 v4, v4, v5
	global_load_dwordx4 v[24:27], v[24:25], off
	s_nop 0
	global_load_dwordx4 v[28:31], v[28:29], off
	s_nop 0
	global_load_dwordx4 v[32:35], v[104:105], off
	global_load_dwordx4 v[36:39], v[108:109], off
	global_load_dwordx4 v[40:43], v[104:105], off offset:64
	global_load_dwordx4 v[44:47], v[108:109], off offset:64
	global_load_dwordx4 v[48:51], v[112:113], off offset:64
	global_load_dwordx4 v[52:55], v[116:117], off offset:64
	global_load_dwordx4 v[56:59], v[120:121], off offset:64
	global_load_dwordx4 v[60:63], v[124:125], off offset:64
	global_load_dwordx4 v[64:67], v[128:129], off offset:64
	global_load_dwordx4 v[68:71], v[132:133], off offset:64
	global_load_dwordx4 v[72:75], v[104:105], off offset:128
	global_load_dwordx4 v[76:79], v[108:109], off offset:128
	global_load_dwordx4 v[80:83], v[112:113], off offset:128
	global_load_dwordx4 v[84:87], v[116:117], off offset:128
	global_load_dwordx4 v[88:91], v[120:121], off offset:128
	global_load_dwordx4 v[92:95], v[124:125], off offset:128
	global_load_dwordx4 v[96:99], v[128:129], off offset:128
	global_load_dwordx4 v[100:103], v[132:133], off offset:128
	s_nop 0
	global_load_dwordx4 v[104:107], v[104:105], off offset:192
	s_nop 0
	global_load_dwordx4 v[108:111], v[108:109], off offset:192
	s_nop 0
	global_load_dwordx4 v[112:115], v[112:113], off offset:192
	s_nop 0
	global_load_dwordx4 v[116:119], v[116:117], off offset:192
	s_nop 0
	global_load_dwordx4 v[120:123], v[120:121], off offset:192
	s_nop 0
	global_load_dwordx4 v[124:127], v[124:125], off offset:192
	s_nop 0
	global_load_dwordx4 v[128:131], v[128:129], off offset:192
	s_nop 0
	global_load_dwordx4 v[132:135], v[132:133], off offset:192
	s_movk_i32 s2, 0x617
	v_cmp_lt_i32_e32 vcc, s2, v4
	s_or_b64 s[14:15], vcc, s[14:15]
	s_waitcnt vmcnt(24)
	s_nop 0
	s_setprio 3
	v_mfma_f32_16x16x32_bf16 v[136:139], v[36:39], v[32:35], 0
	s_waitcnt vmcnt(16)
	v_mfma_f32_16x16x32_bf16 v[140:143], v[36:39], v[24:27], 0
	s_waitcnt vmcnt(8)
	v_mfma_f32_16x16x32_bf16 v[144:147], v[36:39], v[16:19], 0
	s_waitcnt vmcnt(0)
	v_mfma_f32_16x16x32_bf16 v[36:39], v[36:39], v[8:11], 0
	v_mfma_f32_16x16x32_bf16 v[148:151], v[28:31], v[32:35], 0
	v_mfma_f32_16x16x32_bf16 v[152:155], v[28:31], v[24:27], 0
	v_mfma_f32_16x16x32_bf16 v[156:159], v[28:31], v[16:19], 0
	v_mfma_f32_16x16x32_bf16 v[28:31], v[28:31], v[8:11], 0
	v_mfma_f32_16x16x32_bf16 v[160:163], v[20:23], v[32:35], 0
	v_mfma_f32_16x16x32_bf16 v[164:167], v[20:23], v[24:27], 0
	v_mfma_f32_16x16x32_bf16 v[168:171], v[20:23], v[16:19], 0
	v_mfma_f32_16x16x32_bf16 v[20:23], v[20:23], v[8:11], 0
	v_mfma_f32_16x16x32_bf16 v[32:35], v[12:15], v[32:35], 0
	v_mfma_f32_16x16x32_bf16 v[24:27], v[12:15], v[24:27], 0
	v_mfma_f32_16x16x32_bf16 v[16:19], v[12:15], v[16:19], 0
	v_mfma_f32_16x16x32_bf16 v[8:11], v[12:15], v[8:11], 0
	v_mfma_f32_16x16x32_bf16 v[12:15], v[44:47], v[40:43], v[136:139]
	v_mfma_f32_16x16x32_bf16 v[136:139], v[44:47], v[64:67], v[140:143]
	v_mfma_f32_16x16x32_bf16 v[140:143], v[44:47], v[56:59], v[144:147]
	v_mfma_f32_16x16x32_bf16 v[36:39], v[44:47], v[48:51], v[36:39]
	v_mfma_f32_16x16x32_bf16 v[12:15], v[76:79], v[72:75], v[12:15]
	v_mfma_f32_16x16x32_bf16 v[44:47], v[68:71], v[40:43], v[148:151]
	v_mfma_f32_16x16x32_bf16 v[144:147], v[68:71], v[64:67], v[152:155]
	v_mfma_f32_16x16x32_bf16 v[148:151], v[68:71], v[56:59], v[156:159]
	v_mfma_f32_16x16x32_bf16 v[28:31], v[68:71], v[48:51], v[28:31]
	v_mfma_f32_16x16x32_bf16 v[68:71], v[60:63], v[40:43], v[160:163]
	v_mfma_f32_16x16x32_bf16 v[32:35], v[52:55], v[40:43], v[32:35]
	v_mfma_f32_16x16x32_bf16 v[40:43], v[76:79], v[96:99], v[136:139]
	v_mfma_f32_16x16x32_bf16 v[20:23], v[60:63], v[48:51], v[20:23]
	v_mfma_f32_16x16x32_bf16 v[8:11], v[52:55], v[48:51], v[8:11]
	v_mfma_f32_16x16x32_bf16 v[48:51], v[76:79], v[88:91], v[140:143]
	v_mfma_f32_16x16x32_bf16 v[36:39], v[76:79], v[80:83], v[36:39]
	v_lshlrev_b32_e32 v76, 8, v174
	v_or_b32_e32 v0, v76, v7
	v_lshlrev_b32_e32 v0, 2, v0
	v_mfma_f32_16x16x32_bf16 v[12:15], v[108:111], v[104:107], v[12:15]
	v_mfma_f32_16x16x32_bf16 v[152:155], v[60:63], v[64:67], v[164:167]
	v_mfma_f32_16x16x32_bf16 v[156:159], v[60:63], v[56:59], v[168:171]
	v_mfma_f32_16x16x32_bf16 v[44:47], v[100:103], v[72:75], v[44:47]
	v_mfma_f32_16x16x32_bf16 v[60:63], v[92:95], v[72:75], v[68:71]
	v_mfma_f32_16x16x32_bf16 v[32:35], v[84:87], v[72:75], v[32:35]
	v_lshl_add_u64 v[72:73], s[94:95], 0, v[172:173]
	v_lshl_add_u64 v[74:75], v[72:73], 0, v[0:1]
	v_or_b32_e32 v0, v76, v175
	v_mfma_f32_16x16x32_bf16 v[40:43], v[108:111], v[128:131], v[40:43]
	v_lshlrev_b32_e32 v0, 2, v0
	global_store_dword v[74:75], v12, off
	global_store_dword v[74:75], v13, off offset:256
	global_store_dword v[74:75], v14, off offset:512
	global_store_dword v[74:75], v15, off offset:768
	s_nop 2
	global_store_dword v[74:75], v40, off offset:64
	v_lshl_add_u64 v[12:13], v[72:73], 0, v[0:1]
	v_mfma_f32_16x16x32_bf16 v[48:51], v[108:111], v[120:123], v[48:51]
	v_or_b32_e32 v0, v76, v176
	v_lshlrev_b32_e32 v0, 2, v0
	global_store_dword v[12:13], v41, off offset:256
	global_store_dword v[12:13], v42, off offset:512
	global_store_dword v[12:13], v43, off offset:768
	s_nop 2
	global_store_dword v[74:75], v48, off offset:128
	v_mfma_f32_16x16x32_bf16 v[36:39], v[108:111], v[112:115], v[36:39]
	v_lshl_add_u64 v[12:13], v[72:73], 0, v[0:1]
	v_or_b32_e32 v0, v76, v177
	v_lshlrev_b32_e32 v0, 2, v0
	v_or_b32_e32 v14, 0x400, v76
	v_mfma_f32_16x16x32_bf16 v[44:47], v[132:135], v[104:107], v[44:47]
	global_store_dword v[12:13], v49, off offset:256
	global_store_dword v[12:13], v50, off offset:512
	global_store_dword v[12:13], v51, off offset:768
	global_store_dword v[74:75], v36, off offset:192
	v_lshl_add_u64 v[12:13], v[72:73], 0, v[0:1]
	v_or_b32_e32 v0, v14, v7
	v_lshlrev_b32_e32 v0, 2, v0
	v_or_b32_e32 v15, 0x440, v76
	global_store_dword v[12:13], v37, off offset:256
	global_store_dword v[12:13], v38, off offset:512
	global_store_dword v[12:13], v39, off offset:768
	v_lshl_add_u64 v[12:13], v[72:73], 0, v[0:1]
	v_or_b32_e32 v0, v15, v7
	v_lshlrev_b32_e32 v0, 2, v0
	v_or_b32_e32 v36, 0x480, v76
	v_mfma_f32_16x16x32_bf16 v[24:27], v[52:55], v[64:67], v[24:27]
	global_store_dword v[12:13], v44, off
	v_lshl_add_u64 v[12:13], v[72:73], 0, v[0:1]
	v_or_b32_e32 v0, v36, v7
	v_mfma_f32_16x16x32_bf16 v[16:19], v[52:55], v[56:59], v[16:19]
	v_lshlrev_b32_e32 v0, 2, v0
	v_or_b32_e32 v37, 0x4c0, v76
	global_store_dword v[12:13], v45, off
	v_mfma_f32_16x16x32_bf16 v[52:55], v[100:103], v[96:99], v[144:147]
	v_lshl_add_u64 v[12:13], v[72:73], 0, v[0:1]
	v_or_b32_e32 v0, v37, v7
	v_lshlrev_b32_e32 v0, 2, v0
	v_mfma_f32_16x16x32_bf16 v[52:55], v[132:135], v[128:131], v[52:55]
	global_store_dword v[12:13], v46, off
	v_lshl_add_u64 v[12:13], v[72:73], 0, v[0:1]
	v_or_b32_e32 v0, v14, v175
	v_lshlrev_b32_e32 v0, 2, v0
	global_store_dword v[12:13], v47, off
	v_lshl_add_u64 v[12:13], v[72:73], 0, v[0:1]
	v_or_b32_e32 v0, v15, v175
	v_lshlrev_b32_e32 v0, 2, v0
	v_mfma_f32_16x16x32_bf16 v[56:59], v[100:103], v[88:91], v[148:151]
	global_store_dword v[12:13], v52, off
	v_lshl_add_u64 v[12:13], v[72:73], 0, v[0:1]
	v_or_b32_e32 v0, v36, v175
	v_lshlrev_b32_e32 v0, 2, v0
	global_store_dword v[12:13], v53, off
	v_lshl_add_u64 v[12:13], v[72:73], 0, v[0:1]
	v_or_b32_e32 v0, v37, v175
	v_lshlrev_b32_e32 v0, 2, v0
	v_mfma_f32_16x16x32_bf16 v[56:59], v[132:135], v[120:123], v[56:59]
	global_store_dword v[12:13], v54, off
	v_lshl_add_u64 v[12:13], v[72:73], 0, v[0:1]
	v_or_b32_e32 v0, v14, v176
	v_lshlrev_b32_e32 v0, 2, v0
	global_store_dword v[12:13], v55, off
	v_lshl_add_u64 v[12:13], v[72:73], 0, v[0:1]
	v_or_b32_e32 v0, v15, v176
	v_lshlrev_b32_e32 v0, 2, v0
	v_mfma_f32_16x16x32_bf16 v[28:31], v[100:103], v[80:83], v[28:31]
	global_store_dword v[12:13], v56, off
	v_lshl_add_u64 v[12:13], v[72:73], 0, v[0:1]
	v_or_b32_e32 v0, v36, v176
	v_lshlrev_b32_e32 v0, 2, v0
	global_store_dword v[12:13], v57, off
	v_lshl_add_u64 v[12:13], v[72:73], 0, v[0:1]
	v_or_b32_e32 v0, v37, v176
	v_lshlrev_b32_e32 v0, 2, v0
	v_mfma_f32_16x16x32_bf16 v[28:31], v[132:135], v[112:115], v[28:31]
	global_store_dword v[12:13], v58, off
	v_lshl_add_u64 v[12:13], v[72:73], 0, v[0:1]
	v_or_b32_e32 v0, v14, v177
	v_lshlrev_b32_e32 v0, 2, v0
	global_store_dword v[12:13], v59, off
	v_lshl_add_u64 v[12:13], v[72:73], 0, v[0:1]
	v_or_b32_e32 v0, v15, v177
	v_lshlrev_b32_e32 v0, 2, v0
	global_store_dword v[12:13], v28, off
	v_lshl_add_u64 v[12:13], v[72:73], 0, v[0:1]
	v_or_b32_e32 v0, v36, v177
	v_lshlrev_b32_e32 v0, 2, v0
	global_store_dword v[12:13], v29, off
	v_lshl_add_u64 v[12:13], v[72:73], 0, v[0:1]
	v_or_b32_e32 v0, v37, v177
	v_lshlrev_b32_e32 v0, 2, v0
	v_or_b32_e32 v14, 0x800, v76
	v_mfma_f32_16x16x32_bf16 v[60:63], v[124:127], v[104:107], v[60:63]
	global_store_dword v[12:13], v30, off
	v_lshl_add_u64 v[12:13], v[72:73], 0, v[0:1]
	v_or_b32_e32 v0, v14, v7
	v_lshlrev_b32_e32 v0, 2, v0
	v_or_b32_e32 v15, 0x840, v76
	global_store_dword v[12:13], v31, off
	v_lshl_add_u64 v[12:13], v[72:73], 0, v[0:1]
	v_or_b32_e32 v0, v15, v7
	v_lshlrev_b32_e32 v0, 2, v0
	v_or_b32_e32 v28, 0x880, v76
	v_mfma_f32_16x16x32_bf16 v[64:67], v[92:95], v[96:99], v[152:155]
	global_store_dword v[12:13], v60, off
	v_lshl_add_u64 v[12:13], v[72:73], 0, v[0:1]
	v_or_b32_e32 v0, v28, v7
	v_lshlrev_b32_e32 v0, 2, v0
	v_or_b32_e32 v29, 0x8c0, v76
	global_store_dword v[12:13], v61, off
	v_lshl_add_u64 v[12:13], v[72:73], 0, v[0:1]
	v_or_b32_e32 v0, v29, v7
	v_lshlrev_b32_e32 v0, 2, v0
	v_mfma_f32_16x16x32_bf16 v[64:67], v[124:127], v[128:131], v[64:67]
	global_store_dword v[12:13], v62, off
	v_lshl_add_u64 v[12:13], v[72:73], 0, v[0:1]
	v_or_b32_e32 v0, v14, v175
	v_lshlrev_b32_e32 v0, 2, v0
	global_store_dword v[12:13], v63, off
	v_lshl_add_u64 v[12:13], v[72:73], 0, v[0:1]
	v_or_b32_e32 v0, v15, v175
	v_lshlrev_b32_e32 v0, 2, v0
	v_mfma_f32_16x16x32_bf16 v[68:71], v[92:95], v[88:91], v[156:159]
	global_store_dword v[12:13], v64, off
	v_lshl_add_u64 v[12:13], v[72:73], 0, v[0:1]
	v_or_b32_e32 v0, v28, v175
	v_lshlrev_b32_e32 v0, 2, v0
	global_store_dword v[12:13], v65, off
	v_lshl_add_u64 v[12:13], v[72:73], 0, v[0:1]
	v_or_b32_e32 v0, v29, v175
	v_lshlrev_b32_e32 v0, 2, v0
	v_mfma_f32_16x16x32_bf16 v[68:71], v[124:127], v[120:123], v[68:71]
	global_store_dword v[12:13], v66, off
	v_lshl_add_u64 v[12:13], v[72:73], 0, v[0:1]
	v_or_b32_e32 v0, v14, v176
	v_lshlrev_b32_e32 v0, 2, v0
	global_store_dword v[12:13], v67, off
	v_lshl_add_u64 v[12:13], v[72:73], 0, v[0:1]
	v_or_b32_e32 v0, v15, v176
	v_lshlrev_b32_e32 v0, 2, v0
	v_mfma_f32_16x16x32_bf16 v[20:23], v[92:95], v[80:83], v[20:23]
	global_store_dword v[12:13], v68, off
	v_lshl_add_u64 v[12:13], v[72:73], 0, v[0:1]
	v_or_b32_e32 v0, v28, v176
	v_lshlrev_b32_e32 v0, 2, v0
	global_store_dword v[12:13], v69, off
	v_lshl_add_u64 v[12:13], v[72:73], 0, v[0:1]
	v_or_b32_e32 v0, v29, v176
	v_lshlrev_b32_e32 v0, 2, v0
	v_mfma_f32_16x16x32_bf16 v[20:23], v[124:127], v[112:115], v[20:23]
	global_store_dword v[12:13], v70, off
	v_lshl_add_u64 v[12:13], v[72:73], 0, v[0:1]
	v_or_b32_e32 v0, v14, v177
	v_lshlrev_b32_e32 v0, 2, v0
	global_store_dword v[12:13], v71, off
	v_lshl_add_u64 v[12:13], v[72:73], 0, v[0:1]
	v_or_b32_e32 v0, v15, v177
	v_lshlrev_b32_e32 v0, 2, v0
	global_store_dword v[12:13], v20, off
	v_lshl_add_u64 v[12:13], v[72:73], 0, v[0:1]
	v_or_b32_e32 v0, v28, v177
	v_lshlrev_b32_e32 v0, 2, v0
	global_store_dword v[12:13], v21, off
	v_lshl_add_u64 v[12:13], v[72:73], 0, v[0:1]
	v_or_b32_e32 v0, v29, v177
	v_lshlrev_b32_e32 v0, 2, v0
	v_or_b32_e32 v14, 0xc00, v76
	v_mfma_f32_16x16x32_bf16 v[32:35], v[116:119], v[104:107], v[32:35]
	global_store_dword v[12:13], v22, off
	v_lshl_add_u64 v[12:13], v[72:73], 0, v[0:1]
	v_or_b32_e32 v0, v14, v7
	v_lshlrev_b32_e32 v0, 2, v0
	v_or_b32_e32 v15, 0xc40, v76
	global_store_dword v[12:13], v23, off
	v_lshl_add_u64 v[12:13], v[72:73], 0, v[0:1]
	v_or_b32_e32 v0, v15, v7
	v_lshlrev_b32_e32 v0, 2, v0
	v_or_b32_e32 v20, 0xc80, v76
	v_mfma_f32_16x16x32_bf16 v[24:27], v[84:87], v[96:99], v[24:27]
	global_store_dword v[12:13], v32, off
	v_lshl_add_u64 v[12:13], v[72:73], 0, v[0:1]
	v_or_b32_e32 v0, v20, v7
	v_lshlrev_b32_e32 v0, 2, v0
	v_or_b32_e32 v21, 0xcc0, v76
	global_store_dword v[12:13], v33, off
	v_lshl_add_u64 v[12:13], v[72:73], 0, v[0:1]
	v_or_b32_e32 v0, v21, v7
	v_lshlrev_b32_e32 v0, 2, v0
	v_mfma_f32_16x16x32_bf16 v[24:27], v[116:119], v[128:131], v[24:27]
	global_store_dword v[12:13], v34, off
	v_lshl_add_u64 v[12:13], v[72:73], 0, v[0:1]
	v_or_b32_e32 v0, v14, v175
	v_lshlrev_b32_e32 v0, 2, v0
	global_store_dword v[12:13], v35, off
	v_lshl_add_u64 v[12:13], v[72:73], 0, v[0:1]
	v_or_b32_e32 v0, v15, v175
	v_lshlrev_b32_e32 v0, 2, v0
	v_mfma_f32_16x16x32_bf16 v[16:19], v[84:87], v[88:91], v[16:19]
	global_store_dword v[12:13], v24, off
	v_lshl_add_u64 v[12:13], v[72:73], 0, v[0:1]
	v_or_b32_e32 v0, v20, v175
	v_lshlrev_b32_e32 v0, 2, v0
	global_store_dword v[12:13], v25, off
	v_lshl_add_u64 v[12:13], v[72:73], 0, v[0:1]
	v_or_b32_e32 v0, v21, v175
	v_lshlrev_b32_e32 v0, 2, v0
	v_mfma_f32_16x16x32_bf16 v[16:19], v[116:119], v[120:123], v[16:19]
	global_store_dword v[12:13], v26, off
	v_lshl_add_u64 v[12:13], v[72:73], 0, v[0:1]
	v_or_b32_e32 v0, v14, v176
	v_lshlrev_b32_e32 v0, 2, v0
	global_store_dword v[12:13], v27, off
	v_lshl_add_u64 v[12:13], v[72:73], 0, v[0:1]
	v_or_b32_e32 v0, v15, v176
	v_lshlrev_b32_e32 v0, 2, v0
	v_mfma_f32_16x16x32_bf16 v[8:11], v[84:87], v[80:83], v[8:11]
	global_store_dword v[12:13], v16, off
	v_lshl_add_u64 v[12:13], v[72:73], 0, v[0:1]
	v_or_b32_e32 v0, v20, v176
	v_lshlrev_b32_e32 v0, 2, v0
	global_store_dword v[12:13], v17, off
	v_lshl_add_u64 v[12:13], v[72:73], 0, v[0:1]
	v_or_b32_e32 v0, v21, v176
	v_lshlrev_b32_e32 v0, 2, v0
	v_mfma_f32_16x16x32_bf16 v[8:11], v[116:119], v[112:115], v[8:11]
	s_setprio 0
	global_store_dword v[12:13], v18, off
	v_lshl_add_u64 v[12:13], v[72:73], 0, v[0:1]
	v_or_b32_e32 v0, v14, v177
	v_lshlrev_b32_e32 v0, 2, v0
	global_store_dword v[12:13], v19, off
	v_lshl_add_u64 v[12:13], v[72:73], 0, v[0:1]
	v_or_b32_e32 v0, v15, v177
	v_lshlrev_b32_e32 v0, 2, v0
	global_store_dword v[12:13], v8, off
	v_lshl_add_u64 v[12:13], v[72:73], 0, v[0:1]
	v_or_b32_e32 v0, v20, v177
	v_lshlrev_b32_e32 v0, 2, v0
	global_store_dword v[12:13], v9, off
	v_lshl_add_u64 v[8:9], v[72:73], 0, v[0:1]
	v_or_b32_e32 v0, v21, v177
	v_lshlrev_b32_e32 v0, 2, v0
	global_store_dword v[8:9], v10, off
	v_lshl_add_u64 v[8:9], v[72:73], 0, v[0:1]
	global_store_dword v[8:9], v11, off
	s_andn2_b64 exec, exec, s[14:15]
	s_cbranch_execnz .LBB0_347

.LBB0_366:
	s_add_u32 s2, s0, 0xfffc0080
	s_addc_u32 s3, s1, -1
	s_add_i32 s12, 0, 0x10000
	v_add_u32_e32 v142, s12, v227
	ds_read_b128 v[130:133], v142
	ds_read_b128 v[134:137], v142 offset:1024
	ds_read_b128 v[138:141], v142 offset:2048
	ds_read_b128 v[142:145], v142 offset:3072
	s_cmp_eq_u32 s47, 12
	s_cselect_b32 s17, s15, s3
	s_cselect_b32 s16, s19, s2
	s_cselect_b32 s3, s43, s46
	s_cselect_b32 s2, s44, s45
	v_lshl_add_u64 v[190:191], s[0:1], 0, v[162:163]
	s_add_i32 m0, s54, 0xc000
	ds_read_b128 v[146:149], v233
	ds_read_b128 v[150:153], v233 offset:1024
	ds_read_b128 v[166:169], v233 offset:2048
	ds_read_b128 v[170:173], v233 offset:3072
	ds_read_b128 v[174:177], v233 offset:4096
	ds_read_b128 v[178:181], v233 offset:5120
	ds_read_b128 v[182:185], v233 offset:6144
	ds_read_b128 v[186:189], v233 offset:7168
	global_load_lds_dwordx4 v[190:191], off
	v_lshl_add_u64 v[190:191], s[0:1], 0, v[164:165]
	s_add_i32 m0, s54, 0xe000
	s_nop 0
	global_load_lds_dwordx4 v[190:191], off
	s_waitcnt lgkmcnt(8)
	s_barrier
	s_waitcnt lgkmcnt(0)
	s_setprio 3
	v_mfma_f32_16x16x32_bf16 v[126:129], v[130:133], v[146:149], v[126:129]
	v_mfma_f32_16x16x32_bf16 v[122:125], v[138:141], v[146:149], v[122:125]
	v_mfma_f32_16x16x32_bf16 v[118:121], v[130:133], v[166:169], v[118:121]
	v_mfma_f32_16x16x32_bf16 v[114:117], v[138:141], v[166:169], v[114:117]
	v_mfma_f32_16x16x32_bf16 v[110:113], v[130:133], v[174:177], v[110:113]
	v_mfma_f32_16x16x32_bf16 v[106:109], v[138:141], v[174:177], v[106:109]
	v_mfma_f32_16x16x32_bf16 v[102:105], v[130:133], v[182:185], v[102:105]
	v_mfma_f32_16x16x32_bf16 v[98:101], v[138:141], v[182:185], v[98:101]
	v_mfma_f32_16x16x32_bf16 v[126:129], v[134:137], v[150:153], v[126:129]
	v_mfma_f32_16x16x32_bf16 v[122:125], v[142:145], v[150:153], v[122:125]
	v_mfma_f32_16x16x32_bf16 v[118:121], v[134:137], v[170:173], v[118:121]
	v_mfma_f32_16x16x32_bf16 v[114:117], v[142:145], v[170:173], v[114:117]
	v_mfma_f32_16x16x32_bf16 v[110:113], v[134:137], v[178:181], v[110:113]
	v_mfma_f32_16x16x32_bf16 v[106:109], v[142:145], v[178:181], v[106:109]
	v_mfma_f32_16x16x32_bf16 v[102:105], v[134:137], v[186:189], v[102:105]
	v_mfma_f32_16x16x32_bf16 v[98:101], v[142:145], v[186:189], v[98:101]
	s_setprio 0
	s_barrier
	s_add_i32 s13, 0, 0x14000
	s_add_i32 s12, s12, s35
	v_add_u32_e32 v234, s13, v227
	v_lshl_add_u64 v[242:243], s[2:3], 0, v[0:1]
	s_mov_b32 m0, s12
	ds_read_b128 v[190:193], v234
	ds_read_b128 v[194:197], v234 offset:1024
	ds_read_b128 v[198:201], v234 offset:2048
	ds_read_b128 v[234:237], v234 offset:3072
	global_load_lds_dwordx4 v[242:243], off
	v_lshl_add_u64 v[244:245], s[2:3], 0, v[154:155]
	s_add_i32 m0, s12, 0x2000
	s_nop 0
	global_load_lds_dwordx4 v[244:245], off
	s_barrier
	s_waitcnt lgkmcnt(0)
	s_setprio 3
	s_nop 0
	v_mfma_f32_16x16x32_bf16 v[62:65], v[190:193], v[146:149], v[62:65]
	v_mfma_f32_16x16x32_bf16 v[58:61], v[198:201], v[146:149], v[58:61]
	v_mfma_f32_16x16x32_bf16 v[54:57], v[190:193], v[166:169], v[54:57]
	v_mfma_f32_16x16x32_bf16 v[50:53], v[198:201], v[166:169], v[50:53]
	v_mfma_f32_16x16x32_bf16 v[46:49], v[190:193], v[174:177], v[46:49]
	v_mfma_f32_16x16x32_bf16 v[42:45], v[198:201], v[174:177], v[42:45]
	v_mfma_f32_16x16x32_bf16 v[38:41], v[190:193], v[182:185], v[38:41]
	v_mfma_f32_16x16x32_bf16 v[34:37], v[198:201], v[182:185], v[34:37]
	v_mfma_f32_16x16x32_bf16 v[62:65], v[194:197], v[150:153], v[62:65]
	v_mfma_f32_16x16x32_bf16 v[58:61], v[234:237], v[150:153], v[58:61]
	v_mfma_f32_16x16x32_bf16 v[54:57], v[194:197], v[170:173], v[54:57]
	v_mfma_f32_16x16x32_bf16 v[50:53], v[234:237], v[170:173], v[50:53]
	s_mov_b32 m0, s54
	v_mfma_f32_16x16x32_bf16 v[46:49], v[194:197], v[178:181], v[46:49]
	v_mfma_f32_16x16x32_bf16 v[42:45], v[234:237], v[178:181], v[42:45]
	v_mfma_f32_16x16x32_bf16 v[38:41], v[194:197], v[186:189], v[38:41]
	v_mfma_f32_16x16x32_bf16 v[34:37], v[234:237], v[186:189], v[34:37]
	s_setprio 0
	s_barrier
	ds_read_b128 v[146:149], v233 offset:16384
	ds_read_b128 v[150:153], v233 offset:17408
	ds_read_b128 v[166:169], v233 offset:18432
	ds_read_b128 v[170:173], v233 offset:19456
	ds_read_b128 v[174:177], v233 offset:20480
	ds_read_b128 v[178:181], v233 offset:21504
	ds_read_b128 v[182:185], v233 offset:22528
	ds_read_b128 v[186:189], v233 offset:23552
	global_load_lds_dwordx4 v250, s[16:17]
	s_nop 0
	s_mov_b32 m0, s55
	s_nop 0
	global_load_lds_dwordx4 v251, s[16:17]
	s_barrier
	s_waitcnt lgkmcnt(0)
	s_setprio 3
	s_nop 0
	v_mfma_f32_16x16x32_bf16 v[94:97], v[130:133], v[146:149], v[94:97]
	v_mfma_f32_16x16x32_bf16 v[90:93], v[138:141], v[146:149], v[90:93]
	v_mfma_f32_16x16x32_bf16 v[86:89], v[130:133], v[166:169], v[86:89]
	v_mfma_f32_16x16x32_bf16 v[82:85], v[138:141], v[166:169], v[82:85]
	v_mfma_f32_16x16x32_bf16 v[78:81], v[130:133], v[174:177], v[78:81]
	v_mfma_f32_16x16x32_bf16 v[74:77], v[138:141], v[174:177], v[74:77]
	v_mfma_f32_16x16x32_bf16 v[70:73], v[130:133], v[182:185], v[70:73]
	v_mfma_f32_16x16x32_bf16 v[66:69], v[138:141], v[182:185], v[66:69]
	v_mfma_f32_16x16x32_bf16 v[94:97], v[134:137], v[150:153], v[94:97]
	v_mfma_f32_16x16x32_bf16 v[90:93], v[142:145], v[150:153], v[90:93]
	v_mfma_f32_16x16x32_bf16 v[86:89], v[134:137], v[170:173], v[86:89]
	v_mfma_f32_16x16x32_bf16 v[82:85], v[142:145], v[170:173], v[82:85]
	v_mfma_f32_16x16x32_bf16 v[78:81], v[134:137], v[178:181], v[78:81]
	v_mfma_f32_16x16x32_bf16 v[74:77], v[142:145], v[178:181], v[74:77]
	v_mfma_f32_16x16x32_bf16 v[70:73], v[134:137], v[186:189], v[70:73]
	v_mfma_f32_16x16x32_bf16 v[66:69], v[142:145], v[186:189], v[66:69]
	s_setprio 0
	s_barrier
	s_add_u32 s78, s2, 0x40000
	s_addc_u32 s79, s3, 0
	s_add_i32 s12, s13, s35
	v_lshl_add_u64 v[130:131], s[78:79], 0, v[0:1]
	s_mov_b32 m0, s12
	s_nop 0
	global_load_lds_dwordx4 v[130:131], off
	v_lshl_add_u64 v[130:131], s[78:79], 0, v[154:155]
	s_add_i32 m0, s12, 0x2000
	s_nop 0
	global_load_lds_dwordx4 v[130:131], off
	s_waitcnt vmcnt(6)
	s_barrier
	s_setprio 3
	v_mfma_f32_16x16x32_bf16 v[30:33], v[190:193], v[146:149], v[30:33]
	v_mfma_f32_16x16x32_bf16 v[26:29], v[198:201], v[146:149], v[26:29]
	v_mfma_f32_16x16x32_bf16 v[22:25], v[190:193], v[166:169], v[22:25]
	v_mfma_f32_16x16x32_bf16 v[18:21], v[198:201], v[166:169], v[18:21]
	v_mfma_f32_16x16x32_bf16 v[14:17], v[190:193], v[174:177], v[14:17]
	v_mfma_f32_16x16x32_bf16 v[10:13], v[198:201], v[174:177], v[10:13]
	v_mfma_f32_16x16x32_bf16 v[6:9], v[190:193], v[182:185], v[6:9]
	v_mfma_f32_16x16x32_bf16 v[2:5], v[198:201], v[182:185], v[2:5]
	v_mfma_f32_16x16x32_bf16 v[30:33], v[194:197], v[150:153], v[30:33]
	v_mfma_f32_16x16x32_bf16 v[26:29], v[234:237], v[150:153], v[26:29]
	v_mfma_f32_16x16x32_bf16 v[22:25], v[194:197], v[170:173], v[22:25]
	v_mfma_f32_16x16x32_bf16 v[18:21], v[234:237], v[170:173], v[18:21]
	s_add_i32 s12, 0, 0x18000
	v_add_u32_e32 v142, s12, v227
	v_mfma_f32_16x16x32_bf16 v[14:17], v[194:197], v[178:181], v[14:17]
	v_mfma_f32_16x16x32_bf16 v[10:13], v[234:237], v[178:181], v[10:13]
	v_mfma_f32_16x16x32_bf16 v[6:9], v[194:197], v[186:189], v[6:9]
	v_mfma_f32_16x16x32_bf16 v[2:5], v[234:237], v[186:189], v[2:5]
	s_setprio 0
	s_barrier
	ds_read_b128 v[130:133], v142
	ds_read_b128 v[134:137], v142 offset:1024
	ds_read_b128 v[138:141], v142 offset:2048
	ds_read_b128 v[142:145], v142 offset:3072
	s_add_u32 s16, s16, 0x40000
	s_addc_u32 s17, s17, 0
	s_mov_b32 m0, s58
	s_nop 0
	ds_read_b128 v[146:149], v233 offset:32768
	ds_read_b128 v[150:153], v233 offset:33792
	ds_read_b128 v[166:169], v233 offset:34816
	ds_read_b128 v[170:173], v233 offset:35840
	ds_read_b128 v[174:177], v233 offset:36864
	ds_read_b128 v[178:181], v233 offset:37888
	ds_read_b128 v[182:185], v233 offset:38912
	ds_read_b128 v[186:189], v233 offset:39936
	global_load_lds_dwordx4 v250, s[16:17]
	s_nop 0
	s_mov_b32 m0, s59
	s_nop 0
	global_load_lds_dwordx4 v251, s[16:17]
	s_waitcnt lgkmcnt(8)
	s_barrier
	s_waitcnt lgkmcnt(0)
	s_setprio 3
	s_nop 0
	v_mfma_f32_16x16x32_bf16 v[126:129], v[130:133], v[146:149], v[126:129]
	v_mfma_f32_16x16x32_bf16 v[122:125], v[138:141], v[146:149], v[122:125]
	v_mfma_f32_16x16x32_bf16 v[118:121], v[130:133], v[166:169], v[118:121]
	v_mfma_f32_16x16x32_bf16 v[114:117], v[138:141], v[166:169], v[114:117]
	v_mfma_f32_16x16x32_bf16 v[110:113], v[130:133], v[174:177], v[110:113]
	v_mfma_f32_16x16x32_bf16 v[106:109], v[138:141], v[174:177], v[106:109]
	v_mfma_f32_16x16x32_bf16 v[102:105], v[130:133], v[182:185], v[102:105]
	v_mfma_f32_16x16x32_bf16 v[98:101], v[138:141], v[182:185], v[98:101]
	v_mfma_f32_16x16x32_bf16 v[126:129], v[134:137], v[150:153], v[126:129]
	v_mfma_f32_16x16x32_bf16 v[122:125], v[142:145], v[150:153], v[122:125]
	v_mfma_f32_16x16x32_bf16 v[118:121], v[134:137], v[170:173], v[118:121]
	v_mfma_f32_16x16x32_bf16 v[114:117], v[142:145], v[170:173], v[114:117]
	v_mfma_f32_16x16x32_bf16 v[110:113], v[134:137], v[178:181], v[110:113]
	v_mfma_f32_16x16x32_bf16 v[106:109], v[142:145], v[178:181], v[106:109]
	v_mfma_f32_16x16x32_bf16 v[102:105], v[134:137], v[186:189], v[102:105]
	v_mfma_f32_16x16x32_bf16 v[98:101], v[142:145], v[186:189], v[98:101]
	s_setprio 0
	s_barrier
	s_add_i32 s13, 0, 0x1c000
	s_add_i32 s12, s12, s35
	v_add_u32_e32 v234, s13, v227
	v_lshl_add_u64 v[242:243], v[242:243], 0, s[20:21]
	s_mov_b32 m0, s12
	ds_read_b128 v[190:193], v234
	ds_read_b128 v[194:197], v234 offset:1024
	ds_read_b128 v[198:201], v234 offset:2048
	ds_read_b128 v[234:237], v234 offset:3072
	global_load_lds_dwordx4 v[242:243], off
	v_lshl_add_u64 v[242:243], v[244:245], 0, s[20:21]
	s_add_i32 m0, s12, 0x2000
	s_nop 0
	global_load_lds_dwordx4 v[242:243], off
	s_barrier
	s_waitcnt lgkmcnt(0)
	s_setprio 3
	s_nop 0
	v_mfma_f32_16x16x32_bf16 v[62:65], v[190:193], v[146:149], v[62:65]
	v_mfma_f32_16x16x32_bf16 v[58:61], v[198:201], v[146:149], v[58:61]
	v_mfma_f32_16x16x32_bf16 v[54:57], v[190:193], v[166:169], v[54:57]
	v_mfma_f32_16x16x32_bf16 v[50:53], v[198:201], v[166:169], v[50:53]
	v_mfma_f32_16x16x32_bf16 v[46:49], v[190:193], v[174:177], v[46:49]
	v_mfma_f32_16x16x32_bf16 v[42:45], v[198:201], v[174:177], v[42:45]
	v_mfma_f32_16x16x32_bf16 v[38:41], v[190:193], v[182:185], v[38:41]
	v_mfma_f32_16x16x32_bf16 v[34:37], v[198:201], v[182:185], v[34:37]
	v_mfma_f32_16x16x32_bf16 v[62:65], v[194:197], v[150:153], v[62:65]
	v_mfma_f32_16x16x32_bf16 v[58:61], v[234:237], v[150:153], v[58:61]
	v_mfma_f32_16x16x32_bf16 v[54:57], v[194:197], v[170:173], v[54:57]
	v_mfma_f32_16x16x32_bf16 v[50:53], v[234:237], v[170:173], v[50:53]
	s_mov_b32 m0, s96
	s_add_u32 s78, s16, 0xfffc0080
	s_addc_u32 s79, s17, -1
	v_mfma_f32_16x16x32_bf16 v[46:49], v[194:197], v[178:181], v[46:49]
	v_mfma_f32_16x16x32_bf16 v[42:45], v[234:237], v[178:181], v[42:45]
	v_mfma_f32_16x16x32_bf16 v[38:41], v[194:197], v[186:189], v[38:41]
	v_mfma_f32_16x16x32_bf16 v[34:37], v[234:237], v[186:189], v[34:37]
	s_setprio 0
	s_barrier
	ds_read_b128 v[146:149], v233 offset:49152
	ds_read_b128 v[150:153], v233 offset:50176
	ds_read_b128 v[166:169], v233 offset:51200
	ds_read_b128 v[170:173], v233 offset:52224
	ds_read_b128 v[174:177], v233 offset:53248
	ds_read_b128 v[178:181], v233 offset:54272
	ds_read_b128 v[182:185], v233 offset:55296
	ds_read_b128 v[186:189], v233 offset:56320
	global_load_lds_dwordx4 v250, s[78:79]
	s_nop 0
	s_mov_b32 m0, s97
	s_nop 0
	global_load_lds_dwordx4 v251, s[78:79]
	s_barrier
	s_waitcnt lgkmcnt(0)
	s_setprio 3
	v_mfma_f32_16x16x32_bf16 v[94:97], v[130:133], v[146:149], v[94:97]
	v_mfma_f32_16x16x32_bf16 v[90:93], v[138:141], v[146:149], v[90:93]
	v_mfma_f32_16x16x32_bf16 v[86:89], v[130:133], v[166:169], v[86:89]
	v_mfma_f32_16x16x32_bf16 v[82:85], v[138:141], v[166:169], v[82:85]
	v_mfma_f32_16x16x32_bf16 v[78:81], v[130:133], v[174:177], v[78:81]
	v_mfma_f32_16x16x32_bf16 v[74:77], v[138:141], v[174:177], v[74:77]
	v_mfma_f32_16x16x32_bf16 v[70:73], v[130:133], v[182:185], v[70:73]
	v_mfma_f32_16x16x32_bf16 v[66:69], v[138:141], v[182:185], v[66:69]
	v_mfma_f32_16x16x32_bf16 v[94:97], v[134:137], v[150:153], v[94:97]
	v_mfma_f32_16x16x32_bf16 v[90:93], v[142:145], v[150:153], v[90:93]
	v_mfma_f32_16x16x32_bf16 v[86:89], v[134:137], v[170:173], v[86:89]
	v_mfma_f32_16x16x32_bf16 v[82:85], v[142:145], v[170:173], v[82:85]
	v_mfma_f32_16x16x32_bf16 v[78:81], v[134:137], v[178:181], v[78:81]
	v_mfma_f32_16x16x32_bf16 v[74:77], v[142:145], v[178:181], v[74:77]
	v_mfma_f32_16x16x32_bf16 v[70:73], v[134:137], v[186:189], v[70:73]
	v_mfma_f32_16x16x32_bf16 v[66:69], v[142:145], v[186:189], v[66:69]
	s_setprio 0
	s_barrier
	s_add_u32 s2, s2, 0x40080
	s_addc_u32 s3, s3, 0
	s_add_i32 s12, s13, s35
	v_lshl_add_u64 v[130:131], s[2:3], 0, v[0:1]
	s_mov_b32 m0, s12
	s_nop 0
	global_load_lds_dwordx4 v[130:131], off
	v_lshl_add_u64 v[130:131], s[2:3], 0, v[154:155]
	s_add_i32 m0, s12, 0x2000
	s_nop 0
	global_load_lds_dwordx4 v[130:131], off
	s_waitcnt vmcnt(6)
	s_barrier
	s_setprio 3
	v_mfma_f32_16x16x32_bf16 v[30:33], v[190:193], v[146:149], v[30:33]
	v_mfma_f32_16x16x32_bf16 v[26:29], v[198:201], v[146:149], v[26:29]
	v_mfma_f32_16x16x32_bf16 v[22:25], v[190:193], v[166:169], v[22:25]
	v_mfma_f32_16x16x32_bf16 v[18:21], v[198:201], v[166:169], v[18:21]
	v_mfma_f32_16x16x32_bf16 v[14:17], v[190:193], v[174:177], v[14:17]
	v_mfma_f32_16x16x32_bf16 v[10:13], v[198:201], v[174:177], v[10:13]
	v_mfma_f32_16x16x32_bf16 v[6:9], v[190:193], v[182:185], v[6:9]
	v_mfma_f32_16x16x32_bf16 v[2:5], v[198:201], v[182:185], v[2:5]
	v_mfma_f32_16x16x32_bf16 v[30:33], v[194:197], v[150:153], v[30:33]
	v_mfma_f32_16x16x32_bf16 v[26:29], v[234:237], v[150:153], v[26:29]
	v_mfma_f32_16x16x32_bf16 v[22:25], v[194:197], v[170:173], v[22:25]
	v_mfma_f32_16x16x32_bf16 v[18:21], v[234:237], v[170:173], v[18:21]
	s_add_i32 s47, s47, 2
	s_add_u32 s0, s0, 0x100
	s_addc_u32 s1, s1, 0
	s_add_u32 s45, s45, 0x100
	s_addc_u32 s46, s46, 0
	s_cmp_gt_u32 s47, 13
	v_mfma_f32_16x16x32_bf16 v[14:17], v[194:197], v[178:181], v[14:17]
	v_mfma_f32_16x16x32_bf16 v[10:13], v[234:237], v[178:181], v[10:13]
	v_mfma_f32_16x16x32_bf16 v[6:9], v[194:197], v[186:189], v[6:9]
	v_mfma_f32_16x16x32_bf16 v[2:5], v[234:237], v[186:189], v[2:5]
	s_setprio 0
	s_barrier
	s_cbranch_scc0 .LBB0_366

.Lq_aligned:
	s_barrier
	s_add_i32 m0, s46, 0x0
	s_nop 0
	global_load_lds_dwordx4 v250, s[0:1]
	s_add_i32 m0, s46, 0x2000
	s_nop 0
	global_load_lds_dwordx4 v251, s[0:1]
	s_add_i32 m0, s47, 0x0
	s_nop 0
	global_load_lds_dwordx4 v0, s[16:17]
	s_add_i32 m0, s47, 0x2000
	s_nop 0
	global_load_lds_dwordx4 v154, s[16:17]
	s_add_u32 s0, s0, 0x80
	s_addc_u32 s1, s1, 0
	s_add_u32 s16, s16, 0x80
	s_addc_u32 s17, s17, 0
	s_add_i32 m0, s46, 0x8000
	s_nop 0
	global_load_lds_dwordx4 v250, s[0:1]
	s_add_i32 m0, s46, 0xa000
	s_nop 0
	global_load_lds_dwordx4 v251, s[0:1]
	s_add_i32 m0, s47, 0x8000
	s_nop 0
	global_load_lds_dwordx4 v0, s[16:17]
	s_add_i32 m0, s47, 0xa000
	s_nop 0
	global_load_lds_dwordx4 v154, s[16:17]
	s_add_u32 s0, s0, 0x80
	s_addc_u32 s1, s1, 0
	s_add_u32 s16, s16, 0x80
	s_addc_u32 s17, s17, 0
	ds_read_b128 v[130:133], v191 offset:0
	ds_read_b128 v[134:137], v191 offset:1024
	ds_read_b128 v[138:141], v191 offset:2048
	ds_read_b128 v[142:145], v191 offset:3072
	ds_read_b128 v[146:149], v190 offset:0
	ds_read_b128 v[150:153], v190 offset:1024
	ds_read_b128 v[166:169], v190 offset:2048
	ds_read_b128 v[170:173], v190 offset:3072
	ds_read_b128 v[174:177], v190 offset:4096
	ds_read_b128 v[178:181], v190 offset:5120
	ds_read_b128 v[182:185], v190 offset:6144
	ds_read_b128 v[186:189], v190 offset:7168
	s_waitcnt lgkmcnt(0)
	s_waitcnt vmcnt(8)
	s_barrier
	s_add_i32 m0, s44, 0x0
	s_nop 0
	global_load_lds_dwordx4 v250, s[0:1]
	s_add_i32 m0, s44, 0x2000
	s_nop 0
	global_load_lds_dwordx4 v251, s[0:1]
	s_add_i32 m0, s45, 0x0
	s_nop 0
	global_load_lds_dwordx4 v0, s[16:17]
	s_add_i32 m0, s45, 0x2000
	s_nop 0
	global_load_lds_dwordx4 v154, s[16:17]
	s_add_u32 s0, s0, 0x80
	s_addc_u32 s1, s1, 0
	s_add_u32 s16, s16, 0x80
	s_addc_u32 s17, s17, 0
	s_setprio 3
	v_mfma_f32_16x16x32_bf16 v[126:129], v[130:133], v[146:149], v[126:129]
	v_mfma_f32_16x16x32_bf16 v[122:125], v[138:141], v[146:149], v[122:125]
	v_mfma_f32_16x16x32_bf16 v[118:121], v[130:133], v[166:169], v[118:121]
	v_mfma_f32_16x16x32_bf16 v[114:117], v[138:141], v[166:169], v[114:117]
	v_mfma_f32_16x16x32_bf16 v[110:113], v[130:133], v[174:177], v[110:113]
	v_mfma_f32_16x16x32_bf16 v[106:109], v[138:141], v[174:177], v[106:109]
	v_mfma_f32_16x16x32_bf16 v[102:105], v[130:133], v[182:185], v[102:105]
	v_mfma_f32_16x16x32_bf16 v[98:101], v[138:141], v[182:185], v[98:101]
	v_mfma_f32_16x16x32_bf16 v[126:129], v[134:137], v[150:153], v[126:129]
	v_mfma_f32_16x16x32_bf16 v[122:125], v[142:145], v[150:153], v[122:125]
	v_mfma_f32_16x16x32_bf16 v[118:121], v[134:137], v[170:173], v[118:121]
	v_mfma_f32_16x16x32_bf16 v[114:117], v[142:145], v[170:173], v[114:117]
	v_mfma_f32_16x16x32_bf16 v[110:113], v[134:137], v[178:181], v[110:113]
	v_mfma_f32_16x16x32_bf16 v[106:109], v[142:145], v[178:181], v[106:109]
	v_mfma_f32_16x16x32_bf16 v[102:105], v[134:137], v[186:189], v[102:105]
	v_mfma_f32_16x16x32_bf16 v[98:101], v[142:145], v[186:189], v[98:101]
	s_setprio 0
	ds_read_b128 v[130:133], v191 offset:32768
	ds_read_b128 v[134:137], v191 offset:33792
	ds_read_b128 v[138:141], v191 offset:34816
	ds_read_b128 v[142:145], v191 offset:35840
	ds_read_b128 v[146:149], v190 offset:32768
	ds_read_b128 v[150:153], v190 offset:33792
	ds_read_b128 v[166:169], v190 offset:34816
	ds_read_b128 v[170:173], v190 offset:35840
	ds_read_b128 v[174:177], v190 offset:36864
	ds_read_b128 v[178:181], v190 offset:37888
	ds_read_b128 v[182:185], v190 offset:38912
	ds_read_b128 v[186:189], v190 offset:39936
	s_waitcnt lgkmcnt(0)
	s_waitcnt vmcnt(8)
	s_barrier
	s_add_i32 m0, s44, 0x8000
	s_nop 0
	global_load_lds_dwordx4 v250, s[0:1]
	s_add_i32 m0, s44, 0xa000
	s_nop 0
	global_load_lds_dwordx4 v251, s[0:1]
	s_add_i32 m0, s45, 0x8000
	s_nop 0
	global_load_lds_dwordx4 v0, s[16:17]
	s_add_i32 m0, s45, 0xa000
	s_nop 0
	global_load_lds_dwordx4 v154, s[16:17]
	s_add_u32 s0, s0, 0x80
	s_addc_u32 s1, s1, 0
	s_add_u32 s16, s16, 0x80
	s_addc_u32 s17, s17, 0
	s_setprio 3
	s_nop 0
	v_mfma_f32_16x16x32_bf16 v[126:129], v[130:133], v[146:149], v[126:129]
	v_mfma_f32_16x16x32_bf16 v[122:125], v[138:141], v[146:149], v[122:125]
	v_mfma_f32_16x16x32_bf16 v[118:121], v[130:133], v[166:169], v[118:121]
	v_mfma_f32_16x16x32_bf16 v[114:117], v[138:141], v[166:169], v[114:117]
	v_mfma_f32_16x16x32_bf16 v[110:113], v[130:133], v[174:177], v[110:113]
	v_mfma_f32_16x16x32_bf16 v[106:109], v[138:141], v[174:177], v[106:109]
	v_mfma_f32_16x16x32_bf16 v[102:105], v[130:133], v[182:185], v[102:105]
	v_mfma_f32_16x16x32_bf16 v[98:101], v[138:141], v[182:185], v[98:101]
	v_mfma_f32_16x16x32_bf16 v[126:129], v[134:137], v[150:153], v[126:129]
	v_mfma_f32_16x16x32_bf16 v[122:125], v[142:145], v[150:153], v[122:125]
	v_mfma_f32_16x16x32_bf16 v[118:121], v[134:137], v[170:173], v[118:121]
	v_mfma_f32_16x16x32_bf16 v[114:117], v[142:145], v[170:173], v[114:117]
	v_mfma_f32_16x16x32_bf16 v[110:113], v[134:137], v[178:181], v[110:113]
	v_mfma_f32_16x16x32_bf16 v[106:109], v[142:145], v[178:181], v[106:109]
	v_mfma_f32_16x16x32_bf16 v[102:105], v[134:137], v[186:189], v[102:105]
	v_mfma_f32_16x16x32_bf16 v[98:101], v[142:145], v[186:189], v[98:101]
	s_setprio 0
	ds_read_b128 v[130:133], v193 offset:0
	ds_read_b128 v[134:137], v193 offset:1024
	ds_read_b128 v[138:141], v193 offset:2048
	ds_read_b128 v[142:145], v193 offset:3072
	ds_read_b128 v[146:149], v192 offset:0
	ds_read_b128 v[150:153], v192 offset:1024
	ds_read_b128 v[166:169], v192 offset:2048
	ds_read_b128 v[170:173], v192 offset:3072
	ds_read_b128 v[174:177], v192 offset:4096
	ds_read_b128 v[178:181], v192 offset:5120
	ds_read_b128 v[182:185], v192 offset:6144
	ds_read_b128 v[186:189], v192 offset:7168
	s_waitcnt lgkmcnt(0)
	s_waitcnt vmcnt(8)
	s_barrier
	s_add_i32 m0, s46, 0x0
	s_nop 0
	global_load_lds_dwordx4 v250, s[0:1]
	s_add_i32 m0, s46, 0x2000
	s_nop 0
	global_load_lds_dwordx4 v251, s[0:1]
	s_add_i32 m0, s47, 0x0
	s_nop 0
	global_load_lds_dwordx4 v0, s[16:17]
	s_add_i32 m0, s47, 0x2000
	s_nop 0
	global_load_lds_dwordx4 v154, s[16:17]
	s_add_u32 s0, s0, 0x80
	s_addc_u32 s1, s1, 0
	s_add_u32 s16, s16, 0x80
	s_addc_u32 s17, s17, 0
	s_setprio 3
	s_nop 0
	v_mfma_f32_16x16x32_bf16 v[126:129], v[130:133], v[146:149], v[126:129]
	v_mfma_f32_16x16x32_bf16 v[122:125], v[138:141], v[146:149], v[122:125]
	v_mfma_f32_16x16x32_bf16 v[118:121], v[130:133], v[166:169], v[118:121]
	v_mfma_f32_16x16x32_bf16 v[114:117], v[138:141], v[166:169], v[114:117]
	v_mfma_f32_16x16x32_bf16 v[110:113], v[130:133], v[174:177], v[110:113]
	v_mfma_f32_16x16x32_bf16 v[106:109], v[138:141], v[174:177], v[106:109]
	v_mfma_f32_16x16x32_bf16 v[102:105], v[130:133], v[182:185], v[102:105]
	v_mfma_f32_16x16x32_bf16 v[98:101], v[138:141], v[182:185], v[98:101]
	v_mfma_f32_16x16x32_bf16 v[126:129], v[134:137], v[150:153], v[126:129]
	v_mfma_f32_16x16x32_bf16 v[122:125], v[142:145], v[150:153], v[122:125]
	v_mfma_f32_16x16x32_bf16 v[118:121], v[134:137], v[170:173], v[118:121]
	v_mfma_f32_16x16x32_bf16 v[114:117], v[142:145], v[170:173], v[114:117]
	v_mfma_f32_16x16x32_bf16 v[110:113], v[134:137], v[178:181], v[110:113]
	v_mfma_f32_16x16x32_bf16 v[106:109], v[142:145], v[178:181], v[106:109]
	v_mfma_f32_16x16x32_bf16 v[102:105], v[134:137], v[186:189], v[102:105]
	v_mfma_f32_16x16x32_bf16 v[98:101], v[142:145], v[186:189], v[98:101]
	s_setprio 0
	ds_read_b128 v[130:133], v193 offset:32768
	ds_read_b128 v[134:137], v193 offset:33792
	ds_read_b128 v[138:141], v193 offset:34816
	ds_read_b128 v[142:145], v193 offset:35840
	ds_read_b128 v[146:149], v192 offset:32768
	ds_read_b128 v[150:153], v192 offset:33792
	ds_read_b128 v[166:169], v192 offset:34816
	ds_read_b128 v[170:173], v192 offset:35840
	ds_read_b128 v[174:177], v192 offset:36864
	ds_read_b128 v[178:181], v192 offset:37888
	ds_read_b128 v[182:185], v192 offset:38912
	ds_read_b128 v[186:189], v192 offset:39936
	s_waitcnt lgkmcnt(0)
	s_waitcnt vmcnt(8)
	s_barrier
	s_add_i32 m0, s46, 0x8000
	s_nop 0
	global_load_lds_dwordx4 v250, s[0:1]
	s_add_i32 m0, s46, 0xa000
	s_nop 0
	global_load_lds_dwordx4 v251, s[0:1]
	s_add_i32 m0, s47, 0x8000
	s_nop 0
	global_load_lds_dwordx4 v0, s[16:17]
	s_add_i32 m0, s47, 0xa000
	s_nop 0
	global_load_lds_dwordx4 v154, s[16:17]
	s_add_u32 s0, s0, 0x80
	s_addc_u32 s1, s1, 0
	s_add_u32 s16, s16, 0x80
	s_addc_u32 s17, s17, 0
	s_setprio 3
	s_nop 0
	v_mfma_f32_16x16x32_bf16 v[126:129], v[130:133], v[146:149], v[126:129]
	v_mfma_f32_16x16x32_bf16 v[122:125], v[138:141], v[146:149], v[122:125]
	v_mfma_f32_16x16x32_bf16 v[118:121], v[130:133], v[166:169], v[118:121]
	v_mfma_f32_16x16x32_bf16 v[114:117], v[138:141], v[166:169], v[114:117]
	v_mfma_f32_16x16x32_bf16 v[110:113], v[130:133], v[174:177], v[110:113]
	v_mfma_f32_16x16x32_bf16 v[106:109], v[138:141], v[174:177], v[106:109]
	v_mfma_f32_16x16x32_bf16 v[102:105], v[130:133], v[182:185], v[102:105]
	v_mfma_f32_16x16x32_bf16 v[98:101], v[138:141], v[182:185], v[98:101]
	v_mfma_f32_16x16x32_bf16 v[126:129], v[134:137], v[150:153], v[126:129]
	v_mfma_f32_16x16x32_bf16 v[122:125], v[142:145], v[150:153], v[122:125]
	v_mfma_f32_16x16x32_bf16 v[118:121], v[134:137], v[170:173], v[118:121]
	v_mfma_f32_16x16x32_bf16 v[114:117], v[142:145], v[170:173], v[114:117]
	v_mfma_f32_16x16x32_bf16 v[110:113], v[134:137], v[178:181], v[110:113]
	v_mfma_f32_16x16x32_bf16 v[106:109], v[142:145], v[178:181], v[106:109]
	v_mfma_f32_16x16x32_bf16 v[102:105], v[134:137], v[186:189], v[102:105]
	v_mfma_f32_16x16x32_bf16 v[98:101], v[142:145], v[186:189], v[98:101]
	s_setprio 0
	ds_read_b128 v[130:133], v191 offset:0
	ds_read_b128 v[134:137], v191 offset:1024
	ds_read_b128 v[138:141], v191 offset:2048
	ds_read_b128 v[142:145], v191 offset:3072
	ds_read_b128 v[146:149], v190 offset:0
	ds_read_b128 v[150:153], v190 offset:1024
	ds_read_b128 v[166:169], v190 offset:2048
	ds_read_b128 v[170:173], v190 offset:3072
	ds_read_b128 v[174:177], v190 offset:4096
	ds_read_b128 v[178:181], v190 offset:5120
	ds_read_b128 v[182:185], v190 offset:6144
	ds_read_b128 v[186:189], v190 offset:7168
	s_waitcnt lgkmcnt(0)
	s_waitcnt vmcnt(8)
	s_barrier
	s_add_i32 m0, s44, 0x0
	s_nop 0
	global_load_lds_dwordx4 v250, s[0:1]
	s_add_i32 m0, s44, 0x2000
	s_nop 0
	global_load_lds_dwordx4 v251, s[0:1]
	s_add_i32 m0, s45, 0x0
	s_nop 0
	global_load_lds_dwordx4 v0, s[16:17]
	s_add_i32 m0, s45, 0x2000
	s_nop 0
	global_load_lds_dwordx4 v154, s[16:17]
	s_add_u32 s0, s0, 0x80
	s_addc_u32 s1, s1, 0
	s_add_u32 s16, s16, 0x80
	s_addc_u32 s17, s17, 0
	s_setprio 3
	s_nop 0
	v_mfma_f32_16x16x32_bf16 v[126:129], v[130:133], v[146:149], v[126:129]
	v_mfma_f32_16x16x32_bf16 v[122:125], v[138:141], v[146:149], v[122:125]
	v_mfma_f32_16x16x32_bf16 v[118:121], v[130:133], v[166:169], v[118:121]
	v_mfma_f32_16x16x32_bf16 v[114:117], v[138:141], v[166:169], v[114:117]
	v_mfma_f32_16x16x32_bf16 v[110:113], v[130:133], v[174:177], v[110:113]
	v_mfma_f32_16x16x32_bf16 v[106:109], v[138:141], v[174:177], v[106:109]
	v_mfma_f32_16x16x32_bf16 v[102:105], v[130:133], v[182:185], v[102:105]
	v_mfma_f32_16x16x32_bf16 v[98:101], v[138:141], v[182:185], v[98:101]
	v_mfma_f32_16x16x32_bf16 v[126:129], v[134:137], v[150:153], v[126:129]
	v_mfma_f32_16x16x32_bf16 v[122:125], v[142:145], v[150:153], v[122:125]
	v_mfma_f32_16x16x32_bf16 v[118:121], v[134:137], v[170:173], v[118:121]
	v_mfma_f32_16x16x32_bf16 v[114:117], v[142:145], v[170:173], v[114:117]
	v_mfma_f32_16x16x32_bf16 v[110:113], v[134:137], v[178:181], v[110:113]
	v_mfma_f32_16x16x32_bf16 v[106:109], v[142:145], v[178:181], v[106:109]
	v_mfma_f32_16x16x32_bf16 v[102:105], v[134:137], v[186:189], v[102:105]
	v_mfma_f32_16x16x32_bf16 v[98:101], v[142:145], v[186:189], v[98:101]
	s_setprio 0
	ds_read_b128 v[130:133], v191 offset:32768
	ds_read_b128 v[134:137], v191 offset:33792
	ds_read_b128 v[138:141], v191 offset:34816
	ds_read_b128 v[142:145], v191 offset:35840
	ds_read_b128 v[146:149], v190 offset:32768
	ds_read_b128 v[150:153], v190 offset:33792
	ds_read_b128 v[166:169], v190 offset:34816
	ds_read_b128 v[170:173], v190 offset:35840
	ds_read_b128 v[174:177], v190 offset:36864
	ds_read_b128 v[178:181], v190 offset:37888
	ds_read_b128 v[182:185], v190 offset:38912
	ds_read_b128 v[186:189], v190 offset:39936
	s_waitcnt lgkmcnt(0)
	s_waitcnt vmcnt(8)
	s_barrier
	s_add_i32 m0, s44, 0x8000
	s_nop 0
	global_load_lds_dwordx4 v250, s[0:1]
	s_add_i32 m0, s44, 0xa000
	s_nop 0
	global_load_lds_dwordx4 v251, s[0:1]
	s_add_i32 m0, s45, 0x8000
	s_nop 0
	global_load_lds_dwordx4 v0, s[16:17]
	s_add_i32 m0, s45, 0xa000
	s_nop 0
	global_load_lds_dwordx4 v154, s[16:17]
	s_add_u32 s0, s0, 0x80
	s_addc_u32 s1, s1, 0
	s_add_u32 s16, s16, 0x80
	s_addc_u32 s17, s17, 0
	s_setprio 3
	s_nop 0
	v_mfma_f32_16x16x32_bf16 v[126:129], v[130:133], v[146:149], v[126:129]
	v_mfma_f32_16x16x32_bf16 v[122:125], v[138:141], v[146:149], v[122:125]
	v_mfma_f32_16x16x32_bf16 v[118:121], v[130:133], v[166:169], v[118:121]
	v_mfma_f32_16x16x32_bf16 v[114:117], v[138:141], v[166:169], v[114:117]
	v_mfma_f32_16x16x32_bf16 v[110:113], v[130:133], v[174:177], v[110:113]
	v_mfma_f32_16x16x32_bf16 v[106:109], v[138:141], v[174:177], v[106:109]
	v_mfma_f32_16x16x32_bf16 v[102:105], v[130:133], v[182:185], v[102:105]
	v_mfma_f32_16x16x32_bf16 v[98:101], v[138:141], v[182:185], v[98:101]
	v_mfma_f32_16x16x32_bf16 v[126:129], v[134:137], v[150:153], v[126:129]
	v_mfma_f32_16x16x32_bf16 v[122:125], v[142:145], v[150:153], v[122:125]
	v_mfma_f32_16x16x32_bf16 v[118:121], v[134:137], v[170:173], v[118:121]
	v_mfma_f32_16x16x32_bf16 v[114:117], v[142:145], v[170:173], v[114:117]
	v_mfma_f32_16x16x32_bf16 v[110:113], v[134:137], v[178:181], v[110:113]
	v_mfma_f32_16x16x32_bf16 v[106:109], v[142:145], v[178:181], v[106:109]
	v_mfma_f32_16x16x32_bf16 v[102:105], v[134:137], v[186:189], v[102:105]
	v_mfma_f32_16x16x32_bf16 v[98:101], v[142:145], v[186:189], v[98:101]
	s_setprio 0
	ds_read_b128 v[130:133], v193 offset:0
	ds_read_b128 v[134:137], v193 offset:1024
	ds_read_b128 v[138:141], v193 offset:2048
	ds_read_b128 v[142:145], v193 offset:3072
	ds_read_b128 v[146:149], v192 offset:0
	ds_read_b128 v[150:153], v192 offset:1024
	ds_read_b128 v[166:169], v192 offset:2048
	ds_read_b128 v[170:173], v192 offset:3072
	ds_read_b128 v[174:177], v192 offset:4096
	ds_read_b128 v[178:181], v192 offset:5120
	ds_read_b128 v[182:185], v192 offset:6144
	ds_read_b128 v[186:189], v192 offset:7168
	s_waitcnt lgkmcnt(0)
	s_waitcnt vmcnt(8)
	s_barrier
	s_add_i32 m0, s46, 0x0
	s_nop 0
	global_load_lds_dwordx4 v250, s[0:1]
	s_add_i32 m0, s46, 0x2000
	s_nop 0
	global_load_lds_dwordx4 v251, s[0:1]
	s_add_i32 m0, s47, 0x0
	s_nop 0
	global_load_lds_dwordx4 v0, s[16:17]
	s_add_i32 m0, s47, 0x2000
	s_nop 0
	global_load_lds_dwordx4 v154, s[16:17]
	s_add_u32 s0, s0, 0x80
	s_addc_u32 s1, s1, 0
	s_add_u32 s16, s16, 0x80
	s_addc_u32 s17, s17, 0
	s_setprio 3
	s_nop 0
	v_mfma_f32_16x16x32_bf16 v[126:129], v[130:133], v[146:149], v[126:129]
	v_mfma_f32_16x16x32_bf16 v[122:125], v[138:141], v[146:149], v[122:125]
	v_mfma_f32_16x16x32_bf16 v[118:121], v[130:133], v[166:169], v[118:121]
	v_mfma_f32_16x16x32_bf16 v[114:117], v[138:141], v[166:169], v[114:117]
	v_mfma_f32_16x16x32_bf16 v[110:113], v[130:133], v[174:177], v[110:113]
	v_mfma_f32_16x16x32_bf16 v[106:109], v[138:141], v[174:177], v[106:109]
	v_mfma_f32_16x16x32_bf16 v[102:105], v[130:133], v[182:185], v[102:105]
	v_mfma_f32_16x16x32_bf16 v[98:101], v[138:141], v[182:185], v[98:101]
	v_mfma_f32_16x16x32_bf16 v[126:129], v[134:137], v[150:153], v[126:129]
	v_mfma_f32_16x16x32_bf16 v[122:125], v[142:145], v[150:153], v[122:125]
	v_mfma_f32_16x16x32_bf16 v[118:121], v[134:137], v[170:173], v[118:121]
	v_mfma_f32_16x16x32_bf16 v[114:117], v[142:145], v[170:173], v[114:117]
	v_mfma_f32_16x16x32_bf16 v[110:113], v[134:137], v[178:181], v[110:113]
	v_mfma_f32_16x16x32_bf16 v[106:109], v[142:145], v[178:181], v[106:109]
	v_mfma_f32_16x16x32_bf16 v[102:105], v[134:137], v[186:189], v[102:105]
	v_mfma_f32_16x16x32_bf16 v[98:101], v[142:145], v[186:189], v[98:101]
	s_setprio 0
	ds_read_b128 v[130:133], v193 offset:32768
	ds_read_b128 v[134:137], v193 offset:33792
	ds_read_b128 v[138:141], v193 offset:34816
	ds_read_b128 v[142:145], v193 offset:35840
	ds_read_b128 v[146:149], v192 offset:32768
	ds_read_b128 v[150:153], v192 offset:33792
	ds_read_b128 v[166:169], v192 offset:34816
	ds_read_b128 v[170:173], v192 offset:35840
	ds_read_b128 v[174:177], v192 offset:36864
	ds_read_b128 v[178:181], v192 offset:37888
	ds_read_b128 v[182:185], v192 offset:38912
	ds_read_b128 v[186:189], v192 offset:39936
	s_waitcnt lgkmcnt(0)
	s_waitcnt vmcnt(8)
	s_barrier
	s_add_i32 m0, s46, 0x8000
	s_nop 0
	global_load_lds_dwordx4 v250, s[0:1]
	s_add_i32 m0, s46, 0xa000
	s_nop 0
	global_load_lds_dwordx4 v251, s[0:1]
	s_add_i32 m0, s47, 0x8000
	s_nop 0
	global_load_lds_dwordx4 v0, s[16:17]
	s_add_i32 m0, s47, 0xa000
	s_nop 0
	global_load_lds_dwordx4 v154, s[16:17]
	s_add_u32 s0, s0, 0x80
	s_addc_u32 s1, s1, 0
	s_add_u32 s16, s16, 0x80
	s_addc_u32 s17, s17, 0
	s_setprio 3
	s_nop 0
	v_mfma_f32_16x16x32_bf16 v[126:129], v[130:133], v[146:149], v[126:129]
	v_mfma_f32_16x16x32_bf16 v[122:125], v[138:141], v[146:149], v[122:125]
	v_mfma_f32_16x16x32_bf16 v[118:121], v[130:133], v[166:169], v[118:121]
	v_mfma_f32_16x16x32_bf16 v[114:117], v[138:141], v[166:169], v[114:117]
	v_mfma_f32_16x16x32_bf16 v[110:113], v[130:133], v[174:177], v[110:113]
	v_mfma_f32_16x16x32_bf16 v[106:109], v[138:141], v[174:177], v[106:109]
	v_mfma_f32_16x16x32_bf16 v[102:105], v[130:133], v[182:185], v[102:105]
	v_mfma_f32_16x16x32_bf16 v[98:101], v[138:141], v[182:185], v[98:101]
	v_mfma_f32_16x16x32_bf16 v[126:129], v[134:137], v[150:153], v[126:129]
	v_mfma_f32_16x16x32_bf16 v[122:125], v[142:145], v[150:153], v[122:125]
	v_mfma_f32_16x16x32_bf16 v[118:121], v[134:137], v[170:173], v[118:121]
	v_mfma_f32_16x16x32_bf16 v[114:117], v[142:145], v[170:173], v[114:117]
	v_mfma_f32_16x16x32_bf16 v[110:113], v[134:137], v[178:181], v[110:113]
	v_mfma_f32_16x16x32_bf16 v[106:109], v[142:145], v[178:181], v[106:109]
	v_mfma_f32_16x16x32_bf16 v[102:105], v[134:137], v[186:189], v[102:105]
	v_mfma_f32_16x16x32_bf16 v[98:101], v[142:145], v[186:189], v[98:101]
	s_setprio 0
	ds_read_b128 v[130:133], v191 offset:0
	ds_read_b128 v[134:137], v191 offset:1024
	ds_read_b128 v[138:141], v191 offset:2048
	ds_read_b128 v[142:145], v191 offset:3072
	ds_read_b128 v[146:149], v190 offset:0
	ds_read_b128 v[150:153], v190 offset:1024
	ds_read_b128 v[166:169], v190 offset:2048
	ds_read_b128 v[170:173], v190 offset:3072
	ds_read_b128 v[174:177], v190 offset:4096
	ds_read_b128 v[178:181], v190 offset:5120
	ds_read_b128 v[182:185], v190 offset:6144
	ds_read_b128 v[186:189], v190 offset:7168
	s_waitcnt lgkmcnt(0)
	s_waitcnt vmcnt(8)
	s_barrier
	s_add_i32 m0, s44, 0x0
	s_nop 0
	global_load_lds_dwordx4 v250, s[0:1]
	s_add_i32 m0, s44, 0x2000
	s_nop 0
	global_load_lds_dwordx4 v251, s[0:1]
	s_add_i32 m0, s45, 0x0
	s_nop 0
	global_load_lds_dwordx4 v0, s[16:17]
	s_add_i32 m0, s45, 0x2000
	s_nop 0
	global_load_lds_dwordx4 v154, s[16:17]
	s_add_u32 s0, s0, 0x80
	s_addc_u32 s1, s1, 0
	s_add_u32 s16, s16, 0x80
	s_addc_u32 s17, s17, 0
	s_setprio 3
	s_nop 0
	v_mfma_f32_16x16x32_bf16 v[126:129], v[130:133], v[146:149], v[126:129]
	v_mfma_f32_16x16x32_bf16 v[122:125], v[138:141], v[146:149], v[122:125]
	v_mfma_f32_16x16x32_bf16 v[118:121], v[130:133], v[166:169], v[118:121]
	v_mfma_f32_16x16x32_bf16 v[114:117], v[138:141], v[166:169], v[114:117]
	v_mfma_f32_16x16x32_bf16 v[110:113], v[130:133], v[174:177], v[110:113]
	v_mfma_f32_16x16x32_bf16 v[106:109], v[138:141], v[174:177], v[106:109]
	v_mfma_f32_16x16x32_bf16 v[102:105], v[130:133], v[182:185], v[102:105]
	v_mfma_f32_16x16x32_bf16 v[98:101], v[138:141], v[182:185], v[98:101]
	v_mfma_f32_16x16x32_bf16 v[126:129], v[134:137], v[150:153], v[126:129]
	v_mfma_f32_16x16x32_bf16 v[122:125], v[142:145], v[150:153], v[122:125]
	v_mfma_f32_16x16x32_bf16 v[118:121], v[134:137], v[170:173], v[118:121]
	v_mfma_f32_16x16x32_bf16 v[114:117], v[142:145], v[170:173], v[114:117]
	v_mfma_f32_16x16x32_bf16 v[110:113], v[134:137], v[178:181], v[110:113]
	v_mfma_f32_16x16x32_bf16 v[106:109], v[142:145], v[178:181], v[106:109]
	v_mfma_f32_16x16x32_bf16 v[102:105], v[134:137], v[186:189], v[102:105]
	v_mfma_f32_16x16x32_bf16 v[98:101], v[142:145], v[186:189], v[98:101]
	s_setprio 0
	ds_read_b128 v[130:133], v191 offset:32768
	ds_read_b128 v[134:137], v191 offset:33792
	ds_read_b128 v[138:141], v191 offset:34816
	ds_read_b128 v[142:145], v191 offset:35840
	ds_read_b128 v[146:149], v190 offset:32768
	ds_read_b128 v[150:153], v190 offset:33792
	ds_read_b128 v[166:169], v190 offset:34816
	ds_read_b128 v[170:173], v190 offset:35840
	ds_read_b128 v[174:177], v190 offset:36864
	ds_read_b128 v[178:181], v190 offset:37888
	ds_read_b128 v[182:185], v190 offset:38912
	ds_read_b128 v[186:189], v190 offset:39936
	s_waitcnt lgkmcnt(0)
	s_waitcnt vmcnt(8)
	s_barrier
	s_add_i32 m0, s44, 0x8000
	s_nop 0
	global_load_lds_dwordx4 v250, s[0:1]
	s_add_i32 m0, s44, 0xa000
	s_nop 0
	global_load_lds_dwordx4 v251, s[0:1]
	s_add_i32 m0, s45, 0x8000
	s_nop 0
	global_load_lds_dwordx4 v0, s[16:17]
	s_add_i32 m0, s45, 0xa000
	s_nop 0
	global_load_lds_dwordx4 v154, s[16:17]
	s_add_u32 s0, s0, 0x80
	s_addc_u32 s1, s1, 0
	s_add_u32 s16, s16, 0x80
	s_addc_u32 s17, s17, 0
	s_setprio 3
	s_nop 0
	v_mfma_f32_16x16x32_bf16 v[126:129], v[130:133], v[146:149], v[126:129]
	v_mfma_f32_16x16x32_bf16 v[122:125], v[138:141], v[146:149], v[122:125]
	v_mfma_f32_16x16x32_bf16 v[118:121], v[130:133], v[166:169], v[118:121]
	v_mfma_f32_16x16x32_bf16 v[114:117], v[138:141], v[166:169], v[114:117]
	v_mfma_f32_16x16x32_bf16 v[110:113], v[130:133], v[174:177], v[110:113]
	v_mfma_f32_16x16x32_bf16 v[106:109], v[138:141], v[174:177], v[106:109]
	v_mfma_f32_16x16x32_bf16 v[102:105], v[130:133], v[182:185], v[102:105]
	v_mfma_f32_16x16x32_bf16 v[98:101], v[138:141], v[182:185], v[98:101]
	v_mfma_f32_16x16x32_bf16 v[126:129], v[134:137], v[150:153], v[126:129]
	v_mfma_f32_16x16x32_bf16 v[122:125], v[142:145], v[150:153], v[122:125]
	v_mfma_f32_16x16x32_bf16 v[118:121], v[134:137], v[170:173], v[118:121]
	v_mfma_f32_16x16x32_bf16 v[114:117], v[142:145], v[170:173], v[114:117]
	v_mfma_f32_16x16x32_bf16 v[110:113], v[134:137], v[178:181], v[110:113]
	v_mfma_f32_16x16x32_bf16 v[106:109], v[142:145], v[178:181], v[106:109]
	v_mfma_f32_16x16x32_bf16 v[102:105], v[134:137], v[186:189], v[102:105]
	v_mfma_f32_16x16x32_bf16 v[98:101], v[142:145], v[186:189], v[98:101]
	s_setprio 0
	ds_read_b128 v[130:133], v193 offset:0
	ds_read_b128 v[134:137], v193 offset:1024
	ds_read_b128 v[138:141], v193 offset:2048
	ds_read_b128 v[142:145], v193 offset:3072
	ds_read_b128 v[146:149], v192 offset:0
	ds_read_b128 v[150:153], v192 offset:1024
	ds_read_b128 v[166:169], v192 offset:2048
	ds_read_b128 v[170:173], v192 offset:3072
	ds_read_b128 v[174:177], v192 offset:4096
	ds_read_b128 v[178:181], v192 offset:5120
	ds_read_b128 v[182:185], v192 offset:6144
	ds_read_b128 v[186:189], v192 offset:7168
	s_waitcnt lgkmcnt(0)
	s_waitcnt vmcnt(8)
	s_barrier
	s_add_i32 m0, s46, 0x0
	s_nop 0
	global_load_lds_dwordx4 v250, s[0:1]
	s_add_i32 m0, s46, 0x2000
	s_nop 0
	global_load_lds_dwordx4 v251, s[0:1]
	s_add_i32 m0, s47, 0x0
	s_nop 0
	global_load_lds_dwordx4 v0, s[16:17]
	s_add_i32 m0, s47, 0x2000
	s_nop 0
	global_load_lds_dwordx4 v154, s[16:17]
	s_add_u32 s0, s0, 0x80
	s_addc_u32 s1, s1, 0
	s_add_u32 s16, s16, 0x80
	s_addc_u32 s17, s17, 0
	s_setprio 3
	s_nop 0
	v_mfma_f32_16x16x32_bf16 v[126:129], v[130:133], v[146:149], v[126:129]
	v_mfma_f32_16x16x32_bf16 v[122:125], v[138:141], v[146:149], v[122:125]
	v_mfma_f32_16x16x32_bf16 v[118:121], v[130:133], v[166:169], v[118:121]
	v_mfma_f32_16x16x32_bf16 v[114:117], v[138:141], v[166:169], v[114:117]
	v_mfma_f32_16x16x32_bf16 v[110:113], v[130:133], v[174:177], v[110:113]
	v_mfma_f32_16x16x32_bf16 v[106:109], v[138:141], v[174:177], v[106:109]
	v_mfma_f32_16x16x32_bf16 v[102:105], v[130:133], v[182:185], v[102:105]
	v_mfma_f32_16x16x32_bf16 v[98:101], v[138:141], v[182:185], v[98:101]
	v_mfma_f32_16x16x32_bf16 v[126:129], v[134:137], v[150:153], v[126:129]
	v_mfma_f32_16x16x32_bf16 v[122:125], v[142:145], v[150:153], v[122:125]
	v_mfma_f32_16x16x32_bf16 v[118:121], v[134:137], v[170:173], v[118:121]
	v_mfma_f32_16x16x32_bf16 v[114:117], v[142:145], v[170:173], v[114:117]
	v_mfma_f32_16x16x32_bf16 v[110:113], v[134:137], v[178:181], v[110:113]
	v_mfma_f32_16x16x32_bf16 v[106:109], v[142:145], v[178:181], v[106:109]
	v_mfma_f32_16x16x32_bf16 v[102:105], v[134:137], v[186:189], v[102:105]
	v_mfma_f32_16x16x32_bf16 v[98:101], v[142:145], v[186:189], v[98:101]
	s_setprio 0
	ds_read_b128 v[130:133], v193 offset:32768
	ds_read_b128 v[134:137], v193 offset:33792
	ds_read_b128 v[138:141], v193 offset:34816
	ds_read_b128 v[142:145], v193 offset:35840
	ds_read_b128 v[146:149], v192 offset:32768
	ds_read_b128 v[150:153], v192 offset:33792
	ds_read_b128 v[166:169], v192 offset:34816
	ds_read_b128 v[170:173], v192 offset:35840
	ds_read_b128 v[174:177], v192 offset:36864
	ds_read_b128 v[178:181], v192 offset:37888
	ds_read_b128 v[182:185], v192 offset:38912
	ds_read_b128 v[186:189], v192 offset:39936
	s_waitcnt lgkmcnt(0)
	s_waitcnt vmcnt(8)
	s_barrier
	s_add_i32 m0, s46, 0x8000
	s_nop 0
	global_load_lds_dwordx4 v250, s[0:1]
	s_add_i32 m0, s46, 0xa000
	s_nop 0
	global_load_lds_dwordx4 v251, s[0:1]
	s_add_i32 m0, s47, 0x8000
	s_nop 0
	global_load_lds_dwordx4 v0, s[16:17]
	s_add_i32 m0, s47, 0xa000
	s_nop 0
	global_load_lds_dwordx4 v154, s[16:17]
	s_add_u32 s0, s0, 0x80
	s_addc_u32 s1, s1, 0
	s_add_u32 s16, s16, 0x80
	s_addc_u32 s17, s17, 0
	s_setprio 3
	s_nop 0
	v_mfma_f32_16x16x32_bf16 v[126:129], v[130:133], v[146:149], v[126:129]
	v_mfma_f32_16x16x32_bf16 v[122:125], v[138:141], v[146:149], v[122:125]
	v_mfma_f32_16x16x32_bf16 v[118:121], v[130:133], v[166:169], v[118:121]
	v_mfma_f32_16x16x32_bf16 v[114:117], v[138:141], v[166:169], v[114:117]
	v_mfma_f32_16x16x32_bf16 v[110:113], v[130:133], v[174:177], v[110:113]
	v_mfma_f32_16x16x32_bf16 v[106:109], v[138:141], v[174:177], v[106:109]
	v_mfma_f32_16x16x32_bf16 v[102:105], v[130:133], v[182:185], v[102:105]
	v_mfma_f32_16x16x32_bf16 v[98:101], v[138:141], v[182:185], v[98:101]
	v_mfma_f32_16x16x32_bf16 v[126:129], v[134:137], v[150:153], v[126:129]
	v_mfma_f32_16x16x32_bf16 v[122:125], v[142:145], v[150:153], v[122:125]
	v_mfma_f32_16x16x32_bf16 v[118:121], v[134:137], v[170:173], v[118:121]
	v_mfma_f32_16x16x32_bf16 v[114:117], v[142:145], v[170:173], v[114:117]
	v_mfma_f32_16x16x32_bf16 v[110:113], v[134:137], v[178:181], v[110:113]
	v_mfma_f32_16x16x32_bf16 v[106:109], v[142:145], v[178:181], v[106:109]
	v_mfma_f32_16x16x32_bf16 v[102:105], v[134:137], v[186:189], v[102:105]
	v_mfma_f32_16x16x32_bf16 v[98:101], v[142:145], v[186:189], v[98:101]
	s_setprio 0
	ds_read_b128 v[130:133], v191 offset:0
	ds_read_b128 v[134:137], v191 offset:1024
	ds_read_b128 v[138:141], v191 offset:2048
	ds_read_b128 v[142:145], v191 offset:3072
	ds_read_b128 v[146:149], v190 offset:0
	ds_read_b128 v[150:153], v190 offset:1024
	ds_read_b128 v[166:169], v190 offset:2048
	ds_read_b128 v[170:173], v190 offset:3072
	ds_read_b128 v[174:177], v190 offset:4096
	ds_read_b128 v[178:181], v190 offset:5120
	ds_read_b128 v[182:185], v190 offset:6144
	ds_read_b128 v[186:189], v190 offset:7168
	s_waitcnt lgkmcnt(0)
	s_waitcnt vmcnt(8)
	s_barrier
	s_setprio 3
	s_nop 0
	v_mfma_f32_16x16x32_bf16 v[126:129], v[130:133], v[146:149], v[126:129]
	v_mfma_f32_16x16x32_bf16 v[122:125], v[138:141], v[146:149], v[122:125]
	v_mfma_f32_16x16x32_bf16 v[118:121], v[130:133], v[166:169], v[118:121]
	v_mfma_f32_16x16x32_bf16 v[114:117], v[138:141], v[166:169], v[114:117]
	v_mfma_f32_16x16x32_bf16 v[110:113], v[130:133], v[174:177], v[110:113]
	v_mfma_f32_16x16x32_bf16 v[106:109], v[138:141], v[174:177], v[106:109]
	v_mfma_f32_16x16x32_bf16 v[102:105], v[130:133], v[182:185], v[102:105]
	v_mfma_f32_16x16x32_bf16 v[98:101], v[138:141], v[182:185], v[98:101]
	v_mfma_f32_16x16x32_bf16 v[126:129], v[134:137], v[150:153], v[126:129]
	v_mfma_f32_16x16x32_bf16 v[122:125], v[142:145], v[150:153], v[122:125]
	v_mfma_f32_16x16x32_bf16 v[118:121], v[134:137], v[170:173], v[118:121]
	v_mfma_f32_16x16x32_bf16 v[114:117], v[142:145], v[170:173], v[114:117]
	v_mfma_f32_16x16x32_bf16 v[110:113], v[134:137], v[178:181], v[110:113]
	v_mfma_f32_16x16x32_bf16 v[106:109], v[142:145], v[178:181], v[106:109]
	v_mfma_f32_16x16x32_bf16 v[102:105], v[134:137], v[186:189], v[102:105]
	v_mfma_f32_16x16x32_bf16 v[98:101], v[142:145], v[186:189], v[98:101]
	s_setprio 0
	ds_read_b128 v[130:133], v191 offset:32768
	ds_read_b128 v[134:137], v191 offset:33792
	ds_read_b128 v[138:141], v191 offset:34816
	ds_read_b128 v[142:145], v191 offset:35840
	ds_read_b128 v[146:149], v190 offset:32768
	ds_read_b128 v[150:153], v190 offset:33792
	ds_read_b128 v[166:169], v190 offset:34816
	ds_read_b128 v[170:173], v190 offset:35840
	ds_read_b128 v[174:177], v190 offset:36864
	ds_read_b128 v[178:181], v190 offset:37888
	ds_read_b128 v[182:185], v190 offset:38912
	ds_read_b128 v[186:189], v190 offset:39936
	s_waitcnt lgkmcnt(0)
	s_waitcnt vmcnt(4)
	s_barrier
	s_setprio 3
	s_nop 0
	v_mfma_f32_16x16x32_bf16 v[126:129], v[130:133], v[146:149], v[126:129]
	v_mfma_f32_16x16x32_bf16 v[122:125], v[138:141], v[146:149], v[122:125]
	v_mfma_f32_16x16x32_bf16 v[118:121], v[130:133], v[166:169], v[118:121]
	v_mfma_f32_16x16x32_bf16 v[114:117], v[138:141], v[166:169], v[114:117]
	v_mfma_f32_16x16x32_bf16 v[110:113], v[130:133], v[174:177], v[110:113]
	v_mfma_f32_16x16x32_bf16 v[106:109], v[138:141], v[174:177], v[106:109]
	v_mfma_f32_16x16x32_bf16 v[102:105], v[130:133], v[182:185], v[102:105]
	v_mfma_f32_16x16x32_bf16 v[98:101], v[138:141], v[182:185], v[98:101]
	v_mfma_f32_16x16x32_bf16 v[126:129], v[134:137], v[150:153], v[126:129]
	v_mfma_f32_16x16x32_bf16 v[122:125], v[142:145], v[150:153], v[122:125]
	v_mfma_f32_16x16x32_bf16 v[118:121], v[134:137], v[170:173], v[118:121]
	v_mfma_f32_16x16x32_bf16 v[114:117], v[142:145], v[170:173], v[114:117]
	v_mfma_f32_16x16x32_bf16 v[110:113], v[134:137], v[178:181], v[110:113]
	v_mfma_f32_16x16x32_bf16 v[106:109], v[142:145], v[178:181], v[106:109]
	v_mfma_f32_16x16x32_bf16 v[102:105], v[134:137], v[186:189], v[102:105]
	v_mfma_f32_16x16x32_bf16 v[98:101], v[142:145], v[186:189], v[98:101]
	s_setprio 0
	ds_read_b128 v[130:133], v193 offset:0
	ds_read_b128 v[134:137], v193 offset:1024
	ds_read_b128 v[138:141], v193 offset:2048
	ds_read_b128 v[142:145], v193 offset:3072
	ds_read_b128 v[146:149], v192 offset:0
	ds_read_b128 v[150:153], v192 offset:1024
	ds_read_b128 v[166:169], v192 offset:2048
	ds_read_b128 v[170:173], v192 offset:3072
	ds_read_b128 v[174:177], v192 offset:4096
	ds_read_b128 v[178:181], v192 offset:5120
	ds_read_b128 v[182:185], v192 offset:6144
	ds_read_b128 v[186:189], v192 offset:7168
	s_waitcnt lgkmcnt(0)
	s_waitcnt vmcnt(0)
	s_barrier
	s_setprio 3
	s_nop 0
	v_mfma_f32_16x16x32_bf16 v[126:129], v[130:133], v[146:149], v[126:129]
	v_mfma_f32_16x16x32_bf16 v[122:125], v[138:141], v[146:149], v[122:125]
	v_mfma_f32_16x16x32_bf16 v[118:121], v[130:133], v[166:169], v[118:121]
	v_mfma_f32_16x16x32_bf16 v[114:117], v[138:141], v[166:169], v[114:117]
	v_mfma_f32_16x16x32_bf16 v[110:113], v[130:133], v[174:177], v[110:113]
	v_mfma_f32_16x16x32_bf16 v[106:109], v[138:141], v[174:177], v[106:109]
	v_mfma_f32_16x16x32_bf16 v[102:105], v[130:133], v[182:185], v[102:105]
	v_mfma_f32_16x16x32_bf16 v[98:101], v[138:141], v[182:185], v[98:101]
	v_mfma_f32_16x16x32_bf16 v[126:129], v[134:137], v[150:153], v[126:129]
	v_mfma_f32_16x16x32_bf16 v[122:125], v[142:145], v[150:153], v[122:125]
	v_mfma_f32_16x16x32_bf16 v[118:121], v[134:137], v[170:173], v[118:121]
	v_mfma_f32_16x16x32_bf16 v[114:117], v[142:145], v[170:173], v[114:117]
	v_mfma_f32_16x16x32_bf16 v[110:113], v[134:137], v[178:181], v[110:113]
	v_mfma_f32_16x16x32_bf16 v[106:109], v[142:145], v[178:181], v[106:109]
	v_mfma_f32_16x16x32_bf16 v[102:105], v[134:137], v[186:189], v[102:105]
	v_mfma_f32_16x16x32_bf16 v[98:101], v[142:145], v[186:189], v[98:101]
	ds_read_b128 v[130:133], v193 offset:32768
	ds_read_b128 v[134:137], v193 offset:33792
	ds_read_b128 v[138:141], v193 offset:34816
	ds_read_b128 v[142:145], v193 offset:35840
	ds_read_b128 v[146:149], v192 offset:32768
	ds_read_b128 v[150:153], v192 offset:33792
	ds_read_b128 v[166:169], v192 offset:34816
	ds_read_b128 v[170:173], v192 offset:35840
	ds_read_b128 v[174:177], v192 offset:36864
	ds_read_b128 v[178:181], v192 offset:37888
	ds_read_b128 v[182:185], v192 offset:38912
	ds_read_b128 v[186:189], v192 offset:39936
	s_waitcnt lgkmcnt(0)
	s_nop 0
	v_mfma_f32_16x16x32_bf16 v[126:129], v[130:133], v[146:149], v[126:129]
	v_mfma_f32_16x16x32_bf16 v[122:125], v[138:141], v[146:149], v[122:125]
	v_mfma_f32_16x16x32_bf16 v[118:121], v[130:133], v[166:169], v[118:121]
	v_mfma_f32_16x16x32_bf16 v[114:117], v[138:141], v[166:169], v[114:117]
	v_mfma_f32_16x16x32_bf16 v[110:113], v[130:133], v[174:177], v[110:113]
	v_mfma_f32_16x16x32_bf16 v[106:109], v[138:141], v[174:177], v[106:109]
	v_mfma_f32_16x16x32_bf16 v[102:105], v[130:133], v[182:185], v[102:105]
	v_mfma_f32_16x16x32_bf16 v[98:101], v[138:141], v[182:185], v[98:101]
	v_mfma_f32_16x16x32_bf16 v[126:129], v[134:137], v[150:153], v[126:129]
	v_mfma_f32_16x16x32_bf16 v[122:125], v[142:145], v[150:153], v[122:125]
	v_mfma_f32_16x16x32_bf16 v[118:121], v[134:137], v[170:173], v[118:121]
	v_mfma_f32_16x16x32_bf16 v[114:117], v[142:145], v[170:173], v[114:117]
	v_mfma_f32_16x16x32_bf16 v[110:113], v[134:137], v[178:181], v[110:113]
	v_mfma_f32_16x16x32_bf16 v[106:109], v[142:145], v[178:181], v[106:109]
	v_mfma_f32_16x16x32_bf16 v[102:105], v[134:137], v[186:189], v[102:105]
	v_mfma_f32_16x16x32_bf16 v[98:101], v[142:145], v[186:189], v[98:101]
	s_setprio 0
	s_nop 7
	s_nop 7
	s_bitcmp1_b32 s98, 0
	s_cbranch_scc1 .Lq_epi
	s_bitcmp1_b32 s98, 1
	s_cbranch_scc0 .Lq_mv1
	v_mov_b32_e32 v34, v98
	v_mov_b32_e32 v35, v99
	v_mov_b32_e32 v36, v100
	v_mov_b32_e32 v37, v101
	v_mov_b32_e32 v38, v102
	v_mov_b32_e32 v39, v103
	v_mov_b32_e32 v40, v104
	v_mov_b32_e32 v41, v105
	v_mov_b32_e32 v42, v106
	v_mov_b32_e32 v43, v107
	v_mov_b32_e32 v44, v108
	v_mov_b32_e32 v45, v109
	v_mov_b32_e32 v46, v110
	v_mov_b32_e32 v47, v111
	v_mov_b32_e32 v48, v112
	v_mov_b32_e32 v49, v113
	v_mov_b32_e32 v50, v114
	v_mov_b32_e32 v51, v115
	v_mov_b32_e32 v52, v116
	v_mov_b32_e32 v53, v117
	v_mov_b32_e32 v54, v118
	v_mov_b32_e32 v55, v119
	v_mov_b32_e32 v56, v120
	v_mov_b32_e32 v57, v121
	v_mov_b32_e32 v58, v122
	v_mov_b32_e32 v59, v123
	v_mov_b32_e32 v60, v124
	v_mov_b32_e32 v61, v125
	v_mov_b32_e32 v62, v126
	v_mov_b32_e32 v63, v127
	v_mov_b32_e32 v64, v128
	v_mov_b32_e32 v65, v129
	v_mov_b32_e32 v98, 0
	v_mov_b32_e32 v99, 0
	v_mov_b32_e32 v100, 0
	v_mov_b32_e32 v101, 0
	v_mov_b32_e32 v102, 0
	v_mov_b32_e32 v103, 0
	v_mov_b32_e32 v104, 0
	v_mov_b32_e32 v105, 0
	v_mov_b32_e32 v106, 0
	v_mov_b32_e32 v107, 0
	v_mov_b32_e32 v108, 0
	v_mov_b32_e32 v109, 0
	v_mov_b32_e32 v110, 0
	v_mov_b32_e32 v111, 0
	v_mov_b32_e32 v112, 0
	v_mov_b32_e32 v113, 0
	v_mov_b32_e32 v114, 0
	v_mov_b32_e32 v115, 0
	v_mov_b32_e32 v116, 0
	v_mov_b32_e32 v117, 0
	v_mov_b32_e32 v118, 0
	v_mov_b32_e32 v119, 0
	v_mov_b32_e32 v120, 0
	v_mov_b32_e32 v121, 0
	v_mov_b32_e32 v122, 0
	v_mov_b32_e32 v123, 0
	v_mov_b32_e32 v124, 0
	v_mov_b32_e32 v125, 0
	v_mov_b32_e32 v126, 0
	v_mov_b32_e32 v127, 0
	v_mov_b32_e32 v128, 0
	v_mov_b32_e32 v129, 0
	s_branch .Lq_epi
